# remove the second (already satisfied) lgkmcnt wait at the head of each GEMM compute segment
# speedup vs baseline: 1.0025x; 1.0025x over previous
; #define PG8_STAGE(bufoff, gbase, voff) do { _Pragma("unroll") for (int _i = 0; _i < 2; ++_i) \
;         __builtin_amdgcn_global_load_lds((const unsigned*)((const char*)(gbase) + (voff)[_i]), (LAS unsigned*)(lds + (bufoff) + ldsw + _i * 8192), 16, 0, 0); } while (0)
; #define PG8_LDA(dst, b, h) do { _Pragma("unroll") for (int m = 0; m < 4; ++m) _Pragma("unroll") for (int k = 0; k < 2; ++k) dst[m][k] = *(const LAS bf16x8*)(lds + PG8_SA(b, h) + aoff + m * 2048 + k * 1024); } while (0)
; #define PG8_LDB(dst, b, h) do { _Pragma("unroll") for (int n = 0; n < 2; ++n) _Pragma("unroll") for (int k = 0; k < 2; ++k) dst[n][k] = *(const LAS bf16x8*)(lds + PG8_SB(b, h) + boff + n * 2048 + k * 1024); } while (0)
; #define PG8_MMA(ai, bj, At, Bt) do { __builtin_amdgcn_s_setprio(1); _Pragma("unroll") for (int m = 0; m < 4; ++m) _Pragma("unroll") for (int n = 0; n < 2; ++n) _Pragma("unroll") for (int k = 0; k < 2; ++k) \
;         acc[ai][bj][m][n] = __builtin_amdgcn_mfma_f32_16x16x32_bf16(Bt[n][k], At[m][k], acc[ai][bj][m][n], 0, 0, 0); __builtin_amdgcn_s_setprio(0); } while (0)
; #define PG8_BAR __builtin_amdgcn_s_barrier()
; template <class Epi, class Sched, bool ALIGN_EPI>
; __device__ __forceinline__ void gemm_phase(LAS unsigned char* lds, const bf16_t* Ab, const bf16_t* Bb, int lda, int ldb, int K, const Sched& S, Epi& E) {
;     ...
;             PG8_LDB(B0, 0, 0); PG8_LDB(B1, 0, 1); PG8_SCHED; PG8_LDA(At, 0, 0); PG8_STAGE(PG8_SA(1, 1), a1 + hstepA, voffA);
;             PG8_WAIT_V(8); PG8_WAIT_L(0); PG8_BAR; PG8_MMA(0, 0, At, B0); PG8_MMA(0, 1, At, B1); PG8_BAR; PG8_SCHED;
;             PG8_LDA(At, 0, 1); PG8_STAGE(PG8_SB(0, 0), b2, voffB); PG8_STAGE(PG8_SB(0, 1), b2 + hstepB, voffB); PG8_STAGE(PG8_SA(0, 0), a2, voffA);
;             PG8_WAIT_V(8); PG8_WAIT_L(0); PG8_BAR; PG8_MMA(1, 0, At, B0); PG8_MMA(1, 1, At, B1); PG8_BAR; PG8_SCHED;
;             PG8_LDB(B0, 1, 0); PG8_LDB(B1, 1, 1); PG8_SCHED; PG8_LDA(At, 1, 0); PG8_STAGE(PG8_SA(0, 1), a2 + hstepA, voffA);
;             PG8_WAIT_V(8); PG8_WAIT_L(0); PG8_BAR; PG8_MMA(0, 0, At, B0); PG8_MMA(0, 1, At, B1); PG8_BAR; PG8_SCHED;
;             PG8_LDA(At, 1, 1); PG8_STAGE(PG8_SB(1, 0), b3, voffB); PG8_STAGE(PG8_SB(1, 1), b3 + hstepB, voffB); PG8_STAGE(PG8_SA(1, 0), a3, voffA);
;             PG8_WAIT_V(8); PG8_WAIT_L(0); PG8_BAR; PG8_MMA(1, 0, At, B0); PG8_MMA(1, 1, At, B1); PG8_BAR; PG8_SCHED;
;         }
.LBB0_527:
	s_add_u32 s62, s54, s60
	s_addc_u32 s63, s55, s61
	s_add_u32 s62, s62, 0x100
	s_addc_u32 s63, s63, 0
	s_add_u32 s80, s25, s60
	s_addc_u32 s81, s31, s61
	s_add_i32 s82, 0, 0x10000
	s_cmpk_eq_i32 s60, 0x700
	s_cselect_b32 s65, s17, s63
	s_cselect_b32 s64, s77, s62
	s_cselect_b32 s63, s53, s81
	s_cselect_b32 s62, s78, s80
	s_add_i32 s83, 0, 0x14000
	v_add_u32_e32 v154, s82, v141
	v_add_u32_e32 v170, s83, v141
	ds_read_b128 v[142:145], v154
	ds_read_b128 v[146:149], v154 offset:1024
	ds_read_b128 v[150:153], v154 offset:2048
	ds_read_b128 v[154:157], v154 offset:3072
	ds_read_b128 v[158:161], v170
	ds_read_b128 v[162:165], v170 offset:1024
	ds_read_b128 v[166:169], v170 offset:2048
	ds_read_b128 v[170:173], v170 offset:3072
	v_add_u32_e32 v190, 0, v140
	v_lshl_add_u64 v[186:187], v[136:137], 0, s[60:61]
	s_add_i32 m0, s44, 0xc000
	ds_read_b128 v[174:177], v190
	ds_read_b128 v[178:181], v190 offset:1024
	ds_read_b128 v[182:185], v190 offset:2048
	ds_read_b128 v[200:203], v190 offset:3072
	ds_read_b128 v[206:209], v190 offset:4096
	ds_read_b128 v[210:213], v190 offset:5120
	ds_read_b128 v[238:241], v190 offset:6144
	ds_read_b128 v[242:245], v190 offset:7168
	global_load_lds_dwordx4 v[186:187], off
	v_lshl_add_u64 v[186:187], v[138:139], 0, s[60:61]
	s_add_i32 m0, s44, 0xe000
	s_nop 0
	global_load_lds_dwordx4 v[186:187], off
	s_waitcnt vmcnt(8)
	s_waitcnt lgkmcnt(0)
	s_barrier
	s_setprio 1
	v_mfma_f32_16x16x32_bf16 v[126:129], v[142:145], v[174:177], v[126:129]
	v_mfma_f32_16x16x32_bf16 v[122:125], v[150:153], v[174:177], v[122:125]
	v_mfma_f32_16x16x32_bf16 v[118:121], v[142:145], v[182:185], v[118:121]
	v_mfma_f32_16x16x32_bf16 v[114:117], v[150:153], v[182:185], v[114:117]
	v_mfma_f32_16x16x32_bf16 v[110:113], v[142:145], v[206:209], v[110:113]
	v_mfma_f32_16x16x32_bf16 v[106:109], v[150:153], v[206:209], v[106:109]
	v_mfma_f32_16x16x32_bf16 v[102:105], v[142:145], v[238:241], v[102:105]
	v_mfma_f32_16x16x32_bf16 v[98:101], v[150:153], v[238:241], v[98:101]
	v_mfma_f32_16x16x32_bf16 v[126:129], v[146:149], v[178:181], v[126:129]
	v_mfma_f32_16x16x32_bf16 v[122:125], v[154:157], v[178:181], v[122:125]
	v_mfma_f32_16x16x32_bf16 v[118:121], v[146:149], v[200:203], v[118:121]
	v_mfma_f32_16x16x32_bf16 v[114:117], v[154:157], v[200:203], v[114:117]
	v_mfma_f32_16x16x32_bf16 v[110:113], v[146:149], v[210:213], v[110:113]
	v_mfma_f32_16x16x32_bf16 v[106:109], v[154:157], v[210:213], v[106:109]
	v_mfma_f32_16x16x32_bf16 v[102:105], v[146:149], v[242:245], v[102:105]
	v_mfma_f32_16x16x32_bf16 v[98:101], v[154:157], v[242:245], v[98:101]
	s_setprio 0
	s_setprio 1
	v_mfma_f32_16x16x32_bf16 v[94:97], v[158:161], v[174:177], v[94:97]
	v_mfma_f32_16x16x32_bf16 v[90:93], v[166:169], v[174:177], v[90:93]
	v_mfma_f32_16x16x32_bf16 v[86:89], v[158:161], v[182:185], v[86:89]
	v_mfma_f32_16x16x32_bf16 v[82:85], v[166:169], v[182:185], v[82:85]
	v_mfma_f32_16x16x32_bf16 v[78:81], v[158:161], v[206:209], v[78:81]
	v_mfma_f32_16x16x32_bf16 v[74:77], v[166:169], v[206:209], v[74:77]
	v_mfma_f32_16x16x32_bf16 v[70:73], v[158:161], v[238:241], v[70:73]
	v_mfma_f32_16x16x32_bf16 v[66:69], v[166:169], v[238:241], v[66:69]
	v_mfma_f32_16x16x32_bf16 v[94:97], v[162:165], v[178:181], v[94:97]
	v_mfma_f32_16x16x32_bf16 v[90:93], v[170:173], v[178:181], v[90:93]
	v_mfma_f32_16x16x32_bf16 v[86:89], v[162:165], v[200:203], v[86:89]
	v_mfma_f32_16x16x32_bf16 v[82:85], v[170:173], v[200:203], v[82:85]
	v_mfma_f32_16x16x32_bf16 v[78:81], v[162:165], v[210:213], v[78:81]
	v_mfma_f32_16x16x32_bf16 v[74:77], v[170:173], v[210:213], v[74:77]
	v_mfma_f32_16x16x32_bf16 v[70:73], v[162:165], v[242:245], v[70:73]
	v_mfma_f32_16x16x32_bf16 v[66:69], v[170:173], v[242:245], v[66:69]
	s_setprio 0
	s_barrier
	s_add_i32 s80, s82, s39
	v_lshl_add_u64 v[186:187], s[62:63], 0, v[134:135]
	s_mov_b32 m0, s80
	ds_read_b128 v[174:177], v190 offset:16384
	ds_read_b128 v[178:181], v190 offset:17408
	ds_read_b128 v[182:185], v190 offset:18432
	ds_read_b128 v[200:203], v190 offset:19456
	ds_read_b128 v[206:209], v190 offset:20480
	ds_read_b128 v[210:213], v190 offset:21504
	ds_read_b128 v[238:241], v190 offset:22528
	ds_read_b128 v[242:245], v190 offset:23552
	global_load_lds_dwordx4 v[186:187], off
	s_add_i32 m0, s80, 0x2000
	s_add_u32 s80, s62, 0x40000
	v_lshl_add_u64 v[188:189], s[62:63], 0, v[132:133]
	s_addc_u32 s81, s63, 0
	s_add_i32 s82, s83, s39
	global_load_lds_dwordx4 v[188:189], off
	v_lshl_add_u64 v[196:197], s[80:81], 0, v[134:135]
	s_mov_b32 m0, s82
	v_lshl_add_u64 v[198:199], s[64:65], 0, v[130:131]
	global_load_lds_dwordx4 v[196:197], off
	v_lshl_add_u64 v[196:197], s[80:81], 0, v[132:133]
	s_add_i32 m0, s82, 0x2000
	s_nop 0
	global_load_lds_dwordx4 v[196:197], off
	v_lshl_add_u64 v[196:197], s[64:65], 0, v[0:1]
	s_mov_b32 m0, s44
	s_nop 0
	global_load_lds_dwordx4 v[196:197], off
	s_mov_b32 m0, s45
	s_nop 0
	global_load_lds_dwordx4 v[198:199], off
	s_waitcnt vmcnt(8)
	s_waitcnt lgkmcnt(0)
	s_barrier
; #define PG8_STAGE(bufoff, gbase, voff) do { _Pragma("unroll") for (int _i = 0; _i < 2; ++_i) \
;         __builtin_amdgcn_global_load_lds((const unsigned*)((const char*)(gbase) + (voff)[_i]), (LAS unsigned*)(lds + (bufoff) + ldsw + _i * 8192), 16, 0, 0); } while (0)
; #define PG8_LDA(dst, b, h) do { _Pragma("unroll") for (int m = 0; m < 4; ++m) _Pragma("unroll") for (int k = 0; k < 2; ++k) dst[m][k] = *(const LAS bf16x8*)(lds + PG8_SA(b, h) + aoff + m * 2048 + k * 1024); } while (0)
; #define PG8_LDB(dst, b, h) do { _Pragma("unroll") for (int n = 0; n < 2; ++n) _Pragma("unroll") for (int k = 0; k < 2; ++k) dst[n][k] = *(const LAS bf16x8*)(lds + PG8_SB(b, h) + boff + n * 2048 + k * 1024); } while (0)
; #define PG8_MMA(ai, bj, At, Bt) do { __builtin_amdgcn_s_setprio(1); _Pragma("unroll") for (int m = 0; m < 4; ++m) _Pragma("unroll") for (int n = 0; n < 2; ++n) _Pragma("unroll") for (int k = 0; k < 2; ++k) \
;         acc[ai][bj][m][n] = __builtin_amdgcn_mfma_f32_16x16x32_bf16(Bt[n][k], At[m][k], acc[ai][bj][m][n], 0, 0, 0); __builtin_amdgcn_s_setprio(0); } while (0)
; #define PG8_BAR __builtin_amdgcn_s_barrier()
; template <class Epi, class Sched, bool ALIGN_EPI>
; __device__ __forceinline__ void gemm_phase(LAS unsigned char* lds, const bf16_t* Ab, const bf16_t* Bb, int lda, int ldb, int K, const Sched& S, Epi& E) {
;     ...
;             PG8_LDB(B0, 0, 0); PG8_LDB(B1, 0, 1); PG8_SCHED; PG8_LDA(At, 0, 0); PG8_STAGE(PG8_SA(1, 1), a1 + hstepA, voffA);
;             PG8_WAIT_V(8); PG8_WAIT_L(0); PG8_BAR; PG8_MMA(0, 0, At, B0); PG8_MMA(0, 1, At, B1); PG8_BAR; PG8_SCHED;
;             PG8_LDA(At, 0, 1); PG8_STAGE(PG8_SB(0, 0), b2, voffB); PG8_STAGE(PG8_SB(0, 1), b2 + hstepB, voffB); PG8_STAGE(PG8_SA(0, 0), a2, voffA);
;             PG8_WAIT_V(8); PG8_WAIT_L(0); PG8_BAR; PG8_MMA(1, 0, At, B0); PG8_MMA(1, 1, At, B1); PG8_BAR; PG8_SCHED;
;             PG8_LDB(B0, 1, 0); PG8_LDB(B1, 1, 1); PG8_SCHED; PG8_LDA(At, 1, 0); PG8_STAGE(PG8_SA(0, 1), a2 + hstepA, voffA);
;             PG8_WAIT_V(8); PG8_WAIT_L(0); PG8_BAR; PG8_MMA(0, 0, At, B0); PG8_MMA(0, 1, At, B1); PG8_BAR; PG8_SCHED;
;             PG8_LDA(At, 1, 1); PG8_STAGE(PG8_SB(1, 0), b3, voffB); PG8_STAGE(PG8_SB(1, 1), b3 + hstepB, voffB); PG8_STAGE(PG8_SA(1, 0), a3, voffA);
;             PG8_WAIT_V(8); PG8_WAIT_L(0); PG8_BAR; PG8_MMA(1, 0, At, B0); PG8_MMA(1, 1, At, B1); PG8_BAR; PG8_SCHED;
;         }
	s_setprio 1
	v_mfma_f32_16x16x32_bf16 v[62:65], v[142:145], v[174:177], v[62:65]
	v_mfma_f32_16x16x32_bf16 v[58:61], v[150:153], v[174:177], v[58:61]
	v_mfma_f32_16x16x32_bf16 v[54:57], v[142:145], v[182:185], v[54:57]
	v_mfma_f32_16x16x32_bf16 v[50:53], v[150:153], v[182:185], v[50:53]
	v_mfma_f32_16x16x32_bf16 v[46:49], v[142:145], v[206:209], v[46:49]
	v_mfma_f32_16x16x32_bf16 v[42:45], v[150:153], v[206:209], v[42:45]
	v_mfma_f32_16x16x32_bf16 v[38:41], v[142:145], v[238:241], v[38:41]
	v_mfma_f32_16x16x32_bf16 v[34:37], v[150:153], v[238:241], v[34:37]
	v_mfma_f32_16x16x32_bf16 v[62:65], v[146:149], v[178:181], v[62:65]
	v_mfma_f32_16x16x32_bf16 v[58:61], v[154:157], v[178:181], v[58:61]
	v_mfma_f32_16x16x32_bf16 v[54:57], v[146:149], v[200:203], v[54:57]
	v_mfma_f32_16x16x32_bf16 v[50:53], v[154:157], v[200:203], v[50:53]
	v_mfma_f32_16x16x32_bf16 v[46:49], v[146:149], v[210:213], v[46:49]
	v_mfma_f32_16x16x32_bf16 v[42:45], v[154:157], v[210:213], v[42:45]
	v_mfma_f32_16x16x32_bf16 v[38:41], v[146:149], v[242:245], v[38:41]
	v_mfma_f32_16x16x32_bf16 v[34:37], v[154:157], v[242:245], v[34:37]
	s_setprio 0
	s_setprio 1
	v_mfma_f32_16x16x32_bf16 v[30:33], v[158:161], v[174:177], v[30:33]
	v_mfma_f32_16x16x32_bf16 v[26:29], v[166:169], v[174:177], v[26:29]
	v_mfma_f32_16x16x32_bf16 v[22:25], v[158:161], v[182:185], v[22:25]
	v_mfma_f32_16x16x32_bf16 v[18:21], v[166:169], v[182:185], v[18:21]
	v_mfma_f32_16x16x32_bf16 v[14:17], v[158:161], v[206:209], v[14:17]
	v_mfma_f32_16x16x32_bf16 v[10:13], v[166:169], v[206:209], v[10:13]
	v_mfma_f32_16x16x32_bf16 v[6:9], v[158:161], v[238:241], v[6:9]
	v_mfma_f32_16x16x32_bf16 v[2:5], v[166:169], v[238:241], v[2:5]
	v_mfma_f32_16x16x32_bf16 v[30:33], v[162:165], v[178:181], v[30:33]
	v_mfma_f32_16x16x32_bf16 v[26:29], v[170:173], v[178:181], v[26:29]
	v_mfma_f32_16x16x32_bf16 v[22:25], v[162:165], v[200:203], v[22:25]
	v_mfma_f32_16x16x32_bf16 v[18:21], v[170:173], v[200:203], v[18:21]
	v_mfma_f32_16x16x32_bf16 v[14:17], v[162:165], v[210:213], v[14:17]
	v_mfma_f32_16x16x32_bf16 v[10:13], v[170:173], v[210:213], v[10:13]
	v_mfma_f32_16x16x32_bf16 v[6:9], v[162:165], v[242:245], v[6:9]
	v_mfma_f32_16x16x32_bf16 v[2:5], v[170:173], v[242:245], v[2:5]
	s_setprio 0
	s_barrier
	s_add_i32 s80, 0, 0x18000
	s_add_i32 s81, 0, 0x1c000
	v_add_u32_e32 v154, s80, v141
	v_add_u32_e32 v170, s81, v141
	ds_read_b128 v[142:145], v154
	ds_read_b128 v[146:149], v154 offset:1024
	ds_read_b128 v[150:153], v154 offset:2048
	ds_read_b128 v[154:157], v154 offset:3072
	ds_read_b128 v[158:161], v170
	ds_read_b128 v[162:165], v170 offset:1024
	ds_read_b128 v[166:169], v170 offset:2048
	ds_read_b128 v[170:173], v170 offset:3072
	s_add_u32 s64, s64, 0x40000
	s_addc_u32 s65, s65, 0
	s_mov_b32 m0, s49
	v_lshl_add_u64 v[220:221], s[64:65], 0, v[0:1]
	ds_read_b128 v[174:177], v190 offset:32768
	ds_read_b128 v[178:181], v190 offset:33792
	ds_read_b128 v[182:185], v190 offset:34816
	ds_read_b128 v[200:203], v190 offset:35840
	ds_read_b128 v[206:209], v190 offset:36864
	ds_read_b128 v[210:213], v190 offset:37888
	ds_read_b128 v[238:241], v190 offset:38912
	ds_read_b128 v[242:245], v190 offset:39936
	global_load_lds_dwordx4 v[220:221], off
	v_lshl_add_u64 v[220:221], s[64:65], 0, v[130:131]
	s_mov_b32 m0, s66
	s_nop 0
	global_load_lds_dwordx4 v[220:221], off
	s_waitcnt vmcnt(8)
	s_waitcnt lgkmcnt(0)
	s_barrier
	s_setprio 1
	v_mfma_f32_16x16x32_bf16 v[126:129], v[142:145], v[174:177], v[126:129]
	v_mfma_f32_16x16x32_bf16 v[122:125], v[150:153], v[174:177], v[122:125]
	v_mfma_f32_16x16x32_bf16 v[118:121], v[142:145], v[182:185], v[118:121]
	v_mfma_f32_16x16x32_bf16 v[114:117], v[150:153], v[182:185], v[114:117]
	v_mfma_f32_16x16x32_bf16 v[110:113], v[142:145], v[206:209], v[110:113]
	v_mfma_f32_16x16x32_bf16 v[106:109], v[150:153], v[206:209], v[106:109]
	v_mfma_f32_16x16x32_bf16 v[102:105], v[142:145], v[238:241], v[102:105]
	v_mfma_f32_16x16x32_bf16 v[98:101], v[150:153], v[238:241], v[98:101]
	v_mfma_f32_16x16x32_bf16 v[126:129], v[146:149], v[178:181], v[126:129]
	v_mfma_f32_16x16x32_bf16 v[122:125], v[154:157], v[178:181], v[122:125]
	v_mfma_f32_16x16x32_bf16 v[118:121], v[146:149], v[200:203], v[118:121]
	v_mfma_f32_16x16x32_bf16 v[114:117], v[154:157], v[200:203], v[114:117]
	v_mfma_f32_16x16x32_bf16 v[110:113], v[146:149], v[210:213], v[110:113]
	v_mfma_f32_16x16x32_bf16 v[106:109], v[154:157], v[210:213], v[106:109]
	v_mfma_f32_16x16x32_bf16 v[102:105], v[146:149], v[242:245], v[102:105]
	v_mfma_f32_16x16x32_bf16 v[98:101], v[154:157], v[242:245], v[98:101]
	s_setprio 0
	s_setprio 1
	v_mfma_f32_16x16x32_bf16 v[94:97], v[158:161], v[174:177], v[94:97]
	v_mfma_f32_16x16x32_bf16 v[90:93], v[166:169], v[174:177], v[90:93]
	v_mfma_f32_16x16x32_bf16 v[86:89], v[158:161], v[182:185], v[86:89]
	v_mfma_f32_16x16x32_bf16 v[82:85], v[166:169], v[182:185], v[82:85]
	v_mfma_f32_16x16x32_bf16 v[78:81], v[158:161], v[206:209], v[78:81]
	v_mfma_f32_16x16x32_bf16 v[74:77], v[166:169], v[206:209], v[74:77]
	v_mfma_f32_16x16x32_bf16 v[70:73], v[158:161], v[238:241], v[70:73]
	v_mfma_f32_16x16x32_bf16 v[66:69], v[166:169], v[238:241], v[66:69]
	v_mfma_f32_16x16x32_bf16 v[94:97], v[162:165], v[178:181], v[94:97]
	v_mfma_f32_16x16x32_bf16 v[90:93], v[170:173], v[178:181], v[90:93]
	v_mfma_f32_16x16x32_bf16 v[86:89], v[162:165], v[200:203], v[86:89]
	v_mfma_f32_16x16x32_bf16 v[82:85], v[170:173], v[200:203], v[82:85]
	v_mfma_f32_16x16x32_bf16 v[78:81], v[162:165], v[210:213], v[78:81]
	v_mfma_f32_16x16x32_bf16 v[74:77], v[170:173], v[210:213], v[74:77]
	v_mfma_f32_16x16x32_bf16 v[70:73], v[162:165], v[242:245], v[70:73]
	v_mfma_f32_16x16x32_bf16 v[66:69], v[170:173], v[242:245], v[66:69]
	s_setprio 0
	s_barrier
; #define PG8_STAGE(bufoff, gbase, voff) do { _Pragma("unroll") for (int _i = 0; _i < 2; ++_i) \
;         __builtin_amdgcn_global_load_lds((const unsigned*)((const char*)(gbase) + (voff)[_i]), (LAS unsigned*)(lds + (bufoff) + ldsw + _i * 8192), 16, 0, 0); } while (0)
; #define PG8_LDA(dst, b, h) do { _Pragma("unroll") for (int m = 0; m < 4; ++m) _Pragma("unroll") for (int k = 0; k < 2; ++k) dst[m][k] = *(const LAS bf16x8*)(lds + PG8_SA(b, h) + aoff + m * 2048 + k * 1024); } while (0)
; #define PG8_LDB(dst, b, h) do { _Pragma("unroll") for (int n = 0; n < 2; ++n) _Pragma("unroll") for (int k = 0; k < 2; ++k) dst[n][k] = *(const LAS bf16x8*)(lds + PG8_SB(b, h) + boff + n * 2048 + k * 1024); } while (0)
; #define PG8_MMA(ai, bj, At, Bt) do { __builtin_amdgcn_s_setprio(1); _Pragma("unroll") for (int m = 0; m < 4; ++m) _Pragma("unroll") for (int n = 0; n < 2; ++n) _Pragma("unroll") for (int k = 0; k < 2; ++k) \
;         acc[ai][bj][m][n] = __builtin_amdgcn_mfma_f32_16x16x32_bf16(Bt[n][k], At[m][k], acc[ai][bj][m][n], 0, 0, 0); __builtin_amdgcn_s_setprio(0); } while (0)
; #define PG8_BAR __builtin_amdgcn_s_barrier()
; template <class Epi, class Sched, bool ALIGN_EPI>
; __device__ __forceinline__ void gemm_phase(LAS unsigned char* lds, const bf16_t* Ab, const bf16_t* Bb, int lda, int ldb, int K, const Sched& S, Epi& E) {
;     ...
;             PG8_LDB(B0, 0, 0); PG8_LDB(B1, 0, 1); PG8_SCHED; PG8_LDA(At, 0, 0); PG8_STAGE(PG8_SA(1, 1), a1 + hstepA, voffA);
;             PG8_WAIT_V(8); PG8_WAIT_L(0); PG8_BAR; PG8_MMA(0, 0, At, B0); PG8_MMA(0, 1, At, B1); PG8_BAR; PG8_SCHED;
;             PG8_LDA(At, 0, 1); PG8_STAGE(PG8_SB(0, 0), b2, voffB); PG8_STAGE(PG8_SB(0, 1), b2 + hstepB, voffB); PG8_STAGE(PG8_SA(0, 0), a2, voffA);
;             PG8_WAIT_V(8); PG8_WAIT_L(0); PG8_BAR; PG8_MMA(1, 0, At, B0); PG8_MMA(1, 1, At, B1); PG8_BAR; PG8_SCHED;
;             PG8_LDB(B0, 1, 0); PG8_LDB(B1, 1, 1); PG8_SCHED; PG8_LDA(At, 1, 0); PG8_STAGE(PG8_SA(0, 1), a2 + hstepA, voffA);
;             PG8_WAIT_V(8); PG8_WAIT_L(0); PG8_BAR; PG8_MMA(0, 0, At, B0); PG8_MMA(0, 1, At, B1); PG8_BAR; PG8_SCHED;
;             PG8_LDA(At, 1, 1); PG8_STAGE(PG8_SB(1, 0), b3, voffB); PG8_STAGE(PG8_SB(1, 1), b3 + hstepB, voffB); PG8_STAGE(PG8_SA(1, 0), a3, voffA);
;             PG8_WAIT_V(8); PG8_WAIT_L(0); PG8_BAR; PG8_MMA(1, 0, At, B0); PG8_MMA(1, 1, At, B1); PG8_BAR; PG8_SCHED;
;         }
	s_add_i32 s64, s80, s39
	v_lshl_add_u64 v[186:187], v[186:187], 0, s[26:27]
	s_mov_b32 m0, s64
	ds_read_b128 v[174:177], v190 offset:49152
	ds_read_b128 v[178:181], v190 offset:50176
	ds_read_b128 v[182:185], v190 offset:51200
	ds_read_b128 v[200:203], v190 offset:52224
	ds_read_b128 v[206:209], v190 offset:53248
	ds_read_b128 v[210:213], v190 offset:54272
	ds_read_b128 v[238:241], v190 offset:55296
	ds_read_b128 v[242:245], v190 offset:56320
	global_load_lds_dwordx4 v[186:187], off
	s_add_i32 m0, s64, 0x2000
	s_add_u32 s62, s62, 0x40080
	v_lshl_add_u64 v[186:187], v[188:189], 0, s[26:27]
	s_addc_u32 s63, s63, 0
	s_add_i32 s64, s81, s39
	global_load_lds_dwordx4 v[186:187], off
	v_lshl_add_u64 v[186:187], s[62:63], 0, v[134:135]
	s_mov_b32 m0, s64
	s_nop 0
	global_load_lds_dwordx4 v[186:187], off
	v_lshl_add_u64 v[186:187], s[62:63], 0, v[132:133]
	s_add_i32 m0, s64, 0x2000
	s_nop 0
	global_load_lds_dwordx4 v[186:187], off
	v_lshl_add_u64 v[186:187], v[196:197], 0, s[26:27]
	s_mov_b32 m0, s70
	s_nop 0
	global_load_lds_dwordx4 v[186:187], off
	v_lshl_add_u64 v[186:187], v[198:199], 0, s[26:27]
	s_mov_b32 m0, s71
	s_nop 0
	global_load_lds_dwordx4 v[186:187], off
	s_waitcnt vmcnt(8)
	s_waitcnt lgkmcnt(0)
	s_barrier
	s_setprio 1
	v_mfma_f32_16x16x32_bf16 v[62:65], v[142:145], v[174:177], v[62:65]
	v_mfma_f32_16x16x32_bf16 v[58:61], v[150:153], v[174:177], v[58:61]
	v_mfma_f32_16x16x32_bf16 v[54:57], v[142:145], v[182:185], v[54:57]
	v_mfma_f32_16x16x32_bf16 v[50:53], v[150:153], v[182:185], v[50:53]
	v_mfma_f32_16x16x32_bf16 v[46:49], v[142:145], v[206:209], v[46:49]
	v_mfma_f32_16x16x32_bf16 v[42:45], v[150:153], v[206:209], v[42:45]
	v_mfma_f32_16x16x32_bf16 v[38:41], v[142:145], v[238:241], v[38:41]
	v_mfma_f32_16x16x32_bf16 v[34:37], v[150:153], v[238:241], v[34:37]
	v_mfma_f32_16x16x32_bf16 v[62:65], v[146:149], v[178:181], v[62:65]
	v_mfma_f32_16x16x32_bf16 v[58:61], v[154:157], v[178:181], v[58:61]
	v_mfma_f32_16x16x32_bf16 v[54:57], v[146:149], v[200:203], v[54:57]
	v_mfma_f32_16x16x32_bf16 v[50:53], v[154:157], v[200:203], v[50:53]
	v_mfma_f32_16x16x32_bf16 v[46:49], v[146:149], v[210:213], v[46:49]
	v_mfma_f32_16x16x32_bf16 v[42:45], v[154:157], v[210:213], v[42:45]
	v_mfma_f32_16x16x32_bf16 v[38:41], v[146:149], v[242:245], v[38:41]
	v_mfma_f32_16x16x32_bf16 v[34:37], v[154:157], v[242:245], v[34:37]
	s_setprio 0
	s_setprio 1
	v_mfma_f32_16x16x32_bf16 v[30:33], v[158:161], v[174:177], v[30:33]
	v_mfma_f32_16x16x32_bf16 v[26:29], v[166:169], v[174:177], v[26:29]
	v_mfma_f32_16x16x32_bf16 v[22:25], v[158:161], v[182:185], v[22:25]
	v_mfma_f32_16x16x32_bf16 v[18:21], v[166:169], v[182:185], v[18:21]
	v_mfma_f32_16x16x32_bf16 v[14:17], v[158:161], v[206:209], v[14:17]
	v_mfma_f32_16x16x32_bf16 v[10:13], v[166:169], v[206:209], v[10:13]
	v_mfma_f32_16x16x32_bf16 v[6:9], v[158:161], v[238:241], v[6:9]
	v_mfma_f32_16x16x32_bf16 v[2:5], v[166:169], v[238:241], v[2:5]
	v_mfma_f32_16x16x32_bf16 v[30:33], v[162:165], v[178:181], v[30:33]
	v_mfma_f32_16x16x32_bf16 v[26:29], v[170:173], v[178:181], v[26:29]
	v_mfma_f32_16x16x32_bf16 v[22:25], v[162:165], v[200:203], v[22:25]
	v_mfma_f32_16x16x32_bf16 v[18:21], v[170:173], v[200:203], v[18:21]
	v_mfma_f32_16x16x32_bf16 v[14:17], v[162:165], v[210:213], v[14:17]
	v_mfma_f32_16x16x32_bf16 v[10:13], v[170:173], v[210:213], v[10:13]
	v_mfma_f32_16x16x32_bf16 v[6:9], v[162:165], v[242:245], v[6:9]
	v_mfma_f32_16x16x32_bf16 v[2:5], v[170:173], v[242:245], v[2:5]
	s_setprio 0
	s_barrier
	s_add_i32 s79, s79, 2
	s_add_u32 s60, s60, 0x100
	s_addc_u32 s61, s61, 0
	s_cmp_gt_u32 s79, 13
	s_cbranch_scc0 .LBB0_527
	s_and_b64 vcc, exec, s[14:15]
	s_cbranch_vccz .LBB0_530
	s_barrier

; #define PG8_STAGE(bufoff, gbase, voff) do { _Pragma("unroll") for (int _i = 0; _i < 2; ++_i) \
;         __builtin_amdgcn_global_load_lds((const unsigned*)((const char*)(gbase) + (voff)[_i]), (LAS unsigned*)(lds + (bufoff) + ldsw + _i * 8192), 16, 0, 0); } while (0)
; #define PG8_LDA(dst, b, h) do { _Pragma("unroll") for (int m = 0; m < 4; ++m) _Pragma("unroll") for (int k = 0; k < 2; ++k) dst[m][k] = *(const LAS bf16x8*)(lds + PG8_SA(b, h) + aoff + m * 2048 + k * 1024); } while (0)
; #define PG8_LDB(dst, b, h) do { _Pragma("unroll") for (int n = 0; n < 2; ++n) _Pragma("unroll") for (int k = 0; k < 2; ++k) dst[n][k] = *(const LAS bf16x8*)(lds + PG8_SB(b, h) + boff + n * 2048 + k * 1024); } while (0)
; #define PG8_MMA(ai, bj, At, Bt) do { __builtin_amdgcn_s_setprio(1); _Pragma("unroll") for (int m = 0; m < 4; ++m) _Pragma("unroll") for (int n = 0; n < 2; ++n) _Pragma("unroll") for (int k = 0; k < 2; ++k) \
;         acc[ai][bj][m][n] = __builtin_amdgcn_mfma_f32_16x16x32_bf16(Bt[n][k], At[m][k], acc[ai][bj][m][n], 0, 0, 0); __builtin_amdgcn_s_setprio(0); } while (0)
; #define PG8_BAR __builtin_amdgcn_s_barrier()
; template <class Epi, class Sched, bool ALIGN_EPI>
; __device__ __forceinline__ void gemm_phase(LAS unsigned char* lds, const bf16_t* Ab, const bf16_t* Bb, int lda, int ldb, int K, const Sched& S, Epi& E) {
;     ...
;             PG8_LDB(B0, 0, 0); PG8_LDB(B1, 0, 1); PG8_SCHED; PG8_LDA(At, 0, 0); PG8_STAGE(PG8_SA(1, 1), a1 + hstepA, voffA);
;             PG8_WAIT_V(8); PG8_WAIT_L(0); PG8_BAR; PG8_MMA(0, 0, At, B0); PG8_MMA(0, 1, At, B1); PG8_BAR; PG8_SCHED;
;             PG8_LDA(At, 0, 1); PG8_STAGE(PG8_SB(0, 0), b2, voffB); PG8_STAGE(PG8_SB(0, 1), b2 + hstepB, voffB); PG8_STAGE(PG8_SA(0, 0), a2, voffA);
;             PG8_WAIT_V(8); PG8_WAIT_L(0); PG8_BAR; PG8_MMA(1, 0, At, B0); PG8_MMA(1, 1, At, B1); PG8_BAR; PG8_SCHED;
;             PG8_LDB(B0, 1, 0); PG8_LDB(B1, 1, 1); PG8_SCHED; PG8_LDA(At, 1, 0); PG8_STAGE(PG8_SA(0, 1), a2 + hstepA, voffA);
;             PG8_WAIT_V(8); PG8_WAIT_L(0); PG8_BAR; PG8_MMA(0, 0, At, B0); PG8_MMA(0, 1, At, B1); PG8_BAR; PG8_SCHED;
;             PG8_LDA(At, 1, 1); PG8_STAGE(PG8_SB(1, 0), b3, voffB); PG8_STAGE(PG8_SB(1, 1), b3 + hstepB, voffB); PG8_STAGE(PG8_SA(1, 0), a3, voffA);
;             PG8_WAIT_V(8); PG8_WAIT_L(0); PG8_BAR; PG8_MMA(1, 0, At, B0); PG8_MMA(1, 1, At, B1); PG8_BAR; PG8_SCHED;
;         }
.LBB0_607:
	s_add_u32 s60, s58, 0xfff50080
	s_addc_u32 s61, s59, -1
	s_add_i32 s80, 0, 0x10000
	s_cmp_eq_u32 s79, 40
	s_cselect_b32 s63, s17, s61
	s_cselect_b32 s62, s18, s60
	s_cselect_b32 s61, s25, s78
	s_cselect_b32 s60, s53, s77
	s_add_i32 s82, 0, 0x14000
	v_add_u32_e32 v150, s80, v136
	v_add_u32_e32 v166, s82, v136
	ds_read_b128 v[138:141], v150
	ds_read_b128 v[142:145], v150 offset:1024
	ds_read_b128 v[146:149], v150 offset:2048
	ds_read_b128 v[150:153], v150 offset:3072
	ds_read_b128 v[154:157], v166
	ds_read_b128 v[158:161], v166 offset:1024
	ds_read_b128 v[162:165], v166 offset:2048
	ds_read_b128 v[166:169], v166 offset:3072
	v_lshl_add_u64 v[186:187], s[58:59], 0, v[0:1]
	s_add_i32 m0, s33, 0xc000
	ds_read_b128 v[170:173], v137
	ds_read_b128 v[174:177], v137 offset:1024
	ds_read_b128 v[178:181], v137 offset:2048
	ds_read_b128 v[182:185], v137 offset:3072
	ds_read_b128 v[200:203], v137 offset:4096
	ds_read_b128 v[206:209], v137 offset:5120
	ds_read_b128 v[210:213], v137 offset:6144
	ds_read_b128 v[238:241], v137 offset:7168
	global_load_lds_dwordx4 v[186:187], off
	v_lshl_add_u64 v[186:187], s[58:59], 0, v[132:133]
	s_add_i32 m0, s33, 0xe000
	s_nop 0
	global_load_lds_dwordx4 v[186:187], off
	s_waitcnt vmcnt(8)
	s_waitcnt lgkmcnt(0)
	s_barrier
	s_setprio 1
	v_mfma_f32_16x16x32_bf16 v[126:129], v[138:141], v[170:173], v[126:129]
	v_mfma_f32_16x16x32_bf16 v[122:125], v[146:149], v[170:173], v[122:125]
	v_mfma_f32_16x16x32_bf16 v[110:113], v[138:141], v[178:181], v[110:113]
	v_mfma_f32_16x16x32_bf16 v[106:109], v[146:149], v[178:181], v[106:109]
	v_mfma_f32_16x16x32_bf16 v[94:97], v[138:141], v[200:203], v[94:97]
	v_mfma_f32_16x16x32_bf16 v[90:93], v[146:149], v[200:203], v[90:93]
	v_mfma_f32_16x16x32_bf16 v[78:81], v[138:141], v[210:213], v[78:81]
	v_mfma_f32_16x16x32_bf16 v[74:77], v[146:149], v[210:213], v[74:77]
	v_mfma_f32_16x16x32_bf16 v[126:129], v[142:145], v[174:177], v[126:129]
	v_mfma_f32_16x16x32_bf16 v[122:125], v[150:153], v[174:177], v[122:125]
	v_mfma_f32_16x16x32_bf16 v[110:113], v[142:145], v[182:185], v[110:113]
	v_mfma_f32_16x16x32_bf16 v[106:109], v[150:153], v[182:185], v[106:109]
	v_mfma_f32_16x16x32_bf16 v[94:97], v[142:145], v[206:209], v[94:97]
	v_mfma_f32_16x16x32_bf16 v[90:93], v[150:153], v[206:209], v[90:93]
	v_mfma_f32_16x16x32_bf16 v[78:81], v[142:145], v[238:241], v[78:81]
	v_mfma_f32_16x16x32_bf16 v[74:77], v[150:153], v[238:241], v[74:77]
	s_setprio 0
	s_setprio 1
	v_mfma_f32_16x16x32_bf16 v[118:121], v[154:157], v[170:173], v[118:121]
	v_mfma_f32_16x16x32_bf16 v[114:117], v[162:165], v[170:173], v[114:117]
	v_mfma_f32_16x16x32_bf16 v[102:105], v[154:157], v[178:181], v[102:105]
	v_mfma_f32_16x16x32_bf16 v[98:101], v[162:165], v[178:181], v[98:101]
	v_mfma_f32_16x16x32_bf16 v[86:89], v[154:157], v[200:203], v[86:89]
	v_mfma_f32_16x16x32_bf16 v[82:85], v[162:165], v[200:203], v[82:85]
	v_mfma_f32_16x16x32_bf16 v[70:73], v[154:157], v[210:213], v[70:73]
	v_mfma_f32_16x16x32_bf16 v[66:69], v[162:165], v[210:213], v[66:69]
	v_mfma_f32_16x16x32_bf16 v[118:121], v[158:161], v[174:177], v[118:121]
	v_mfma_f32_16x16x32_bf16 v[114:117], v[166:169], v[174:177], v[114:117]
	v_mfma_f32_16x16x32_bf16 v[102:105], v[158:161], v[182:185], v[102:105]
	v_mfma_f32_16x16x32_bf16 v[98:101], v[166:169], v[182:185], v[98:101]
	v_mfma_f32_16x16x32_bf16 v[86:89], v[158:161], v[206:209], v[86:89]
	v_mfma_f32_16x16x32_bf16 v[82:85], v[166:169], v[206:209], v[82:85]
	v_mfma_f32_16x16x32_bf16 v[70:73], v[158:161], v[238:241], v[70:73]
	v_mfma_f32_16x16x32_bf16 v[66:69], v[166:169], v[238:241], v[66:69]
	s_setprio 0
	s_barrier
	s_add_i32 s80, s80, s24
	v_lshl_add_u64 v[186:187], s[60:61], 0, v[130:131]
	s_mov_b32 m0, s80
	ds_read_b128 v[170:173], v137 offset:16384
	ds_read_b128 v[174:177], v137 offset:17408
	ds_read_b128 v[178:181], v137 offset:18432
	ds_read_b128 v[182:185], v137 offset:19456
	ds_read_b128 v[200:203], v137 offset:20480
	ds_read_b128 v[206:209], v137 offset:21504
	ds_read_b128 v[210:213], v137 offset:22528
	ds_read_b128 v[238:241], v137 offset:23552
	global_load_lds_dwordx4 v[186:187], off
	s_add_i32 m0, s80, 0x2000
	s_add_u32 s80, s60, 0xb0000
	v_lshl_add_u64 v[188:189], s[60:61], 0, v[134:135]
	s_addc_u32 s81, s61, 0
	s_add_i32 s82, s82, s24
	global_load_lds_dwordx4 v[188:189], off
	v_lshl_add_u64 v[196:197], s[80:81], 0, v[130:131]
	s_mov_b32 m0, s82
	v_lshl_add_u64 v[198:199], s[62:63], 0, v[132:133]
	global_load_lds_dwordx4 v[196:197], off
	v_lshl_add_u64 v[196:197], s[80:81], 0, v[134:135]
	s_add_i32 m0, s82, 0x2000
	s_nop 0
	global_load_lds_dwordx4 v[196:197], off
	v_lshl_add_u64 v[196:197], s[62:63], 0, v[0:1]
	s_mov_b32 m0, s33
	s_nop 0
	global_load_lds_dwordx4 v[196:197], off
	s_mov_b32 m0, s31
	s_nop 0
	global_load_lds_dwordx4 v[198:199], off
	s_waitcnt vmcnt(8)
	s_waitcnt lgkmcnt(0)
	s_barrier
; #define PG8_STAGE(bufoff, gbase, voff) do { _Pragma("unroll") for (int _i = 0; _i < 2; ++_i) \
;         __builtin_amdgcn_global_load_lds((const unsigned*)((const char*)(gbase) + (voff)[_i]), (LAS unsigned*)(lds + (bufoff) + ldsw + _i * 8192), 16, 0, 0); } while (0)
; #define PG8_LDA(dst, b, h) do { _Pragma("unroll") for (int m = 0; m < 4; ++m) _Pragma("unroll") for (int k = 0; k < 2; ++k) dst[m][k] = *(const LAS bf16x8*)(lds + PG8_SA(b, h) + aoff + m * 2048 + k * 1024); } while (0)
; #define PG8_LDB(dst, b, h) do { _Pragma("unroll") for (int n = 0; n < 2; ++n) _Pragma("unroll") for (int k = 0; k < 2; ++k) dst[n][k] = *(const LAS bf16x8*)(lds + PG8_SB(b, h) + boff + n * 2048 + k * 1024); } while (0)
; #define PG8_MMA(ai, bj, At, Bt) do { __builtin_amdgcn_s_setprio(1); _Pragma("unroll") for (int m = 0; m < 4; ++m) _Pragma("unroll") for (int n = 0; n < 2; ++n) _Pragma("unroll") for (int k = 0; k < 2; ++k) \
;         acc[ai][bj][m][n] = __builtin_amdgcn_mfma_f32_16x16x32_bf16(Bt[n][k], At[m][k], acc[ai][bj][m][n], 0, 0, 0); __builtin_amdgcn_s_setprio(0); } while (0)
; #define PG8_BAR __builtin_amdgcn_s_barrier()
; template <class Epi, class Sched, bool ALIGN_EPI>
; __device__ __forceinline__ void gemm_phase(LAS unsigned char* lds, const bf16_t* Ab, const bf16_t* Bb, int lda, int ldb, int K, const Sched& S, Epi& E) {
;     ...
;             PG8_LDB(B0, 0, 0); PG8_LDB(B1, 0, 1); PG8_SCHED; PG8_LDA(At, 0, 0); PG8_STAGE(PG8_SA(1, 1), a1 + hstepA, voffA);
;             PG8_WAIT_V(8); PG8_WAIT_L(0); PG8_BAR; PG8_MMA(0, 0, At, B0); PG8_MMA(0, 1, At, B1); PG8_BAR; PG8_SCHED;
;             PG8_LDA(At, 0, 1); PG8_STAGE(PG8_SB(0, 0), b2, voffB); PG8_STAGE(PG8_SB(0, 1), b2 + hstepB, voffB); PG8_STAGE(PG8_SA(0, 0), a2, voffA);
;             PG8_WAIT_V(8); PG8_WAIT_L(0); PG8_BAR; PG8_MMA(1, 0, At, B0); PG8_MMA(1, 1, At, B1); PG8_BAR; PG8_SCHED;
;             PG8_LDB(B0, 1, 0); PG8_LDB(B1, 1, 1); PG8_SCHED; PG8_LDA(At, 1, 0); PG8_STAGE(PG8_SA(0, 1), a2 + hstepA, voffA);
;             PG8_WAIT_V(8); PG8_WAIT_L(0); PG8_BAR; PG8_MMA(0, 0, At, B0); PG8_MMA(0, 1, At, B1); PG8_BAR; PG8_SCHED;
;             PG8_LDA(At, 1, 1); PG8_STAGE(PG8_SB(1, 0), b3, voffB); PG8_STAGE(PG8_SB(1, 1), b3 + hstepB, voffB); PG8_STAGE(PG8_SA(1, 0), a3, voffA);
;             PG8_WAIT_V(8); PG8_WAIT_L(0); PG8_BAR; PG8_MMA(1, 0, At, B0); PG8_MMA(1, 1, At, B1); PG8_BAR; PG8_SCHED;
;         }
	s_setprio 1
	v_mfma_f32_16x16x32_bf16 v[62:65], v[138:141], v[170:173], v[62:65]
	v_mfma_f32_16x16x32_bf16 v[58:61], v[146:149], v[170:173], v[58:61]
	v_mfma_f32_16x16x32_bf16 v[46:49], v[138:141], v[178:181], v[46:49]
	v_mfma_f32_16x16x32_bf16 v[42:45], v[146:149], v[178:181], v[42:45]
	v_mfma_f32_16x16x32_bf16 v[30:33], v[138:141], v[200:203], v[30:33]
	v_mfma_f32_16x16x32_bf16 v[26:29], v[146:149], v[200:203], v[26:29]
	v_mfma_f32_16x16x32_bf16 v[14:17], v[138:141], v[210:213], v[14:17]
	v_mfma_f32_16x16x32_bf16 v[10:13], v[146:149], v[210:213], v[10:13]
	v_mfma_f32_16x16x32_bf16 v[62:65], v[142:145], v[174:177], v[62:65]
	v_mfma_f32_16x16x32_bf16 v[58:61], v[150:153], v[174:177], v[58:61]
	v_mfma_f32_16x16x32_bf16 v[46:49], v[142:145], v[182:185], v[46:49]
	v_mfma_f32_16x16x32_bf16 v[42:45], v[150:153], v[182:185], v[42:45]
	v_mfma_f32_16x16x32_bf16 v[30:33], v[142:145], v[206:209], v[30:33]
	v_mfma_f32_16x16x32_bf16 v[26:29], v[150:153], v[206:209], v[26:29]
	v_mfma_f32_16x16x32_bf16 v[14:17], v[142:145], v[238:241], v[14:17]
	v_mfma_f32_16x16x32_bf16 v[10:13], v[150:153], v[238:241], v[10:13]
	s_setprio 0
	s_setprio 1
	v_mfma_f32_16x16x32_bf16 v[54:57], v[154:157], v[170:173], v[54:57]
	v_mfma_f32_16x16x32_bf16 v[50:53], v[162:165], v[170:173], v[50:53]
	v_mfma_f32_16x16x32_bf16 v[38:41], v[154:157], v[178:181], v[38:41]
	v_mfma_f32_16x16x32_bf16 v[34:37], v[162:165], v[178:181], v[34:37]
	v_mfma_f32_16x16x32_bf16 v[22:25], v[154:157], v[200:203], v[22:25]
	v_mfma_f32_16x16x32_bf16 v[18:21], v[162:165], v[200:203], v[18:21]
	v_mfma_f32_16x16x32_bf16 v[6:9], v[154:157], v[210:213], v[6:9]
	v_mfma_f32_16x16x32_bf16 v[2:5], v[162:165], v[210:213], v[2:5]
	v_mfma_f32_16x16x32_bf16 v[54:57], v[158:161], v[174:177], v[54:57]
	v_mfma_f32_16x16x32_bf16 v[50:53], v[166:169], v[174:177], v[50:53]
	v_mfma_f32_16x16x32_bf16 v[38:41], v[158:161], v[182:185], v[38:41]
	v_mfma_f32_16x16x32_bf16 v[34:37], v[166:169], v[182:185], v[34:37]
	v_mfma_f32_16x16x32_bf16 v[22:25], v[158:161], v[206:209], v[22:25]
	v_mfma_f32_16x16x32_bf16 v[18:21], v[166:169], v[206:209], v[18:21]
	v_mfma_f32_16x16x32_bf16 v[6:9], v[158:161], v[238:241], v[6:9]
	v_mfma_f32_16x16x32_bf16 v[2:5], v[166:169], v[238:241], v[2:5]
	s_setprio 0
	s_barrier
	s_add_i32 s80, 0, 0x18000
	s_add_i32 s81, 0, 0x1c000
	v_add_u32_e32 v150, s80, v136
	v_add_u32_e32 v166, s81, v136
	ds_read_b128 v[138:141], v150
	ds_read_b128 v[142:145], v150 offset:1024
	ds_read_b128 v[146:149], v150 offset:2048
	ds_read_b128 v[150:153], v150 offset:3072
	ds_read_b128 v[154:157], v166
	ds_read_b128 v[158:161], v166 offset:1024
	ds_read_b128 v[162:165], v166 offset:2048
	ds_read_b128 v[166:169], v166 offset:3072
	s_add_u32 s62, s62, 0xb0000
	s_addc_u32 s63, s63, 0
	s_mov_b32 m0, s39
	v_lshl_add_u64 v[220:221], s[62:63], 0, v[0:1]
	ds_read_b128 v[170:173], v137 offset:32768
	ds_read_b128 v[174:177], v137 offset:33792
	ds_read_b128 v[178:181], v137 offset:34816
	ds_read_b128 v[182:185], v137 offset:35840
	ds_read_b128 v[200:203], v137 offset:36864
	ds_read_b128 v[206:209], v137 offset:37888
	ds_read_b128 v[210:213], v137 offset:38912
	ds_read_b128 v[238:241], v137 offset:39936
	global_load_lds_dwordx4 v[220:221], off
	v_lshl_add_u64 v[220:221], s[62:63], 0, v[132:133]
	s_mov_b32 m0, s44
	s_nop 0
	global_load_lds_dwordx4 v[220:221], off
	s_waitcnt vmcnt(8)
	s_waitcnt lgkmcnt(0)
	s_barrier
	s_setprio 1
	v_mfma_f32_16x16x32_bf16 v[126:129], v[138:141], v[170:173], v[126:129]
	v_mfma_f32_16x16x32_bf16 v[122:125], v[146:149], v[170:173], v[122:125]
	v_mfma_f32_16x16x32_bf16 v[110:113], v[138:141], v[178:181], v[110:113]
	v_mfma_f32_16x16x32_bf16 v[106:109], v[146:149], v[178:181], v[106:109]
	v_mfma_f32_16x16x32_bf16 v[94:97], v[138:141], v[200:203], v[94:97]
	v_mfma_f32_16x16x32_bf16 v[90:93], v[146:149], v[200:203], v[90:93]
	v_mfma_f32_16x16x32_bf16 v[78:81], v[138:141], v[210:213], v[78:81]
	v_mfma_f32_16x16x32_bf16 v[74:77], v[146:149], v[210:213], v[74:77]
	v_mfma_f32_16x16x32_bf16 v[126:129], v[142:145], v[174:177], v[126:129]
	v_mfma_f32_16x16x32_bf16 v[122:125], v[150:153], v[174:177], v[122:125]
	v_mfma_f32_16x16x32_bf16 v[110:113], v[142:145], v[182:185], v[110:113]
	v_mfma_f32_16x16x32_bf16 v[106:109], v[150:153], v[182:185], v[106:109]
	v_mfma_f32_16x16x32_bf16 v[94:97], v[142:145], v[206:209], v[94:97]
	v_mfma_f32_16x16x32_bf16 v[90:93], v[150:153], v[206:209], v[90:93]
	v_mfma_f32_16x16x32_bf16 v[78:81], v[142:145], v[238:241], v[78:81]
	v_mfma_f32_16x16x32_bf16 v[74:77], v[150:153], v[238:241], v[74:77]
	s_setprio 0
	s_setprio 1
	v_mfma_f32_16x16x32_bf16 v[118:121], v[154:157], v[170:173], v[118:121]
	v_mfma_f32_16x16x32_bf16 v[114:117], v[162:165], v[170:173], v[114:117]
	v_mfma_f32_16x16x32_bf16 v[102:105], v[154:157], v[178:181], v[102:105]
	v_mfma_f32_16x16x32_bf16 v[98:101], v[162:165], v[178:181], v[98:101]
	v_mfma_f32_16x16x32_bf16 v[86:89], v[154:157], v[200:203], v[86:89]
	v_mfma_f32_16x16x32_bf16 v[82:85], v[162:165], v[200:203], v[82:85]
	v_mfma_f32_16x16x32_bf16 v[70:73], v[154:157], v[210:213], v[70:73]
	v_mfma_f32_16x16x32_bf16 v[66:69], v[162:165], v[210:213], v[66:69]
	v_mfma_f32_16x16x32_bf16 v[118:121], v[158:161], v[174:177], v[118:121]
	v_mfma_f32_16x16x32_bf16 v[114:117], v[166:169], v[174:177], v[114:117]
	v_mfma_f32_16x16x32_bf16 v[102:105], v[158:161], v[182:185], v[102:105]
	v_mfma_f32_16x16x32_bf16 v[98:101], v[166:169], v[182:185], v[98:101]
	v_mfma_f32_16x16x32_bf16 v[86:89], v[158:161], v[206:209], v[86:89]
	v_mfma_f32_16x16x32_bf16 v[82:85], v[166:169], v[206:209], v[82:85]
	v_mfma_f32_16x16x32_bf16 v[70:73], v[158:161], v[238:241], v[70:73]
	v_mfma_f32_16x16x32_bf16 v[66:69], v[166:169], v[238:241], v[66:69]
	s_setprio 0
	s_barrier
; #define PG8_STAGE(bufoff, gbase, voff) do { _Pragma("unroll") for (int _i = 0; _i < 2; ++_i) \
;         __builtin_amdgcn_global_load_lds((const unsigned*)((const char*)(gbase) + (voff)[_i]), (LAS unsigned*)(lds + (bufoff) + ldsw + _i * 8192), 16, 0, 0); } while (0)
; #define PG8_LDA(dst, b, h) do { _Pragma("unroll") for (int m = 0; m < 4; ++m) _Pragma("unroll") for (int k = 0; k < 2; ++k) dst[m][k] = *(const LAS bf16x8*)(lds + PG8_SA(b, h) + aoff + m * 2048 + k * 1024); } while (0)
; #define PG8_MMA(ai, bj, At, Bt) do { __builtin_amdgcn_s_setprio(1); _Pragma("unroll") for (int m = 0; m < 4; ++m) _Pragma("unroll") for (int n = 0; n < 2; ++n) _Pragma("unroll") for (int k = 0; k < 2; ++k) \
;         acc[ai][bj][m][n] = __builtin_amdgcn_mfma_f32_16x16x32_bf16(Bt[n][k], At[m][k], acc[ai][bj][m][n], 0, 0, 0); __builtin_amdgcn_s_setprio(0); } while (0)
; #define PG8_WAIT_V(n) asm volatile("s_waitcnt vmcnt(" #n ")" ::: "memory")
; #define PG8_WAIT_L(n) asm volatile("s_waitcnt lgkmcnt(" #n ")" ::: "memory")
; #define PG8_BAR __builtin_amdgcn_s_barrier()
; #define PG8_SCHED __builtin_amdgcn_sched_barrier(0)
; template <class Epi, class Sched, bool ALIGN_EPI>
; __device__ __forceinline__ void gemm_phase(LAS unsigned char* lds, const bf16_t* Ab, const bf16_t* Bb, int lda, int ldb, int K, const Sched& S, Epi& E) {
;     ...
;             PG8_LDA(At, 1, 1); PG8_STAGE(PG8_SB(1, 0), b3, voffB); PG8_STAGE(PG8_SB(1, 1), b3 + hstepB, voffB); PG8_STAGE(PG8_SA(1, 0), a3, voffA);
;             PG8_WAIT_V(8); PG8_WAIT_L(0); PG8_BAR; PG8_MMA(1, 0, At, B0); PG8_MMA(1, 1, At, B1); PG8_BAR; PG8_SCHED;
;         }
;         if constexpr (ALIGN_EPI) { if (wr == 0) PG8_BAR; }
	s_add_i32 s62, s80, s24
	v_lshl_add_u64 v[186:187], v[186:187], 0, s[26:27]
	s_mov_b32 m0, s62
	ds_read_b128 v[170:173], v137 offset:49152
	ds_read_b128 v[174:177], v137 offset:50176
	ds_read_b128 v[178:181], v137 offset:51200
	ds_read_b128 v[182:185], v137 offset:52224
	ds_read_b128 v[200:203], v137 offset:53248
	ds_read_b128 v[206:209], v137 offset:54272
	ds_read_b128 v[210:213], v137 offset:55296
	ds_read_b128 v[238:241], v137 offset:56320
	global_load_lds_dwordx4 v[186:187], off
	s_add_i32 m0, s62, 0x2000
	s_add_u32 s60, s60, 0xb0080
	v_lshl_add_u64 v[186:187], v[188:189], 0, s[26:27]
	s_addc_u32 s61, s61, 0
	s_add_i32 s62, s81, s24
	global_load_lds_dwordx4 v[186:187], off
	v_lshl_add_u64 v[186:187], s[60:61], 0, v[130:131]
	s_mov_b32 m0, s62
	s_nop 0
	global_load_lds_dwordx4 v[186:187], off
	v_lshl_add_u64 v[186:187], s[60:61], 0, v[134:135]
	s_add_i32 m0, s62, 0x2000
	s_nop 0
	global_load_lds_dwordx4 v[186:187], off
	v_lshl_add_u64 v[186:187], v[196:197], 0, s[26:27]
	s_mov_b32 m0, s65
	s_nop 0
	global_load_lds_dwordx4 v[186:187], off
	v_lshl_add_u64 v[186:187], v[198:199], 0, s[26:27]
	s_mov_b32 m0, s66
	s_nop 0
	global_load_lds_dwordx4 v[186:187], off
	s_waitcnt vmcnt(8)
	s_waitcnt lgkmcnt(0)
	s_barrier
	s_setprio 1
	v_mfma_f32_16x16x32_bf16 v[62:65], v[138:141], v[170:173], v[62:65]
	v_mfma_f32_16x16x32_bf16 v[58:61], v[146:149], v[170:173], v[58:61]
	v_mfma_f32_16x16x32_bf16 v[46:49], v[138:141], v[178:181], v[46:49]
	v_mfma_f32_16x16x32_bf16 v[42:45], v[146:149], v[178:181], v[42:45]
	v_mfma_f32_16x16x32_bf16 v[30:33], v[138:141], v[200:203], v[30:33]
	v_mfma_f32_16x16x32_bf16 v[26:29], v[146:149], v[200:203], v[26:29]
	v_mfma_f32_16x16x32_bf16 v[14:17], v[138:141], v[210:213], v[14:17]
	v_mfma_f32_16x16x32_bf16 v[10:13], v[146:149], v[210:213], v[10:13]
	v_mfma_f32_16x16x32_bf16 v[62:65], v[142:145], v[174:177], v[62:65]
	v_mfma_f32_16x16x32_bf16 v[58:61], v[150:153], v[174:177], v[58:61]
	v_mfma_f32_16x16x32_bf16 v[46:49], v[142:145], v[182:185], v[46:49]
	v_mfma_f32_16x16x32_bf16 v[42:45], v[150:153], v[182:185], v[42:45]
	v_mfma_f32_16x16x32_bf16 v[30:33], v[142:145], v[206:209], v[30:33]
	v_mfma_f32_16x16x32_bf16 v[26:29], v[150:153], v[206:209], v[26:29]
	v_mfma_f32_16x16x32_bf16 v[14:17], v[142:145], v[238:241], v[14:17]
	v_mfma_f32_16x16x32_bf16 v[10:13], v[150:153], v[238:241], v[10:13]
	s_setprio 0
	s_setprio 1
	v_mfma_f32_16x16x32_bf16 v[54:57], v[154:157], v[170:173], v[54:57]
	v_mfma_f32_16x16x32_bf16 v[50:53], v[162:165], v[170:173], v[50:53]
	v_mfma_f32_16x16x32_bf16 v[38:41], v[154:157], v[178:181], v[38:41]
	v_mfma_f32_16x16x32_bf16 v[34:37], v[162:165], v[178:181], v[34:37]
	v_mfma_f32_16x16x32_bf16 v[22:25], v[154:157], v[200:203], v[22:25]
	v_mfma_f32_16x16x32_bf16 v[18:21], v[162:165], v[200:203], v[18:21]
	v_mfma_f32_16x16x32_bf16 v[6:9], v[154:157], v[210:213], v[6:9]
	v_mfma_f32_16x16x32_bf16 v[2:5], v[162:165], v[210:213], v[2:5]
	v_mfma_f32_16x16x32_bf16 v[54:57], v[158:161], v[174:177], v[54:57]
	v_mfma_f32_16x16x32_bf16 v[50:53], v[166:169], v[174:177], v[50:53]
	v_mfma_f32_16x16x32_bf16 v[38:41], v[158:161], v[182:185], v[38:41]
	v_mfma_f32_16x16x32_bf16 v[34:37], v[166:169], v[182:185], v[34:37]
	v_mfma_f32_16x16x32_bf16 v[22:25], v[158:161], v[206:209], v[22:25]
	v_mfma_f32_16x16x32_bf16 v[18:21], v[166:169], v[206:209], v[18:21]
	v_mfma_f32_16x16x32_bf16 v[6:9], v[158:161], v[238:241], v[6:9]
	v_mfma_f32_16x16x32_bf16 v[2:5], v[166:169], v[238:241], v[2:5]
	s_setprio 0
	s_barrier
	s_add_i32 s79, s79, 2
	s_add_u32 s77, s77, 0x100
	s_addc_u32 s78, s78, 0
	s_add_u32 s58, s58, 0x100
	s_addc_u32 s59, s59, 0
	s_cmp_gt_u32 s79, 41
	s_cbranch_scc0 .LBB0_607
	s_and_b64 vcc, exec, s[14:15]
	s_cbranch_vccz .LBB0_610
	s_barrier

; #define PG8_STAGE(bufoff, gbase, voff) do { _Pragma("unroll") for (int _i = 0; _i < 2; ++_i) \
;         __builtin_amdgcn_global_load_lds((const unsigned*)((const char*)(gbase) + (voff)[_i]), (LAS unsigned*)(lds + (bufoff) + ldsw + _i * 8192), 16, 0, 0); } while (0)
; #define PG8_LDA(dst, b, h) do { _Pragma("unroll") for (int m = 0; m < 4; ++m) _Pragma("unroll") for (int k = 0; k < 2; ++k) dst[m][k] = *(const LAS bf16x8*)(lds + PG8_SA(b, h) + aoff + m * 2048 + k * 1024); } while (0)
; #define PG8_LDB(dst, b, h) do { _Pragma("unroll") for (int n = 0; n < 2; ++n) _Pragma("unroll") for (int k = 0; k < 2; ++k) dst[n][k] = *(const LAS bf16x8*)(lds + PG8_SB(b, h) + boff + n * 2048 + k * 1024); } while (0)
; #define PG8_MMA(ai, bj, At, Bt) do { __builtin_amdgcn_s_setprio(1); _Pragma("unroll") for (int m = 0; m < 4; ++m) _Pragma("unroll") for (int n = 0; n < 2; ++n) _Pragma("unroll") for (int k = 0; k < 2; ++k) \
;         acc[ai][bj][m][n] = __builtin_amdgcn_mfma_f32_16x16x32_bf16(Bt[n][k], At[m][k], acc[ai][bj][m][n], 0, 0, 0); __builtin_amdgcn_s_setprio(0); } while (0)
; template <class Epi, class Sched, bool ALIGN_EPI>
; __device__ __forceinline__ void gemm_phase(LAS unsigned char* lds, const bf16_t* Ab, const bf16_t* Bb, int lda, int ldb, int K, const Sched& S, Epi& E) {
;     ...
;         const bool has_next = S.next(ui + 1, nxt); nxt.ui = ui + 1;
;         const char* nA = has_next ? (const char*)(Ab + nxt.a_off) : cA; const char* nB = has_next ? (const char*)(Bb + nxt.b_off) : cB;
;         for (int t = 0; t < nt; t += 2) {
;             const bool last = (t == nt - 2);
;             const char* a1 = cA + (unsigned)(t + 1) * kstep;
;             const char* a2 = last ? nA : cA + (unsigned)(t + 2) * kstep; const char* b2 = last ? nB : cB + (unsigned)(t + 2) * kstep;
;             const char* a3 = a2 + kstep; const char* b3 = b2 + kstep;
;             PG8_LDB(B0, 0, 0); PG8_LDB(B1, 0, 1); PG8_SCHED; PG8_LDA(At, 0, 0); PG8_STAGE(PG8_SA(1, 1), a1 + hstepA, voffA);
;             PG8_WAIT_V(8); PG8_WAIT_L(0); PG8_BAR; PG8_MMA(0, 0, At, B0); PG8_MMA(0, 1, At, B1); PG8_BAR; PG8_SCHED;
;             PG8_LDA(At, 0, 1); PG8_STAGE(PG8_SB(0, 0), b2, voffB); PG8_STAGE(PG8_SB(0, 1), b2 + hstepB, voffB); PG8_STAGE(PG8_SA(0, 0), a2, voffA);
;             PG8_WAIT_V(8); PG8_WAIT_L(0); PG8_BAR; PG8_MMA(1, 0, At, B0); PG8_MMA(1, 1, At, B1); PG8_BAR; PG8_SCHED;
.LBB0_749:
	s_add_u32 s12, s66, s10
	s_addc_u32 s13, s67, s11
	s_add_u32 s12, s12, 0x100
	s_addc_u32 s13, s13, 0
	s_add_u32 s74, s33, s10
	s_addc_u32 s75, s39, s11
	s_add_i32 s76, 0, 0x10000
	s_cmpk_eq_i32 s10, 0x700
	s_cselect_b32 s15, s25, s13
	s_cselect_b32 s14, s31, s12
	s_cselect_b32 s13, s65, s75
	s_cselect_b32 s12, s72, s74
	s_add_i32 s77, 0, 0x14000
	v_add_u32_e32 v152, s76, v161
	v_add_u32_e32 v170, s77, v161
	ds_read_b128 v[140:143], v152
	ds_read_b128 v[144:147], v152 offset:1024
	ds_read_b128 v[148:151], v152 offset:2048
	ds_read_b128 v[152:155], v152 offset:3072
	ds_read_b128 v[156:159], v170
	ds_read_b128 v[162:165], v170 offset:1024
	ds_read_b128 v[166:169], v170 offset:2048
	ds_read_b128 v[170:173], v170 offset:3072
	v_add_u32_e32 v190, 0, v160
	v_lshl_add_u64 v[186:187], v[136:137], 0, s[10:11]
	s_add_i32 m0, s47, 0xc000
	ds_read_b128 v[174:177], v190
	ds_read_b128 v[178:181], v190 offset:1024
	ds_read_b128 v[182:185], v190 offset:2048
	ds_read_b128 v[200:203], v190 offset:3072
	ds_read_b128 v[206:209], v190 offset:4096
	ds_read_b128 v[210:213], v190 offset:5120
	ds_read_b128 v[238:241], v190 offset:6144
	ds_read_b128 v[242:245], v190 offset:7168
	global_load_lds_dwordx4 v[186:187], off
	v_lshl_add_u64 v[186:187], v[138:139], 0, s[10:11]
	s_add_i32 m0, s47, 0xe000
	s_nop 0
	global_load_lds_dwordx4 v[186:187], off
	s_waitcnt vmcnt(8)
	s_waitcnt lgkmcnt(0)
	s_barrier
	s_setprio 1
	v_mfma_f32_16x16x32_bf16 v[126:129], v[140:143], v[174:177], v[126:129]
	v_mfma_f32_16x16x32_bf16 v[122:125], v[148:151], v[174:177], v[122:125]
	v_mfma_f32_16x16x32_bf16 v[118:121], v[140:143], v[182:185], v[118:121]
	v_mfma_f32_16x16x32_bf16 v[114:117], v[148:151], v[182:185], v[114:117]
	v_mfma_f32_16x16x32_bf16 v[110:113], v[140:143], v[206:209], v[110:113]
	v_mfma_f32_16x16x32_bf16 v[106:109], v[148:151], v[206:209], v[106:109]
	v_mfma_f32_16x16x32_bf16 v[102:105], v[140:143], v[238:241], v[102:105]
	v_mfma_f32_16x16x32_bf16 v[98:101], v[148:151], v[238:241], v[98:101]
	v_mfma_f32_16x16x32_bf16 v[126:129], v[144:147], v[178:181], v[126:129]
	v_mfma_f32_16x16x32_bf16 v[122:125], v[152:155], v[178:181], v[122:125]
	v_mfma_f32_16x16x32_bf16 v[118:121], v[144:147], v[200:203], v[118:121]
	v_mfma_f32_16x16x32_bf16 v[114:117], v[152:155], v[200:203], v[114:117]
	v_mfma_f32_16x16x32_bf16 v[110:113], v[144:147], v[210:213], v[110:113]
	v_mfma_f32_16x16x32_bf16 v[106:109], v[152:155], v[210:213], v[106:109]
	v_mfma_f32_16x16x32_bf16 v[102:105], v[144:147], v[242:245], v[102:105]
	v_mfma_f32_16x16x32_bf16 v[98:101], v[152:155], v[242:245], v[98:101]
	s_setprio 0
	s_setprio 1
	v_mfma_f32_16x16x32_bf16 v[94:97], v[156:159], v[174:177], v[94:97]
	v_mfma_f32_16x16x32_bf16 v[90:93], v[166:169], v[174:177], v[90:93]
	v_mfma_f32_16x16x32_bf16 v[86:89], v[156:159], v[182:185], v[86:89]
	v_mfma_f32_16x16x32_bf16 v[82:85], v[166:169], v[182:185], v[82:85]
	v_mfma_f32_16x16x32_bf16 v[78:81], v[156:159], v[206:209], v[78:81]
	v_mfma_f32_16x16x32_bf16 v[74:77], v[166:169], v[206:209], v[74:77]
	v_mfma_f32_16x16x32_bf16 v[70:73], v[156:159], v[238:241], v[70:73]
	v_mfma_f32_16x16x32_bf16 v[66:69], v[166:169], v[238:241], v[66:69]
	v_mfma_f32_16x16x32_bf16 v[94:97], v[162:165], v[178:181], v[94:97]
	v_mfma_f32_16x16x32_bf16 v[90:93], v[170:173], v[178:181], v[90:93]
	v_mfma_f32_16x16x32_bf16 v[86:89], v[162:165], v[200:203], v[86:89]
	v_mfma_f32_16x16x32_bf16 v[82:85], v[170:173], v[200:203], v[82:85]
	v_mfma_f32_16x16x32_bf16 v[78:81], v[162:165], v[210:213], v[78:81]
	v_mfma_f32_16x16x32_bf16 v[74:77], v[170:173], v[210:213], v[74:77]
	v_mfma_f32_16x16x32_bf16 v[70:73], v[162:165], v[242:245], v[70:73]
	v_mfma_f32_16x16x32_bf16 v[66:69], v[170:173], v[242:245], v[66:69]
	s_setprio 0
	s_barrier
	s_add_i32 s74, s76, s46
	v_lshl_add_u64 v[186:187], s[12:13], 0, v[134:135]
	s_mov_b32 m0, s74
	ds_read_b128 v[174:177], v190 offset:16384
	ds_read_b128 v[178:181], v190 offset:17408
	ds_read_b128 v[182:185], v190 offset:18432
	ds_read_b128 v[200:203], v190 offset:19456
	ds_read_b128 v[206:209], v190 offset:20480
	ds_read_b128 v[210:213], v190 offset:21504
	ds_read_b128 v[238:241], v190 offset:22528
	ds_read_b128 v[242:245], v190 offset:23552
	global_load_lds_dwordx4 v[186:187], off
	s_add_i32 m0, s74, 0x2000
	s_add_u32 s74, s12, 0x40000
	v_lshl_add_u64 v[188:189], s[12:13], 0, v[132:133]
	s_addc_u32 s75, s13, 0
	s_add_i32 s76, s77, s46
	global_load_lds_dwordx4 v[188:189], off
	v_lshl_add_u64 v[196:197], s[74:75], 0, v[134:135]
	s_mov_b32 m0, s76
	v_lshl_add_u64 v[198:199], s[14:15], 0, v[130:131]
	global_load_lds_dwordx4 v[196:197], off
	v_lshl_add_u64 v[196:197], s[74:75], 0, v[132:133]
	s_add_i32 m0, s76, 0x2000
	s_nop 0
	global_load_lds_dwordx4 v[196:197], off
	v_lshl_add_u64 v[196:197], s[14:15], 0, v[0:1]
	s_mov_b32 m0, s47
	s_nop 0
	global_load_lds_dwordx4 v[196:197], off
	s_mov_b32 m0, s44
	s_nop 0
	global_load_lds_dwordx4 v[198:199], off
	s_waitcnt vmcnt(8)
	s_waitcnt lgkmcnt(0)
	s_barrier
; #define PG8_STAGE(bufoff, gbase, voff) do { _Pragma("unroll") for (int _i = 0; _i < 2; ++_i) \
;         __builtin_amdgcn_global_load_lds((const unsigned*)((const char*)(gbase) + (voff)[_i]), (LAS unsigned*)(lds + (bufoff) + ldsw + _i * 8192), 16, 0, 0); } while (0)
; #define PG8_LDA(dst, b, h) do { _Pragma("unroll") for (int m = 0; m < 4; ++m) _Pragma("unroll") for (int k = 0; k < 2; ++k) dst[m][k] = *(const LAS bf16x8*)(lds + PG8_SA(b, h) + aoff + m * 2048 + k * 1024); } while (0)
; #define PG8_LDB(dst, b, h) do { _Pragma("unroll") for (int n = 0; n < 2; ++n) _Pragma("unroll") for (int k = 0; k < 2; ++k) dst[n][k] = *(const LAS bf16x8*)(lds + PG8_SB(b, h) + boff + n * 2048 + k * 1024); } while (0)
; #define PG8_MMA(ai, bj, At, Bt) do { __builtin_amdgcn_s_setprio(1); _Pragma("unroll") for (int m = 0; m < 4; ++m) _Pragma("unroll") for (int n = 0; n < 2; ++n) _Pragma("unroll") for (int k = 0; k < 2; ++k) \
;         acc[ai][bj][m][n] = __builtin_amdgcn_mfma_f32_16x16x32_bf16(Bt[n][k], At[m][k], acc[ai][bj][m][n], 0, 0, 0); __builtin_amdgcn_s_setprio(0); } while (0)
; #define PG8_WAIT_V(n) asm volatile("s_waitcnt vmcnt(" #n ")" ::: "memory")
; #define PG8_WAIT_L(n) asm volatile("s_waitcnt lgkmcnt(" #n ")" ::: "memory")
; #define PG8_BAR __builtin_amdgcn_s_barrier()
; #define PG8_SCHED __builtin_amdgcn_sched_barrier(0)
; template <class Epi, class Sched, bool ALIGN_EPI>
; __device__ __forceinline__ void gemm_phase(LAS unsigned char* lds, const bf16_t* Ab, const bf16_t* Bb, int lda, int ldb, int K, const Sched& S, Epi& E) {
;     ...
;             PG8_WAIT_V(8); PG8_WAIT_L(0); PG8_BAR; PG8_MMA(1, 0, At, B0); PG8_MMA(1, 1, At, B1); PG8_BAR; PG8_SCHED;
;             PG8_LDB(B0, 1, 0); PG8_LDB(B1, 1, 1); PG8_SCHED; PG8_LDA(At, 1, 0); PG8_STAGE(PG8_SA(0, 1), a2 + hstepA, voffA);
;             PG8_WAIT_V(8); PG8_WAIT_L(0); PG8_BAR; PG8_MMA(0, 0, At, B0); PG8_MMA(0, 1, At, B1); PG8_BAR; PG8_SCHED;
	s_setprio 1
	v_mfma_f32_16x16x32_bf16 v[62:65], v[140:143], v[174:177], v[62:65]
	v_mfma_f32_16x16x32_bf16 v[58:61], v[148:151], v[174:177], v[58:61]
	v_mfma_f32_16x16x32_bf16 v[54:57], v[140:143], v[182:185], v[54:57]
	v_mfma_f32_16x16x32_bf16 v[50:53], v[148:151], v[182:185], v[50:53]
	v_mfma_f32_16x16x32_bf16 v[46:49], v[140:143], v[206:209], v[46:49]
	v_mfma_f32_16x16x32_bf16 v[42:45], v[148:151], v[206:209], v[42:45]
	v_mfma_f32_16x16x32_bf16 v[38:41], v[140:143], v[238:241], v[38:41]
	v_mfma_f32_16x16x32_bf16 v[34:37], v[148:151], v[238:241], v[34:37]
	v_mfma_f32_16x16x32_bf16 v[62:65], v[144:147], v[178:181], v[62:65]
	v_mfma_f32_16x16x32_bf16 v[58:61], v[152:155], v[178:181], v[58:61]
	v_mfma_f32_16x16x32_bf16 v[54:57], v[144:147], v[200:203], v[54:57]
	v_mfma_f32_16x16x32_bf16 v[50:53], v[152:155], v[200:203], v[50:53]
	v_mfma_f32_16x16x32_bf16 v[46:49], v[144:147], v[210:213], v[46:49]
	v_mfma_f32_16x16x32_bf16 v[42:45], v[152:155], v[210:213], v[42:45]
	v_mfma_f32_16x16x32_bf16 v[38:41], v[144:147], v[242:245], v[38:41]
	v_mfma_f32_16x16x32_bf16 v[34:37], v[152:155], v[242:245], v[34:37]
	s_setprio 0
	s_setprio 1
	v_mfma_f32_16x16x32_bf16 v[30:33], v[156:159], v[174:177], v[30:33]
	v_mfma_f32_16x16x32_bf16 v[26:29], v[166:169], v[174:177], v[26:29]
	v_mfma_f32_16x16x32_bf16 v[22:25], v[156:159], v[182:185], v[22:25]
	v_mfma_f32_16x16x32_bf16 v[18:21], v[166:169], v[182:185], v[18:21]
	v_mfma_f32_16x16x32_bf16 v[14:17], v[156:159], v[206:209], v[14:17]
	v_mfma_f32_16x16x32_bf16 v[10:13], v[166:169], v[206:209], v[10:13]
	v_mfma_f32_16x16x32_bf16 v[6:9], v[156:159], v[238:241], v[6:9]
	v_mfma_f32_16x16x32_bf16 v[2:5], v[166:169], v[238:241], v[2:5]
	v_mfma_f32_16x16x32_bf16 v[30:33], v[162:165], v[178:181], v[30:33]
	v_mfma_f32_16x16x32_bf16 v[26:29], v[170:173], v[178:181], v[26:29]
	v_mfma_f32_16x16x32_bf16 v[22:25], v[162:165], v[200:203], v[22:25]
	v_mfma_f32_16x16x32_bf16 v[18:21], v[170:173], v[200:203], v[18:21]
	v_mfma_f32_16x16x32_bf16 v[14:17], v[162:165], v[210:213], v[14:17]
	v_mfma_f32_16x16x32_bf16 v[10:13], v[170:173], v[210:213], v[10:13]
	v_mfma_f32_16x16x32_bf16 v[6:9], v[162:165], v[242:245], v[6:9]
	v_mfma_f32_16x16x32_bf16 v[2:5], v[170:173], v[242:245], v[2:5]
	s_setprio 0
	s_barrier
	s_add_i32 s74, 0, 0x18000
	s_add_i32 s75, 0, 0x1c000
	v_add_u32_e32 v152, s74, v161
	v_add_u32_e32 v170, s75, v161
	ds_read_b128 v[140:143], v152
	ds_read_b128 v[144:147], v152 offset:1024
	ds_read_b128 v[148:151], v152 offset:2048
	ds_read_b128 v[152:155], v152 offset:3072
	ds_read_b128 v[156:159], v170
	ds_read_b128 v[162:165], v170 offset:1024
	ds_read_b128 v[166:169], v170 offset:2048
	ds_read_b128 v[170:173], v170 offset:3072
	s_add_u32 s14, s14, 0x40000
	s_addc_u32 s15, s15, 0
	s_mov_b32 m0, s45
	v_lshl_add_u64 v[220:221], s[14:15], 0, v[0:1]
	ds_read_b128 v[174:177], v190 offset:32768
	ds_read_b128 v[178:181], v190 offset:33792
	ds_read_b128 v[182:185], v190 offset:34816
	ds_read_b128 v[200:203], v190 offset:35840
	ds_read_b128 v[206:209], v190 offset:36864
	ds_read_b128 v[210:213], v190 offset:37888
	ds_read_b128 v[238:241], v190 offset:38912
	ds_read_b128 v[242:245], v190 offset:39936
	global_load_lds_dwordx4 v[220:221], off
	v_lshl_add_u64 v[220:221], s[14:15], 0, v[130:131]
	s_mov_b32 m0, s22
	s_nop 0
	global_load_lds_dwordx4 v[220:221], off
	s_waitcnt vmcnt(8)
	s_waitcnt lgkmcnt(0)
	s_barrier
	s_setprio 1
	v_mfma_f32_16x16x32_bf16 v[126:129], v[140:143], v[174:177], v[126:129]
	v_mfma_f32_16x16x32_bf16 v[122:125], v[148:151], v[174:177], v[122:125]
	v_mfma_f32_16x16x32_bf16 v[118:121], v[140:143], v[182:185], v[118:121]
	v_mfma_f32_16x16x32_bf16 v[114:117], v[148:151], v[182:185], v[114:117]
	v_mfma_f32_16x16x32_bf16 v[110:113], v[140:143], v[206:209], v[110:113]
	v_mfma_f32_16x16x32_bf16 v[106:109], v[148:151], v[206:209], v[106:109]
	v_mfma_f32_16x16x32_bf16 v[102:105], v[140:143], v[238:241], v[102:105]
	v_mfma_f32_16x16x32_bf16 v[98:101], v[148:151], v[238:241], v[98:101]
	v_mfma_f32_16x16x32_bf16 v[126:129], v[144:147], v[178:181], v[126:129]
	v_mfma_f32_16x16x32_bf16 v[122:125], v[152:155], v[178:181], v[122:125]
	v_mfma_f32_16x16x32_bf16 v[118:121], v[144:147], v[200:203], v[118:121]
	v_mfma_f32_16x16x32_bf16 v[114:117], v[152:155], v[200:203], v[114:117]
	v_mfma_f32_16x16x32_bf16 v[110:113], v[144:147], v[210:213], v[110:113]
	v_mfma_f32_16x16x32_bf16 v[106:109], v[152:155], v[210:213], v[106:109]
	v_mfma_f32_16x16x32_bf16 v[102:105], v[144:147], v[242:245], v[102:105]
	v_mfma_f32_16x16x32_bf16 v[98:101], v[152:155], v[242:245], v[98:101]
	s_setprio 0
	s_setprio 1
	v_mfma_f32_16x16x32_bf16 v[94:97], v[156:159], v[174:177], v[94:97]
	v_mfma_f32_16x16x32_bf16 v[90:93], v[166:169], v[174:177], v[90:93]
	v_mfma_f32_16x16x32_bf16 v[86:89], v[156:159], v[182:185], v[86:89]
	v_mfma_f32_16x16x32_bf16 v[82:85], v[166:169], v[182:185], v[82:85]
	v_mfma_f32_16x16x32_bf16 v[78:81], v[156:159], v[206:209], v[78:81]
	v_mfma_f32_16x16x32_bf16 v[74:77], v[166:169], v[206:209], v[74:77]
	v_mfma_f32_16x16x32_bf16 v[70:73], v[156:159], v[238:241], v[70:73]
	v_mfma_f32_16x16x32_bf16 v[66:69], v[166:169], v[238:241], v[66:69]
	v_mfma_f32_16x16x32_bf16 v[94:97], v[162:165], v[178:181], v[94:97]
	v_mfma_f32_16x16x32_bf16 v[90:93], v[170:173], v[178:181], v[90:93]
	v_mfma_f32_16x16x32_bf16 v[86:89], v[162:165], v[200:203], v[86:89]
	v_mfma_f32_16x16x32_bf16 v[82:85], v[170:173], v[200:203], v[82:85]
	v_mfma_f32_16x16x32_bf16 v[78:81], v[162:165], v[210:213], v[78:81]
	v_mfma_f32_16x16x32_bf16 v[74:77], v[170:173], v[210:213], v[74:77]
	v_mfma_f32_16x16x32_bf16 v[70:73], v[162:165], v[242:245], v[70:73]
	v_mfma_f32_16x16x32_bf16 v[66:69], v[170:173], v[242:245], v[66:69]
	s_setprio 0
	s_barrier
; #define PG8_STAGE(bufoff, gbase, voff) do { _Pragma("unroll") for (int _i = 0; _i < 2; ++_i) \
;         __builtin_amdgcn_global_load_lds((const unsigned*)((const char*)(gbase) + (voff)[_i]), (LAS unsigned*)(lds + (bufoff) + ldsw + _i * 8192), 16, 0, 0); } while (0)
; #define PG8_LDA(dst, b, h) do { _Pragma("unroll") for (int m = 0; m < 4; ++m) _Pragma("unroll") for (int k = 0; k < 2; ++k) dst[m][k] = *(const LAS bf16x8*)(lds + PG8_SA(b, h) + aoff + m * 2048 + k * 1024); } while (0)
; #define PG8_MMA(ai, bj, At, Bt) do { __builtin_amdgcn_s_setprio(1); _Pragma("unroll") for (int m = 0; m < 4; ++m) _Pragma("unroll") for (int n = 0; n < 2; ++n) _Pragma("unroll") for (int k = 0; k < 2; ++k) \
;         acc[ai][bj][m][n] = __builtin_amdgcn_mfma_f32_16x16x32_bf16(Bt[n][k], At[m][k], acc[ai][bj][m][n], 0, 0, 0); __builtin_amdgcn_s_setprio(0); } while (0)
; #define PG8_WAIT_V(n) asm volatile("s_waitcnt vmcnt(" #n ")" ::: "memory")
; #define PG8_WAIT_L(n) asm volatile("s_waitcnt lgkmcnt(" #n ")" ::: "memory")
; #define PG8_BAR __builtin_amdgcn_s_barrier()
; #define PG8_SCHED __builtin_amdgcn_sched_barrier(0)
; template <class Epi, class Sched, bool ALIGN_EPI>
; __device__ __forceinline__ void gemm_phase(LAS unsigned char* lds, const bf16_t* Ab, const bf16_t* Bb, int lda, int ldb, int K, const Sched& S, Epi& E) {
;     ...
;             PG8_LDA(At, 1, 1); PG8_STAGE(PG8_SB(1, 0), b3, voffB); PG8_STAGE(PG8_SB(1, 1), b3 + hstepB, voffB); PG8_STAGE(PG8_SA(1, 0), a3, voffA);
;             PG8_WAIT_V(8); PG8_WAIT_L(0); PG8_BAR; PG8_MMA(1, 0, At, B0); PG8_MMA(1, 1, At, B1); PG8_BAR; PG8_SCHED;
;         }
;         if constexpr (ALIGN_EPI) { if (wr == 0) PG8_BAR; }
	s_add_i32 s14, s74, s46
	v_lshl_add_u64 v[186:187], v[186:187], 0, s[26:27]
	s_mov_b32 m0, s14
	ds_read_b128 v[174:177], v190 offset:49152
	ds_read_b128 v[178:181], v190 offset:50176
	ds_read_b128 v[182:185], v190 offset:51200
	ds_read_b128 v[200:203], v190 offset:52224
	ds_read_b128 v[206:209], v190 offset:53248
	ds_read_b128 v[210:213], v190 offset:54272
	ds_read_b128 v[238:241], v190 offset:55296
	ds_read_b128 v[242:245], v190 offset:56320
	global_load_lds_dwordx4 v[186:187], off
	s_add_i32 m0, s14, 0x2000
	s_add_u32 s12, s12, 0x40080
	v_lshl_add_u64 v[186:187], v[188:189], 0, s[26:27]
	s_addc_u32 s13, s13, 0
	s_add_i32 s14, s75, s46
	global_load_lds_dwordx4 v[186:187], off
	v_lshl_add_u64 v[186:187], s[12:13], 0, v[134:135]
	s_mov_b32 m0, s14
	s_nop 0
	global_load_lds_dwordx4 v[186:187], off
	v_lshl_add_u64 v[186:187], s[12:13], 0, v[132:133]
	s_add_i32 m0, s14, 0x2000
	s_nop 0
	global_load_lds_dwordx4 v[186:187], off
	v_lshl_add_u64 v[186:187], v[196:197], 0, s[26:27]
	s_mov_b32 m0, s24
	s_nop 0
	global_load_lds_dwordx4 v[186:187], off
	v_lshl_add_u64 v[186:187], v[198:199], 0, s[26:27]
	s_mov_b32 m0, s87
	s_nop 0
	global_load_lds_dwordx4 v[186:187], off
	s_waitcnt vmcnt(8)
	s_waitcnt lgkmcnt(0)
	s_barrier
	s_setprio 1
	v_mfma_f32_16x16x32_bf16 v[62:65], v[140:143], v[174:177], v[62:65]
	v_mfma_f32_16x16x32_bf16 v[58:61], v[148:151], v[174:177], v[58:61]
	v_mfma_f32_16x16x32_bf16 v[54:57], v[140:143], v[182:185], v[54:57]
	v_mfma_f32_16x16x32_bf16 v[50:53], v[148:151], v[182:185], v[50:53]
	v_mfma_f32_16x16x32_bf16 v[46:49], v[140:143], v[206:209], v[46:49]
	v_mfma_f32_16x16x32_bf16 v[42:45], v[148:151], v[206:209], v[42:45]
	v_mfma_f32_16x16x32_bf16 v[38:41], v[140:143], v[238:241], v[38:41]
	v_mfma_f32_16x16x32_bf16 v[34:37], v[148:151], v[238:241], v[34:37]
	v_mfma_f32_16x16x32_bf16 v[62:65], v[144:147], v[178:181], v[62:65]
	v_mfma_f32_16x16x32_bf16 v[58:61], v[152:155], v[178:181], v[58:61]
	v_mfma_f32_16x16x32_bf16 v[54:57], v[144:147], v[200:203], v[54:57]
	v_mfma_f32_16x16x32_bf16 v[50:53], v[152:155], v[200:203], v[50:53]
	v_mfma_f32_16x16x32_bf16 v[46:49], v[144:147], v[210:213], v[46:49]
	v_mfma_f32_16x16x32_bf16 v[42:45], v[152:155], v[210:213], v[42:45]
	v_mfma_f32_16x16x32_bf16 v[38:41], v[144:147], v[242:245], v[38:41]
	v_mfma_f32_16x16x32_bf16 v[34:37], v[152:155], v[242:245], v[34:37]
	s_setprio 0
	s_setprio 1
	v_mfma_f32_16x16x32_bf16 v[30:33], v[156:159], v[174:177], v[30:33]
	v_mfma_f32_16x16x32_bf16 v[26:29], v[166:169], v[174:177], v[26:29]
	v_mfma_f32_16x16x32_bf16 v[22:25], v[156:159], v[182:185], v[22:25]
	v_mfma_f32_16x16x32_bf16 v[18:21], v[166:169], v[182:185], v[18:21]
	v_mfma_f32_16x16x32_bf16 v[14:17], v[156:159], v[206:209], v[14:17]
	v_mfma_f32_16x16x32_bf16 v[10:13], v[166:169], v[206:209], v[10:13]
	v_mfma_f32_16x16x32_bf16 v[6:9], v[156:159], v[238:241], v[6:9]
	v_mfma_f32_16x16x32_bf16 v[2:5], v[166:169], v[238:241], v[2:5]
	v_mfma_f32_16x16x32_bf16 v[30:33], v[162:165], v[178:181], v[30:33]
	v_mfma_f32_16x16x32_bf16 v[26:29], v[170:173], v[178:181], v[26:29]
	v_mfma_f32_16x16x32_bf16 v[22:25], v[162:165], v[200:203], v[22:25]
	v_mfma_f32_16x16x32_bf16 v[18:21], v[170:173], v[200:203], v[18:21]
	v_mfma_f32_16x16x32_bf16 v[14:17], v[162:165], v[210:213], v[14:17]
	v_mfma_f32_16x16x32_bf16 v[10:13], v[170:173], v[210:213], v[10:13]
	v_mfma_f32_16x16x32_bf16 v[6:9], v[162:165], v[242:245], v[6:9]
	v_mfma_f32_16x16x32_bf16 v[2:5], v[170:173], v[242:245], v[2:5]
	s_setprio 0
	s_barrier
	s_add_i32 s73, s73, 2
	s_add_u32 s10, s10, 0x100
	s_addc_u32 s11, s11, 0
	s_cmp_gt_u32 s73, 13
	s_cbranch_scc0 .LBB0_749
	s_and_b64 vcc, exec, s[56:57]
	s_cbranch_vccz .LBB0_752
	s_barrier

; #define PG8_STAGE(bufoff, gbase, voff) do { _Pragma("unroll") for (int _i = 0; _i < 2; ++_i) \
;         __builtin_amdgcn_global_load_lds((const unsigned*)((const char*)(gbase) + (voff)[_i]), (LAS unsigned*)(lds + (bufoff) + ldsw + _i * 8192), 16, 0, 0); } while (0)
; #define PG8_LDA(dst, b, h) do { _Pragma("unroll") for (int m = 0; m < 4; ++m) _Pragma("unroll") for (int k = 0; k < 2; ++k) dst[m][k] = *(const LAS bf16x8*)(lds + PG8_SA(b, h) + aoff + m * 2048 + k * 1024); } while (0)
; #define PG8_LDB(dst, b, h) do { _Pragma("unroll") for (int n = 0; n < 2; ++n) _Pragma("unroll") for (int k = 0; k < 2; ++k) dst[n][k] = *(const LAS bf16x8*)(lds + PG8_SB(b, h) + boff + n * 2048 + k * 1024); } while (0)
; #define PG8_MMA(ai, bj, At, Bt) do { __builtin_amdgcn_s_setprio(1); _Pragma("unroll") for (int m = 0; m < 4; ++m) _Pragma("unroll") for (int n = 0; n < 2; ++n) _Pragma("unroll") for (int k = 0; k < 2; ++k) \
;         acc[ai][bj][m][n] = __builtin_amdgcn_mfma_f32_16x16x32_bf16(Bt[n][k], At[m][k], acc[ai][bj][m][n], 0, 0, 0); __builtin_amdgcn_s_setprio(0); } while (0)
; template <class Epi, class Sched, bool ALIGN_EPI>
; __device__ __forceinline__ void gemm_phase(LAS unsigned char* lds, const bf16_t* Ab, const bf16_t* Bb, int lda, int ldb, int K, const Sched& S, Epi& E) {
;     ...
;         const bool has_next = S.next(ui + 1, nxt); nxt.ui = ui + 1;
;         const char* nA = has_next ? (const char*)(Ab + nxt.a_off) : cA; const char* nB = has_next ? (const char*)(Bb + nxt.b_off) : cB;
;         for (int t = 0; t < nt; t += 2) {
;             const bool last = (t == nt - 2);
;             const char* a1 = cA + (unsigned)(t + 1) * kstep;
;             const char* a2 = last ? nA : cA + (unsigned)(t + 2) * kstep; const char* b2 = last ? nB : cB + (unsigned)(t + 2) * kstep;
;             const char* a3 = a2 + kstep; const char* b3 = b2 + kstep;
;             PG8_LDB(B0, 0, 0); PG8_LDB(B1, 0, 1); PG8_SCHED; PG8_LDA(At, 0, 0); PG8_STAGE(PG8_SA(1, 1), a1 + hstepA, voffA);
;             PG8_WAIT_V(8); PG8_WAIT_L(0); PG8_BAR; PG8_MMA(0, 0, At, B0); PG8_MMA(0, 1, At, B1); PG8_BAR; PG8_SCHED;
;             PG8_LDA(At, 0, 1); PG8_STAGE(PG8_SB(0, 0), b2, voffB); PG8_STAGE(PG8_SB(0, 1), b2 + hstepB, voffB); PG8_STAGE(PG8_SA(0, 0), a2, voffA);
;             PG8_WAIT_V(8); PG8_WAIT_L(0); PG8_BAR; PG8_MMA(1, 0, At, B0); PG8_MMA(1, 1, At, B1); PG8_BAR; PG8_SCHED;
.LBB0_1017:
	s_add_u32 s52, s50, 0xfffc0080
	s_addc_u32 s53, s51, -1
	s_add_i32 s74, 0, 0x10000
	s_cmp_eq_u32 s73, 12
	s_cselect_b32 s55, s7, s53
	s_cselect_b32 s54, s69, s52
	s_cselect_b32 s53, s11, s72
	s_cselect_b32 s52, s70, s71
	s_add_i32 s76, 0, 0x14000
	v_add_u32_e32 v150, s74, v136
	v_add_u32_e32 v166, s76, v136
	ds_read_b128 v[138:141], v150
	ds_read_b128 v[142:145], v150 offset:1024
	ds_read_b128 v[146:149], v150 offset:2048
	ds_read_b128 v[150:153], v150 offset:3072
	ds_read_b128 v[154:157], v166
	ds_read_b128 v[158:161], v166 offset:1024
	ds_read_b128 v[162:165], v166 offset:2048
	ds_read_b128 v[166:169], v166 offset:3072
	v_lshl_add_u64 v[186:187], s[50:51], 0, v[0:1]
	s_add_i32 m0, s31, 0xc000
	ds_read_b128 v[170:173], v137
	ds_read_b128 v[174:177], v137 offset:1024
	ds_read_b128 v[178:181], v137 offset:2048
	ds_read_b128 v[182:185], v137 offset:3072
	ds_read_b128 v[200:203], v137 offset:4096
	ds_read_b128 v[206:209], v137 offset:5120
	ds_read_b128 v[210:213], v137 offset:6144
	ds_read_b128 v[238:241], v137 offset:7168
	global_load_lds_dwordx4 v[186:187], off
	v_lshl_add_u64 v[186:187], s[50:51], 0, v[134:135]
	s_add_i32 m0, s31, 0xe000
	s_nop 0
	global_load_lds_dwordx4 v[186:187], off
	s_waitcnt vmcnt(8)
	s_waitcnt lgkmcnt(0)
	s_barrier
	s_setprio 1
	v_mfma_f32_16x16x32_bf16 v[126:129], v[138:141], v[170:173], v[126:129]
	v_mfma_f32_16x16x32_bf16 v[122:125], v[146:149], v[170:173], v[122:125]
	v_mfma_f32_16x16x32_bf16 v[110:113], v[138:141], v[178:181], v[110:113]
	v_mfma_f32_16x16x32_bf16 v[106:109], v[146:149], v[178:181], v[106:109]
	v_mfma_f32_16x16x32_bf16 v[94:97], v[138:141], v[200:203], v[94:97]
	v_mfma_f32_16x16x32_bf16 v[90:93], v[146:149], v[200:203], v[90:93]
	v_mfma_f32_16x16x32_bf16 v[78:81], v[138:141], v[210:213], v[78:81]
	v_mfma_f32_16x16x32_bf16 v[74:77], v[146:149], v[210:213], v[74:77]
	v_mfma_f32_16x16x32_bf16 v[126:129], v[142:145], v[174:177], v[126:129]
	v_mfma_f32_16x16x32_bf16 v[122:125], v[150:153], v[174:177], v[122:125]
	v_mfma_f32_16x16x32_bf16 v[110:113], v[142:145], v[182:185], v[110:113]
	v_mfma_f32_16x16x32_bf16 v[106:109], v[150:153], v[182:185], v[106:109]
	v_mfma_f32_16x16x32_bf16 v[94:97], v[142:145], v[206:209], v[94:97]
	v_mfma_f32_16x16x32_bf16 v[90:93], v[150:153], v[206:209], v[90:93]
	v_mfma_f32_16x16x32_bf16 v[78:81], v[142:145], v[238:241], v[78:81]
	v_mfma_f32_16x16x32_bf16 v[74:77], v[150:153], v[238:241], v[74:77]
	s_setprio 0
	s_setprio 1
	v_mfma_f32_16x16x32_bf16 v[118:121], v[154:157], v[170:173], v[118:121]
	v_mfma_f32_16x16x32_bf16 v[114:117], v[162:165], v[170:173], v[114:117]
	v_mfma_f32_16x16x32_bf16 v[102:105], v[154:157], v[178:181], v[102:105]
	v_mfma_f32_16x16x32_bf16 v[98:101], v[162:165], v[178:181], v[98:101]
	v_mfma_f32_16x16x32_bf16 v[86:89], v[154:157], v[200:203], v[86:89]
	v_mfma_f32_16x16x32_bf16 v[82:85], v[162:165], v[200:203], v[82:85]
	v_mfma_f32_16x16x32_bf16 v[70:73], v[154:157], v[210:213], v[70:73]
	v_mfma_f32_16x16x32_bf16 v[66:69], v[162:165], v[210:213], v[66:69]
	v_mfma_f32_16x16x32_bf16 v[118:121], v[158:161], v[174:177], v[118:121]
	v_mfma_f32_16x16x32_bf16 v[114:117], v[166:169], v[174:177], v[114:117]
	v_mfma_f32_16x16x32_bf16 v[102:105], v[158:161], v[182:185], v[102:105]
	v_mfma_f32_16x16x32_bf16 v[98:101], v[166:169], v[182:185], v[98:101]
	v_mfma_f32_16x16x32_bf16 v[86:89], v[158:161], v[206:209], v[86:89]
	v_mfma_f32_16x16x32_bf16 v[82:85], v[166:169], v[206:209], v[82:85]
	v_mfma_f32_16x16x32_bf16 v[70:73], v[158:161], v[238:241], v[70:73]
	v_mfma_f32_16x16x32_bf16 v[66:69], v[166:169], v[238:241], v[66:69]
	s_setprio 0
	s_barrier
	s_add_i32 s74, s74, s24
	v_lshl_add_u64 v[186:187], s[52:53], 0, v[130:131]
	s_mov_b32 m0, s74
	ds_read_b128 v[170:173], v137 offset:16384
	ds_read_b128 v[174:177], v137 offset:17408
	ds_read_b128 v[178:181], v137 offset:18432
	ds_read_b128 v[182:185], v137 offset:19456
	ds_read_b128 v[200:203], v137 offset:20480
	ds_read_b128 v[206:209], v137 offset:21504
	ds_read_b128 v[210:213], v137 offset:22528
	ds_read_b128 v[238:241], v137 offset:23552
	global_load_lds_dwordx4 v[186:187], off
	s_add_i32 m0, s74, 0x2000
	s_add_u32 s74, s52, 0x40000
	v_lshl_add_u64 v[188:189], s[52:53], 0, v[132:133]
	s_addc_u32 s75, s53, 0
	s_add_i32 s76, s76, s24
	global_load_lds_dwordx4 v[188:189], off
	v_lshl_add_u64 v[196:197], s[74:75], 0, v[130:131]
	s_mov_b32 m0, s76
	v_lshl_add_u64 v[198:199], s[54:55], 0, v[134:135]
	global_load_lds_dwordx4 v[196:197], off
	v_lshl_add_u64 v[196:197], s[74:75], 0, v[132:133]
	s_add_i32 m0, s76, 0x2000
	s_nop 0
	global_load_lds_dwordx4 v[196:197], off
	v_lshl_add_u64 v[196:197], s[54:55], 0, v[0:1]
	s_mov_b32 m0, s31
	s_nop 0
	global_load_lds_dwordx4 v[196:197], off
	s_mov_b32 m0, s33
	s_nop 0
	global_load_lds_dwordx4 v[198:199], off
	s_waitcnt vmcnt(8)
	s_waitcnt lgkmcnt(0)
	s_barrier
; #define PG8_STAGE(bufoff, gbase, voff) do { _Pragma("unroll") for (int _i = 0; _i < 2; ++_i) \
;         __builtin_amdgcn_global_load_lds((const unsigned*)((const char*)(gbase) + (voff)[_i]), (LAS unsigned*)(lds + (bufoff) + ldsw + _i * 8192), 16, 0, 0); } while (0)
; #define PG8_LDA(dst, b, h) do { _Pragma("unroll") for (int m = 0; m < 4; ++m) _Pragma("unroll") for (int k = 0; k < 2; ++k) dst[m][k] = *(const LAS bf16x8*)(lds + PG8_SA(b, h) + aoff + m * 2048 + k * 1024); } while (0)
; #define PG8_LDB(dst, b, h) do { _Pragma("unroll") for (int n = 0; n < 2; ++n) _Pragma("unroll") for (int k = 0; k < 2; ++k) dst[n][k] = *(const LAS bf16x8*)(lds + PG8_SB(b, h) + boff + n * 2048 + k * 1024); } while (0)
; #define PG8_MMA(ai, bj, At, Bt) do { __builtin_amdgcn_s_setprio(1); _Pragma("unroll") for (int m = 0; m < 4; ++m) _Pragma("unroll") for (int n = 0; n < 2; ++n) _Pragma("unroll") for (int k = 0; k < 2; ++k) \
;         acc[ai][bj][m][n] = __builtin_amdgcn_mfma_f32_16x16x32_bf16(Bt[n][k], At[m][k], acc[ai][bj][m][n], 0, 0, 0); __builtin_amdgcn_s_setprio(0); } while (0)
; #define PG8_WAIT_V(n) asm volatile("s_waitcnt vmcnt(" #n ")" ::: "memory")
; #define PG8_WAIT_L(n) asm volatile("s_waitcnt lgkmcnt(" #n ")" ::: "memory")
; #define PG8_BAR __builtin_amdgcn_s_barrier()
; #define PG8_SCHED __builtin_amdgcn_sched_barrier(0)
; template <class Epi, class Sched, bool ALIGN_EPI>
; __device__ __forceinline__ void gemm_phase(LAS unsigned char* lds, const bf16_t* Ab, const bf16_t* Bb, int lda, int ldb, int K, const Sched& S, Epi& E) {
;     ...
;             PG8_WAIT_V(8); PG8_WAIT_L(0); PG8_BAR; PG8_MMA(1, 0, At, B0); PG8_MMA(1, 1, At, B1); PG8_BAR; PG8_SCHED;
;             PG8_LDB(B0, 1, 0); PG8_LDB(B1, 1, 1); PG8_SCHED; PG8_LDA(At, 1, 0); PG8_STAGE(PG8_SA(0, 1), a2 + hstepA, voffA);
;             PG8_WAIT_V(8); PG8_WAIT_L(0); PG8_BAR; PG8_MMA(0, 0, At, B0); PG8_MMA(0, 1, At, B1); PG8_BAR; PG8_SCHED;
	s_setprio 1
	v_mfma_f32_16x16x32_bf16 v[62:65], v[138:141], v[170:173], v[62:65]
	v_mfma_f32_16x16x32_bf16 v[58:61], v[146:149], v[170:173], v[58:61]
	v_mfma_f32_16x16x32_bf16 v[46:49], v[138:141], v[178:181], v[46:49]
	v_mfma_f32_16x16x32_bf16 v[42:45], v[146:149], v[178:181], v[42:45]
	v_mfma_f32_16x16x32_bf16 v[30:33], v[138:141], v[200:203], v[30:33]
	v_mfma_f32_16x16x32_bf16 v[26:29], v[146:149], v[200:203], v[26:29]
	v_mfma_f32_16x16x32_bf16 v[14:17], v[138:141], v[210:213], v[14:17]
	v_mfma_f32_16x16x32_bf16 v[10:13], v[146:149], v[210:213], v[10:13]
	v_mfma_f32_16x16x32_bf16 v[62:65], v[142:145], v[174:177], v[62:65]
	v_mfma_f32_16x16x32_bf16 v[58:61], v[150:153], v[174:177], v[58:61]
	v_mfma_f32_16x16x32_bf16 v[46:49], v[142:145], v[182:185], v[46:49]
	v_mfma_f32_16x16x32_bf16 v[42:45], v[150:153], v[182:185], v[42:45]
	v_mfma_f32_16x16x32_bf16 v[30:33], v[142:145], v[206:209], v[30:33]
	v_mfma_f32_16x16x32_bf16 v[26:29], v[150:153], v[206:209], v[26:29]
	v_mfma_f32_16x16x32_bf16 v[14:17], v[142:145], v[238:241], v[14:17]
	v_mfma_f32_16x16x32_bf16 v[10:13], v[150:153], v[238:241], v[10:13]
	s_setprio 0
	s_setprio 1
	v_mfma_f32_16x16x32_bf16 v[54:57], v[154:157], v[170:173], v[54:57]
	v_mfma_f32_16x16x32_bf16 v[50:53], v[162:165], v[170:173], v[50:53]
	v_mfma_f32_16x16x32_bf16 v[38:41], v[154:157], v[178:181], v[38:41]
	v_mfma_f32_16x16x32_bf16 v[34:37], v[162:165], v[178:181], v[34:37]
	v_mfma_f32_16x16x32_bf16 v[22:25], v[154:157], v[200:203], v[22:25]
	v_mfma_f32_16x16x32_bf16 v[18:21], v[162:165], v[200:203], v[18:21]
	v_mfma_f32_16x16x32_bf16 v[6:9], v[154:157], v[210:213], v[6:9]
	v_mfma_f32_16x16x32_bf16 v[2:5], v[162:165], v[210:213], v[2:5]
	v_mfma_f32_16x16x32_bf16 v[54:57], v[158:161], v[174:177], v[54:57]
	v_mfma_f32_16x16x32_bf16 v[50:53], v[166:169], v[174:177], v[50:53]
	v_mfma_f32_16x16x32_bf16 v[38:41], v[158:161], v[182:185], v[38:41]
	v_mfma_f32_16x16x32_bf16 v[34:37], v[166:169], v[182:185], v[34:37]
	v_mfma_f32_16x16x32_bf16 v[22:25], v[158:161], v[206:209], v[22:25]
	v_mfma_f32_16x16x32_bf16 v[18:21], v[166:169], v[206:209], v[18:21]
	v_mfma_f32_16x16x32_bf16 v[6:9], v[158:161], v[238:241], v[6:9]
	v_mfma_f32_16x16x32_bf16 v[2:5], v[166:169], v[238:241], v[2:5]
	s_setprio 0
	s_barrier
	s_add_i32 s74, 0, 0x18000
	s_add_i32 s75, 0, 0x1c000
	v_add_u32_e32 v150, s74, v136
	v_add_u32_e32 v166, s75, v136
	ds_read_b128 v[138:141], v150
	ds_read_b128 v[142:145], v150 offset:1024
	ds_read_b128 v[146:149], v150 offset:2048
	ds_read_b128 v[150:153], v150 offset:3072
	ds_read_b128 v[154:157], v166
	ds_read_b128 v[158:161], v166 offset:1024
	ds_read_b128 v[162:165], v166 offset:2048
	ds_read_b128 v[166:169], v166 offset:3072
	s_add_u32 s54, s54, 0x40000
	s_addc_u32 s55, s55, 0
	s_mov_b32 m0, s39
	v_lshl_add_u64 v[220:221], s[54:55], 0, v[0:1]
	ds_read_b128 v[170:173], v137 offset:32768
	ds_read_b128 v[174:177], v137 offset:33792
	ds_read_b128 v[178:181], v137 offset:34816
	ds_read_b128 v[182:185], v137 offset:35840
	ds_read_b128 v[200:203], v137 offset:36864
	ds_read_b128 v[206:209], v137 offset:37888
	ds_read_b128 v[210:213], v137 offset:38912
	ds_read_b128 v[238:241], v137 offset:39936
	global_load_lds_dwordx4 v[220:221], off
	v_lshl_add_u64 v[220:221], s[54:55], 0, v[134:135]
	s_mov_b32 m0, s44
	s_nop 0
	global_load_lds_dwordx4 v[220:221], off
	s_waitcnt vmcnt(8)
	s_waitcnt lgkmcnt(0)
	s_barrier
	s_setprio 1
	v_mfma_f32_16x16x32_bf16 v[126:129], v[138:141], v[170:173], v[126:129]
	v_mfma_f32_16x16x32_bf16 v[122:125], v[146:149], v[170:173], v[122:125]
	v_mfma_f32_16x16x32_bf16 v[110:113], v[138:141], v[178:181], v[110:113]
	v_mfma_f32_16x16x32_bf16 v[106:109], v[146:149], v[178:181], v[106:109]
	v_mfma_f32_16x16x32_bf16 v[94:97], v[138:141], v[200:203], v[94:97]
	v_mfma_f32_16x16x32_bf16 v[90:93], v[146:149], v[200:203], v[90:93]
	v_mfma_f32_16x16x32_bf16 v[78:81], v[138:141], v[210:213], v[78:81]
	v_mfma_f32_16x16x32_bf16 v[74:77], v[146:149], v[210:213], v[74:77]
	v_mfma_f32_16x16x32_bf16 v[126:129], v[142:145], v[174:177], v[126:129]
	v_mfma_f32_16x16x32_bf16 v[122:125], v[150:153], v[174:177], v[122:125]
	v_mfma_f32_16x16x32_bf16 v[110:113], v[142:145], v[182:185], v[110:113]
	v_mfma_f32_16x16x32_bf16 v[106:109], v[150:153], v[182:185], v[106:109]
	v_mfma_f32_16x16x32_bf16 v[94:97], v[142:145], v[206:209], v[94:97]
	v_mfma_f32_16x16x32_bf16 v[90:93], v[150:153], v[206:209], v[90:93]
	v_mfma_f32_16x16x32_bf16 v[78:81], v[142:145], v[238:241], v[78:81]
	v_mfma_f32_16x16x32_bf16 v[74:77], v[150:153], v[238:241], v[74:77]
	s_setprio 0
	s_setprio 1
	v_mfma_f32_16x16x32_bf16 v[118:121], v[154:157], v[170:173], v[118:121]
	v_mfma_f32_16x16x32_bf16 v[114:117], v[162:165], v[170:173], v[114:117]
	v_mfma_f32_16x16x32_bf16 v[102:105], v[154:157], v[178:181], v[102:105]
	v_mfma_f32_16x16x32_bf16 v[98:101], v[162:165], v[178:181], v[98:101]
	v_mfma_f32_16x16x32_bf16 v[86:89], v[154:157], v[200:203], v[86:89]
	v_mfma_f32_16x16x32_bf16 v[82:85], v[162:165], v[200:203], v[82:85]
	v_mfma_f32_16x16x32_bf16 v[70:73], v[154:157], v[210:213], v[70:73]
	v_mfma_f32_16x16x32_bf16 v[66:69], v[162:165], v[210:213], v[66:69]
	v_mfma_f32_16x16x32_bf16 v[118:121], v[158:161], v[174:177], v[118:121]
	v_mfma_f32_16x16x32_bf16 v[114:117], v[166:169], v[174:177], v[114:117]
	v_mfma_f32_16x16x32_bf16 v[102:105], v[158:161], v[182:185], v[102:105]
	v_mfma_f32_16x16x32_bf16 v[98:101], v[166:169], v[182:185], v[98:101]
	v_mfma_f32_16x16x32_bf16 v[86:89], v[158:161], v[206:209], v[86:89]
	v_mfma_f32_16x16x32_bf16 v[82:85], v[166:169], v[206:209], v[82:85]
	v_mfma_f32_16x16x32_bf16 v[70:73], v[158:161], v[238:241], v[70:73]
	v_mfma_f32_16x16x32_bf16 v[66:69], v[166:169], v[238:241], v[66:69]
	s_setprio 0
	s_barrier
; __device__ __forceinline__ u32x4 pack8(f32x4 a, f32x4 b) { u32x4 w; w.x = cvtpk(a[0], a[1]); w.y = cvtpk(a[2], a[3]); w.z = cvtpk(b[0], b[1]); w.w = cvtpk(b[2], b[3]); return w; }
; #define PG8_STAGE(bufoff, gbase, voff) do { _Pragma("unroll") for (int _i = 0; _i < 2; ++_i) \
;         __builtin_amdgcn_global_load_lds((const unsigned*)((const char*)(gbase) + (voff)[_i]), (LAS unsigned*)(lds + (bufoff) + ldsw + _i * 8192), 16, 0, 0); } while (0)
; #define PG8_LDA(dst, b, h) do { _Pragma("unroll") for (int m = 0; m < 4; ++m) _Pragma("unroll") for (int k = 0; k < 2; ++k) dst[m][k] = *(const LAS bf16x8*)(lds + PG8_SA(b, h) + aoff + m * 2048 + k * 1024); } while (0)
; #define PG8_WAIT_V(n) asm volatile("s_waitcnt vmcnt(" #n ")" ::: "memory")
; #define PG8_BAR __builtin_amdgcn_s_barrier()
; template <class Epi, class Sched, bool ALIGN_EPI>
; __device__ __forceinline__ void gemm_phase(LAS unsigned char* lds, const bf16_t* Ab, const bf16_t* Bb, int lda, int ldb, int K, const Sched& S, Epi& E) {
;     ...
;             PG8_LDA(At, 1, 1); PG8_STAGE(PG8_SB(1, 0), b3, voffB); PG8_STAGE(PG8_SB(1, 1), b3 + hstepB, voffB); PG8_STAGE(PG8_SA(1, 0), a3, voffA);
;             PG8_WAIT_V(8); PG8_WAIT_L(0); PG8_BAR; PG8_MMA(1, 0, At, B0); PG8_MMA(1, 1, At, B1); PG8_BAR; PG8_SCHED;
;         }
;         if constexpr (ALIGN_EPI) { if (wr == 0) PG8_BAR; }
;     __device__ __forceinline__ void operator()(AccRef acc, const Unit& u, int wr, int wc, int fr, int fq) const {
;     ...
;                 const int row = u.pm * 256 + ai * 128 + wr * 64 + m * 16 + fr;
; #pragma unroll
;                 for (int bj = 0; bj < 2; ++bj) {
;                     const int col = u.pn * 256 + bj * 128 + wc * 32 + 8 * fq;
;                     const u32x4 w = pack8(acc[ai][bj][m][0], acc[ai][bj][m][1]);
;                     if (u.pn < 4) *(u32x4*)(kx + lo + (size_t)row * 1024 + col) = w;
;                     else { const int c2 = col - 1024, h = c2 >> 8, d = c2 & 255, b = row >> 8, mm = row & 255;
;                         bf16_t* p = vxt + lo + ((size_t)((b * 4 + h) * 256 + d)) * 256 + mm;
;                         p[0] = (bf16_t)(w.x & 0xffff); p[256] = (bf16_t)(w.x >> 16); p[512] = (bf16_t)(w.y & 0xffff); p[768] = (bf16_t)(w.y >> 16);
;                         p[1024] = (bf16_t)(w.z & 0xffff); p[1280] = (bf16_t)(w.z >> 16); p[1536] = (bf16_t)(w.w & 0xffff); p[1792] = (bf16_t)(w.w >> 16); }
	s_add_i32 s54, s74, s24
	v_lshl_add_u64 v[186:187], v[186:187], 0, s[26:27]
	s_mov_b32 m0, s54
	ds_read_b128 v[170:173], v137 offset:49152
	ds_read_b128 v[174:177], v137 offset:50176
	ds_read_b128 v[178:181], v137 offset:51200
	ds_read_b128 v[182:185], v137 offset:52224
	ds_read_b128 v[200:203], v137 offset:53248
	ds_read_b128 v[206:209], v137 offset:54272
	ds_read_b128 v[210:213], v137 offset:55296
	ds_read_b128 v[238:241], v137 offset:56320
	global_load_lds_dwordx4 v[186:187], off
	s_add_i32 m0, s54, 0x2000
	s_add_u32 s52, s52, 0x40080
	v_lshl_add_u64 v[186:187], v[188:189], 0, s[26:27]
	s_addc_u32 s53, s53, 0
	s_add_i32 s54, s75, s24
	global_load_lds_dwordx4 v[186:187], off
	v_lshl_add_u64 v[186:187], s[52:53], 0, v[130:131]
	s_mov_b32 m0, s54
	s_nop 0
	global_load_lds_dwordx4 v[186:187], off
	v_lshl_add_u64 v[186:187], s[52:53], 0, v[132:133]
	s_add_i32 m0, s54, 0x2000
	s_nop 0
	global_load_lds_dwordx4 v[186:187], off
	v_lshl_add_u64 v[186:187], v[196:197], 0, s[26:27]
	s_mov_b32 m0, s60
	s_nop 0
	global_load_lds_dwordx4 v[186:187], off
	v_lshl_add_u64 v[186:187], v[198:199], 0, s[26:27]
	s_mov_b32 m0, s61
	s_nop 0
	global_load_lds_dwordx4 v[186:187], off
	s_waitcnt vmcnt(8)
	s_waitcnt lgkmcnt(0)
	s_barrier
	s_setprio 1
	v_mfma_f32_16x16x32_bf16 v[62:65], v[138:141], v[170:173], v[62:65]
	v_mfma_f32_16x16x32_bf16 v[58:61], v[146:149], v[170:173], v[58:61]
	v_mfma_f32_16x16x32_bf16 v[46:49], v[138:141], v[178:181], v[46:49]
	v_mfma_f32_16x16x32_bf16 v[42:45], v[146:149], v[178:181], v[42:45]
	v_mfma_f32_16x16x32_bf16 v[30:33], v[138:141], v[200:203], v[30:33]
	v_mfma_f32_16x16x32_bf16 v[26:29], v[146:149], v[200:203], v[26:29]
	v_mfma_f32_16x16x32_bf16 v[14:17], v[138:141], v[210:213], v[14:17]
	v_mfma_f32_16x16x32_bf16 v[10:13], v[146:149], v[210:213], v[10:13]
	v_mfma_f32_16x16x32_bf16 v[62:65], v[142:145], v[174:177], v[62:65]
	v_mfma_f32_16x16x32_bf16 v[58:61], v[150:153], v[174:177], v[58:61]
	v_mfma_f32_16x16x32_bf16 v[46:49], v[142:145], v[182:185], v[46:49]
	v_mfma_f32_16x16x32_bf16 v[42:45], v[150:153], v[182:185], v[42:45]
	v_mfma_f32_16x16x32_bf16 v[30:33], v[142:145], v[206:209], v[30:33]
	v_mfma_f32_16x16x32_bf16 v[26:29], v[150:153], v[206:209], v[26:29]
	v_mfma_f32_16x16x32_bf16 v[14:17], v[142:145], v[238:241], v[14:17]
	v_mfma_f32_16x16x32_bf16 v[10:13], v[150:153], v[238:241], v[10:13]
	s_setprio 0
	s_setprio 1
	v_mfma_f32_16x16x32_bf16 v[54:57], v[154:157], v[170:173], v[54:57]
	v_mfma_f32_16x16x32_bf16 v[50:53], v[162:165], v[170:173], v[50:53]
	v_mfma_f32_16x16x32_bf16 v[38:41], v[154:157], v[178:181], v[38:41]
	v_mfma_f32_16x16x32_bf16 v[34:37], v[162:165], v[178:181], v[34:37]
	v_mfma_f32_16x16x32_bf16 v[22:25], v[154:157], v[200:203], v[22:25]
	v_mfma_f32_16x16x32_bf16 v[18:21], v[162:165], v[200:203], v[18:21]
	v_mfma_f32_16x16x32_bf16 v[6:9], v[154:157], v[210:213], v[6:9]
	v_mfma_f32_16x16x32_bf16 v[2:5], v[162:165], v[210:213], v[2:5]
	v_mfma_f32_16x16x32_bf16 v[54:57], v[158:161], v[174:177], v[54:57]
	v_mfma_f32_16x16x32_bf16 v[50:53], v[166:169], v[174:177], v[50:53]
	v_mfma_f32_16x16x32_bf16 v[38:41], v[158:161], v[182:185], v[38:41]
	v_mfma_f32_16x16x32_bf16 v[34:37], v[166:169], v[182:185], v[34:37]
	v_mfma_f32_16x16x32_bf16 v[22:25], v[158:161], v[206:209], v[22:25]
	v_mfma_f32_16x16x32_bf16 v[18:21], v[166:169], v[206:209], v[18:21]
	v_mfma_f32_16x16x32_bf16 v[6:9], v[158:161], v[238:241], v[6:9]
	v_mfma_f32_16x16x32_bf16 v[2:5], v[166:169], v[238:241], v[2:5]
	s_setprio 0
	s_barrier
	s_add_i32 s73, s73, 2
	s_add_u32 s50, s50, 0x100
	s_addc_u32 s51, s51, 0
	s_add_u32 s71, s71, 0x100
	s_addc_u32 s72, s72, 0
	s_cmp_gt_u32 s73, 13
	s_cbranch_scc0 .LBB0_1017
	v_mov_b32_e32 v0, v236
	s_lshl_b32 s25, s25, 8
	v_and_b32_e32 v133, 15, v0
	s_ashr_i32 s7, s6, 31
	v_lshrrev_b32_e32 v0, 1, v0
	s_add_i32 s25, s25, s56
	s_lshl_b64 s[50:51], s[6:7], 20
	v_and_or_b32 v132, v0, 24, s58
	v_mov_b32_e32 v0, s25
	s_movk_i32 s6, 0xcf
	v_bitop3_b32 v0, v133, s6, v0 bitop3:0xc8
	s_lshl_b32 s6, s25, 2
	s_and_b32 s69, s6, 0xfffffc00
	s_addk_i32 s69, 0xfc00
	s_lshl_b32 s11, s68, 8
	s_cmp_gt_i32 s68, 3
	s_cselect_b64 s[52:53], -1, 0
	v_cvt_pk_bf16_f32 v126, v126, v127
	v_cvt_pk_bf16_f32 v127, v128, v129
	v_cvt_pk_bf16_f32 v128, v122, v123
	v_cvt_pk_bf16_f32 v129, v124, v125
	s_mov_b64 s[6:7], -1
	s_and_b64 vcc, exec, s[52:53]
	v_lshlrev_b32_e32 v0, 1, v0
	v_or_b32_e32 v130, s11, v132
	s_cbranch_vccz .LBB0_1020
	s_lshl_b64 s[6:7], s[50:51], 1
	s_add_u32 s6, s47, s6
	s_addc_u32 s7, s49, s7
	s_add_i32 s54, s69, s11
	v_or_b32_e32 v122, s54, v132
	v_ashrrev_i32_e32 v123, 31, v122
	v_lshlrev_b64 v[122:123], 9, v[122:123]
	v_lshl_add_u64 v[122:123], s[6:7], 0, v[122:123]
	v_lshl_add_u64 v[122:123], v[122:123], 0, v[0:1]
	global_store_short v[122:123], v126, off
	global_store_short_d16_hi v[122:123], v126, off offset:512
	global_store_short v[122:123], v127, off offset:1024
	global_store_short_d16_hi v[122:123], v127, off offset:1536
	global_store_short v[122:123], v128, off offset:2048
	global_store_short_d16_hi v[122:123], v128, off offset:2560
	global_store_short v[122:123], v129, off offset:3072
	global_store_short_d16_hi v[122:123], v129, off offset:3584
	v_or_b32_e32 v122, s11, v132
	s_mov_b64 s[6:7], 0

; #define PG8_STAGE(bufoff, gbase, voff) do { _Pragma("unroll") for (int _i = 0; _i < 2; ++_i) \
;         __builtin_amdgcn_global_load_lds((const unsigned*)((const char*)(gbase) + (voff)[_i]), (LAS unsigned*)(lds + (bufoff) + ldsw + _i * 8192), 16, 0, 0); } while (0)
; #define PG8_LDA(dst, b, h) do { _Pragma("unroll") for (int m = 0; m < 4; ++m) _Pragma("unroll") for (int k = 0; k < 2; ++k) dst[m][k] = *(const LAS bf16x8*)(lds + PG8_SA(b, h) + aoff + m * 2048 + k * 1024); } while (0)
; #define PG8_LDB(dst, b, h) do { _Pragma("unroll") for (int n = 0; n < 2; ++n) _Pragma("unroll") for (int k = 0; k < 2; ++k) dst[n][k] = *(const LAS bf16x8*)(lds + PG8_SB(b, h) + boff + n * 2048 + k * 1024); } while (0)
; #define PG8_MMA(ai, bj, At, Bt) do { __builtin_amdgcn_s_setprio(1); _Pragma("unroll") for (int m = 0; m < 4; ++m) _Pragma("unroll") for (int n = 0; n < 2; ++n) _Pragma("unroll") for (int k = 0; k < 2; ++k) \
;         acc[ai][bj][m][n] = __builtin_amdgcn_mfma_f32_16x16x32_bf16(Bt[n][k], At[m][k], acc[ai][bj][m][n], 0, 0, 0); __builtin_amdgcn_s_setprio(0); } while (0)
; #define PG8_WAIT_V(n) asm volatile("s_waitcnt vmcnt(" #n ")" ::: "memory")
; #define PG8_WAIT_L(n) asm volatile("s_waitcnt lgkmcnt(" #n ")" ::: "memory")
; #define PG8_BAR __builtin_amdgcn_s_barrier()
; template <class Epi, class Sched, bool ALIGN_EPI>
; __device__ __forceinline__ void gemm_phase(LAS unsigned char* lds, const bf16_t* Ab, const bf16_t* Bb, int lda, int ldb, int K, const Sched& S, Epi& E) {
;     ...
;         for (int t = 0; t < nt; t += 2) {
;             const bool last = (t == nt - 2);
;             const char* a1 = cA + (unsigned)(t + 1) * kstep;
;             const char* a2 = last ? nA : cA + (unsigned)(t + 2) * kstep; const char* b2 = last ? nB : cB + (unsigned)(t + 2) * kstep;
;             const char* a3 = a2 + kstep; const char* b3 = b2 + kstep;
;             PG8_LDB(B0, 0, 0); PG8_LDB(B1, 0, 1); PG8_SCHED; PG8_LDA(At, 0, 0); PG8_STAGE(PG8_SA(1, 1), a1 + hstepA, voffA);
;             PG8_WAIT_V(8); PG8_WAIT_L(0); PG8_BAR; PG8_MMA(0, 0, At, B0); PG8_MMA(0, 1, At, B1); PG8_BAR; PG8_SCHED;
;             PG8_LDA(At, 0, 1); PG8_STAGE(PG8_SB(0, 0), b2, voffB); PG8_STAGE(PG8_SB(0, 1), b2 + hstepB, voffB); PG8_STAGE(PG8_SA(0, 0), a2, voffA);
;             PG8_WAIT_V(8); PG8_WAIT_L(0); PG8_BAR; PG8_MMA(1, 0, At, B0); PG8_MMA(1, 1, At, B1); PG8_BAR; PG8_SCHED;
.LBB0_1093:
	s_add_u32 s52, s59, s50
	s_addc_u32 s53, s60, s51
	s_add_u32 s52, s52, 0xe800100
	s_addc_u32 s53, s53, 0
	s_add_u32 s64, s61, s50
	s_addc_u32 s65, s62, s51
	s_add_i32 s66, 0, 0x10000
	v_add_u32_e32 v92, s66, v78
	ds_read_b128 v[80:83], v92
	ds_read_b128 v[84:87], v92 offset:1024
	ds_read_b128 v[88:91], v92 offset:2048
	ds_read_b128 v[92:95], v92 offset:3072
	s_cmpk_eq_i32 s50, 0x300
	s_cselect_b32 s55, s15, s53
	s_cselect_b32 s54, s14, s52
	s_cselect_b32 s53, s7, s65
	s_cselect_b32 s52, s6, s64
	v_lshl_add_u64 v[128:129], v[72:73], 0, s[50:51]
	s_add_i32 m0, s24, 0xc000
	ds_read_b128 v[96:99], v79
	ds_read_b128 v[100:103], v79 offset:1024
	ds_read_b128 v[104:107], v79 offset:2048
	ds_read_b128 v[108:111], v79 offset:3072
	ds_read_b128 v[112:115], v79 offset:4096
	ds_read_b128 v[116:119], v79 offset:5120
	ds_read_b128 v[120:123], v79 offset:6144
	ds_read_b128 v[124:127], v79 offset:7168
	global_load_lds_dwordx4 v[128:129], off
	v_lshl_add_u64 v[128:129], v[74:75], 0, s[50:51]
	s_add_i32 m0, s24, 0xe000
	s_nop 0
	global_load_lds_dwordx4 v[128:129], off
	s_waitcnt vmcnt(8)
	s_waitcnt lgkmcnt(0)
	s_barrier
	s_setprio 1
	v_mfma_f32_16x16x32_bf16 v[62:65], v[80:83], v[96:99], v[62:65]
	v_mfma_f32_16x16x32_bf16 v[58:61], v[88:91], v[96:99], v[58:61]
	v_mfma_f32_16x16x32_bf16 v[54:57], v[80:83], v[104:107], v[54:57]
	v_mfma_f32_16x16x32_bf16 v[50:53], v[88:91], v[104:107], v[50:53]
	v_mfma_f32_16x16x32_bf16 v[46:49], v[80:83], v[112:115], v[46:49]
	v_mfma_f32_16x16x32_bf16 v[42:45], v[88:91], v[112:115], v[42:45]
	v_mfma_f32_16x16x32_bf16 v[38:41], v[80:83], v[120:123], v[38:41]
	v_mfma_f32_16x16x32_bf16 v[34:37], v[88:91], v[120:123], v[34:37]
	v_mfma_f32_16x16x32_bf16 v[62:65], v[84:87], v[100:103], v[62:65]
	v_mfma_f32_16x16x32_bf16 v[58:61], v[92:95], v[100:103], v[58:61]
	v_mfma_f32_16x16x32_bf16 v[54:57], v[84:87], v[108:111], v[54:57]
	v_mfma_f32_16x16x32_bf16 v[50:53], v[92:95], v[108:111], v[50:53]
	v_mfma_f32_16x16x32_bf16 v[46:49], v[84:87], v[116:119], v[46:49]
	v_mfma_f32_16x16x32_bf16 v[42:45], v[92:95], v[116:119], v[42:45]
	v_mfma_f32_16x16x32_bf16 v[38:41], v[84:87], v[124:127], v[38:41]
	v_mfma_f32_16x16x32_bf16 v[34:37], v[92:95], v[124:127], v[34:37]
	s_setprio 0
	s_setprio 1
	s_setprio 0
	s_barrier
	s_add_i32 s64, s66, s22
	v_lshl_add_u64 v[128:129], s[52:53], 0, v[0:1]
	s_mov_b32 m0, s64
	ds_read_b128 v[96:99], v79 offset:16384
	ds_read_b128 v[100:103], v79 offset:17408
	ds_read_b128 v[104:107], v79 offset:18432
	ds_read_b128 v[108:111], v79 offset:19456
	ds_read_b128 v[112:115], v79 offset:20480
	ds_read_b128 v[116:119], v79 offset:21504
	ds_read_b128 v[120:123], v79 offset:22528
	ds_read_b128 v[124:127], v79 offset:23552
	global_load_lds_dwordx4 v[128:129], off
	s_add_i32 m0, s64, 0x2000
	s_add_u32 s64, s52, 0x20000
	v_lshl_add_u64 v[130:131], s[52:53], 0, v[66:67]
	s_addc_u32 s65, s53, 0
	global_load_lds_dwordx4 v[130:131], off
	v_lshl_add_u64 v[132:133], s[64:65], 0, v[0:1]
	s_mov_b32 m0, s25
	v_lshl_add_u64 v[134:135], s[54:55], 0, v[68:69]
	global_load_lds_dwordx4 v[132:133], off
	v_lshl_add_u64 v[132:133], s[64:65], 0, v[66:67]
	s_mov_b32 m0, s31
	s_nop 0
	global_load_lds_dwordx4 v[132:133], off
	v_lshl_add_u64 v[132:133], s[54:55], 0, v[70:71]
	s_mov_b32 m0, s24
	s_nop 0
	global_load_lds_dwordx4 v[132:133], off
	s_mov_b32 m0, s33
	s_nop 0
	global_load_lds_dwordx4 v[134:135], off
	s_waitcnt vmcnt(8)
	s_waitcnt lgkmcnt(0)
	s_barrier
	s_setprio 1
	v_mfma_f32_16x16x32_bf16 v[30:33], v[80:83], v[96:99], v[30:33]
	v_mfma_f32_16x16x32_bf16 v[26:29], v[88:91], v[96:99], v[26:29]
	v_mfma_f32_16x16x32_bf16 v[22:25], v[80:83], v[104:107], v[22:25]
	v_mfma_f32_16x16x32_bf16 v[18:21], v[88:91], v[104:107], v[18:21]
	v_mfma_f32_16x16x32_bf16 v[14:17], v[80:83], v[112:115], v[14:17]
	v_mfma_f32_16x16x32_bf16 v[10:13], v[88:91], v[112:115], v[10:13]
	v_mfma_f32_16x16x32_bf16 v[6:9], v[80:83], v[120:123], v[6:9]
	v_mfma_f32_16x16x32_bf16 v[2:5], v[88:91], v[120:123], v[2:5]
	v_mfma_f32_16x16x32_bf16 v[30:33], v[84:87], v[100:103], v[30:33]
	v_mfma_f32_16x16x32_bf16 v[26:29], v[92:95], v[100:103], v[26:29]
	v_mfma_f32_16x16x32_bf16 v[22:25], v[84:87], v[108:111], v[22:25]
	v_mfma_f32_16x16x32_bf16 v[18:21], v[92:95], v[108:111], v[18:21]
	v_mfma_f32_16x16x32_bf16 v[14:17], v[84:87], v[116:119], v[14:17]
	v_mfma_f32_16x16x32_bf16 v[10:13], v[92:95], v[116:119], v[10:13]
	v_mfma_f32_16x16x32_bf16 v[6:9], v[84:87], v[124:127], v[6:9]
	v_mfma_f32_16x16x32_bf16 v[2:5], v[92:95], v[124:127], v[2:5]
	s_setprio 0
	s_setprio 1
	s_setprio 0
	s_barrier
; #define PG8_STAGE(bufoff, gbase, voff) do { _Pragma("unroll") for (int _i = 0; _i < 2; ++_i) \
;         __builtin_amdgcn_global_load_lds((const unsigned*)((const char*)(gbase) + (voff)[_i]), (LAS unsigned*)(lds + (bufoff) + ldsw + _i * 8192), 16, 0, 0); } while (0)
; #define PG8_LDA(dst, b, h) do { _Pragma("unroll") for (int m = 0; m < 4; ++m) _Pragma("unroll") for (int k = 0; k < 2; ++k) dst[m][k] = *(const LAS bf16x8*)(lds + PG8_SA(b, h) + aoff + m * 2048 + k * 1024); } while (0)
; #define PG8_LDB(dst, b, h) do { _Pragma("unroll") for (int n = 0; n < 2; ++n) _Pragma("unroll") for (int k = 0; k < 2; ++k) dst[n][k] = *(const LAS bf16x8*)(lds + PG8_SB(b, h) + boff + n * 2048 + k * 1024); } while (0)
; #define PG8_WAIT_V(n) asm volatile("s_waitcnt vmcnt(" #n ")" ::: "memory")
; #define PG8_BAR __builtin_amdgcn_s_barrier()
; template <class Epi, class Sched, bool ALIGN_EPI>
; __device__ __forceinline__ void gemm_phase(LAS unsigned char* lds, const bf16_t* Ab, const bf16_t* Bb, int lda, int ldb, int K, const Sched& S, Epi& E) {
;     ...
;             PG8_LDB(B0, 1, 0); PG8_LDB(B1, 1, 1); PG8_SCHED; PG8_LDA(At, 1, 0); PG8_STAGE(PG8_SA(0, 1), a2 + hstepA, voffA);
;             PG8_WAIT_V(8); PG8_WAIT_L(0); PG8_BAR; PG8_MMA(0, 0, At, B0); PG8_MMA(0, 1, At, B1); PG8_BAR; PG8_SCHED;
;             PG8_LDA(At, 1, 1); PG8_STAGE(PG8_SB(1, 0), b3, voffB); PG8_STAGE(PG8_SB(1, 1), b3 + hstepB, voffB); PG8_STAGE(PG8_SA(1, 0), a3, voffA);
;             PG8_WAIT_V(8); PG8_WAIT_L(0); PG8_BAR; PG8_MMA(1, 0, At, B0); PG8_MMA(1, 1, At, B1); PG8_BAR; PG8_SCHED;
;         }
;         if constexpr (ALIGN_EPI) { if (wr == 0) PG8_BAR; }
;         if constexpr (!Epi::AFTER_DRAIN) { int t2 = threadIdx.x; asm volatile("" : "+v"(t2)); E(acc, cur, wr, wc, t2 & 15, (t2 >> 4) & 3); }
;         if (!has_next) break;
; #pragma unroll
;         for (int a = 0; a < 2; ++a)
; #pragma unroll
;             for (int b = 0; b < 2; ++b)
; #pragma unroll
;                 for (int m = 0; m < 4; ++m)
; #pragma unroll
;                     for (int n = 0; n < 2; ++n) acc[a][b][m][n] = (f32x4){0.f, 0.f, 0.f, 0.f};
;         cur = nxt; cA = nA; cB = nB; ++ui;
;         { int t3 = threadIdx.x; asm volatile("" : "+v"(t3)); PG8_LANEOFFS(t3); }
;         if constexpr (ALIGN_EPI) { if (wr == 1) PG8_BAR; }
;     }
;     PG8_WAIT_V(0);
;     if constexpr (!ALIGN_EPI) { if (wr == 0) PG8_BAR; }
	s_add_i32 s64, 0, 0x18000
	v_add_u32_e32 v92, s64, v78
	ds_read_b128 v[80:83], v92
	ds_read_b128 v[84:87], v92 offset:1024
	ds_read_b128 v[88:91], v92 offset:2048
	ds_read_b128 v[92:95], v92 offset:3072
	s_add_u32 s54, s54, 0x28000
	s_addc_u32 s55, s55, 0
	s_mov_b32 m0, s45
	v_lshl_add_u64 v[136:137], s[54:55], 0, v[70:71]
	ds_read_b128 v[96:99], v79 offset:32768
	ds_read_b128 v[100:103], v79 offset:33792
	ds_read_b128 v[104:107], v79 offset:34816
	ds_read_b128 v[108:111], v79 offset:35840
	ds_read_b128 v[112:115], v79 offset:36864
	ds_read_b128 v[116:119], v79 offset:37888
	ds_read_b128 v[120:123], v79 offset:38912
	ds_read_b128 v[124:127], v79 offset:39936
	global_load_lds_dwordx4 v[136:137], off
	v_lshl_add_u64 v[136:137], s[54:55], 0, v[68:69]
	s_mov_b32 m0, s46
	s_nop 0
	global_load_lds_dwordx4 v[136:137], off
	s_waitcnt vmcnt(8)
	s_waitcnt lgkmcnt(0)
	s_barrier
	s_setprio 1
	v_mfma_f32_16x16x32_bf16 v[62:65], v[80:83], v[96:99], v[62:65]
	v_mfma_f32_16x16x32_bf16 v[58:61], v[88:91], v[96:99], v[58:61]
	v_mfma_f32_16x16x32_bf16 v[54:57], v[80:83], v[104:107], v[54:57]
	v_mfma_f32_16x16x32_bf16 v[50:53], v[88:91], v[104:107], v[50:53]
	v_mfma_f32_16x16x32_bf16 v[46:49], v[80:83], v[112:115], v[46:49]
	v_mfma_f32_16x16x32_bf16 v[42:45], v[88:91], v[112:115], v[42:45]
	v_mfma_f32_16x16x32_bf16 v[38:41], v[80:83], v[120:123], v[38:41]
	v_mfma_f32_16x16x32_bf16 v[34:37], v[88:91], v[120:123], v[34:37]
	v_mfma_f32_16x16x32_bf16 v[62:65], v[84:87], v[100:103], v[62:65]
	v_mfma_f32_16x16x32_bf16 v[58:61], v[92:95], v[100:103], v[58:61]
	v_mfma_f32_16x16x32_bf16 v[54:57], v[84:87], v[108:111], v[54:57]
	v_mfma_f32_16x16x32_bf16 v[50:53], v[92:95], v[108:111], v[50:53]
	v_mfma_f32_16x16x32_bf16 v[46:49], v[84:87], v[116:119], v[46:49]
	v_mfma_f32_16x16x32_bf16 v[42:45], v[92:95], v[116:119], v[42:45]
	v_mfma_f32_16x16x32_bf16 v[38:41], v[84:87], v[124:127], v[38:41]
	v_mfma_f32_16x16x32_bf16 v[34:37], v[92:95], v[124:127], v[34:37]
	s_setprio 0
	s_setprio 1
	s_setprio 0
	s_barrier
	s_add_i32 s54, s64, s22
	v_lshl_add_u64 v[128:129], v[128:129], 0, s[26:27]
	s_mov_b32 m0, s54
	ds_read_b128 v[96:99], v79 offset:49152
	ds_read_b128 v[100:103], v79 offset:50176
	ds_read_b128 v[104:107], v79 offset:51200
	ds_read_b128 v[108:111], v79 offset:52224
	ds_read_b128 v[112:115], v79 offset:53248
	ds_read_b128 v[116:119], v79 offset:54272
	ds_read_b128 v[120:123], v79 offset:55296
	ds_read_b128 v[124:127], v79 offset:56320
	global_load_lds_dwordx4 v[128:129], off
	s_add_i32 m0, s54, 0x2000
	s_add_u32 s52, s52, 0x20080
	v_lshl_add_u64 v[128:129], v[130:131], 0, s[26:27]
	s_addc_u32 s53, s53, 0
	global_load_lds_dwordx4 v[128:129], off
	v_lshl_add_u64 v[128:129], s[52:53], 0, v[0:1]
	s_mov_b32 m0, s57
	s_nop 0
	global_load_lds_dwordx4 v[128:129], off
	v_lshl_add_u64 v[128:129], s[52:53], 0, v[66:67]
	s_mov_b32 m0, s58
	s_nop 0
	global_load_lds_dwordx4 v[128:129], off
	v_lshl_add_u64 v[128:129], v[132:133], 0, s[26:27]
	s_mov_b32 m0, s47
	s_nop 0
	global_load_lds_dwordx4 v[128:129], off
	v_lshl_add_u64 v[128:129], v[134:135], 0, s[26:27]
	s_mov_b32 m0, s56
	s_nop 0
	global_load_lds_dwordx4 v[128:129], off
	s_waitcnt vmcnt(8)
	s_waitcnt lgkmcnt(0)
	s_barrier
	s_setprio 1
	v_mfma_f32_16x16x32_bf16 v[30:33], v[80:83], v[96:99], v[30:33]
	v_mfma_f32_16x16x32_bf16 v[26:29], v[88:91], v[96:99], v[26:29]
	v_mfma_f32_16x16x32_bf16 v[22:25], v[80:83], v[104:107], v[22:25]
	v_mfma_f32_16x16x32_bf16 v[18:21], v[88:91], v[104:107], v[18:21]
	v_mfma_f32_16x16x32_bf16 v[14:17], v[80:83], v[112:115], v[14:17]
	v_mfma_f32_16x16x32_bf16 v[10:13], v[88:91], v[112:115], v[10:13]
	v_mfma_f32_16x16x32_bf16 v[6:9], v[80:83], v[120:123], v[6:9]
	v_mfma_f32_16x16x32_bf16 v[2:5], v[88:91], v[120:123], v[2:5]
	v_mfma_f32_16x16x32_bf16 v[30:33], v[84:87], v[100:103], v[30:33]
	v_mfma_f32_16x16x32_bf16 v[26:29], v[92:95], v[100:103], v[26:29]
	v_mfma_f32_16x16x32_bf16 v[22:25], v[84:87], v[108:111], v[22:25]
	v_mfma_f32_16x16x32_bf16 v[18:21], v[92:95], v[108:111], v[18:21]
	v_mfma_f32_16x16x32_bf16 v[14:17], v[84:87], v[116:119], v[14:17]
	v_mfma_f32_16x16x32_bf16 v[10:13], v[92:95], v[116:119], v[10:13]
	v_mfma_f32_16x16x32_bf16 v[6:9], v[84:87], v[124:127], v[6:9]
	v_mfma_f32_16x16x32_bf16 v[2:5], v[92:95], v[124:127], v[2:5]
	s_setprio 0
	s_setprio 1
	s_setprio 0
	s_barrier
	s_add_i32 s63, s63, 2
	s_add_u32 s50, s50, 0x100
	s_addc_u32 s51, s51, 0
	s_cmp_lt_u32 s63, 6
	s_cbranch_scc1 .LBB0_1093
	s_waitcnt vmcnt(0)
	s_cmpk_gt_u32 s5, 0xff
	s_cbranch_scc1 .LBB0_1096
	s_barrier

; #define PG8_STAGE(bufoff, gbase, voff) do { _Pragma("unroll") for (int _i = 0; _i < 2; ++_i) \
;         __builtin_amdgcn_global_load_lds((const unsigned*)((const char*)(gbase) + (voff)[_i]), (LAS unsigned*)(lds + (bufoff) + ldsw + _i * 8192), 16, 0, 0); } while (0)
; #define PG8_LDA(dst, b, h) do { _Pragma("unroll") for (int m = 0; m < 4; ++m) _Pragma("unroll") for (int k = 0; k < 2; ++k) dst[m][k] = *(const LAS bf16x8*)(lds + PG8_SA(b, h) + aoff + m * 2048 + k * 1024); } while (0)
; #define PG8_LDB(dst, b, h) do { _Pragma("unroll") for (int n = 0; n < 2; ++n) _Pragma("unroll") for (int k = 0; k < 2; ++k) dst[n][k] = *(const LAS bf16x8*)(lds + PG8_SB(b, h) + boff + n * 2048 + k * 1024); } while (0)
; #define PG8_MMA(ai, bj, At, Bt) do { __builtin_amdgcn_s_setprio(1); _Pragma("unroll") for (int m = 0; m < 4; ++m) _Pragma("unroll") for (int n = 0; n < 2; ++n) _Pragma("unroll") for (int k = 0; k < 2; ++k) \
;         acc[ai][bj][m][n] = __builtin_amdgcn_mfma_f32_16x16x32_bf16(Bt[n][k], At[m][k], acc[ai][bj][m][n], 0, 0, 0); __builtin_amdgcn_s_setprio(0); } while (0)
; template <class Epi, class Sched, bool ALIGN_EPI>
; __device__ __forceinline__ void gemm_phase(LAS unsigned char* lds, const bf16_t* Ab, const bf16_t* Bb, int lda, int ldb, int K, const Sched& S, Epi& E) {
;     ...
;         const bool has_next = S.next(ui + 1, nxt); nxt.ui = ui + 1;
;         const char* nA = has_next ? (const char*)(Ab + nxt.a_off) : cA; const char* nB = has_next ? (const char*)(Bb + nxt.b_off) : cB;
;         for (int t = 0; t < nt; t += 2) {
;             const bool last = (t == nt - 2);
;             const char* a1 = cA + (unsigned)(t + 1) * kstep;
;             const char* a2 = last ? nA : cA + (unsigned)(t + 2) * kstep; const char* b2 = last ? nB : cB + (unsigned)(t + 2) * kstep;
;             const char* a3 = a2 + kstep; const char* b3 = b2 + kstep;
;             PG8_LDB(B0, 0, 0); PG8_LDB(B1, 0, 1); PG8_SCHED; PG8_LDA(At, 0, 0); PG8_STAGE(PG8_SA(1, 1), a1 + hstepA, voffA);
;             PG8_WAIT_V(8); PG8_WAIT_L(0); PG8_BAR; PG8_MMA(0, 0, At, B0); PG8_MMA(0, 1, At, B1); PG8_BAR; PG8_SCHED;
;             PG8_LDA(At, 0, 1); PG8_STAGE(PG8_SB(0, 0), b2, voffB); PG8_STAGE(PG8_SB(0, 1), b2 + hstepB, voffB); PG8_STAGE(PG8_SA(0, 0), a2, voffA);
;             PG8_WAIT_V(8); PG8_WAIT_L(0); PG8_BAR; PG8_MMA(1, 0, At, B0); PG8_MMA(1, 1, At, B1); PG8_BAR; PG8_SCHED;
.LBB0_1176:
	s_add_u32 s50, s16, 0xfffd8080
	s_addc_u32 s51, s17, -1
	s_add_i32 s70, 0, 0x10000
	s_cmp_eq_u32 s69, 6
	s_cselect_b32 s53, s64, s51
	s_cselect_b32 s52, s65, s50
	s_cselect_b32 s51, s9, s68
	s_cselect_b32 s50, s66, s67
	s_add_i32 s72, 0, 0x14000
	v_add_u32_e32 v150, s70, v136
	v_add_u32_e32 v166, s72, v136
	ds_read_b128 v[138:141], v150
	ds_read_b128 v[142:145], v150 offset:1024
	ds_read_b128 v[146:149], v150 offset:2048
	ds_read_b128 v[150:153], v150 offset:3072
	ds_read_b128 v[154:157], v166
	ds_read_b128 v[158:161], v166 offset:1024
	ds_read_b128 v[162:165], v166 offset:2048
	ds_read_b128 v[166:169], v166 offset:3072
	v_lshl_add_u64 v[186:187], s[16:17], 0, v[0:1]
	s_add_i32 m0, s44, 0xc000
	ds_read_b128 v[170:173], v137
	ds_read_b128 v[174:177], v137 offset:1024
	ds_read_b128 v[178:181], v137 offset:2048
	ds_read_b128 v[182:185], v137 offset:3072
	ds_read_b128 v[200:203], v137 offset:4096
	ds_read_b128 v[206:209], v137 offset:5120
	ds_read_b128 v[210:213], v137 offset:6144
	ds_read_b128 v[238:241], v137 offset:7168
	global_load_lds_dwordx4 v[186:187], off
	v_lshl_add_u64 v[186:187], s[16:17], 0, v[132:133]
	s_add_i32 m0, s44, 0xe000
	s_nop 0
	global_load_lds_dwordx4 v[186:187], off
	s_waitcnt vmcnt(8)
	s_waitcnt lgkmcnt(0)
	s_barrier
	s_setprio 1
	v_mfma_f32_16x16x32_bf16 v[126:129], v[138:141], v[170:173], v[126:129]
	v_mfma_f32_16x16x32_bf16 v[122:125], v[146:149], v[170:173], v[122:125]
	v_mfma_f32_16x16x32_bf16 v[110:113], v[138:141], v[178:181], v[110:113]
	v_mfma_f32_16x16x32_bf16 v[106:109], v[146:149], v[178:181], v[106:109]
	v_mfma_f32_16x16x32_bf16 v[94:97], v[138:141], v[200:203], v[94:97]
	v_mfma_f32_16x16x32_bf16 v[90:93], v[146:149], v[200:203], v[90:93]
	v_mfma_f32_16x16x32_bf16 v[78:81], v[138:141], v[210:213], v[78:81]
	v_mfma_f32_16x16x32_bf16 v[74:77], v[146:149], v[210:213], v[74:77]
	v_mfma_f32_16x16x32_bf16 v[126:129], v[142:145], v[174:177], v[126:129]
	v_mfma_f32_16x16x32_bf16 v[122:125], v[150:153], v[174:177], v[122:125]
	v_mfma_f32_16x16x32_bf16 v[110:113], v[142:145], v[182:185], v[110:113]
	v_mfma_f32_16x16x32_bf16 v[106:109], v[150:153], v[182:185], v[106:109]
	v_mfma_f32_16x16x32_bf16 v[94:97], v[142:145], v[206:209], v[94:97]
	v_mfma_f32_16x16x32_bf16 v[90:93], v[150:153], v[206:209], v[90:93]
	v_mfma_f32_16x16x32_bf16 v[78:81], v[142:145], v[238:241], v[78:81]
	v_mfma_f32_16x16x32_bf16 v[74:77], v[150:153], v[238:241], v[74:77]
	s_setprio 0
	s_setprio 1
	v_mfma_f32_16x16x32_bf16 v[118:121], v[154:157], v[170:173], v[118:121]
	v_mfma_f32_16x16x32_bf16 v[114:117], v[162:165], v[170:173], v[114:117]
	v_mfma_f32_16x16x32_bf16 v[102:105], v[154:157], v[178:181], v[102:105]
	v_mfma_f32_16x16x32_bf16 v[98:101], v[162:165], v[178:181], v[98:101]
	v_mfma_f32_16x16x32_bf16 v[86:89], v[154:157], v[200:203], v[86:89]
	v_mfma_f32_16x16x32_bf16 v[82:85], v[162:165], v[200:203], v[82:85]
	v_mfma_f32_16x16x32_bf16 v[70:73], v[154:157], v[210:213], v[70:73]
	v_mfma_f32_16x16x32_bf16 v[66:69], v[162:165], v[210:213], v[66:69]
	v_mfma_f32_16x16x32_bf16 v[118:121], v[158:161], v[174:177], v[118:121]
	v_mfma_f32_16x16x32_bf16 v[114:117], v[166:169], v[174:177], v[114:117]
	v_mfma_f32_16x16x32_bf16 v[102:105], v[158:161], v[182:185], v[102:105]
	v_mfma_f32_16x16x32_bf16 v[98:101], v[166:169], v[182:185], v[98:101]
	v_mfma_f32_16x16x32_bf16 v[86:89], v[158:161], v[206:209], v[86:89]
	v_mfma_f32_16x16x32_bf16 v[82:85], v[166:169], v[206:209], v[82:85]
	v_mfma_f32_16x16x32_bf16 v[70:73], v[158:161], v[238:241], v[70:73]
	v_mfma_f32_16x16x32_bf16 v[66:69], v[166:169], v[238:241], v[66:69]
	s_setprio 0
	s_barrier
	s_add_i32 s70, s70, s39
	v_lshl_add_u64 v[186:187], s[50:51], 0, v[130:131]
	s_mov_b32 m0, s70
	ds_read_b128 v[170:173], v137 offset:16384
	ds_read_b128 v[174:177], v137 offset:17408
	ds_read_b128 v[178:181], v137 offset:18432
	ds_read_b128 v[182:185], v137 offset:19456
	ds_read_b128 v[200:203], v137 offset:20480
	ds_read_b128 v[206:209], v137 offset:21504
	ds_read_b128 v[210:213], v137 offset:22528
	ds_read_b128 v[238:241], v137 offset:23552
	global_load_lds_dwordx4 v[186:187], off
	s_add_i32 m0, s70, 0x2000
	s_add_u32 s70, s50, 0x28000
	v_lshl_add_u64 v[188:189], s[50:51], 0, v[134:135]
	s_addc_u32 s71, s51, 0
	s_add_i32 s72, s72, s39
	global_load_lds_dwordx4 v[188:189], off
	v_lshl_add_u64 v[196:197], s[70:71], 0, v[130:131]
	s_mov_b32 m0, s72
	v_lshl_add_u64 v[198:199], s[52:53], 0, v[132:133]
	global_load_lds_dwordx4 v[196:197], off
	v_lshl_add_u64 v[196:197], s[70:71], 0, v[134:135]
	s_add_i32 m0, s72, 0x2000
	s_nop 0
	global_load_lds_dwordx4 v[196:197], off
	v_lshl_add_u64 v[196:197], s[52:53], 0, v[0:1]
	s_mov_b32 m0, s44
	s_nop 0
	global_load_lds_dwordx4 v[196:197], off
	s_mov_b32 m0, s45
	s_nop 0
	global_load_lds_dwordx4 v[198:199], off
	s_waitcnt vmcnt(8)
	s_waitcnt lgkmcnt(0)
	s_barrier
; #define PG8_STAGE(bufoff, gbase, voff) do { _Pragma("unroll") for (int _i = 0; _i < 2; ++_i) \
;         __builtin_amdgcn_global_load_lds((const unsigned*)((const char*)(gbase) + (voff)[_i]), (LAS unsigned*)(lds + (bufoff) + ldsw + _i * 8192), 16, 0, 0); } while (0)
; #define PG8_LDA(dst, b, h) do { _Pragma("unroll") for (int m = 0; m < 4; ++m) _Pragma("unroll") for (int k = 0; k < 2; ++k) dst[m][k] = *(const LAS bf16x8*)(lds + PG8_SA(b, h) + aoff + m * 2048 + k * 1024); } while (0)
; #define PG8_LDB(dst, b, h) do { _Pragma("unroll") for (int n = 0; n < 2; ++n) _Pragma("unroll") for (int k = 0; k < 2; ++k) dst[n][k] = *(const LAS bf16x8*)(lds + PG8_SB(b, h) + boff + n * 2048 + k * 1024); } while (0)
; #define PG8_MMA(ai, bj, At, Bt) do { __builtin_amdgcn_s_setprio(1); _Pragma("unroll") for (int m = 0; m < 4; ++m) _Pragma("unroll") for (int n = 0; n < 2; ++n) _Pragma("unroll") for (int k = 0; k < 2; ++k) \
;         acc[ai][bj][m][n] = __builtin_amdgcn_mfma_f32_16x16x32_bf16(Bt[n][k], At[m][k], acc[ai][bj][m][n], 0, 0, 0); __builtin_amdgcn_s_setprio(0); } while (0)
; #define PG8_WAIT_V(n) asm volatile("s_waitcnt vmcnt(" #n ")" ::: "memory")
; #define PG8_WAIT_L(n) asm volatile("s_waitcnt lgkmcnt(" #n ")" ::: "memory")
; #define PG8_BAR __builtin_amdgcn_s_barrier()
; #define PG8_SCHED __builtin_amdgcn_sched_barrier(0)
; template <class Epi, class Sched, bool ALIGN_EPI>
; __device__ __forceinline__ void gemm_phase(LAS unsigned char* lds, const bf16_t* Ab, const bf16_t* Bb, int lda, int ldb, int K, const Sched& S, Epi& E) {
;     ...
;             PG8_WAIT_V(8); PG8_WAIT_L(0); PG8_BAR; PG8_MMA(1, 0, At, B0); PG8_MMA(1, 1, At, B1); PG8_BAR; PG8_SCHED;
;             PG8_LDB(B0, 1, 0); PG8_LDB(B1, 1, 1); PG8_SCHED; PG8_LDA(At, 1, 0); PG8_STAGE(PG8_SA(0, 1), a2 + hstepA, voffA);
;             PG8_WAIT_V(8); PG8_WAIT_L(0); PG8_BAR; PG8_MMA(0, 0, At, B0); PG8_MMA(0, 1, At, B1); PG8_BAR; PG8_SCHED;
	s_setprio 1
	v_mfma_f32_16x16x32_bf16 v[62:65], v[138:141], v[170:173], v[62:65]
	v_mfma_f32_16x16x32_bf16 v[58:61], v[146:149], v[170:173], v[58:61]
	v_mfma_f32_16x16x32_bf16 v[46:49], v[138:141], v[178:181], v[46:49]
	v_mfma_f32_16x16x32_bf16 v[42:45], v[146:149], v[178:181], v[42:45]
	v_mfma_f32_16x16x32_bf16 v[30:33], v[138:141], v[200:203], v[30:33]
	v_mfma_f32_16x16x32_bf16 v[26:29], v[146:149], v[200:203], v[26:29]
	v_mfma_f32_16x16x32_bf16 v[14:17], v[138:141], v[210:213], v[14:17]
	v_mfma_f32_16x16x32_bf16 v[10:13], v[146:149], v[210:213], v[10:13]
	v_mfma_f32_16x16x32_bf16 v[62:65], v[142:145], v[174:177], v[62:65]
	v_mfma_f32_16x16x32_bf16 v[58:61], v[150:153], v[174:177], v[58:61]
	v_mfma_f32_16x16x32_bf16 v[46:49], v[142:145], v[182:185], v[46:49]
	v_mfma_f32_16x16x32_bf16 v[42:45], v[150:153], v[182:185], v[42:45]
	v_mfma_f32_16x16x32_bf16 v[30:33], v[142:145], v[206:209], v[30:33]
	v_mfma_f32_16x16x32_bf16 v[26:29], v[150:153], v[206:209], v[26:29]
	v_mfma_f32_16x16x32_bf16 v[14:17], v[142:145], v[238:241], v[14:17]
	v_mfma_f32_16x16x32_bf16 v[10:13], v[150:153], v[238:241], v[10:13]
	s_setprio 0
	s_setprio 1
	v_mfma_f32_16x16x32_bf16 v[54:57], v[154:157], v[170:173], v[54:57]
	v_mfma_f32_16x16x32_bf16 v[50:53], v[162:165], v[170:173], v[50:53]
	v_mfma_f32_16x16x32_bf16 v[38:41], v[154:157], v[178:181], v[38:41]
	v_mfma_f32_16x16x32_bf16 v[34:37], v[162:165], v[178:181], v[34:37]
	v_mfma_f32_16x16x32_bf16 v[22:25], v[154:157], v[200:203], v[22:25]
	v_mfma_f32_16x16x32_bf16 v[18:21], v[162:165], v[200:203], v[18:21]
	v_mfma_f32_16x16x32_bf16 v[6:9], v[154:157], v[210:213], v[6:9]
	v_mfma_f32_16x16x32_bf16 v[2:5], v[162:165], v[210:213], v[2:5]
	v_mfma_f32_16x16x32_bf16 v[54:57], v[158:161], v[174:177], v[54:57]
	v_mfma_f32_16x16x32_bf16 v[50:53], v[166:169], v[174:177], v[50:53]
	v_mfma_f32_16x16x32_bf16 v[38:41], v[158:161], v[182:185], v[38:41]
	v_mfma_f32_16x16x32_bf16 v[34:37], v[166:169], v[182:185], v[34:37]
	v_mfma_f32_16x16x32_bf16 v[22:25], v[158:161], v[206:209], v[22:25]
	v_mfma_f32_16x16x32_bf16 v[18:21], v[166:169], v[206:209], v[18:21]
	v_mfma_f32_16x16x32_bf16 v[6:9], v[158:161], v[238:241], v[6:9]
	v_mfma_f32_16x16x32_bf16 v[2:5], v[166:169], v[238:241], v[2:5]
	s_setprio 0
	s_barrier
	s_add_i32 s70, 0, 0x18000
	s_add_i32 s71, 0, 0x1c000
	v_add_u32_e32 v150, s70, v136
	v_add_u32_e32 v166, s71, v136
	ds_read_b128 v[138:141], v150
	ds_read_b128 v[142:145], v150 offset:1024
	ds_read_b128 v[146:149], v150 offset:2048
	ds_read_b128 v[150:153], v150 offset:3072
	ds_read_b128 v[154:157], v166
	ds_read_b128 v[158:161], v166 offset:1024
	ds_read_b128 v[162:165], v166 offset:2048
	ds_read_b128 v[166:169], v166 offset:3072
	s_add_u32 s52, s52, 0x28000
	s_addc_u32 s53, s53, 0
	s_mov_b32 m0, s46
	v_lshl_add_u64 v[220:221], s[52:53], 0, v[0:1]
	ds_read_b128 v[170:173], v137 offset:32768
	ds_read_b128 v[174:177], v137 offset:33792
	ds_read_b128 v[178:181], v137 offset:34816
	ds_read_b128 v[182:185], v137 offset:35840
	ds_read_b128 v[200:203], v137 offset:36864
	ds_read_b128 v[206:209], v137 offset:37888
	ds_read_b128 v[210:213], v137 offset:38912
	ds_read_b128 v[238:241], v137 offset:39936
	global_load_lds_dwordx4 v[220:221], off
	v_lshl_add_u64 v[220:221], s[52:53], 0, v[132:133]
	s_mov_b32 m0, s47
	s_nop 0
	global_load_lds_dwordx4 v[220:221], off
	s_waitcnt vmcnt(8)
	s_waitcnt lgkmcnt(0)
	s_barrier
	s_setprio 1
	v_mfma_f32_16x16x32_bf16 v[126:129], v[138:141], v[170:173], v[126:129]
	v_mfma_f32_16x16x32_bf16 v[122:125], v[146:149], v[170:173], v[122:125]
	v_mfma_f32_16x16x32_bf16 v[110:113], v[138:141], v[178:181], v[110:113]
	v_mfma_f32_16x16x32_bf16 v[106:109], v[146:149], v[178:181], v[106:109]
	v_mfma_f32_16x16x32_bf16 v[94:97], v[138:141], v[200:203], v[94:97]
	v_mfma_f32_16x16x32_bf16 v[90:93], v[146:149], v[200:203], v[90:93]
	v_mfma_f32_16x16x32_bf16 v[78:81], v[138:141], v[210:213], v[78:81]
	v_mfma_f32_16x16x32_bf16 v[74:77], v[146:149], v[210:213], v[74:77]
	v_mfma_f32_16x16x32_bf16 v[126:129], v[142:145], v[174:177], v[126:129]
	v_mfma_f32_16x16x32_bf16 v[122:125], v[150:153], v[174:177], v[122:125]
	v_mfma_f32_16x16x32_bf16 v[110:113], v[142:145], v[182:185], v[110:113]
	v_mfma_f32_16x16x32_bf16 v[106:109], v[150:153], v[182:185], v[106:109]
	v_mfma_f32_16x16x32_bf16 v[94:97], v[142:145], v[206:209], v[94:97]
	v_mfma_f32_16x16x32_bf16 v[90:93], v[150:153], v[206:209], v[90:93]
	v_mfma_f32_16x16x32_bf16 v[78:81], v[142:145], v[238:241], v[78:81]
	v_mfma_f32_16x16x32_bf16 v[74:77], v[150:153], v[238:241], v[74:77]
	s_setprio 0
	s_setprio 1
	v_mfma_f32_16x16x32_bf16 v[118:121], v[154:157], v[170:173], v[118:121]
	v_mfma_f32_16x16x32_bf16 v[114:117], v[162:165], v[170:173], v[114:117]
	v_mfma_f32_16x16x32_bf16 v[102:105], v[154:157], v[178:181], v[102:105]
	v_mfma_f32_16x16x32_bf16 v[98:101], v[162:165], v[178:181], v[98:101]
	v_mfma_f32_16x16x32_bf16 v[86:89], v[154:157], v[200:203], v[86:89]
	v_mfma_f32_16x16x32_bf16 v[82:85], v[162:165], v[200:203], v[82:85]
	v_mfma_f32_16x16x32_bf16 v[70:73], v[154:157], v[210:213], v[70:73]
	v_mfma_f32_16x16x32_bf16 v[66:69], v[162:165], v[210:213], v[66:69]
	v_mfma_f32_16x16x32_bf16 v[118:121], v[158:161], v[174:177], v[118:121]
	v_mfma_f32_16x16x32_bf16 v[114:117], v[166:169], v[174:177], v[114:117]
	v_mfma_f32_16x16x32_bf16 v[102:105], v[158:161], v[182:185], v[102:105]
	v_mfma_f32_16x16x32_bf16 v[98:101], v[166:169], v[182:185], v[98:101]
	v_mfma_f32_16x16x32_bf16 v[86:89], v[158:161], v[206:209], v[86:89]
	v_mfma_f32_16x16x32_bf16 v[82:85], v[166:169], v[206:209], v[82:85]
	v_mfma_f32_16x16x32_bf16 v[70:73], v[158:161], v[238:241], v[70:73]
	v_mfma_f32_16x16x32_bf16 v[66:69], v[166:169], v[238:241], v[66:69]
	s_setprio 0
	s_barrier
; __device__ __forceinline__ float fast_exp2(float x) { return __builtin_amdgcn_exp2f(x); }
; __device__ __forceinline__ float fast_rcp(float x) { return __builtin_amdgcn_rcpf(x); }
; #define PG8_STAGE(bufoff, gbase, voff) do { _Pragma("unroll") for (int _i = 0; _i < 2; ++_i) \
;         __builtin_amdgcn_global_load_lds((const unsigned*)((const char*)(gbase) + (voff)[_i]), (LAS unsigned*)(lds + (bufoff) + ldsw + _i * 8192), 16, 0, 0); } while (0)
; #define PG8_LDA(dst, b, h) do { _Pragma("unroll") for (int m = 0; m < 4; ++m) _Pragma("unroll") for (int k = 0; k < 2; ++k) dst[m][k] = *(const LAS bf16x8*)(lds + PG8_SA(b, h) + aoff + m * 2048 + k * 1024); } while (0)
; #define PG8_WAIT_V(n) asm volatile("s_waitcnt vmcnt(" #n ")" ::: "memory")
; #define PG8_WAIT_L(n) asm volatile("s_waitcnt lgkmcnt(" #n ")" ::: "memory")
; #define PG8_BAR __builtin_amdgcn_s_barrier()
; #define PG8_SCHED __builtin_amdgcn_sched_barrier(0)
; template <class Epi, class Sched, bool ALIGN_EPI>
; __device__ __forceinline__ void gemm_phase(LAS unsigned char* lds, const bf16_t* Ab, const bf16_t* Bb, int lda, int ldb, int K, const Sched& S, Epi& E) {
;     ...
;             PG8_LDA(At, 1, 1); PG8_STAGE(PG8_SB(1, 0), b3, voffB); PG8_STAGE(PG8_SB(1, 1), b3 + hstepB, voffB); PG8_STAGE(PG8_SA(1, 0), a3, voffA);
;             PG8_WAIT_V(8); PG8_WAIT_L(0); PG8_BAR; PG8_MMA(1, 0, At, B0); PG8_MMA(1, 1, At, B1); PG8_BAR; PG8_SCHED;
;         }
;     __device__ __forceinline__ void operator()(AccRef acc, const Unit& u, int wr, int wc, int fr, int fq) const {
;     ...
;                     const int cc = u.pn * 256 + bj * 128 + wc * 32 + 8 * fq, t = cc >> 4, ho0 = cc & 15;
;                     f32x4 v0, v1;
;                     {
;                         const f32x4 x0 = acc[ai][bj][m][0], x1 = acc[ai][bj][m][1];
;                         f32x4 t0 = (x0 * x0 * 0.044715f + 1.0f) * x0 * (-2.f * LOG2E * 0.7978845608028654f), t1 = (x1 * x1 * 0.044715f + 1.0f) * x1 * (-2.f * LOG2E * 0.7978845608028654f);
; #pragma unroll
;                         for (int j = 0; j < 4; ++j) { t0[j] = fast_exp2(t0[j]); t1[j] = fast_exp2(t1[j]); }
;                         t0 = t0 + 1.0f; t1 = t1 + 1.0f;
; #pragma unroll
;                         for (int j = 0; j < 4; ++j) { t0[j] = fast_rcp(t0[j]); t1[j] = fast_rcp(t1[j]); }
;                         v0 = x0 * t0; v1 = x1 * t1;
	s_add_i32 s52, s70, s39
	v_lshl_add_u64 v[186:187], v[186:187], 0, s[26:27]
	s_mov_b32 m0, s52
	ds_read_b128 v[170:173], v137 offset:49152
	ds_read_b128 v[174:177], v137 offset:50176
	ds_read_b128 v[178:181], v137 offset:51200
	ds_read_b128 v[182:185], v137 offset:52224
	ds_read_b128 v[200:203], v137 offset:53248
	ds_read_b128 v[206:209], v137 offset:54272
	ds_read_b128 v[210:213], v137 offset:55296
	ds_read_b128 v[238:241], v137 offset:56320
	global_load_lds_dwordx4 v[186:187], off
	s_add_i32 m0, s52, 0x2000
	s_add_u32 s50, s50, 0x28080
	v_lshl_add_u64 v[186:187], v[188:189], 0, s[26:27]
	s_addc_u32 s51, s51, 0
	s_add_i32 s52, s71, s39
	global_load_lds_dwordx4 v[186:187], off
	v_lshl_add_u64 v[186:187], s[50:51], 0, v[130:131]
	s_mov_b32 m0, s52
	s_nop 0
	global_load_lds_dwordx4 v[186:187], off
	v_lshl_add_u64 v[186:187], s[50:51], 0, v[134:135]
	s_add_i32 m0, s52, 0x2000
	s_nop 0
	global_load_lds_dwordx4 v[186:187], off
	v_lshl_add_u64 v[186:187], v[196:197], 0, s[26:27]
	s_mov_b32 m0, s58
	s_nop 0
	global_load_lds_dwordx4 v[186:187], off
	v_lshl_add_u64 v[186:187], v[198:199], 0, s[26:27]
	s_mov_b32 m0, s59
	s_nop 0
	global_load_lds_dwordx4 v[186:187], off
	s_waitcnt vmcnt(8)
	s_waitcnt lgkmcnt(0)
	s_barrier
	s_setprio 1
	v_mfma_f32_16x16x32_bf16 v[62:65], v[138:141], v[170:173], v[62:65]
	v_mfma_f32_16x16x32_bf16 v[58:61], v[146:149], v[170:173], v[58:61]
	v_mfma_f32_16x16x32_bf16 v[46:49], v[138:141], v[178:181], v[46:49]
	v_mfma_f32_16x16x32_bf16 v[42:45], v[146:149], v[178:181], v[42:45]
	v_mfma_f32_16x16x32_bf16 v[30:33], v[138:141], v[200:203], v[30:33]
	v_mfma_f32_16x16x32_bf16 v[26:29], v[146:149], v[200:203], v[26:29]
	v_mfma_f32_16x16x32_bf16 v[14:17], v[138:141], v[210:213], v[14:17]
	v_mfma_f32_16x16x32_bf16 v[10:13], v[146:149], v[210:213], v[10:13]
	v_mfma_f32_16x16x32_bf16 v[62:65], v[142:145], v[174:177], v[62:65]
	v_mfma_f32_16x16x32_bf16 v[58:61], v[150:153], v[174:177], v[58:61]
	v_mfma_f32_16x16x32_bf16 v[46:49], v[142:145], v[182:185], v[46:49]
	v_mfma_f32_16x16x32_bf16 v[42:45], v[150:153], v[182:185], v[42:45]
	v_mfma_f32_16x16x32_bf16 v[30:33], v[142:145], v[206:209], v[30:33]
	v_mfma_f32_16x16x32_bf16 v[26:29], v[150:153], v[206:209], v[26:29]
	v_mfma_f32_16x16x32_bf16 v[14:17], v[142:145], v[238:241], v[14:17]
	v_mfma_f32_16x16x32_bf16 v[10:13], v[150:153], v[238:241], v[10:13]
	s_setprio 0
	s_setprio 1
	v_mfma_f32_16x16x32_bf16 v[54:57], v[154:157], v[170:173], v[54:57]
	v_mfma_f32_16x16x32_bf16 v[50:53], v[162:165], v[170:173], v[50:53]
	v_mfma_f32_16x16x32_bf16 v[38:41], v[154:157], v[178:181], v[38:41]
	v_mfma_f32_16x16x32_bf16 v[34:37], v[162:165], v[178:181], v[34:37]
	v_mfma_f32_16x16x32_bf16 v[22:25], v[154:157], v[200:203], v[22:25]
	v_mfma_f32_16x16x32_bf16 v[18:21], v[162:165], v[200:203], v[18:21]
	v_mfma_f32_16x16x32_bf16 v[6:9], v[154:157], v[210:213], v[6:9]
	v_mfma_f32_16x16x32_bf16 v[2:5], v[162:165], v[210:213], v[2:5]
	v_mfma_f32_16x16x32_bf16 v[54:57], v[158:161], v[174:177], v[54:57]
	v_mfma_f32_16x16x32_bf16 v[50:53], v[166:169], v[174:177], v[50:53]
	v_mfma_f32_16x16x32_bf16 v[38:41], v[158:161], v[182:185], v[38:41]
	v_mfma_f32_16x16x32_bf16 v[34:37], v[166:169], v[182:185], v[34:37]
	v_mfma_f32_16x16x32_bf16 v[22:25], v[158:161], v[206:209], v[22:25]
	v_mfma_f32_16x16x32_bf16 v[18:21], v[166:169], v[206:209], v[18:21]
	v_mfma_f32_16x16x32_bf16 v[6:9], v[158:161], v[238:241], v[6:9]
	v_mfma_f32_16x16x32_bf16 v[2:5], v[166:169], v[238:241], v[2:5]
	s_setprio 0
	s_barrier
	s_add_i32 s69, s69, 2
	s_add_u32 s16, s16, 0x100
	s_addc_u32 s17, s17, 0
	s_add_u32 s67, s67, 0x100
	s_addc_u32 s68, s68, 0
	s_cmp_gt_u32 s69, 7
	s_cbranch_scc0 .LBB0_1176
	v_pk_mul_f32 v[134:135], v[126:127], v[126:127]
	v_pk_mul_f32 v[132:133], v[128:129], v[128:129]
	v_pk_fma_f32 v[134:135], v[134:135], s[38:39], 1.0 op_sel_hi:[1,0,0]
	v_pk_mul_f32 v[136:137], v[124:125], v[124:125]
	v_pk_mul_f32 v[138:139], v[122:123], v[122:123]
	v_pk_fma_f32 v[132:133], v[132:133], s[38:39], 1.0 op_sel_hi:[1,0,0]
	v_pk_mul_f32 v[134:135], v[126:127], v[134:135]
	v_pk_fma_f32 v[136:137], v[136:137], s[38:39], 1.0 op_sel_hi:[1,0,0]
	v_pk_fma_f32 v[138:139], v[138:139], s[38:39], 1.0 op_sel_hi:[1,0,0]
	v_pk_mul_f32 v[132:133], v[128:129], v[132:133]
	v_pk_mul_f32 v[134:135], v[134:135], s[40:41] op_sel_hi:[1,0]
	v_pk_mul_f32 v[136:137], v[124:125], v[136:137]
	v_pk_mul_f32 v[138:139], v[122:123], v[138:139]
	v_pk_mul_f32 v[132:133], v[132:133], s[40:41] op_sel_hi:[1,0]
	v_pk_mul_f32 v[136:137], v[136:137], s[40:41] op_sel_hi:[1,0]
	v_pk_mul_f32 v[138:139], v[138:139], s[40:41] op_sel_hi:[1,0]
	v_exp_f32_e32 v134, v134
	v_exp_f32_e32 v135, v135
	v_exp_f32_e32 v138, v138
	v_exp_f32_e32 v132, v132
	v_exp_f32_e32 v133, v133
	v_exp_f32_e32 v136, v136
	v_exp_f32_e32 v137, v137
	v_exp_f32_e32 v139, v139
	v_pk_add_f32 v[134:135], v[134:135], 1.0 op_sel_hi:[1,0]
	v_mov_b32_e32 v0, v236
	v_pk_add_f32 v[132:133], v[132:133], 1.0 op_sel_hi:[1,0]
	v_pk_add_f32 v[136:137], v[136:137], 1.0 op_sel_hi:[1,0]
	v_pk_add_f32 v[138:139], v[138:139], 1.0 op_sel_hi:[1,0]
	v_rcp_f32_e32 v134, v134
	v_rcp_f32_e32 v135, v135
	s_lshl_b32 s9, s63, 8
	v_lshrrev_b32_e32 v130, 1, v0
	v_lshlrev_b32_e32 v131, 5, v0
	v_rcp_f32_e32 v138, v138
	v_rcp_f32_e32 v139, v139
	v_rcp_f32_e32 v132, v132
	v_rcp_f32_e32 v133, v133
	v_rcp_f32_e32 v136, v136
	v_rcp_f32_e32 v137, v137
	v_and_or_b32 v130, v130, 16, s9
	s_lshl_b32 s9, s25, 8
	v_and_b32_e32 v131, 0x1e0, v131
	v_or_b32_e32 v130, s56, v130
	s_and_b32 s9, s9, 0xffffe000
	v_or_b32_e32 v131, s31, v131
	v_add_u32_e32 v131, s9, v131
	v_ashrrev_i32_e32 v130, 4, v130
	v_pk_mul_f32 v[126:127], v[126:127], v[134:135]
; __device__ __forceinline__ u32x4 pack8(f32x4 a, f32x4 b) { u32x4 w; w.x = cvtpk(a[0], a[1]); w.y = cvtpk(a[2], a[3]); w.z = cvtpk(b[0], b[1]); w.w = cvtpk(b[2], b[3]); return w; }
; __device__ __forceinline__ float fast_exp2(float x) { return __builtin_amdgcn_exp2f(x); }
; __device__ __forceinline__ float fast_rcp(float x) { return __builtin_amdgcn_rcpf(x); }
;     __device__ __forceinline__ void operator()(AccRef acc, const Unit& u, int wr, int wc, int fr, int fq) const {
;     ...
;                     const int cc = u.pn * 256 + bj * 128 + wc * 32 + 8 * fq, t = cc >> 4, ho0 = cc & 15;
;                     f32x4 v0, v1;
;                     {
;                         const f32x4 x0 = acc[ai][bj][m][0], x1 = acc[ai][bj][m][1];
;                         f32x4 t0 = (x0 * x0 * 0.044715f + 1.0f) * x0 * (-2.f * LOG2E * 0.7978845608028654f), t1 = (x1 * x1 * 0.044715f + 1.0f) * x1 * (-2.f * LOG2E * 0.7978845608028654f);
; #pragma unroll
;                         for (int j = 0; j < 4; ++j) { t0[j] = fast_exp2(t0[j]); t1[j] = fast_exp2(t1[j]); }
;                         t0 = t0 + 1.0f; t1 = t1 + 1.0f;
; #pragma unroll
;                         for (int j = 0; j < 4; ++j) { t0[j] = fast_rcp(t0[j]); t1[j] = fast_rcp(t1[j]); }
;                         v0 = x0 * t0; v1 = x1 * t1;
;                     }
;                     *(u32x4*)(yb + ((size_t)(b * SEQ + ch * CH + t)) * 512 + g * 16 + ho0) = pack8(v0, v1);
	v_pk_mul_f32 v[128:129], v[128:129], v[132:133]
	v_pk_mul_f32 v[132:133], v[124:125], v[136:137]
	v_pk_mul_f32 v[124:125], v[122:123], v[138:139]
	v_cvt_pk_bf16_f32 v122, v126, v127
	v_add_u32_e32 v126, v130, v131
	v_ashrrev_i32_e32 v127, 31, v126
	v_lshlrev_b64 v[126:127], 10, v[126:127]
	s_lshl_b32 s9, s25, 5
	v_lshl_add_u64 v[126:127], s[6:7], 0, v[126:127]
	s_and_b32 s16, s9, 0x3e0
	s_mov_b32 s17, s19
	v_lshl_add_u64 v[126:127], v[126:127], 0, s[16:17]
	v_and_b32_e32 v0, 16, v0
	v_cvt_pk_bf16_f32 v123, v128, v129
	v_cvt_pk_bf16_f32 v124, v124, v125
	v_cvt_pk_bf16_f32 v125, v132, v133
	v_lshl_add_u64 v[126:127], v[126:127], 0, v[0:1]
	global_store_dwordx4 v[126:127], v[122:125], off
	v_pk_mul_f32 v[126:127], v[116:117], v[116:117]
	v_pk_mul_f32 v[128:129], v[114:115], v[114:115]
	v_pk_mul_f32 v[124:125], v[118:119], v[118:119]
	v_pk_fma_f32 v[126:127], v[126:127], s[38:39], 1.0 op_sel_hi:[1,0,0]
	v_pk_fma_f32 v[124:125], v[124:125], s[38:39], 1.0 op_sel_hi:[1,0,0]
	v_pk_fma_f32 v[128:129], v[128:129], s[38:39], 1.0 op_sel_hi:[1,0,0]
	v_pk_mul_f32 v[124:125], v[118:119], v[124:125]
	v_pk_mul_f32 v[126:127], v[116:117], v[126:127]
	v_pk_mul_f32 v[124:125], v[124:125], s[40:41] op_sel_hi:[1,0]
	v_pk_mul_f32 v[128:129], v[114:115], v[128:129]
	v_pk_mul_f32 v[122:123], v[120:121], v[120:121]
	v_pk_mul_f32 v[126:127], v[126:127], s[40:41] op_sel_hi:[1,0]
	v_pk_mul_f32 v[128:129], v[128:129], s[40:41] op_sel_hi:[1,0]
	v_exp_f32_e32 v124, v124
	v_exp_f32_e32 v125, v125
	v_pk_fma_f32 v[122:123], v[122:123], s[38:39], 1.0 op_sel_hi:[1,0,0]
	v_exp_f32_e32 v128, v128
	v_exp_f32_e32 v126, v126
	v_exp_f32_e32 v127, v127
	v_exp_f32_e32 v129, v129
	v_pk_mul_f32 v[122:123], v[120:121], v[122:123]
	v_pk_add_f32 v[124:125], v[124:125], 1.0 op_sel_hi:[1,0]
	v_pk_mul_f32 v[122:123], v[122:123], s[40:41] op_sel_hi:[1,0]
	v_pk_add_f32 v[126:127], v[126:127], 1.0 op_sel_hi:[1,0]
	v_exp_f32_e32 v122, v122
	v_exp_f32_e32 v123, v123
	v_pk_add_f32 v[128:129], v[128:129], 1.0 op_sel_hi:[1,0]
	v_rcp_f32_e32 v124, v124
	v_rcp_f32_e32 v125, v125
	v_rcp_f32_e32 v128, v128
	v_rcp_f32_e32 v129, v129
	v_rcp_f32_e32 v126, v126
	v_rcp_f32_e32 v127, v127
	v_pk_add_f32 v[122:123], v[122:123], 1.0 op_sel_hi:[1,0]
	v_pk_mul_f32 v[118:119], v[118:119], v[124:125]
	v_rcp_f32_e32 v132, v122
	v_or_b32_e32 v122, 8, v130
	v_rcp_f32_e32 v133, v123
	v_pk_mul_f32 v[124:125], v[116:117], v[126:127]
	v_pk_mul_f32 v[116:117], v[114:115], v[128:129]
	v_cvt_pk_bf16_f32 v114, v118, v119
	v_add_u32_e32 v118, v122, v131
	v_ashrrev_i32_e32 v119, 31, v118
	v_lshlrev_b64 v[118:119], 10, v[118:119]
	v_lshl_add_u64 v[118:119], s[6:7], 0, v[118:119]
	v_pk_mul_f32 v[120:121], v[120:121], v[132:133]
	v_lshl_add_u64 v[118:119], v[118:119], 0, s[16:17]
	v_cvt_pk_bf16_f32 v115, v120, v121
	v_cvt_pk_bf16_f32 v116, v116, v117
	v_cvt_pk_bf16_f32 v117, v124, v125
	v_lshl_add_u64 v[118:119], v[118:119], 0, v[0:1]
	global_store_dwordx4 v[118:119], v[114:117], off
	v_pk_mul_f32 v[118:119], v[108:109], v[108:109]
	v_pk_mul_f32 v[120:121], v[106:107], v[106:107]
	v_pk_mul_f32 v[116:117], v[110:111], v[110:111]
	v_pk_mul_f32 v[114:115], v[112:113], v[112:113]
	v_pk_fma_f32 v[116:117], v[116:117], s[38:39], 1.0 op_sel_hi:[1,0,0]
	v_pk_fma_f32 v[114:115], v[114:115], s[38:39], 1.0 op_sel_hi:[1,0,0]
	v_pk_mul_f32 v[116:117], v[110:111], v[116:117]
	v_pk_fma_f32 v[118:119], v[118:119], s[38:39], 1.0 op_sel_hi:[1,0,0]
	v_pk_fma_f32 v[120:121], v[120:121], s[38:39], 1.0 op_sel_hi:[1,0,0]
	v_pk_mul_f32 v[114:115], v[112:113], v[114:115]
	v_pk_mul_f32 v[116:117], v[116:117], s[40:41] op_sel_hi:[1,0]
	v_pk_mul_f32 v[118:119], v[108:109], v[118:119]
	v_pk_mul_f32 v[120:121], v[106:107], v[120:121]
	v_pk_mul_f32 v[114:115], v[114:115], s[40:41] op_sel_hi:[1,0]
	v_pk_mul_f32 v[118:119], v[118:119], s[40:41] op_sel_hi:[1,0]
	v_pk_mul_f32 v[120:121], v[120:121], s[40:41] op_sel_hi:[1,0]
	v_exp_f32_e32 v116, v116
	v_exp_f32_e32 v117, v117
	v_exp_f32_e32 v120, v120
	v_exp_f32_e32 v114, v114
	v_exp_f32_e32 v115, v115
	v_exp_f32_e32 v118, v118
	v_exp_f32_e32 v119, v119
	v_exp_f32_e32 v121, v121
	v_pk_add_f32 v[116:117], v[116:117], 1.0 op_sel_hi:[1,0]
	v_pk_add_f32 v[114:115], v[114:115], 1.0 op_sel_hi:[1,0]
	v_pk_add_f32 v[118:119], v[118:119], 1.0 op_sel_hi:[1,0]
	v_pk_add_f32 v[120:121], v[120:121], 1.0 op_sel_hi:[1,0]
	v_rcp_f32_e32 v116, v116
	v_rcp_f32_e32 v117, v117
	v_rcp_f32_e32 v120, v120
	v_rcp_f32_e32 v114, v114
	v_rcp_f32_e32 v115, v115
	v_rcp_f32_e32 v118, v118
	v_rcp_f32_e32 v119, v119
	v_rcp_f32_e32 v121, v121
	v_add_u32_e32 v123, 0x200, v131
	v_pk_mul_f32 v[110:111], v[110:111], v[116:117]
	v_pk_mul_f32 v[112:113], v[112:113], v[114:115]
	v_pk_mul_f32 v[114:115], v[108:109], v[118:119]
	v_pk_mul_f32 v[108:109], v[106:107], v[120:121]
	v_cvt_pk_bf16_f32 v106, v110, v111
	v_add_u32_e32 v110, v123, v130
	v_ashrrev_i32_e32 v111, 31, v110
	v_lshlrev_b64 v[110:111], 10, v[110:111]
	v_lshl_add_u64 v[110:111], s[6:7], 0, v[110:111]
	v_lshl_add_u64 v[110:111], v[110:111], 0, s[16:17]
	v_cvt_pk_bf16_f32 v107, v112, v113
	v_cvt_pk_bf16_f32 v108, v108, v109
	v_cvt_pk_bf16_f32 v109, v114, v115
	v_lshl_add_u64 v[110:111], v[110:111], 0, v[0:1]
	global_store_dwordx4 v[110:111], v[106:109], off
	v_pk_mul_f32 v[110:111], v[100:101], v[100:101]
	v_pk_mul_f32 v[112:113], v[98:99], v[98:99]
	v_pk_mul_f32 v[108:109], v[102:103], v[102:103]
	v_pk_mul_f32 v[106:107], v[104:105], v[104:105]
	v_pk_fma_f32 v[108:109], v[108:109], s[38:39], 1.0 op_sel_hi:[1,0,0]
	v_pk_fma_f32 v[106:107], v[106:107], s[38:39], 1.0 op_sel_hi:[1,0,0]
	v_pk_mul_f32 v[108:109], v[102:103], v[108:109]
	v_pk_fma_f32 v[110:111], v[110:111], s[38:39], 1.0 op_sel_hi:[1,0,0]
; __device__ __forceinline__ u32x4 pack8(f32x4 a, f32x4 b) { u32x4 w; w.x = cvtpk(a[0], a[1]); w.y = cvtpk(a[2], a[3]); w.z = cvtpk(b[0], b[1]); w.w = cvtpk(b[2], b[3]); return w; }
; __device__ __forceinline__ float fast_exp2(float x) { return __builtin_amdgcn_exp2f(x); }
; __device__ __forceinline__ float fast_rcp(float x) { return __builtin_amdgcn_rcpf(x); }
;     __device__ __forceinline__ void operator()(AccRef acc, const Unit& u, int wr, int wc, int fr, int fq) const {
;     ...
;                     const int cc = u.pn * 256 + bj * 128 + wc * 32 + 8 * fq, t = cc >> 4, ho0 = cc & 15;
;                     f32x4 v0, v1;
;                     {
;                         const f32x4 x0 = acc[ai][bj][m][0], x1 = acc[ai][bj][m][1];
;                         f32x4 t0 = (x0 * x0 * 0.044715f + 1.0f) * x0 * (-2.f * LOG2E * 0.7978845608028654f), t1 = (x1 * x1 * 0.044715f + 1.0f) * x1 * (-2.f * LOG2E * 0.7978845608028654f);
; #pragma unroll
;                         for (int j = 0; j < 4; ++j) { t0[j] = fast_exp2(t0[j]); t1[j] = fast_exp2(t1[j]); }
;                         t0 = t0 + 1.0f; t1 = t1 + 1.0f;
; #pragma unroll
;                         for (int j = 0; j < 4; ++j) { t0[j] = fast_rcp(t0[j]); t1[j] = fast_rcp(t1[j]); }
;                         v0 = x0 * t0; v1 = x1 * t1;
;                     }
;                     *(u32x4*)(yb + ((size_t)(b * SEQ + ch * CH + t)) * 512 + g * 16 + ho0) = pack8(v0, v1);
	v_pk_fma_f32 v[112:113], v[112:113], s[38:39], 1.0 op_sel_hi:[1,0,0]
	v_pk_mul_f32 v[106:107], v[104:105], v[106:107]
	v_pk_mul_f32 v[108:109], v[108:109], s[40:41] op_sel_hi:[1,0]
	v_pk_mul_f32 v[110:111], v[100:101], v[110:111]
	v_pk_mul_f32 v[112:113], v[98:99], v[112:113]
	v_pk_mul_f32 v[106:107], v[106:107], s[40:41] op_sel_hi:[1,0]
	v_pk_mul_f32 v[110:111], v[110:111], s[40:41] op_sel_hi:[1,0]
	v_pk_mul_f32 v[112:113], v[112:113], s[40:41] op_sel_hi:[1,0]
	v_exp_f32_e32 v108, v108
	v_exp_f32_e32 v109, v109
	v_exp_f32_e32 v112, v112
	v_exp_f32_e32 v106, v106
	v_exp_f32_e32 v107, v107
	v_exp_f32_e32 v110, v110
	v_exp_f32_e32 v111, v111
	v_exp_f32_e32 v113, v113
	v_pk_add_f32 v[108:109], v[108:109], 1.0 op_sel_hi:[1,0]
	v_pk_add_f32 v[106:107], v[106:107], 1.0 op_sel_hi:[1,0]
	v_pk_add_f32 v[110:111], v[110:111], 1.0 op_sel_hi:[1,0]
	v_pk_add_f32 v[112:113], v[112:113], 1.0 op_sel_hi:[1,0]
	v_rcp_f32_e32 v108, v108
	v_rcp_f32_e32 v109, v109
	v_rcp_f32_e32 v112, v112
	v_rcp_f32_e32 v106, v106
	v_rcp_f32_e32 v107, v107
	v_rcp_f32_e32 v110, v110
	v_rcp_f32_e32 v111, v111
	v_rcp_f32_e32 v113, v113
	v_pk_mul_f32 v[102:103], v[102:103], v[108:109]
	v_pk_mul_f32 v[104:105], v[104:105], v[106:107]
	v_pk_mul_f32 v[106:107], v[100:101], v[110:111]
	v_pk_mul_f32 v[100:101], v[98:99], v[112:113]
	v_cvt_pk_bf16_f32 v98, v102, v103
	v_add_u32_e32 v102, v122, v123
	v_ashrrev_i32_e32 v103, 31, v102
	v_lshlrev_b64 v[102:103], 10, v[102:103]
	v_lshl_add_u64 v[102:103], s[6:7], 0, v[102:103]
	v_lshl_add_u64 v[102:103], v[102:103], 0, s[16:17]
	v_cvt_pk_bf16_f32 v99, v104, v105
	v_cvt_pk_bf16_f32 v100, v100, v101
	v_cvt_pk_bf16_f32 v101, v106, v107
	v_lshl_add_u64 v[102:103], v[102:103], 0, v[0:1]
	global_store_dwordx4 v[102:103], v[98:101], off
	v_pk_mul_f32 v[102:103], v[92:93], v[92:93]
	v_pk_mul_f32 v[104:105], v[90:91], v[90:91]
	v_pk_mul_f32 v[100:101], v[94:95], v[94:95]
	v_pk_mul_f32 v[98:99], v[96:97], v[96:97]
	v_pk_fma_f32 v[100:101], v[100:101], s[38:39], 1.0 op_sel_hi:[1,0,0]
	v_pk_fma_f32 v[98:99], v[98:99], s[38:39], 1.0 op_sel_hi:[1,0,0]
	v_pk_mul_f32 v[100:101], v[94:95], v[100:101]
	v_pk_fma_f32 v[102:103], v[102:103], s[38:39], 1.0 op_sel_hi:[1,0,0]
	v_pk_fma_f32 v[104:105], v[104:105], s[38:39], 1.0 op_sel_hi:[1,0,0]
	v_pk_mul_f32 v[98:99], v[96:97], v[98:99]
	v_pk_mul_f32 v[100:101], v[100:101], s[40:41] op_sel_hi:[1,0]
	v_pk_mul_f32 v[102:103], v[92:93], v[102:103]
	v_pk_mul_f32 v[104:105], v[90:91], v[104:105]
	v_pk_mul_f32 v[98:99], v[98:99], s[40:41] op_sel_hi:[1,0]
	v_pk_mul_f32 v[102:103], v[102:103], s[40:41] op_sel_hi:[1,0]
	v_pk_mul_f32 v[104:105], v[104:105], s[40:41] op_sel_hi:[1,0]
	v_exp_f32_e32 v100, v100
	v_exp_f32_e32 v101, v101
	v_exp_f32_e32 v104, v104
	v_exp_f32_e32 v98, v98
	v_exp_f32_e32 v99, v99
	v_exp_f32_e32 v102, v102
	v_exp_f32_e32 v103, v103
	v_exp_f32_e32 v105, v105
	v_pk_add_f32 v[100:101], v[100:101], 1.0 op_sel_hi:[1,0]
	v_pk_add_f32 v[98:99], v[98:99], 1.0 op_sel_hi:[1,0]
	v_pk_add_f32 v[102:103], v[102:103], 1.0 op_sel_hi:[1,0]
	v_pk_add_f32 v[104:105], v[104:105], 1.0 op_sel_hi:[1,0]
	v_rcp_f32_e32 v100, v100
	v_rcp_f32_e32 v101, v101
	v_rcp_f32_e32 v104, v104
	v_rcp_f32_e32 v98, v98
	v_rcp_f32_e32 v99, v99
	v_rcp_f32_e32 v102, v102
	v_rcp_f32_e32 v103, v103
	v_rcp_f32_e32 v105, v105
	v_add_u32_e32 v106, 0x400, v131
	v_pk_mul_f32 v[94:95], v[94:95], v[100:101]
	v_pk_mul_f32 v[96:97], v[96:97], v[98:99]
	v_pk_mul_f32 v[98:99], v[92:93], v[102:103]
	v_pk_mul_f32 v[92:93], v[90:91], v[104:105]
	v_cvt_pk_bf16_f32 v90, v94, v95
	v_add_u32_e32 v94, v106, v130
	v_ashrrev_i32_e32 v95, 31, v94
	v_lshlrev_b64 v[94:95], 10, v[94:95]
	v_lshl_add_u64 v[94:95], s[6:7], 0, v[94:95]
	v_lshl_add_u64 v[94:95], v[94:95], 0, s[16:17]
	v_cvt_pk_bf16_f32 v91, v96, v97
	v_cvt_pk_bf16_f32 v92, v92, v93
	v_cvt_pk_bf16_f32 v93, v98, v99
	v_lshl_add_u64 v[94:95], v[94:95], 0, v[0:1]
	global_store_dwordx4 v[94:95], v[90:93], off
	v_pk_mul_f32 v[94:95], v[84:85], v[84:85]
	v_pk_mul_f32 v[96:97], v[82:83], v[82:83]
	v_pk_mul_f32 v[92:93], v[86:87], v[86:87]
	v_pk_mul_f32 v[90:91], v[88:89], v[88:89]
	v_pk_fma_f32 v[92:93], v[92:93], s[38:39], 1.0 op_sel_hi:[1,0,0]
	v_pk_fma_f32 v[90:91], v[90:91], s[38:39], 1.0 op_sel_hi:[1,0,0]
	v_pk_mul_f32 v[92:93], v[86:87], v[92:93]
	v_pk_fma_f32 v[94:95], v[94:95], s[38:39], 1.0 op_sel_hi:[1,0,0]
	v_pk_fma_f32 v[96:97], v[96:97], s[38:39], 1.0 op_sel_hi:[1,0,0]
	v_pk_mul_f32 v[90:91], v[88:89], v[90:91]
	v_pk_mul_f32 v[92:93], v[92:93], s[40:41] op_sel_hi:[1,0]
	v_pk_mul_f32 v[94:95], v[84:85], v[94:95]
	v_pk_mul_f32 v[96:97], v[82:83], v[96:97]
	v_pk_mul_f32 v[90:91], v[90:91], s[40:41] op_sel_hi:[1,0]
	v_pk_mul_f32 v[94:95], v[94:95], s[40:41] op_sel_hi:[1,0]
	v_pk_mul_f32 v[96:97], v[96:97], s[40:41] op_sel_hi:[1,0]
	v_exp_f32_e32 v92, v92
	v_exp_f32_e32 v93, v93
	v_exp_f32_e32 v96, v96
	v_exp_f32_e32 v90, v90
	v_exp_f32_e32 v91, v91
	v_exp_f32_e32 v94, v94
	v_exp_f32_e32 v95, v95
	v_exp_f32_e32 v97, v97
	v_pk_add_f32 v[92:93], v[92:93], 1.0 op_sel_hi:[1,0]
	v_pk_add_f32 v[90:91], v[90:91], 1.0 op_sel_hi:[1,0]
	v_pk_add_f32 v[94:95], v[94:95], 1.0 op_sel_hi:[1,0]
	v_pk_add_f32 v[96:97], v[96:97], 1.0 op_sel_hi:[1,0]
	v_rcp_f32_e32 v92, v92
	v_rcp_f32_e32 v93, v93
	v_rcp_f32_e32 v96, v96
	v_rcp_f32_e32 v90, v90
	v_rcp_f32_e32 v91, v91
	v_rcp_f32_e32 v94, v94
	v_rcp_f32_e32 v95, v95
	v_rcp_f32_e32 v97, v97
	v_pk_mul_f32 v[86:87], v[86:87], v[92:93]
	v_pk_mul_f32 v[88:89], v[88:89], v[90:91]
	v_pk_mul_f32 v[90:91], v[84:85], v[94:95]
	v_pk_mul_f32 v[84:85], v[82:83], v[96:97]
	v_cvt_pk_bf16_f32 v82, v86, v87
	v_add_u32_e32 v86, v122, v106
	v_ashrrev_i32_e32 v87, 31, v86
; __device__ __forceinline__ u32x4 pack8(f32x4 a, f32x4 b) { u32x4 w; w.x = cvtpk(a[0], a[1]); w.y = cvtpk(a[2], a[3]); w.z = cvtpk(b[0], b[1]); w.w = cvtpk(b[2], b[3]); return w; }
; __device__ __forceinline__ float fast_exp2(float x) { return __builtin_amdgcn_exp2f(x); }
; __device__ __forceinline__ float fast_rcp(float x) { return __builtin_amdgcn_rcpf(x); }
;     __device__ __forceinline__ void operator()(AccRef acc, const Unit& u, int wr, int wc, int fr, int fq) const {
;     ...
;                     const int cc = u.pn * 256 + bj * 128 + wc * 32 + 8 * fq, t = cc >> 4, ho0 = cc & 15;
;                     f32x4 v0, v1;
;                     {
;                         const f32x4 x0 = acc[ai][bj][m][0], x1 = acc[ai][bj][m][1];
;                         f32x4 t0 = (x0 * x0 * 0.044715f + 1.0f) * x0 * (-2.f * LOG2E * 0.7978845608028654f), t1 = (x1 * x1 * 0.044715f + 1.0f) * x1 * (-2.f * LOG2E * 0.7978845608028654f);
; #pragma unroll
;                         for (int j = 0; j < 4; ++j) { t0[j] = fast_exp2(t0[j]); t1[j] = fast_exp2(t1[j]); }
;                         t0 = t0 + 1.0f; t1 = t1 + 1.0f;
; #pragma unroll
;                         for (int j = 0; j < 4; ++j) { t0[j] = fast_rcp(t0[j]); t1[j] = fast_rcp(t1[j]); }
;                         v0 = x0 * t0; v1 = x1 * t1;
;                     }
;                     *(u32x4*)(yb + ((size_t)(b * SEQ + ch * CH + t)) * 512 + g * 16 + ho0) = pack8(v0, v1);
	v_lshlrev_b64 v[86:87], 10, v[86:87]
	v_lshl_add_u64 v[86:87], s[6:7], 0, v[86:87]
	v_lshl_add_u64 v[86:87], v[86:87], 0, s[16:17]
	v_cvt_pk_bf16_f32 v83, v88, v89
	v_cvt_pk_bf16_f32 v84, v84, v85
	v_cvt_pk_bf16_f32 v85, v90, v91
	v_lshl_add_u64 v[86:87], v[86:87], 0, v[0:1]
	global_store_dwordx4 v[86:87], v[82:85], off
	v_pk_mul_f32 v[86:87], v[76:77], v[76:77]
	v_pk_mul_f32 v[88:89], v[74:75], v[74:75]
	v_pk_mul_f32 v[84:85], v[78:79], v[78:79]
	v_pk_mul_f32 v[82:83], v[80:81], v[80:81]
	v_pk_fma_f32 v[84:85], v[84:85], s[38:39], 1.0 op_sel_hi:[1,0,0]
	v_pk_fma_f32 v[82:83], v[82:83], s[38:39], 1.0 op_sel_hi:[1,0,0]
	v_pk_mul_f32 v[84:85], v[78:79], v[84:85]
	v_pk_fma_f32 v[86:87], v[86:87], s[38:39], 1.0 op_sel_hi:[1,0,0]
	v_pk_fma_f32 v[88:89], v[88:89], s[38:39], 1.0 op_sel_hi:[1,0,0]
	v_pk_mul_f32 v[82:83], v[80:81], v[82:83]
	v_pk_mul_f32 v[84:85], v[84:85], s[40:41] op_sel_hi:[1,0]
	v_pk_mul_f32 v[86:87], v[76:77], v[86:87]
	v_pk_mul_f32 v[88:89], v[74:75], v[88:89]
	v_pk_mul_f32 v[82:83], v[82:83], s[40:41] op_sel_hi:[1,0]
	v_pk_mul_f32 v[86:87], v[86:87], s[40:41] op_sel_hi:[1,0]
	v_pk_mul_f32 v[88:89], v[88:89], s[40:41] op_sel_hi:[1,0]
	v_exp_f32_e32 v84, v84
	v_exp_f32_e32 v85, v85
	v_exp_f32_e32 v88, v88
	v_exp_f32_e32 v82, v82
	v_exp_f32_e32 v83, v83
	v_exp_f32_e32 v86, v86
	v_exp_f32_e32 v87, v87
	v_exp_f32_e32 v89, v89
	v_pk_add_f32 v[84:85], v[84:85], 1.0 op_sel_hi:[1,0]
	v_pk_add_f32 v[82:83], v[82:83], 1.0 op_sel_hi:[1,0]
	v_pk_add_f32 v[86:87], v[86:87], 1.0 op_sel_hi:[1,0]
	v_pk_add_f32 v[88:89], v[88:89], 1.0 op_sel_hi:[1,0]
	v_rcp_f32_e32 v84, v84
	v_rcp_f32_e32 v85, v85
	v_rcp_f32_e32 v88, v88
	v_rcp_f32_e32 v82, v82
	v_rcp_f32_e32 v83, v83
	v_rcp_f32_e32 v86, v86
	v_rcp_f32_e32 v87, v87
	v_rcp_f32_e32 v89, v89
	v_add_u32_e32 v90, 0x600, v131
	v_pk_mul_f32 v[78:79], v[78:79], v[84:85]
	v_pk_mul_f32 v[80:81], v[80:81], v[82:83]
	v_pk_mul_f32 v[82:83], v[76:77], v[86:87]
	v_pk_mul_f32 v[76:77], v[74:75], v[88:89]
	v_cvt_pk_bf16_f32 v74, v78, v79
	v_add_u32_e32 v78, v90, v130
	v_ashrrev_i32_e32 v79, 31, v78
	v_lshlrev_b64 v[78:79], 10, v[78:79]
	v_lshl_add_u64 v[78:79], s[6:7], 0, v[78:79]
	v_lshl_add_u64 v[78:79], v[78:79], 0, s[16:17]
	v_cvt_pk_bf16_f32 v75, v80, v81
	v_cvt_pk_bf16_f32 v76, v76, v77
	v_cvt_pk_bf16_f32 v77, v82, v83
	v_lshl_add_u64 v[78:79], v[78:79], 0, v[0:1]
	global_store_dwordx4 v[78:79], v[74:77], off
	v_pk_mul_f32 v[78:79], v[68:69], v[68:69]
	v_pk_mul_f32 v[80:81], v[66:67], v[66:67]
	v_pk_mul_f32 v[76:77], v[70:71], v[70:71]
	v_pk_mul_f32 v[74:75], v[72:73], v[72:73]
	v_pk_fma_f32 v[76:77], v[76:77], s[38:39], 1.0 op_sel_hi:[1,0,0]
	v_pk_fma_f32 v[74:75], v[74:75], s[38:39], 1.0 op_sel_hi:[1,0,0]
	v_pk_mul_f32 v[76:77], v[70:71], v[76:77]
	v_pk_fma_f32 v[78:79], v[78:79], s[38:39], 1.0 op_sel_hi:[1,0,0]
	v_pk_fma_f32 v[80:81], v[80:81], s[38:39], 1.0 op_sel_hi:[1,0,0]
	v_pk_mul_f32 v[74:75], v[72:73], v[74:75]
	v_pk_mul_f32 v[76:77], v[76:77], s[40:41] op_sel_hi:[1,0]
	v_pk_mul_f32 v[78:79], v[68:69], v[78:79]
	v_pk_mul_f32 v[80:81], v[66:67], v[80:81]
	v_pk_mul_f32 v[74:75], v[74:75], s[40:41] op_sel_hi:[1,0]
	v_pk_mul_f32 v[78:79], v[78:79], s[40:41] op_sel_hi:[1,0]
	v_pk_mul_f32 v[80:81], v[80:81], s[40:41] op_sel_hi:[1,0]
	v_exp_f32_e32 v76, v76
	v_exp_f32_e32 v77, v77
	v_exp_f32_e32 v80, v80
	v_exp_f32_e32 v74, v74
	v_exp_f32_e32 v75, v75
	v_exp_f32_e32 v78, v78
	v_exp_f32_e32 v79, v79
	v_exp_f32_e32 v81, v81
	v_pk_add_f32 v[76:77], v[76:77], 1.0 op_sel_hi:[1,0]
	v_pk_add_f32 v[74:75], v[74:75], 1.0 op_sel_hi:[1,0]
	v_pk_add_f32 v[78:79], v[78:79], 1.0 op_sel_hi:[1,0]
	v_pk_add_f32 v[80:81], v[80:81], 1.0 op_sel_hi:[1,0]
	v_rcp_f32_e32 v76, v76
	v_rcp_f32_e32 v77, v77
	v_rcp_f32_e32 v80, v80
	v_rcp_f32_e32 v74, v74
	v_rcp_f32_e32 v75, v75
	v_rcp_f32_e32 v78, v78
	v_rcp_f32_e32 v79, v79
	v_rcp_f32_e32 v81, v81
	v_pk_mul_f32 v[70:71], v[70:71], v[76:77]
	v_pk_mul_f32 v[72:73], v[72:73], v[74:75]
	v_pk_mul_f32 v[74:75], v[68:69], v[78:79]
	v_pk_mul_f32 v[68:69], v[66:67], v[80:81]
	v_cvt_pk_bf16_f32 v66, v70, v71
	v_add_u32_e32 v70, v122, v90
	v_ashrrev_i32_e32 v71, 31, v70
	v_lshlrev_b64 v[70:71], 10, v[70:71]
	v_lshl_add_u64 v[70:71], s[6:7], 0, v[70:71]
	v_lshl_add_u64 v[70:71], v[70:71], 0, s[16:17]
	v_cvt_pk_bf16_f32 v67, v72, v73
	v_cvt_pk_bf16_f32 v68, v68, v69
	v_cvt_pk_bf16_f32 v69, v74, v75
	v_lshl_add_u64 v[70:71], v[70:71], 0, v[0:1]
	global_store_dwordx4 v[70:71], v[66:69], off
	v_pk_mul_f32 v[70:71], v[60:61], v[60:61]
	v_pk_mul_f32 v[72:73], v[58:59], v[58:59]
	v_pk_mul_f32 v[68:69], v[62:63], v[62:63]
	v_pk_mul_f32 v[66:67], v[64:65], v[64:65]
	v_pk_fma_f32 v[68:69], v[68:69], s[38:39], 1.0 op_sel_hi:[1,0,0]
	v_pk_fma_f32 v[66:67], v[66:67], s[38:39], 1.0 op_sel_hi:[1,0,0]
	v_pk_mul_f32 v[68:69], v[62:63], v[68:69]
	v_pk_fma_f32 v[70:71], v[70:71], s[38:39], 1.0 op_sel_hi:[1,0,0]
	v_pk_fma_f32 v[72:73], v[72:73], s[38:39], 1.0 op_sel_hi:[1,0,0]
	v_pk_mul_f32 v[66:67], v[64:65], v[66:67]
	v_pk_mul_f32 v[68:69], v[68:69], s[40:41] op_sel_hi:[1,0]
	v_pk_mul_f32 v[70:71], v[60:61], v[70:71]
	v_pk_mul_f32 v[72:73], v[58:59], v[72:73]
	v_pk_mul_f32 v[66:67], v[66:67], s[40:41] op_sel_hi:[1,0]
	v_pk_mul_f32 v[70:71], v[70:71], s[40:41] op_sel_hi:[1,0]
	v_pk_mul_f32 v[72:73], v[72:73], s[40:41] op_sel_hi:[1,0]
	v_exp_f32_e32 v68, v68
	v_exp_f32_e32 v69, v69
	v_exp_f32_e32 v72, v72
	v_exp_f32_e32 v66, v66
	v_exp_f32_e32 v67, v67
	v_exp_f32_e32 v70, v70
	v_exp_f32_e32 v71, v71
	v_exp_f32_e32 v73, v73
	v_pk_add_f32 v[68:69], v[68:69], 1.0 op_sel_hi:[1,0]
	v_pk_add_f32 v[66:67], v[66:67], 1.0 op_sel_hi:[1,0]
	v_pk_add_f32 v[70:71], v[70:71], 1.0 op_sel_hi:[1,0]
; __device__ __forceinline__ u32x4 pack8(f32x4 a, f32x4 b) { u32x4 w; w.x = cvtpk(a[0], a[1]); w.y = cvtpk(a[2], a[3]); w.z = cvtpk(b[0], b[1]); w.w = cvtpk(b[2], b[3]); return w; }
; __device__ __forceinline__ float fast_exp2(float x) { return __builtin_amdgcn_exp2f(x); }
; __device__ __forceinline__ float fast_rcp(float x) { return __builtin_amdgcn_rcpf(x); }
;     __device__ __forceinline__ void operator()(AccRef acc, const Unit& u, int wr, int wc, int fr, int fq) const {
;     ...
;                     const int cc = u.pn * 256 + bj * 128 + wc * 32 + 8 * fq, t = cc >> 4, ho0 = cc & 15;
;                     f32x4 v0, v1;
;                     {
;                         const f32x4 x0 = acc[ai][bj][m][0], x1 = acc[ai][bj][m][1];
;                         f32x4 t0 = (x0 * x0 * 0.044715f + 1.0f) * x0 * (-2.f * LOG2E * 0.7978845608028654f), t1 = (x1 * x1 * 0.044715f + 1.0f) * x1 * (-2.f * LOG2E * 0.7978845608028654f);
; #pragma unroll
;                         for (int j = 0; j < 4; ++j) { t0[j] = fast_exp2(t0[j]); t1[j] = fast_exp2(t1[j]); }
;                         t0 = t0 + 1.0f; t1 = t1 + 1.0f;
; #pragma unroll
;                         for (int j = 0; j < 4; ++j) { t0[j] = fast_rcp(t0[j]); t1[j] = fast_rcp(t1[j]); }
;                         v0 = x0 * t0; v1 = x1 * t1;
;                     }
;                     *(u32x4*)(yb + ((size_t)(b * SEQ + ch * CH + t)) * 512 + g * 16 + ho0) = pack8(v0, v1);
	v_pk_add_f32 v[72:73], v[72:73], 1.0 op_sel_hi:[1,0]
	v_rcp_f32_e32 v68, v68
	v_rcp_f32_e32 v69, v69
	v_rcp_f32_e32 v72, v72
	v_rcp_f32_e32 v66, v66
	v_rcp_f32_e32 v67, v67
	v_rcp_f32_e32 v70, v70
	v_rcp_f32_e32 v71, v71
	v_rcp_f32_e32 v73, v73
	v_add_u32_e32 v74, 0x1000, v131
	v_pk_mul_f32 v[62:63], v[62:63], v[68:69]
	v_pk_mul_f32 v[64:65], v[64:65], v[66:67]
	v_pk_mul_f32 v[66:67], v[60:61], v[70:71]
	v_pk_mul_f32 v[60:61], v[58:59], v[72:73]
	v_cvt_pk_bf16_f32 v58, v62, v63
	v_add_u32_e32 v62, v130, v74
	v_ashrrev_i32_e32 v63, 31, v62
	v_lshlrev_b64 v[62:63], 10, v[62:63]
	v_lshl_add_u64 v[62:63], s[6:7], 0, v[62:63]
	v_lshl_add_u64 v[62:63], v[62:63], 0, s[16:17]
	v_cvt_pk_bf16_f32 v59, v64, v65
	v_cvt_pk_bf16_f32 v60, v60, v61
	v_cvt_pk_bf16_f32 v61, v66, v67
	v_lshl_add_u64 v[62:63], v[62:63], 0, v[0:1]
	global_store_dwordx4 v[62:63], v[58:61], off
	v_pk_mul_f32 v[62:63], v[52:53], v[52:53]
	v_pk_mul_f32 v[64:65], v[50:51], v[50:51]
	v_pk_mul_f32 v[60:61], v[54:55], v[54:55]
	v_pk_mul_f32 v[58:59], v[56:57], v[56:57]
	v_pk_fma_f32 v[60:61], v[60:61], s[38:39], 1.0 op_sel_hi:[1,0,0]
	v_pk_fma_f32 v[58:59], v[58:59], s[38:39], 1.0 op_sel_hi:[1,0,0]
	v_pk_mul_f32 v[60:61], v[54:55], v[60:61]
	v_pk_fma_f32 v[62:63], v[62:63], s[38:39], 1.0 op_sel_hi:[1,0,0]
	v_pk_fma_f32 v[64:65], v[64:65], s[38:39], 1.0 op_sel_hi:[1,0,0]
	v_pk_mul_f32 v[58:59], v[56:57], v[58:59]
	v_pk_mul_f32 v[60:61], v[60:61], s[40:41] op_sel_hi:[1,0]
	v_pk_mul_f32 v[62:63], v[52:53], v[62:63]
	v_pk_mul_f32 v[64:65], v[50:51], v[64:65]
	v_pk_mul_f32 v[58:59], v[58:59], s[40:41] op_sel_hi:[1,0]
	v_pk_mul_f32 v[62:63], v[62:63], s[40:41] op_sel_hi:[1,0]
	v_pk_mul_f32 v[64:65], v[64:65], s[40:41] op_sel_hi:[1,0]
	v_exp_f32_e32 v60, v60
	v_exp_f32_e32 v61, v61
	v_exp_f32_e32 v64, v64
	v_exp_f32_e32 v58, v58
	v_exp_f32_e32 v59, v59
	v_exp_f32_e32 v62, v62
	v_exp_f32_e32 v63, v63
	v_exp_f32_e32 v65, v65
	v_pk_add_f32 v[60:61], v[60:61], 1.0 op_sel_hi:[1,0]
	v_pk_add_f32 v[58:59], v[58:59], 1.0 op_sel_hi:[1,0]
	v_pk_add_f32 v[62:63], v[62:63], 1.0 op_sel_hi:[1,0]
	v_pk_add_f32 v[64:65], v[64:65], 1.0 op_sel_hi:[1,0]
	v_rcp_f32_e32 v60, v60
	v_rcp_f32_e32 v61, v61
	v_rcp_f32_e32 v64, v64
	v_rcp_f32_e32 v58, v58
	v_rcp_f32_e32 v59, v59
	v_rcp_f32_e32 v62, v62
	v_rcp_f32_e32 v63, v63
	v_rcp_f32_e32 v65, v65
	v_pk_mul_f32 v[54:55], v[54:55], v[60:61]
	v_pk_mul_f32 v[56:57], v[56:57], v[58:59]
	v_pk_mul_f32 v[58:59], v[52:53], v[62:63]
	v_pk_mul_f32 v[52:53], v[50:51], v[64:65]
	v_cvt_pk_bf16_f32 v50, v54, v55
	v_add_u32_e32 v54, v122, v74
	v_ashrrev_i32_e32 v55, 31, v54
	v_lshlrev_b64 v[54:55], 10, v[54:55]
	v_lshl_add_u64 v[54:55], s[6:7], 0, v[54:55]
	v_lshl_add_u64 v[54:55], v[54:55], 0, s[16:17]
	v_cvt_pk_bf16_f32 v51, v56, v57
	v_cvt_pk_bf16_f32 v52, v52, v53
	v_cvt_pk_bf16_f32 v53, v58, v59
	v_lshl_add_u64 v[54:55], v[54:55], 0, v[0:1]
	global_store_dwordx4 v[54:55], v[50:53], off
	v_pk_mul_f32 v[54:55], v[44:45], v[44:45]
	v_pk_mul_f32 v[56:57], v[42:43], v[42:43]
	v_pk_mul_f32 v[52:53], v[46:47], v[46:47]
	v_pk_mul_f32 v[50:51], v[48:49], v[48:49]
	v_pk_fma_f32 v[52:53], v[52:53], s[38:39], 1.0 op_sel_hi:[1,0,0]
	v_pk_fma_f32 v[50:51], v[50:51], s[38:39], 1.0 op_sel_hi:[1,0,0]
	v_pk_mul_f32 v[52:53], v[46:47], v[52:53]
	v_pk_fma_f32 v[54:55], v[54:55], s[38:39], 1.0 op_sel_hi:[1,0,0]
	v_pk_fma_f32 v[56:57], v[56:57], s[38:39], 1.0 op_sel_hi:[1,0,0]
	v_pk_mul_f32 v[50:51], v[48:49], v[50:51]
	v_pk_mul_f32 v[52:53], v[52:53], s[40:41] op_sel_hi:[1,0]
	v_pk_mul_f32 v[54:55], v[44:45], v[54:55]
	v_pk_mul_f32 v[56:57], v[42:43], v[56:57]
	v_pk_mul_f32 v[50:51], v[50:51], s[40:41] op_sel_hi:[1,0]
	v_pk_mul_f32 v[54:55], v[54:55], s[40:41] op_sel_hi:[1,0]
	v_pk_mul_f32 v[56:57], v[56:57], s[40:41] op_sel_hi:[1,0]
	v_exp_f32_e32 v52, v52
	v_exp_f32_e32 v53, v53
	v_exp_f32_e32 v56, v56
	v_exp_f32_e32 v50, v50
	v_exp_f32_e32 v51, v51
	v_exp_f32_e32 v54, v54
	v_exp_f32_e32 v55, v55
	v_exp_f32_e32 v57, v57
	v_pk_add_f32 v[52:53], v[52:53], 1.0 op_sel_hi:[1,0]
	v_pk_add_f32 v[50:51], v[50:51], 1.0 op_sel_hi:[1,0]
	v_pk_add_f32 v[54:55], v[54:55], 1.0 op_sel_hi:[1,0]
	v_pk_add_f32 v[56:57], v[56:57], 1.0 op_sel_hi:[1,0]
	v_rcp_f32_e32 v52, v52
	v_rcp_f32_e32 v53, v53
	v_rcp_f32_e32 v56, v56
	v_rcp_f32_e32 v50, v50
	v_rcp_f32_e32 v51, v51
	v_rcp_f32_e32 v54, v54
	v_rcp_f32_e32 v55, v55
	v_rcp_f32_e32 v57, v57
	v_add_u32_e32 v58, 0x1200, v131
	v_pk_mul_f32 v[46:47], v[46:47], v[52:53]
	v_pk_mul_f32 v[48:49], v[48:49], v[50:51]
	v_pk_mul_f32 v[50:51], v[44:45], v[54:55]
	v_pk_mul_f32 v[44:45], v[42:43], v[56:57]
	v_cvt_pk_bf16_f32 v42, v46, v47
	v_add_u32_e32 v46, v130, v58
	v_ashrrev_i32_e32 v47, 31, v46
	v_lshlrev_b64 v[46:47], 10, v[46:47]
	v_lshl_add_u64 v[46:47], s[6:7], 0, v[46:47]
	v_lshl_add_u64 v[46:47], v[46:47], 0, s[16:17]
	v_cvt_pk_bf16_f32 v43, v48, v49
	v_cvt_pk_bf16_f32 v44, v44, v45
	v_cvt_pk_bf16_f32 v45, v50, v51
	v_lshl_add_u64 v[46:47], v[46:47], 0, v[0:1]
	global_store_dwordx4 v[46:47], v[42:45], off
	v_pk_mul_f32 v[46:47], v[36:37], v[36:37]
	v_pk_mul_f32 v[48:49], v[34:35], v[34:35]
	v_pk_mul_f32 v[44:45], v[38:39], v[38:39]
	v_pk_mul_f32 v[42:43], v[40:41], v[40:41]
	v_pk_fma_f32 v[44:45], v[44:45], s[38:39], 1.0 op_sel_hi:[1,0,0]
	v_pk_fma_f32 v[42:43], v[42:43], s[38:39], 1.0 op_sel_hi:[1,0,0]
	v_pk_mul_f32 v[44:45], v[38:39], v[44:45]
	v_pk_fma_f32 v[46:47], v[46:47], s[38:39], 1.0 op_sel_hi:[1,0,0]
	v_pk_fma_f32 v[48:49], v[48:49], s[38:39], 1.0 op_sel_hi:[1,0,0]
	v_pk_mul_f32 v[42:43], v[40:41], v[42:43]
	v_pk_mul_f32 v[44:45], v[44:45], s[40:41] op_sel_hi:[1,0]
	v_pk_mul_f32 v[46:47], v[36:37], v[46:47]
	v_pk_mul_f32 v[48:49], v[34:35], v[48:49]
; __device__ __forceinline__ u32x4 pack8(f32x4 a, f32x4 b) { u32x4 w; w.x = cvtpk(a[0], a[1]); w.y = cvtpk(a[2], a[3]); w.z = cvtpk(b[0], b[1]); w.w = cvtpk(b[2], b[3]); return w; }
; __device__ __forceinline__ float fast_exp2(float x) { return __builtin_amdgcn_exp2f(x); }
; __device__ __forceinline__ float fast_rcp(float x) { return __builtin_amdgcn_rcpf(x); }
;     __device__ __forceinline__ void operator()(AccRef acc, const Unit& u, int wr, int wc, int fr, int fq) const {
;     ...
;                     const int cc = u.pn * 256 + bj * 128 + wc * 32 + 8 * fq, t = cc >> 4, ho0 = cc & 15;
;                     f32x4 v0, v1;
;                     {
;                         const f32x4 x0 = acc[ai][bj][m][0], x1 = acc[ai][bj][m][1];
;                         f32x4 t0 = (x0 * x0 * 0.044715f + 1.0f) * x0 * (-2.f * LOG2E * 0.7978845608028654f), t1 = (x1 * x1 * 0.044715f + 1.0f) * x1 * (-2.f * LOG2E * 0.7978845608028654f);
; #pragma unroll
;                         for (int j = 0; j < 4; ++j) { t0[j] = fast_exp2(t0[j]); t1[j] = fast_exp2(t1[j]); }
;                         t0 = t0 + 1.0f; t1 = t1 + 1.0f;
; #pragma unroll
;                         for (int j = 0; j < 4; ++j) { t0[j] = fast_rcp(t0[j]); t1[j] = fast_rcp(t1[j]); }
;                         v0 = x0 * t0; v1 = x1 * t1;
;                     }
;                     *(u32x4*)(yb + ((size_t)(b * SEQ + ch * CH + t)) * 512 + g * 16 + ho0) = pack8(v0, v1);
	v_pk_mul_f32 v[42:43], v[42:43], s[40:41] op_sel_hi:[1,0]
	v_pk_mul_f32 v[46:47], v[46:47], s[40:41] op_sel_hi:[1,0]
	v_pk_mul_f32 v[48:49], v[48:49], s[40:41] op_sel_hi:[1,0]
	v_exp_f32_e32 v44, v44
	v_exp_f32_e32 v45, v45
	v_exp_f32_e32 v48, v48
	v_exp_f32_e32 v42, v42
	v_exp_f32_e32 v43, v43
	v_exp_f32_e32 v46, v46
	v_exp_f32_e32 v47, v47
	v_exp_f32_e32 v49, v49
	v_pk_add_f32 v[44:45], v[44:45], 1.0 op_sel_hi:[1,0]
	v_pk_add_f32 v[42:43], v[42:43], 1.0 op_sel_hi:[1,0]
	v_pk_add_f32 v[46:47], v[46:47], 1.0 op_sel_hi:[1,0]
	v_pk_add_f32 v[48:49], v[48:49], 1.0 op_sel_hi:[1,0]
	v_rcp_f32_e32 v44, v44
	v_rcp_f32_e32 v45, v45
	v_rcp_f32_e32 v48, v48
	v_rcp_f32_e32 v42, v42
	v_rcp_f32_e32 v43, v43
	v_rcp_f32_e32 v46, v46
	v_rcp_f32_e32 v47, v47
	v_rcp_f32_e32 v49, v49
	v_pk_mul_f32 v[38:39], v[38:39], v[44:45]
	v_pk_mul_f32 v[40:41], v[40:41], v[42:43]
	v_pk_mul_f32 v[42:43], v[36:37], v[46:47]
	v_pk_mul_f32 v[36:37], v[34:35], v[48:49]
	v_cvt_pk_bf16_f32 v34, v38, v39
	v_add_u32_e32 v38, v122, v58
	v_ashrrev_i32_e32 v39, 31, v38
	v_lshlrev_b64 v[38:39], 10, v[38:39]
	v_lshl_add_u64 v[38:39], s[6:7], 0, v[38:39]
	v_lshl_add_u64 v[38:39], v[38:39], 0, s[16:17]
	v_cvt_pk_bf16_f32 v35, v40, v41
	v_cvt_pk_bf16_f32 v36, v36, v37
	v_cvt_pk_bf16_f32 v37, v42, v43
	v_lshl_add_u64 v[38:39], v[38:39], 0, v[0:1]
	global_store_dwordx4 v[38:39], v[34:37], off
	v_pk_mul_f32 v[38:39], v[28:29], v[28:29]
	v_pk_mul_f32 v[40:41], v[26:27], v[26:27]
	v_pk_mul_f32 v[36:37], v[30:31], v[30:31]
	v_pk_mul_f32 v[34:35], v[32:33], v[32:33]
	v_pk_fma_f32 v[36:37], v[36:37], s[38:39], 1.0 op_sel_hi:[1,0,0]
	v_pk_fma_f32 v[34:35], v[34:35], s[38:39], 1.0 op_sel_hi:[1,0,0]
	v_pk_mul_f32 v[36:37], v[30:31], v[36:37]
	v_pk_fma_f32 v[38:39], v[38:39], s[38:39], 1.0 op_sel_hi:[1,0,0]
	v_pk_fma_f32 v[40:41], v[40:41], s[38:39], 1.0 op_sel_hi:[1,0,0]
	v_pk_mul_f32 v[34:35], v[32:33], v[34:35]
	v_pk_mul_f32 v[36:37], v[36:37], s[40:41] op_sel_hi:[1,0]
	v_pk_mul_f32 v[38:39], v[28:29], v[38:39]
	v_pk_mul_f32 v[40:41], v[26:27], v[40:41]
	v_pk_mul_f32 v[34:35], v[34:35], s[40:41] op_sel_hi:[1,0]
	v_pk_mul_f32 v[38:39], v[38:39], s[40:41] op_sel_hi:[1,0]
	v_pk_mul_f32 v[40:41], v[40:41], s[40:41] op_sel_hi:[1,0]
	v_exp_f32_e32 v36, v36
	v_exp_f32_e32 v37, v37
	v_exp_f32_e32 v40, v40
	v_exp_f32_e32 v34, v34
	v_exp_f32_e32 v35, v35
	v_exp_f32_e32 v38, v38
	v_exp_f32_e32 v39, v39
	v_exp_f32_e32 v41, v41
	v_pk_add_f32 v[36:37], v[36:37], 1.0 op_sel_hi:[1,0]
	v_pk_add_f32 v[34:35], v[34:35], 1.0 op_sel_hi:[1,0]
	v_pk_add_f32 v[38:39], v[38:39], 1.0 op_sel_hi:[1,0]
	v_pk_add_f32 v[40:41], v[40:41], 1.0 op_sel_hi:[1,0]
	v_rcp_f32_e32 v36, v36
	v_rcp_f32_e32 v37, v37
	v_rcp_f32_e32 v40, v40
	v_rcp_f32_e32 v34, v34
	v_rcp_f32_e32 v35, v35
	v_rcp_f32_e32 v38, v38
	v_rcp_f32_e32 v39, v39
	v_rcp_f32_e32 v41, v41
	v_add_u32_e32 v42, 0x1400, v131
	v_pk_mul_f32 v[30:31], v[30:31], v[36:37]
	v_pk_mul_f32 v[32:33], v[32:33], v[34:35]
	v_pk_mul_f32 v[34:35], v[28:29], v[38:39]
	v_pk_mul_f32 v[28:29], v[26:27], v[40:41]
	v_cvt_pk_bf16_f32 v26, v30, v31
	v_add_u32_e32 v30, v130, v42
	v_ashrrev_i32_e32 v31, 31, v30
	v_lshlrev_b64 v[30:31], 10, v[30:31]
	v_lshl_add_u64 v[30:31], s[6:7], 0, v[30:31]
	v_lshl_add_u64 v[30:31], v[30:31], 0, s[16:17]
	v_cvt_pk_bf16_f32 v27, v32, v33
	v_cvt_pk_bf16_f32 v28, v28, v29
	v_cvt_pk_bf16_f32 v29, v34, v35
	v_lshl_add_u64 v[30:31], v[30:31], 0, v[0:1]
	global_store_dwordx4 v[30:31], v[26:29], off
	v_pk_mul_f32 v[30:31], v[20:21], v[20:21]
	v_pk_mul_f32 v[32:33], v[18:19], v[18:19]
	v_pk_mul_f32 v[28:29], v[22:23], v[22:23]
	v_pk_mul_f32 v[26:27], v[24:25], v[24:25]
	v_pk_fma_f32 v[28:29], v[28:29], s[38:39], 1.0 op_sel_hi:[1,0,0]
	v_pk_fma_f32 v[26:27], v[26:27], s[38:39], 1.0 op_sel_hi:[1,0,0]
	v_pk_mul_f32 v[28:29], v[22:23], v[28:29]
	v_pk_fma_f32 v[30:31], v[30:31], s[38:39], 1.0 op_sel_hi:[1,0,0]
	v_pk_fma_f32 v[32:33], v[32:33], s[38:39], 1.0 op_sel_hi:[1,0,0]
	v_pk_mul_f32 v[26:27], v[24:25], v[26:27]
	v_pk_mul_f32 v[28:29], v[28:29], s[40:41] op_sel_hi:[1,0]
	v_pk_mul_f32 v[30:31], v[20:21], v[30:31]
	v_pk_mul_f32 v[32:33], v[18:19], v[32:33]
	v_pk_mul_f32 v[26:27], v[26:27], s[40:41] op_sel_hi:[1,0]
	v_pk_mul_f32 v[30:31], v[30:31], s[40:41] op_sel_hi:[1,0]
	v_pk_mul_f32 v[32:33], v[32:33], s[40:41] op_sel_hi:[1,0]
	v_exp_f32_e32 v28, v28
	v_exp_f32_e32 v29, v29
	v_exp_f32_e32 v32, v32
	v_exp_f32_e32 v26, v26
	v_exp_f32_e32 v27, v27
	v_exp_f32_e32 v30, v30
	v_exp_f32_e32 v31, v31
	v_exp_f32_e32 v33, v33
	v_pk_add_f32 v[28:29], v[28:29], 1.0 op_sel_hi:[1,0]
	v_pk_add_f32 v[26:27], v[26:27], 1.0 op_sel_hi:[1,0]
	v_pk_add_f32 v[30:31], v[30:31], 1.0 op_sel_hi:[1,0]
	v_pk_add_f32 v[32:33], v[32:33], 1.0 op_sel_hi:[1,0]
	v_rcp_f32_e32 v28, v28
	v_rcp_f32_e32 v29, v29
	v_rcp_f32_e32 v32, v32
	v_rcp_f32_e32 v26, v26
	v_rcp_f32_e32 v27, v27
	v_rcp_f32_e32 v30, v30
	v_rcp_f32_e32 v31, v31
	v_rcp_f32_e32 v33, v33
	v_pk_mul_f32 v[22:23], v[22:23], v[28:29]
	v_pk_mul_f32 v[24:25], v[24:25], v[26:27]
	v_pk_mul_f32 v[26:27], v[20:21], v[30:31]
	v_pk_mul_f32 v[20:21], v[18:19], v[32:33]
	v_cvt_pk_bf16_f32 v18, v22, v23
	v_add_u32_e32 v22, v122, v42
	v_ashrrev_i32_e32 v23, 31, v22
	v_lshlrev_b64 v[22:23], 10, v[22:23]
	v_lshl_add_u64 v[22:23], s[6:7], 0, v[22:23]
	v_lshl_add_u64 v[22:23], v[22:23], 0, s[16:17]
	v_cvt_pk_bf16_f32 v19, v24, v25
	v_cvt_pk_bf16_f32 v20, v20, v21
	v_cvt_pk_bf16_f32 v21, v26, v27
	v_lshl_add_u64 v[22:23], v[22:23], 0, v[0:1]
	global_store_dwordx4 v[22:23], v[18:21], off
	v_pk_mul_f32 v[22:23], v[12:13], v[12:13]
	v_pk_mul_f32 v[24:25], v[10:11], v[10:11]
	v_pk_mul_f32 v[20:21], v[14:15], v[14:15]
	v_pk_mul_f32 v[18:19], v[16:17], v[16:17]
; __device__ __forceinline__ u32x4 pack8(f32x4 a, f32x4 b) { u32x4 w; w.x = cvtpk(a[0], a[1]); w.y = cvtpk(a[2], a[3]); w.z = cvtpk(b[0], b[1]); w.w = cvtpk(b[2], b[3]); return w; }
; __device__ __forceinline__ float fast_exp2(float x) { return __builtin_amdgcn_exp2f(x); }
; __device__ __forceinline__ float fast_rcp(float x) { return __builtin_amdgcn_rcpf(x); }
;     __device__ __forceinline__ void operator()(AccRef acc, const Unit& u, int wr, int wc, int fr, int fq) const {
;     ...
;                     const int cc = u.pn * 256 + bj * 128 + wc * 32 + 8 * fq, t = cc >> 4, ho0 = cc & 15;
;                     f32x4 v0, v1;
;                     {
;                         const f32x4 x0 = acc[ai][bj][m][0], x1 = acc[ai][bj][m][1];
;                         f32x4 t0 = (x0 * x0 * 0.044715f + 1.0f) * x0 * (-2.f * LOG2E * 0.7978845608028654f), t1 = (x1 * x1 * 0.044715f + 1.0f) * x1 * (-2.f * LOG2E * 0.7978845608028654f);
; #pragma unroll
;                         for (int j = 0; j < 4; ++j) { t0[j] = fast_exp2(t0[j]); t1[j] = fast_exp2(t1[j]); }
;                         t0 = t0 + 1.0f; t1 = t1 + 1.0f;
; #pragma unroll
;                         for (int j = 0; j < 4; ++j) { t0[j] = fast_rcp(t0[j]); t1[j] = fast_rcp(t1[j]); }
;                         v0 = x0 * t0; v1 = x1 * t1;
;                     }
;                     *(u32x4*)(yb + ((size_t)(b * SEQ + ch * CH + t)) * 512 + g * 16 + ho0) = pack8(v0, v1);
	v_pk_fma_f32 v[20:21], v[20:21], s[38:39], 1.0 op_sel_hi:[1,0,0]
	v_pk_fma_f32 v[18:19], v[18:19], s[38:39], 1.0 op_sel_hi:[1,0,0]
	v_pk_mul_f32 v[20:21], v[14:15], v[20:21]
	v_pk_fma_f32 v[22:23], v[22:23], s[38:39], 1.0 op_sel_hi:[1,0,0]
	v_pk_fma_f32 v[24:25], v[24:25], s[38:39], 1.0 op_sel_hi:[1,0,0]
	v_pk_mul_f32 v[18:19], v[16:17], v[18:19]
	v_pk_mul_f32 v[20:21], v[20:21], s[40:41] op_sel_hi:[1,0]
	v_pk_mul_f32 v[22:23], v[12:13], v[22:23]
	v_pk_mul_f32 v[24:25], v[10:11], v[24:25]
	v_pk_mul_f32 v[18:19], v[18:19], s[40:41] op_sel_hi:[1,0]
	v_pk_mul_f32 v[22:23], v[22:23], s[40:41] op_sel_hi:[1,0]
	v_pk_mul_f32 v[24:25], v[24:25], s[40:41] op_sel_hi:[1,0]
	v_exp_f32_e32 v20, v20
	v_exp_f32_e32 v21, v21
	v_exp_f32_e32 v24, v24
	v_exp_f32_e32 v18, v18
	v_exp_f32_e32 v19, v19
	v_exp_f32_e32 v22, v22
	v_exp_f32_e32 v23, v23
	v_exp_f32_e32 v25, v25
	v_pk_add_f32 v[20:21], v[20:21], 1.0 op_sel_hi:[1,0]
	v_pk_add_f32 v[18:19], v[18:19], 1.0 op_sel_hi:[1,0]
	v_pk_add_f32 v[22:23], v[22:23], 1.0 op_sel_hi:[1,0]
	v_pk_add_f32 v[24:25], v[24:25], 1.0 op_sel_hi:[1,0]
	v_rcp_f32_e32 v20, v20
	v_rcp_f32_e32 v21, v21
	v_rcp_f32_e32 v24, v24
	v_rcp_f32_e32 v18, v18
	v_rcp_f32_e32 v19, v19
	v_rcp_f32_e32 v22, v22
	v_rcp_f32_e32 v23, v23
	v_rcp_f32_e32 v25, v25
	v_add_u32_e32 v26, 0x1600, v131
	v_pk_mul_f32 v[14:15], v[14:15], v[20:21]
	v_pk_mul_f32 v[16:17], v[16:17], v[18:19]
	v_pk_mul_f32 v[18:19], v[12:13], v[22:23]
	v_pk_mul_f32 v[12:13], v[10:11], v[24:25]
	v_cvt_pk_bf16_f32 v10, v14, v15
	v_add_u32_e32 v14, v130, v26
	v_ashrrev_i32_e32 v15, 31, v14
	v_lshlrev_b64 v[14:15], 10, v[14:15]
	v_lshl_add_u64 v[14:15], s[6:7], 0, v[14:15]
	v_lshl_add_u64 v[14:15], v[14:15], 0, s[16:17]
	v_cvt_pk_bf16_f32 v11, v16, v17
	v_cvt_pk_bf16_f32 v12, v12, v13
	v_cvt_pk_bf16_f32 v13, v18, v19
	v_lshl_add_u64 v[14:15], v[14:15], 0, v[0:1]
	global_store_dwordx4 v[14:15], v[10:13], off
	v_pk_mul_f32 v[14:15], v[4:5], v[4:5]
	v_pk_mul_f32 v[16:17], v[2:3], v[2:3]
	v_pk_mul_f32 v[12:13], v[6:7], v[6:7]
	v_pk_mul_f32 v[10:11], v[8:9], v[8:9]
	v_pk_fma_f32 v[12:13], v[12:13], s[38:39], 1.0 op_sel_hi:[1,0,0]
	v_pk_fma_f32 v[10:11], v[10:11], s[38:39], 1.0 op_sel_hi:[1,0,0]
	v_pk_mul_f32 v[12:13], v[6:7], v[12:13]
	v_pk_fma_f32 v[14:15], v[14:15], s[38:39], 1.0 op_sel_hi:[1,0,0]
	v_pk_fma_f32 v[16:17], v[16:17], s[38:39], 1.0 op_sel_hi:[1,0,0]
	v_pk_mul_f32 v[10:11], v[8:9], v[10:11]
	v_pk_mul_f32 v[12:13], v[12:13], s[40:41] op_sel_hi:[1,0]
	v_pk_mul_f32 v[14:15], v[4:5], v[14:15]
	v_pk_mul_f32 v[16:17], v[2:3], v[16:17]
	v_pk_mul_f32 v[10:11], v[10:11], s[40:41] op_sel_hi:[1,0]
	v_pk_mul_f32 v[14:15], v[14:15], s[40:41] op_sel_hi:[1,0]
	v_pk_mul_f32 v[16:17], v[16:17], s[40:41] op_sel_hi:[1,0]
	v_exp_f32_e32 v12, v12
	v_exp_f32_e32 v13, v13
	v_exp_f32_e32 v16, v16
	v_exp_f32_e32 v10, v10
	v_exp_f32_e32 v11, v11
	v_exp_f32_e32 v14, v14
	v_exp_f32_e32 v15, v15
	v_exp_f32_e32 v17, v17
	v_pk_add_f32 v[12:13], v[12:13], 1.0 op_sel_hi:[1,0]
	v_pk_add_f32 v[10:11], v[10:11], 1.0 op_sel_hi:[1,0]
	v_pk_add_f32 v[14:15], v[14:15], 1.0 op_sel_hi:[1,0]
	v_pk_add_f32 v[16:17], v[16:17], 1.0 op_sel_hi:[1,0]
	v_rcp_f32_e32 v12, v12
	v_rcp_f32_e32 v13, v13
	v_rcp_f32_e32 v16, v16
	v_rcp_f32_e32 v10, v10
	v_rcp_f32_e32 v11, v11
	v_rcp_f32_e32 v14, v14
	v_rcp_f32_e32 v15, v15
	v_rcp_f32_e32 v17, v17
	v_pk_mul_f32 v[6:7], v[6:7], v[12:13]
	v_pk_mul_f32 v[8:9], v[8:9], v[10:11]
	v_pk_mul_f32 v[10:11], v[4:5], v[14:15]
	v_pk_mul_f32 v[4:5], v[2:3], v[16:17]
	v_cvt_pk_bf16_f32 v2, v6, v7
	v_add_u32_e32 v6, v122, v26
	v_ashrrev_i32_e32 v7, 31, v6
	v_lshlrev_b64 v[6:7], 10, v[6:7]
	v_lshl_add_u64 v[6:7], s[6:7], 0, v[6:7]
	v_lshl_add_u64 v[6:7], v[6:7], 0, s[16:17]
	v_cvt_pk_bf16_f32 v3, v8, v9
	v_cvt_pk_bf16_f32 v4, v4, v5
	v_cvt_pk_bf16_f32 v5, v10, v11
	v_lshl_add_u64 v[6:7], v[6:7], 0, v[0:1]
	s_andn2_b64 vcc, exec, s[14:15]
	s_mov_b64 s[14:15], -1
	global_store_dwordx4 v[6:7], v[2:5], off
	s_cbranch_vccnz .LBB0_1172
	s_nop 0
	v_mov_b32_e32 v3, v236
	s_mov_b32 s9, 0x1ffffe0
	v_bfe_i32 v4, v3, 27, 1
	v_lshlrev_b32_e32 v2, 4, v3
	v_lshrrev_b32_e32 v4, 22, v4
	v_add_u32_e32 v4, v2, v4
	v_and_b32_e32 v4, 0xfffffc00, v4
	v_sub_u32_e32 v4, v2, v4
	v_lshrrev_b32_e32 v5, 4, v4
	v_ashrrev_i32_e32 v0, 31, v3
	v_bitop3_b32 v4, v5, v4, 32 bitop3:0x6c
	v_lshrrev_b32_e32 v0, 26, v0
	v_ashrrev_i32_e32 v6, 31, v4
	v_add_u32_e32 v0, v3, v0
	v_lshrrev_b32_e32 v6, 26, v6
	v_ashrrev_i32_e32 v0, 6, v0
	v_add_u32_e32 v6, v4, v6
	v_lshlrev_b32_e32 v5, 3, v0
	v_ashrrev_i32_e32 v7, 6, v6
	v_and_b32_e32 v6, 0xc0, v6
	v_and_b32_e32 v5, -16, v5
	v_lshlrev_b32_e32 v0, 5, v0
	v_sub_u32_e32 v4, v4, v6
	v_add_u32_e32 v5, v7, v5
	v_and_b32_e32 v0, 32, v0
	v_ashrrev_i16_sdwa v4, v254, sext(v4) dst_sel:DWORD dst_unused:UNUSED_PAD src0_sel:DWORD src1_sel:BYTE_0
	v_add_u32_sdwa v4, v0, sext(v4) dst_sel:DWORD dst_unused:UNUSED_PAD src0_sel:DWORD src1_sel:WORD_0
	v_lshlrev_b32_e32 v0, 1, v5
	v_lshrrev_b32_e32 v6, 2, v5
	v_and_b32_e32 v7, 3, v7
	v_and_b32_e32 v0, 24, v0
	v_and_b32_e32 v6, 4, v6
	v_and_or_b32 v7, v5, s9, v7
	v_or3_b32 v6, v7, v6, v0
	v_mul_lo_u32 v0, v5, s23
	v_mul_lo_u32 v5, v6, s23
	v_add_u32_e32 v2, 0x2000, v2
	v_add_lshl_u32 v0, v4, v0, 1
	v_add_lshl_u32 v130, v5, v4, 1
	v_ashrrev_i32_e32 v4, 31, v2
	v_lshrrev_b32_e32 v4, 22, v4
	v_add_u32_e32 v4, v2, v4
	v_ashrrev_i32_e32 v4, 10, v4
	v_mul_i32_i24_e32 v5, 0x400, v4
	v_sub_u32_e32 v2, v2, v5
	v_lshrrev_b32_e32 v5, 4, v2
	v_bitop3_b32 v2, v5, v2, 32 bitop3:0x6c
	v_ashrrev_i32_e32 v6, 31, v2
	v_lshrrev_b32_e32 v6, 26, v6
	v_add_u32_e32 v6, v2, v6
	v_lshlrev_b32_e32 v5, 3, v4
	v_ashrrev_i32_e32 v7, 6, v6
	v_and_b32_e32 v6, 0xc0, v6
	v_and_b32_e32 v5, -16, v5
	v_lshlrev_b32_e32 v4, 5, v4
	v_sub_u32_e32 v2, v2, v6
	v_add_u32_e32 v5, v7, v5
	v_and_b32_e32 v4, 32, v4
	v_ashrrev_i16_sdwa v2, v254, sext(v2) dst_sel:DWORD dst_unused:UNUSED_PAD src0_sel:DWORD src1_sel:BYTE_0
	v_add_u32_sdwa v2, v4, sext(v2) dst_sel:DWORD dst_unused:UNUSED_PAD src0_sel:DWORD src1_sel:WORD_0
	v_lshlrev_b32_e32 v4, 1, v5
	v_lshrrev_b32_e32 v6, 2, v5
	v_and_b32_e32 v7, 3, v7
	v_and_b32_e32 v4, 24, v4
	v_and_b32_e32 v6, 4, v6
	v_and_or_b32 v7, v5, s9, v7
	v_or3_b32 v4, v7, v6, v4
	v_mul_lo_u32 v4, v4, s23
	v_mul_lo_u32 v5, v5, s23
	v_add_lshl_u32 v134, v4, v2, 1
	v_and_b32_e32 v4, 15, v3
	v_add_lshl_u32 v132, v2, v5, 1
	v_or_b32_e32 v2, s54, v4
	v_and_b32_e32 v5, 48, v3
	v_lshlrev_b32_e32 v6, 6, v2
	v_lshlrev_b32_e32 v2, 2, v2
	v_lshlrev_b32_e32 v3, 2, v3
	v_and_b32_e32 v6, 0x3c0, v6
	v_and_b32_e32 v2, 32, v2
	v_lshl_or_b32 v4, v4, 6, v5
	v_and_b32_e32 v3, 32, v3
	v_bitop3_b32 v2, v6, v2, v5 bitop3:0x36
	v_bitop3_b32 v136, v4, s57, v3 bitop3:0xde
	s_mov_b64 s[14:15], 0
	s_branch .LBB0_1172

; #define PG8_STAGE(bufoff, gbase, voff) do { _Pragma("unroll") for (int _i = 0; _i < 2; ++_i) \
;         __builtin_amdgcn_global_load_lds((const unsigned*)((const char*)(gbase) + (voff)[_i]), (LAS unsigned*)(lds + (bufoff) + ldsw + _i * 8192), 16, 0, 0); } while (0)
; #define PG8_LDA(dst, b, h) do { _Pragma("unroll") for (int m = 0; m < 4; ++m) _Pragma("unroll") for (int k = 0; k < 2; ++k) dst[m][k] = *(const LAS bf16x8*)(lds + PG8_SA(b, h) + aoff + m * 2048 + k * 1024); } while (0)
; #define PG8_LDB(dst, b, h) do { _Pragma("unroll") for (int n = 0; n < 2; ++n) _Pragma("unroll") for (int k = 0; k < 2; ++k) dst[n][k] = *(const LAS bf16x8*)(lds + PG8_SB(b, h) + boff + n * 2048 + k * 1024); } while (0)
; #define PG8_MMA(ai, bj, At, Bt) do { __builtin_amdgcn_s_setprio(1); _Pragma("unroll") for (int m = 0; m < 4; ++m) _Pragma("unroll") for (int n = 0; n < 2; ++n) _Pragma("unroll") for (int k = 0; k < 2; ++k) \
;         acc[ai][bj][m][n] = __builtin_amdgcn_mfma_f32_16x16x32_bf16(Bt[n][k], At[m][k], acc[ai][bj][m][n], 0, 0, 0); __builtin_amdgcn_s_setprio(0); } while (0)
; template <class Epi, class Sched, bool ALIGN_EPI>
; __device__ __forceinline__ void gemm_phase(LAS unsigned char* lds, const bf16_t* Ab, const bf16_t* Bb, int lda, int ldb, int K, const Sched& S, Epi& E) {
;     ...
;         const bool has_next = S.next(ui + 1, nxt); nxt.ui = ui + 1;
;         const char* nA = has_next ? (const char*)(Ab + nxt.a_off) : cA; const char* nB = has_next ? (const char*)(Bb + nxt.b_off) : cB;
;         for (int t = 0; t < nt; t += 2) {
;             const bool last = (t == nt - 2);
;             const char* a1 = cA + (unsigned)(t + 1) * kstep;
;             const char* a2 = last ? nA : cA + (unsigned)(t + 2) * kstep; const char* b2 = last ? nB : cB + (unsigned)(t + 2) * kstep;
;             const char* a3 = a2 + kstep; const char* b3 = b2 + kstep;
;             PG8_LDB(B0, 0, 0); PG8_LDB(B1, 0, 1); PG8_SCHED; PG8_LDA(At, 0, 0); PG8_STAGE(PG8_SA(1, 1), a1 + hstepA, voffA);
;             PG8_WAIT_V(8); PG8_WAIT_L(0); PG8_BAR; PG8_MMA(0, 0, At, B0); PG8_MMA(0, 1, At, B1); PG8_BAR; PG8_SCHED;
;             PG8_LDA(At, 0, 1); PG8_STAGE(PG8_SB(0, 0), b2, voffB); PG8_STAGE(PG8_SB(0, 1), b2 + hstepB, voffB); PG8_STAGE(PG8_SA(0, 0), a2, voffA);
;             PG8_WAIT_V(8); PG8_WAIT_L(0); PG8_BAR; PG8_MMA(1, 0, At, B0); PG8_MMA(1, 1, At, B1); PG8_BAR; PG8_SCHED;
.LBB0_1254:
	s_add_u32 s60, s58, 0xfffe0080
	s_addc_u32 s61, s59, -1
	s_add_i32 s81, 0, 0x10000
	s_cmp_eq_u32 s80, 4
	s_cselect_b32 s63, s25, s61
	s_cselect_b32 s62, s76, s60
	s_cselect_b32 s61, s53, s79
	s_cselect_b32 s60, s77, s78
	s_add_i32 s87, 0, 0x14000
	v_add_u32_e32 v150, s81, v120
	v_add_u32_e32 v166, s87, v120
	ds_read_b128 v[122:125], v150
	ds_read_b128 v[126:129], v150 offset:1024
	ds_read_b128 v[146:149], v150 offset:2048
	ds_read_b128 v[150:153], v150 offset:3072
	ds_read_b128 v[154:157], v166
	ds_read_b128 v[158:161], v166 offset:1024
	ds_read_b128 v[162:165], v166 offset:2048
	ds_read_b128 v[166:169], v166 offset:3072
	v_lshl_add_u64 v[186:187], s[58:59], 0, v[0:1]
	s_add_i32 m0, s33, 0xc000
	ds_read_b128 v[170:173], v121
	ds_read_b128 v[174:177], v121 offset:1024
	ds_read_b128 v[178:181], v121 offset:2048
	ds_read_b128 v[182:185], v121 offset:3072
	ds_read_b128 v[200:203], v121 offset:4096
	ds_read_b128 v[206:209], v121 offset:5120
	ds_read_b128 v[210:213], v121 offset:6144
	ds_read_b128 v[238:241], v121 offset:7168
	global_load_lds_dwordx4 v[186:187], off
	v_lshl_add_u64 v[186:187], s[58:59], 0, v[118:119]
	s_add_i32 m0, s33, 0xe000
	s_nop 0
	global_load_lds_dwordx4 v[186:187], off
	s_waitcnt vmcnt(8)
	s_waitcnt lgkmcnt(0)
	s_barrier
	s_setprio 1
	v_mfma_f32_16x16x32_bf16 v[142:145], v[122:125], v[170:173], v[142:145]
	v_mfma_f32_16x16x32_bf16 v[134:137], v[146:149], v[170:173], v[134:137]
	v_mfma_f32_16x16x32_bf16 v[102:105], v[122:125], v[178:181], v[102:105]
	v_mfma_f32_16x16x32_bf16 v[98:101], v[146:149], v[178:181], v[98:101]
	v_mfma_f32_16x16x32_bf16 v[86:89], v[122:125], v[200:203], v[86:89]
	v_mfma_f32_16x16x32_bf16 v[82:85], v[146:149], v[200:203], v[82:85]
	v_mfma_f32_16x16x32_bf16 v[70:73], v[122:125], v[210:213], v[70:73]
	v_mfma_f32_16x16x32_bf16 v[66:69], v[146:149], v[210:213], v[66:69]
	v_mfma_f32_16x16x32_bf16 v[142:145], v[126:129], v[174:177], v[142:145]
	v_mfma_f32_16x16x32_bf16 v[134:137], v[150:153], v[174:177], v[134:137]
	v_mfma_f32_16x16x32_bf16 v[102:105], v[126:129], v[182:185], v[102:105]
	v_mfma_f32_16x16x32_bf16 v[98:101], v[150:153], v[182:185], v[98:101]
	v_mfma_f32_16x16x32_bf16 v[86:89], v[126:129], v[206:209], v[86:89]
	v_mfma_f32_16x16x32_bf16 v[82:85], v[150:153], v[206:209], v[82:85]
	v_mfma_f32_16x16x32_bf16 v[70:73], v[126:129], v[238:241], v[70:73]
	v_mfma_f32_16x16x32_bf16 v[66:69], v[150:153], v[238:241], v[66:69]
	s_setprio 0
	s_setprio 1
	v_mfma_f32_16x16x32_bf16 v[138:141], v[154:157], v[170:173], v[138:141]
	v_mfma_f32_16x16x32_bf16 v[130:133], v[162:165], v[170:173], v[130:133]
	v_mfma_f32_16x16x32_bf16 v[110:113], v[154:157], v[178:181], v[110:113]
	v_mfma_f32_16x16x32_bf16 v[106:109], v[162:165], v[178:181], v[106:109]
	v_mfma_f32_16x16x32_bf16 v[94:97], v[154:157], v[200:203], v[94:97]
	v_mfma_f32_16x16x32_bf16 v[90:93], v[162:165], v[200:203], v[90:93]
	v_mfma_f32_16x16x32_bf16 v[78:81], v[154:157], v[210:213], v[78:81]
	v_mfma_f32_16x16x32_bf16 v[74:77], v[162:165], v[210:213], v[74:77]
	v_mfma_f32_16x16x32_bf16 v[138:141], v[158:161], v[174:177], v[138:141]
	v_mfma_f32_16x16x32_bf16 v[130:133], v[166:169], v[174:177], v[130:133]
	v_mfma_f32_16x16x32_bf16 v[110:113], v[158:161], v[182:185], v[110:113]
	v_mfma_f32_16x16x32_bf16 v[106:109], v[166:169], v[182:185], v[106:109]
	v_mfma_f32_16x16x32_bf16 v[94:97], v[158:161], v[206:209], v[94:97]
	v_mfma_f32_16x16x32_bf16 v[90:93], v[166:169], v[206:209], v[90:93]
	v_mfma_f32_16x16x32_bf16 v[78:81], v[158:161], v[238:241], v[78:81]
	v_mfma_f32_16x16x32_bf16 v[74:77], v[166:169], v[238:241], v[74:77]
	s_setprio 0
	s_barrier
	s_add_i32 s81, s81, s24
	v_lshl_add_u64 v[186:187], s[60:61], 0, v[114:115]
	s_mov_b32 m0, s81
	ds_read_b128 v[170:173], v121 offset:16384
	ds_read_b128 v[174:177], v121 offset:17408
	ds_read_b128 v[178:181], v121 offset:18432
	ds_read_b128 v[182:185], v121 offset:19456
	ds_read_b128 v[200:203], v121 offset:20480
	ds_read_b128 v[206:209], v121 offset:21504
	ds_read_b128 v[210:213], v121 offset:22528
	ds_read_b128 v[238:241], v121 offset:23552
	global_load_lds_dwordx4 v[186:187], off
	s_add_i32 m0, s81, 0x2000
	s_add_u32 s82, s60, 0x20000
	v_lshl_add_u64 v[188:189], s[60:61], 0, v[116:117]
	s_addc_u32 s83, s61, 0
	s_add_i32 s81, s87, s24
	global_load_lds_dwordx4 v[188:189], off
	v_lshl_add_u64 v[196:197], s[82:83], 0, v[114:115]
	s_mov_b32 m0, s81
	v_lshl_add_u64 v[198:199], s[62:63], 0, v[118:119]
	global_load_lds_dwordx4 v[196:197], off
	v_lshl_add_u64 v[196:197], s[82:83], 0, v[116:117]
	s_add_i32 m0, s81, 0x2000
	s_nop 0
	global_load_lds_dwordx4 v[196:197], off
	v_lshl_add_u64 v[196:197], s[62:63], 0, v[0:1]
	s_mov_b32 m0, s33
	s_nop 0
	global_load_lds_dwordx4 v[196:197], off
	s_mov_b32 m0, s39
	s_nop 0
	global_load_lds_dwordx4 v[198:199], off
	s_waitcnt vmcnt(8)
	s_waitcnt lgkmcnt(0)
	s_barrier
; #define PG8_STAGE(bufoff, gbase, voff) do { _Pragma("unroll") for (int _i = 0; _i < 2; ++_i) \
;         __builtin_amdgcn_global_load_lds((const unsigned*)((const char*)(gbase) + (voff)[_i]), (LAS unsigned*)(lds + (bufoff) + ldsw + _i * 8192), 16, 0, 0); } while (0)
; #define PG8_LDA(dst, b, h) do { _Pragma("unroll") for (int m = 0; m < 4; ++m) _Pragma("unroll") for (int k = 0; k < 2; ++k) dst[m][k] = *(const LAS bf16x8*)(lds + PG8_SA(b, h) + aoff + m * 2048 + k * 1024); } while (0)
; #define PG8_LDB(dst, b, h) do { _Pragma("unroll") for (int n = 0; n < 2; ++n) _Pragma("unroll") for (int k = 0; k < 2; ++k) dst[n][k] = *(const LAS bf16x8*)(lds + PG8_SB(b, h) + boff + n * 2048 + k * 1024); } while (0)
; #define PG8_MMA(ai, bj, At, Bt) do { __builtin_amdgcn_s_setprio(1); _Pragma("unroll") for (int m = 0; m < 4; ++m) _Pragma("unroll") for (int n = 0; n < 2; ++n) _Pragma("unroll") for (int k = 0; k < 2; ++k) \
;         acc[ai][bj][m][n] = __builtin_amdgcn_mfma_f32_16x16x32_bf16(Bt[n][k], At[m][k], acc[ai][bj][m][n], 0, 0, 0); __builtin_amdgcn_s_setprio(0); } while (0)
; #define PG8_WAIT_V(n) asm volatile("s_waitcnt vmcnt(" #n ")" ::: "memory")
; #define PG8_WAIT_L(n) asm volatile("s_waitcnt lgkmcnt(" #n ")" ::: "memory")
; #define PG8_BAR __builtin_amdgcn_s_barrier()
; #define PG8_SCHED __builtin_amdgcn_sched_barrier(0)
; template <class Epi, class Sched, bool ALIGN_EPI>
; __device__ __forceinline__ void gemm_phase(LAS unsigned char* lds, const bf16_t* Ab, const bf16_t* Bb, int lda, int ldb, int K, const Sched& S, Epi& E) {
;     ...
;             PG8_WAIT_V(8); PG8_WAIT_L(0); PG8_BAR; PG8_MMA(1, 0, At, B0); PG8_MMA(1, 1, At, B1); PG8_BAR; PG8_SCHED;
;             PG8_LDB(B0, 1, 0); PG8_LDB(B1, 1, 1); PG8_SCHED; PG8_LDA(At, 1, 0); PG8_STAGE(PG8_SA(0, 1), a2 + hstepA, voffA);
;             PG8_WAIT_V(8); PG8_WAIT_L(0); PG8_BAR; PG8_MMA(0, 0, At, B0); PG8_MMA(0, 1, At, B1); PG8_BAR; PG8_SCHED;
	s_setprio 1
	v_mfma_f32_16x16x32_bf16 v[54:57], v[122:125], v[170:173], v[54:57]
	v_mfma_f32_16x16x32_bf16 v[50:53], v[146:149], v[170:173], v[50:53]
	v_mfma_f32_16x16x32_bf16 v[38:41], v[122:125], v[178:181], v[38:41]
	v_mfma_f32_16x16x32_bf16 v[34:37], v[146:149], v[178:181], v[34:37]
	v_mfma_f32_16x16x32_bf16 v[22:25], v[122:125], v[200:203], v[22:25]
	v_mfma_f32_16x16x32_bf16 v[18:21], v[146:149], v[200:203], v[18:21]
	v_mfma_f32_16x16x32_bf16 v[10:13], v[122:125], v[210:213], v[10:13]
	v_mfma_f32_16x16x32_bf16 v[2:5], v[146:149], v[210:213], v[2:5]
	v_mfma_f32_16x16x32_bf16 v[54:57], v[126:129], v[174:177], v[54:57]
	v_mfma_f32_16x16x32_bf16 v[50:53], v[150:153], v[174:177], v[50:53]
	v_mfma_f32_16x16x32_bf16 v[38:41], v[126:129], v[182:185], v[38:41]
	v_mfma_f32_16x16x32_bf16 v[34:37], v[150:153], v[182:185], v[34:37]
	v_mfma_f32_16x16x32_bf16 v[22:25], v[126:129], v[206:209], v[22:25]
	v_mfma_f32_16x16x32_bf16 v[18:21], v[150:153], v[206:209], v[18:21]
	v_mfma_f32_16x16x32_bf16 v[10:13], v[126:129], v[238:241], v[10:13]
	v_mfma_f32_16x16x32_bf16 v[2:5], v[150:153], v[238:241], v[2:5]
	s_setprio 0
	s_setprio 1
	v_mfma_f32_16x16x32_bf16 v[62:65], v[154:157], v[170:173], v[62:65]
	v_mfma_f32_16x16x32_bf16 v[58:61], v[162:165], v[170:173], v[58:61]
	v_mfma_f32_16x16x32_bf16 v[46:49], v[154:157], v[178:181], v[46:49]
	v_mfma_f32_16x16x32_bf16 v[42:45], v[162:165], v[178:181], v[42:45]
	v_mfma_f32_16x16x32_bf16 v[30:33], v[154:157], v[200:203], v[30:33]
	v_mfma_f32_16x16x32_bf16 v[26:29], v[162:165], v[200:203], v[26:29]
	v_mfma_f32_16x16x32_bf16 v[14:17], v[154:157], v[210:213], v[14:17]
	v_mfma_f32_16x16x32_bf16 v[6:9], v[162:165], v[210:213], v[6:9]
	v_mfma_f32_16x16x32_bf16 v[62:65], v[158:161], v[174:177], v[62:65]
	v_mfma_f32_16x16x32_bf16 v[58:61], v[166:169], v[174:177], v[58:61]
	v_mfma_f32_16x16x32_bf16 v[46:49], v[158:161], v[182:185], v[46:49]
	v_mfma_f32_16x16x32_bf16 v[42:45], v[166:169], v[182:185], v[42:45]
	v_mfma_f32_16x16x32_bf16 v[30:33], v[158:161], v[206:209], v[30:33]
	v_mfma_f32_16x16x32_bf16 v[26:29], v[166:169], v[206:209], v[26:29]
	v_mfma_f32_16x16x32_bf16 v[14:17], v[158:161], v[238:241], v[14:17]
	v_mfma_f32_16x16x32_bf16 v[6:9], v[166:169], v[238:241], v[6:9]
	s_setprio 0
	s_barrier
	s_add_i32 s81, 0, 0x18000
	s_add_i32 s82, 0, 0x1c000
	v_add_u32_e32 v150, s81, v120
	v_add_u32_e32 v166, s82, v120
	ds_read_b128 v[122:125], v150
	ds_read_b128 v[126:129], v150 offset:1024
	ds_read_b128 v[146:149], v150 offset:2048
	ds_read_b128 v[150:153], v150 offset:3072
	ds_read_b128 v[154:157], v166
	ds_read_b128 v[158:161], v166 offset:1024
	ds_read_b128 v[162:165], v166 offset:2048
	ds_read_b128 v[166:169], v166 offset:3072
	s_add_u32 s62, s62, 0x20000
	s_addc_u32 s63, s63, 0
	s_mov_b32 m0, s44
	v_lshl_add_u64 v[220:221], s[62:63], 0, v[0:1]
	ds_read_b128 v[170:173], v121 offset:32768
	ds_read_b128 v[174:177], v121 offset:33792
	ds_read_b128 v[178:181], v121 offset:34816
	ds_read_b128 v[182:185], v121 offset:35840
	ds_read_b128 v[200:203], v121 offset:36864
	ds_read_b128 v[206:209], v121 offset:37888
	ds_read_b128 v[210:213], v121 offset:38912
	ds_read_b128 v[238:241], v121 offset:39936
	global_load_lds_dwordx4 v[220:221], off
	v_lshl_add_u64 v[220:221], s[62:63], 0, v[118:119]
	s_mov_b32 m0, s45
	s_nop 0
	global_load_lds_dwordx4 v[220:221], off
	s_waitcnt vmcnt(8)
	s_waitcnt lgkmcnt(0)
	s_barrier
	s_setprio 1
	v_mfma_f32_16x16x32_bf16 v[142:145], v[122:125], v[170:173], v[142:145]
	v_mfma_f32_16x16x32_bf16 v[134:137], v[146:149], v[170:173], v[134:137]
	v_mfma_f32_16x16x32_bf16 v[102:105], v[122:125], v[178:181], v[102:105]
	v_mfma_f32_16x16x32_bf16 v[98:101], v[146:149], v[178:181], v[98:101]
	v_mfma_f32_16x16x32_bf16 v[86:89], v[122:125], v[200:203], v[86:89]
	v_mfma_f32_16x16x32_bf16 v[82:85], v[146:149], v[200:203], v[82:85]
	v_mfma_f32_16x16x32_bf16 v[70:73], v[122:125], v[210:213], v[70:73]
	v_mfma_f32_16x16x32_bf16 v[66:69], v[146:149], v[210:213], v[66:69]
	v_mfma_f32_16x16x32_bf16 v[142:145], v[126:129], v[174:177], v[142:145]
	v_mfma_f32_16x16x32_bf16 v[134:137], v[150:153], v[174:177], v[134:137]
	v_mfma_f32_16x16x32_bf16 v[102:105], v[126:129], v[182:185], v[102:105]
	v_mfma_f32_16x16x32_bf16 v[98:101], v[150:153], v[182:185], v[98:101]
	v_mfma_f32_16x16x32_bf16 v[86:89], v[126:129], v[206:209], v[86:89]
	v_mfma_f32_16x16x32_bf16 v[82:85], v[150:153], v[206:209], v[82:85]
	v_mfma_f32_16x16x32_bf16 v[70:73], v[126:129], v[238:241], v[70:73]
	v_mfma_f32_16x16x32_bf16 v[66:69], v[150:153], v[238:241], v[66:69]
	s_setprio 0
	s_setprio 1
	v_mfma_f32_16x16x32_bf16 v[138:141], v[154:157], v[170:173], v[138:141]
	v_mfma_f32_16x16x32_bf16 v[130:133], v[162:165], v[170:173], v[130:133]
	v_mfma_f32_16x16x32_bf16 v[110:113], v[154:157], v[178:181], v[110:113]
	v_mfma_f32_16x16x32_bf16 v[106:109], v[162:165], v[178:181], v[106:109]
	v_mfma_f32_16x16x32_bf16 v[94:97], v[154:157], v[200:203], v[94:97]
	v_mfma_f32_16x16x32_bf16 v[90:93], v[162:165], v[200:203], v[90:93]
	v_mfma_f32_16x16x32_bf16 v[78:81], v[154:157], v[210:213], v[78:81]
	v_mfma_f32_16x16x32_bf16 v[74:77], v[162:165], v[210:213], v[74:77]
	v_mfma_f32_16x16x32_bf16 v[138:141], v[158:161], v[174:177], v[138:141]
	v_mfma_f32_16x16x32_bf16 v[130:133], v[166:169], v[174:177], v[130:133]
	v_mfma_f32_16x16x32_bf16 v[110:113], v[158:161], v[182:185], v[110:113]
	v_mfma_f32_16x16x32_bf16 v[106:109], v[166:169], v[182:185], v[106:109]
	v_mfma_f32_16x16x32_bf16 v[94:97], v[158:161], v[206:209], v[94:97]
	v_mfma_f32_16x16x32_bf16 v[90:93], v[166:169], v[206:209], v[90:93]
	v_mfma_f32_16x16x32_bf16 v[78:81], v[158:161], v[238:241], v[78:81]
	v_mfma_f32_16x16x32_bf16 v[74:77], v[166:169], v[238:241], v[74:77]
	s_setprio 0
	s_barrier
; #define PG8_STAGE(bufoff, gbase, voff) do { _Pragma("unroll") for (int _i = 0; _i < 2; ++_i) \
;         __builtin_amdgcn_global_load_lds((const unsigned*)((const char*)(gbase) + (voff)[_i]), (LAS unsigned*)(lds + (bufoff) + ldsw + _i * 8192), 16, 0, 0); } while (0)
; #define PG8_LDA(dst, b, h) do { _Pragma("unroll") for (int m = 0; m < 4; ++m) _Pragma("unroll") for (int k = 0; k < 2; ++k) dst[m][k] = *(const LAS bf16x8*)(lds + PG8_SA(b, h) + aoff + m * 2048 + k * 1024); } while (0)
; #define PG8_MMA(ai, bj, At, Bt) do { __builtin_amdgcn_s_setprio(1); _Pragma("unroll") for (int m = 0; m < 4; ++m) _Pragma("unroll") for (int n = 0; n < 2; ++n) _Pragma("unroll") for (int k = 0; k < 2; ++k) \
;         acc[ai][bj][m][n] = __builtin_amdgcn_mfma_f32_16x16x32_bf16(Bt[n][k], At[m][k], acc[ai][bj][m][n], 0, 0, 0); __builtin_amdgcn_s_setprio(0); } while (0)
; #define PG8_WAIT_V(n) asm volatile("s_waitcnt vmcnt(" #n ")" ::: "memory")
; #define PG8_WAIT_L(n) asm volatile("s_waitcnt lgkmcnt(" #n ")" ::: "memory")
; #define PG8_BAR __builtin_amdgcn_s_barrier()
; #define PG8_SCHED __builtin_amdgcn_sched_barrier(0)
; template <class Epi, class Sched, bool ALIGN_EPI>
; __device__ __forceinline__ void gemm_phase(LAS unsigned char* lds, const bf16_t* Ab, const bf16_t* Bb, int lda, int ldb, int K, const Sched& S, Epi& E) {
;     ...
;             PG8_LDA(At, 1, 1); PG8_STAGE(PG8_SB(1, 0), b3, voffB); PG8_STAGE(PG8_SB(1, 1), b3 + hstepB, voffB); PG8_STAGE(PG8_SA(1, 0), a3, voffA);
;             PG8_WAIT_V(8); PG8_WAIT_L(0); PG8_BAR; PG8_MMA(1, 0, At, B0); PG8_MMA(1, 1, At, B1); PG8_BAR; PG8_SCHED;
;         }
;         if constexpr (ALIGN_EPI) { if (wr == 0) PG8_BAR; }
	s_add_i32 s62, s81, s24
	v_lshl_add_u64 v[186:187], v[186:187], 0, s[26:27]
	s_mov_b32 m0, s62
	ds_read_b128 v[170:173], v121 offset:49152
	ds_read_b128 v[174:177], v121 offset:50176
	ds_read_b128 v[178:181], v121 offset:51200
	ds_read_b128 v[182:185], v121 offset:52224
	ds_read_b128 v[200:203], v121 offset:53248
	ds_read_b128 v[206:209], v121 offset:54272
	ds_read_b128 v[210:213], v121 offset:55296
	ds_read_b128 v[238:241], v121 offset:56320
	global_load_lds_dwordx4 v[186:187], off
	s_add_i32 m0, s62, 0x2000
	s_add_u32 s60, s60, 0x20080
	v_lshl_add_u64 v[186:187], v[188:189], 0, s[26:27]
	s_addc_u32 s61, s61, 0
	s_add_i32 s62, s82, s24
	global_load_lds_dwordx4 v[186:187], off
	v_lshl_add_u64 v[186:187], s[60:61], 0, v[114:115]
	s_mov_b32 m0, s62
	s_nop 0
	global_load_lds_dwordx4 v[186:187], off
	v_lshl_add_u64 v[186:187], s[60:61], 0, v[116:117]
	s_add_i32 m0, s62, 0x2000
	s_nop 0
	global_load_lds_dwordx4 v[186:187], off
	v_lshl_add_u64 v[186:187], v[196:197], 0, s[26:27]
	s_mov_b32 m0, s67
	s_nop 0
	global_load_lds_dwordx4 v[186:187], off
	v_lshl_add_u64 v[186:187], v[198:199], 0, s[26:27]
	s_mov_b32 m0, s68
	s_nop 0
	global_load_lds_dwordx4 v[186:187], off
	s_waitcnt vmcnt(8)
	s_waitcnt lgkmcnt(0)
	s_barrier
	s_setprio 1
	v_mfma_f32_16x16x32_bf16 v[54:57], v[122:125], v[170:173], v[54:57]
	v_mfma_f32_16x16x32_bf16 v[50:53], v[146:149], v[170:173], v[50:53]
	v_mfma_f32_16x16x32_bf16 v[38:41], v[122:125], v[178:181], v[38:41]
	v_mfma_f32_16x16x32_bf16 v[34:37], v[146:149], v[178:181], v[34:37]
	v_mfma_f32_16x16x32_bf16 v[22:25], v[122:125], v[200:203], v[22:25]
	v_mfma_f32_16x16x32_bf16 v[18:21], v[146:149], v[200:203], v[18:21]
	v_mfma_f32_16x16x32_bf16 v[10:13], v[122:125], v[210:213], v[10:13]
	v_mfma_f32_16x16x32_bf16 v[2:5], v[146:149], v[210:213], v[2:5]
	v_mfma_f32_16x16x32_bf16 v[54:57], v[126:129], v[174:177], v[54:57]
	v_mfma_f32_16x16x32_bf16 v[50:53], v[150:153], v[174:177], v[50:53]
	v_mfma_f32_16x16x32_bf16 v[38:41], v[126:129], v[182:185], v[38:41]
	v_mfma_f32_16x16x32_bf16 v[34:37], v[150:153], v[182:185], v[34:37]
	v_mfma_f32_16x16x32_bf16 v[22:25], v[126:129], v[206:209], v[22:25]
	v_mfma_f32_16x16x32_bf16 v[18:21], v[150:153], v[206:209], v[18:21]
	v_mfma_f32_16x16x32_bf16 v[10:13], v[126:129], v[238:241], v[10:13]
	v_mfma_f32_16x16x32_bf16 v[2:5], v[150:153], v[238:241], v[2:5]
	s_setprio 0
	s_setprio 1
	v_mfma_f32_16x16x32_bf16 v[62:65], v[154:157], v[170:173], v[62:65]
	v_mfma_f32_16x16x32_bf16 v[58:61], v[162:165], v[170:173], v[58:61]
	v_mfma_f32_16x16x32_bf16 v[46:49], v[154:157], v[178:181], v[46:49]
	v_mfma_f32_16x16x32_bf16 v[42:45], v[162:165], v[178:181], v[42:45]
	v_mfma_f32_16x16x32_bf16 v[30:33], v[154:157], v[200:203], v[30:33]
	v_mfma_f32_16x16x32_bf16 v[26:29], v[162:165], v[200:203], v[26:29]
	v_mfma_f32_16x16x32_bf16 v[14:17], v[154:157], v[210:213], v[14:17]
	v_mfma_f32_16x16x32_bf16 v[6:9], v[162:165], v[210:213], v[6:9]
	v_mfma_f32_16x16x32_bf16 v[62:65], v[158:161], v[174:177], v[62:65]
	v_mfma_f32_16x16x32_bf16 v[58:61], v[166:169], v[174:177], v[58:61]
	v_mfma_f32_16x16x32_bf16 v[46:49], v[158:161], v[182:185], v[46:49]
	v_mfma_f32_16x16x32_bf16 v[42:45], v[166:169], v[182:185], v[42:45]
	v_mfma_f32_16x16x32_bf16 v[30:33], v[158:161], v[206:209], v[30:33]
	v_mfma_f32_16x16x32_bf16 v[26:29], v[166:169], v[206:209], v[26:29]
	v_mfma_f32_16x16x32_bf16 v[14:17], v[158:161], v[238:241], v[14:17]
	v_mfma_f32_16x16x32_bf16 v[6:9], v[166:169], v[238:241], v[6:9]
	s_setprio 0
	s_barrier
	s_add_i32 s80, s80, 2
	s_add_u32 s58, s58, 0x100
	s_addc_u32 s59, s59, 0
	s_add_u32 s78, s78, 0x100
	s_addc_u32 s79, s79, 0
	s_cmp_gt_u32 s80, 5
	s_cbranch_scc0 .LBB0_1254
	s_and_b64 vcc, exec, s[16:17]
	s_cbranch_vccz .LBB0_1257
	s_barrier

; #define PG8_STAGE(bufoff, gbase, voff) do { _Pragma("unroll") for (int _i = 0; _i < 2; ++_i) \
;         __builtin_amdgcn_global_load_lds((const unsigned*)((const char*)(gbase) + (voff)[_i]), (LAS unsigned*)(lds + (bufoff) + ldsw + _i * 8192), 16, 0, 0); } while (0)
; #define PG8_LDA(dst, b, h) do { _Pragma("unroll") for (int m = 0; m < 4; ++m) _Pragma("unroll") for (int k = 0; k < 2; ++k) dst[m][k] = *(const LAS bf16x8*)(lds + PG8_SA(b, h) + aoff + m * 2048 + k * 1024); } while (0)
; #define PG8_LDB(dst, b, h) do { _Pragma("unroll") for (int n = 0; n < 2; ++n) _Pragma("unroll") for (int k = 0; k < 2; ++k) dst[n][k] = *(const LAS bf16x8*)(lds + PG8_SB(b, h) + boff + n * 2048 + k * 1024); } while (0)
; #define PG8_MMA(ai, bj, At, Bt) do { __builtin_amdgcn_s_setprio(1); _Pragma("unroll") for (int m = 0; m < 4; ++m) _Pragma("unroll") for (int n = 0; n < 2; ++n) _Pragma("unroll") for (int k = 0; k < 2; ++k) \
;         acc[ai][bj][m][n] = __builtin_amdgcn_mfma_f32_16x16x32_bf16(Bt[n][k], At[m][k], acc[ai][bj][m][n], 0, 0, 0); __builtin_amdgcn_s_setprio(0); } while (0)
; template <class Epi, class Sched, bool ALIGN_EPI>
; __device__ __forceinline__ void gemm_phase(LAS unsigned char* lds, const bf16_t* Ab, const bf16_t* Bb, int lda, int ldb, int K, const Sched& S, Epi& E) {
;     ...
;         const bool has_next = S.next(ui + 1, nxt); nxt.ui = ui + 1;
;         const char* nA = has_next ? (const char*)(Ab + nxt.a_off) : cA; const char* nB = has_next ? (const char*)(Bb + nxt.b_off) : cB;
;         for (int t = 0; t < nt; t += 2) {
;             const bool last = (t == nt - 2);
;             const char* a1 = cA + (unsigned)(t + 1) * kstep;
;             const char* a2 = last ? nA : cA + (unsigned)(t + 2) * kstep; const char* b2 = last ? nB : cB + (unsigned)(t + 2) * kstep;
;             const char* a3 = a2 + kstep; const char* b3 = b2 + kstep;
;             PG8_LDB(B0, 0, 0); PG8_LDB(B1, 0, 1); PG8_SCHED; PG8_LDA(At, 0, 0); PG8_STAGE(PG8_SA(1, 1), a1 + hstepA, voffA);
;             PG8_WAIT_V(8); PG8_WAIT_L(0); PG8_BAR; PG8_MMA(0, 0, At, B0); PG8_MMA(0, 1, At, B1); PG8_BAR; PG8_SCHED;
;             PG8_LDA(At, 0, 1); PG8_STAGE(PG8_SB(0, 0), b2, voffB); PG8_STAGE(PG8_SB(0, 1), b2 + hstepB, voffB); PG8_STAGE(PG8_SA(0, 0), a2, voffA);
;             PG8_WAIT_V(8); PG8_WAIT_L(0); PG8_BAR; PG8_MMA(1, 0, At, B0); PG8_MMA(1, 1, At, B1); PG8_BAR; PG8_SCHED;
.LBB0_1501:
	s_add_u32 s64, s56, s62
	s_addc_u32 s65, s57, s63
	s_add_u32 s64, s64, 0x100
	s_addc_u32 s65, s65, 0
	s_add_u32 s87, s81, s62
	s_addc_u32 s88, s82, s63
	s_add_i32 s91, 0, 0x10000
	s_cmpk_eq_i32 s62, 0x700
	s_cselect_b32 s67, s18, s65
	s_cselect_b32 s66, s25, s64
	v_add_u32_e32 v0, s91, v179
	s_cselect_b32 s65, s53, s88
	s_cselect_b32 s64, s55, s87
	s_add_i32 s87, 0, 0x14000
	ds_read_b128 v[134:137], v0
	ds_read_b128 v[138:141], v0 offset:1024
	ds_read_b128 v[142:145], v0 offset:2048
	ds_read_b128 v[146:149], v0 offset:3072
	v_add_u32_e32 v0, s87, v179
	ds_read_b128 v[150:153], v0
	ds_read_b128 v[162:165], v0 offset:1024
	ds_read_b128 v[166:169], v0 offset:2048
	ds_read_b128 v[170:173], v0 offset:3072
	v_add_u32_e32 v0, 0, v178
	v_lshl_add_u64 v[188:189], v[130:131], 0, s[62:63]
	s_add_i32 m0, s44, 0xc000
	ds_read_b128 v[174:177], v0
	ds_read_b128 v[180:183], v0 offset:1024
	ds_read_b128 v[184:187], v0 offset:2048
	ds_read_b128 v[200:203], v0 offset:3072
	ds_read_b128 v[206:209], v0 offset:4096
	ds_read_b128 v[210:213], v0 offset:5120
	ds_read_b128 v[238:241], v0 offset:6144
	ds_read_b128 v[242:245], v0 offset:7168
	global_load_lds_dwordx4 v[188:189], off
	v_lshl_add_u64 v[188:189], v[132:133], 0, s[62:63]
	s_add_i32 m0, s44, 0xe000
	s_nop 0
	global_load_lds_dwordx4 v[188:189], off
	s_waitcnt vmcnt(8)
	s_waitcnt lgkmcnt(0)
	s_barrier
	s_setprio 1
	v_mfma_f32_16x16x32_bf16 v[126:129], v[134:137], v[174:177], v[126:129]
	v_mfma_f32_16x16x32_bf16 v[122:125], v[142:145], v[174:177], v[122:125]
	v_mfma_f32_16x16x32_bf16 v[118:121], v[134:137], v[184:187], v[118:121]
	v_mfma_f32_16x16x32_bf16 v[114:117], v[142:145], v[184:187], v[114:117]
	v_mfma_f32_16x16x32_bf16 v[110:113], v[134:137], v[206:209], v[110:113]
	v_mfma_f32_16x16x32_bf16 v[106:109], v[142:145], v[206:209], v[106:109]
	v_mfma_f32_16x16x32_bf16 v[102:105], v[134:137], v[238:241], v[102:105]
	v_mfma_f32_16x16x32_bf16 v[98:101], v[142:145], v[238:241], v[98:101]
	v_mfma_f32_16x16x32_bf16 v[126:129], v[138:141], v[180:183], v[126:129]
	v_mfma_f32_16x16x32_bf16 v[122:125], v[146:149], v[180:183], v[122:125]
	v_mfma_f32_16x16x32_bf16 v[118:121], v[138:141], v[200:203], v[118:121]
	v_mfma_f32_16x16x32_bf16 v[114:117], v[146:149], v[200:203], v[114:117]
	v_mfma_f32_16x16x32_bf16 v[110:113], v[138:141], v[210:213], v[110:113]
	v_mfma_f32_16x16x32_bf16 v[106:109], v[146:149], v[210:213], v[106:109]
	v_mfma_f32_16x16x32_bf16 v[102:105], v[138:141], v[242:245], v[102:105]
	v_mfma_f32_16x16x32_bf16 v[98:101], v[146:149], v[242:245], v[98:101]
	s_setprio 0
	s_setprio 1
	v_mfma_f32_16x16x32_bf16 v[94:97], v[150:153], v[174:177], v[94:97]
	v_mfma_f32_16x16x32_bf16 v[90:93], v[166:169], v[174:177], v[90:93]
	v_mfma_f32_16x16x32_bf16 v[86:89], v[150:153], v[184:187], v[86:89]
	v_mfma_f32_16x16x32_bf16 v[82:85], v[166:169], v[184:187], v[82:85]
	v_mfma_f32_16x16x32_bf16 v[78:81], v[150:153], v[206:209], v[78:81]
	v_mfma_f32_16x16x32_bf16 v[74:77], v[166:169], v[206:209], v[74:77]
	v_mfma_f32_16x16x32_bf16 v[70:73], v[150:153], v[238:241], v[70:73]
	v_mfma_f32_16x16x32_bf16 v[66:69], v[166:169], v[238:241], v[66:69]
	v_mfma_f32_16x16x32_bf16 v[94:97], v[162:165], v[180:183], v[94:97]
	v_mfma_f32_16x16x32_bf16 v[90:93], v[170:173], v[180:183], v[90:93]
	v_mfma_f32_16x16x32_bf16 v[86:89], v[162:165], v[200:203], v[86:89]
	v_mfma_f32_16x16x32_bf16 v[82:85], v[170:173], v[200:203], v[82:85]
	v_mfma_f32_16x16x32_bf16 v[78:81], v[162:165], v[210:213], v[78:81]
	v_mfma_f32_16x16x32_bf16 v[74:77], v[170:173], v[210:213], v[74:77]
	v_mfma_f32_16x16x32_bf16 v[70:73], v[162:165], v[242:245], v[70:73]
	v_mfma_f32_16x16x32_bf16 v[66:69], v[170:173], v[242:245], v[66:69]
	s_setprio 0
	s_barrier
	s_add_i32 s88, s91, s39
	v_lshl_add_u64 v[188:189], s[64:65], 0, v[160:161]
	s_mov_b32 m0, s88
	ds_read_b128 v[174:177], v0 offset:16384
	ds_read_b128 v[180:183], v0 offset:17408
	ds_read_b128 v[184:187], v0 offset:18432
	ds_read_b128 v[200:203], v0 offset:19456
	ds_read_b128 v[206:209], v0 offset:20480
	ds_read_b128 v[210:213], v0 offset:21504
	ds_read_b128 v[238:241], v0 offset:22528
	ds_read_b128 v[242:245], v0 offset:23552
	global_load_lds_dwordx4 v[188:189], off
	s_add_i32 m0, s88, 0x2000
	s_add_u32 s92, s64, 0x40000
	v_lshl_add_u64 v[196:197], s[64:65], 0, v[158:159]
	s_addc_u32 s93, s65, 0
	s_add_i32 s87, s87, s39
	global_load_lds_dwordx4 v[196:197], off
	v_lshl_add_u64 v[198:199], s[92:93], 0, v[160:161]
	s_mov_b32 m0, s87
	v_lshl_add_u64 v[220:221], s[66:67], 0, v[156:157]
	global_load_lds_dwordx4 v[198:199], off
	v_lshl_add_u64 v[198:199], s[92:93], 0, v[158:159]
	s_add_i32 m0, s87, 0x2000
	s_nop 0
	global_load_lds_dwordx4 v[198:199], off
	v_lshl_add_u64 v[198:199], s[66:67], 0, v[154:155]
	s_mov_b32 m0, s44
	s_nop 0
	global_load_lds_dwordx4 v[198:199], off
	s_mov_b32 m0, s45
	s_nop 0
	global_load_lds_dwordx4 v[220:221], off
	s_waitcnt vmcnt(8)
	s_waitcnt lgkmcnt(0)
	s_barrier
; #define PG8_STAGE(bufoff, gbase, voff) do { _Pragma("unroll") for (int _i = 0; _i < 2; ++_i) \
;         __builtin_amdgcn_global_load_lds((const unsigned*)((const char*)(gbase) + (voff)[_i]), (LAS unsigned*)(lds + (bufoff) + ldsw + _i * 8192), 16, 0, 0); } while (0)
; #define PG8_LDA(dst, b, h) do { _Pragma("unroll") for (int m = 0; m < 4; ++m) _Pragma("unroll") for (int k = 0; k < 2; ++k) dst[m][k] = *(const LAS bf16x8*)(lds + PG8_SA(b, h) + aoff + m * 2048 + k * 1024); } while (0)
; #define PG8_LDB(dst, b, h) do { _Pragma("unroll") for (int n = 0; n < 2; ++n) _Pragma("unroll") for (int k = 0; k < 2; ++k) dst[n][k] = *(const LAS bf16x8*)(lds + PG8_SB(b, h) + boff + n * 2048 + k * 1024); } while (0)
; #define PG8_MMA(ai, bj, At, Bt) do { __builtin_amdgcn_s_setprio(1); _Pragma("unroll") for (int m = 0; m < 4; ++m) _Pragma("unroll") for (int n = 0; n < 2; ++n) _Pragma("unroll") for (int k = 0; k < 2; ++k) \
;         acc[ai][bj][m][n] = __builtin_amdgcn_mfma_f32_16x16x32_bf16(Bt[n][k], At[m][k], acc[ai][bj][m][n], 0, 0, 0); __builtin_amdgcn_s_setprio(0); } while (0)
; #define PG8_WAIT_V(n) asm volatile("s_waitcnt vmcnt(" #n ")" ::: "memory")
; #define PG8_WAIT_L(n) asm volatile("s_waitcnt lgkmcnt(" #n ")" ::: "memory")
; #define PG8_BAR __builtin_amdgcn_s_barrier()
; #define PG8_SCHED __builtin_amdgcn_sched_barrier(0)
; template <class Epi, class Sched, bool ALIGN_EPI>
; __device__ __forceinline__ void gemm_phase(LAS unsigned char* lds, const bf16_t* Ab, const bf16_t* Bb, int lda, int ldb, int K, const Sched& S, Epi& E) {
;     ...
;             PG8_WAIT_V(8); PG8_WAIT_L(0); PG8_BAR; PG8_MMA(1, 0, At, B0); PG8_MMA(1, 1, At, B1); PG8_BAR; PG8_SCHED;
;             PG8_LDB(B0, 1, 0); PG8_LDB(B1, 1, 1); PG8_SCHED; PG8_LDA(At, 1, 0); PG8_STAGE(PG8_SA(0, 1), a2 + hstepA, voffA);
;             PG8_WAIT_V(8); PG8_WAIT_L(0); PG8_BAR; PG8_MMA(0, 0, At, B0); PG8_MMA(0, 1, At, B1); PG8_BAR; PG8_SCHED;
	s_setprio 1
	v_mfma_f32_16x16x32_bf16 v[62:65], v[134:137], v[174:177], v[62:65]
	v_mfma_f32_16x16x32_bf16 v[58:61], v[142:145], v[174:177], v[58:61]
	v_mfma_f32_16x16x32_bf16 v[54:57], v[134:137], v[184:187], v[54:57]
	v_mfma_f32_16x16x32_bf16 v[50:53], v[142:145], v[184:187], v[50:53]
	v_mfma_f32_16x16x32_bf16 v[46:49], v[134:137], v[206:209], v[46:49]
	v_mfma_f32_16x16x32_bf16 v[42:45], v[142:145], v[206:209], v[42:45]
	v_mfma_f32_16x16x32_bf16 v[38:41], v[134:137], v[238:241], v[38:41]
	v_mfma_f32_16x16x32_bf16 v[34:37], v[142:145], v[238:241], v[34:37]
	v_mfma_f32_16x16x32_bf16 v[62:65], v[138:141], v[180:183], v[62:65]
	v_mfma_f32_16x16x32_bf16 v[58:61], v[146:149], v[180:183], v[58:61]
	v_mfma_f32_16x16x32_bf16 v[54:57], v[138:141], v[200:203], v[54:57]
	v_mfma_f32_16x16x32_bf16 v[50:53], v[146:149], v[200:203], v[50:53]
	v_mfma_f32_16x16x32_bf16 v[46:49], v[138:141], v[210:213], v[46:49]
	v_mfma_f32_16x16x32_bf16 v[42:45], v[146:149], v[210:213], v[42:45]
	v_mfma_f32_16x16x32_bf16 v[38:41], v[138:141], v[242:245], v[38:41]
	v_mfma_f32_16x16x32_bf16 v[34:37], v[146:149], v[242:245], v[34:37]
	s_setprio 0
	s_setprio 1
	v_mfma_f32_16x16x32_bf16 v[30:33], v[150:153], v[174:177], v[30:33]
	v_mfma_f32_16x16x32_bf16 v[26:29], v[166:169], v[174:177], v[26:29]
	v_mfma_f32_16x16x32_bf16 v[22:25], v[150:153], v[184:187], v[22:25]
	v_mfma_f32_16x16x32_bf16 v[18:21], v[166:169], v[184:187], v[18:21]
	v_mfma_f32_16x16x32_bf16 v[14:17], v[150:153], v[206:209], v[14:17]
	v_mfma_f32_16x16x32_bf16 v[10:13], v[166:169], v[206:209], v[10:13]
	v_mfma_f32_16x16x32_bf16 v[6:9], v[150:153], v[238:241], v[6:9]
	v_mfma_f32_16x16x32_bf16 v[2:5], v[166:169], v[238:241], v[2:5]
	v_mfma_f32_16x16x32_bf16 v[30:33], v[162:165], v[180:183], v[30:33]
	v_mfma_f32_16x16x32_bf16 v[26:29], v[170:173], v[180:183], v[26:29]
	v_mfma_f32_16x16x32_bf16 v[22:25], v[162:165], v[200:203], v[22:25]
	v_mfma_f32_16x16x32_bf16 v[18:21], v[170:173], v[200:203], v[18:21]
	v_mfma_f32_16x16x32_bf16 v[14:17], v[162:165], v[210:213], v[14:17]
	v_mfma_f32_16x16x32_bf16 v[10:13], v[170:173], v[210:213], v[10:13]
	v_mfma_f32_16x16x32_bf16 v[6:9], v[162:165], v[242:245], v[6:9]
	v_mfma_f32_16x16x32_bf16 v[2:5], v[170:173], v[242:245], v[2:5]
	s_setprio 0
	s_barrier
	s_add_i32 s87, 0, 0x18000
	s_add_i32 s88, 0, 0x1c000
	v_add_u32_e32 v146, s87, v179
	v_add_u32_e32 v170, s88, v179
	ds_read_b128 v[134:137], v146
	ds_read_b128 v[138:141], v146 offset:1024
	ds_read_b128 v[142:145], v146 offset:2048
	ds_read_b128 v[146:149], v146 offset:3072
	ds_read_b128 v[150:153], v170
	ds_read_b128 v[162:165], v170 offset:1024
	ds_read_b128 v[166:169], v170 offset:2048
	ds_read_b128 v[170:173], v170 offset:3072
	s_add_u32 s66, s66, 0x40000
	s_addc_u32 s67, s67, 0
	s_mov_b32 m0, s46
	v_lshl_add_u64 v[222:223], s[66:67], 0, v[154:155]
	ds_read_b128 v[174:177], v0 offset:32768
	ds_read_b128 v[180:183], v0 offset:33792
	ds_read_b128 v[184:187], v0 offset:34816
	ds_read_b128 v[200:203], v0 offset:35840
	ds_read_b128 v[206:209], v0 offset:36864
	ds_read_b128 v[210:213], v0 offset:37888
	ds_read_b128 v[238:241], v0 offset:38912
	ds_read_b128 v[242:245], v0 offset:39936
	global_load_lds_dwordx4 v[222:223], off
	v_lshl_add_u64 v[222:223], s[66:67], 0, v[156:157]
	s_mov_b32 m0, s47
	s_nop 0
	global_load_lds_dwordx4 v[222:223], off
	s_waitcnt vmcnt(8)
	s_waitcnt lgkmcnt(0)
	s_barrier
	s_setprio 1
	v_mfma_f32_16x16x32_bf16 v[126:129], v[134:137], v[174:177], v[126:129]
	v_mfma_f32_16x16x32_bf16 v[122:125], v[142:145], v[174:177], v[122:125]
	v_mfma_f32_16x16x32_bf16 v[118:121], v[134:137], v[184:187], v[118:121]
	v_mfma_f32_16x16x32_bf16 v[114:117], v[142:145], v[184:187], v[114:117]
	v_mfma_f32_16x16x32_bf16 v[110:113], v[134:137], v[206:209], v[110:113]
	v_mfma_f32_16x16x32_bf16 v[106:109], v[142:145], v[206:209], v[106:109]
	v_mfma_f32_16x16x32_bf16 v[102:105], v[134:137], v[238:241], v[102:105]
	v_mfma_f32_16x16x32_bf16 v[98:101], v[142:145], v[238:241], v[98:101]
	v_mfma_f32_16x16x32_bf16 v[126:129], v[138:141], v[180:183], v[126:129]
	v_mfma_f32_16x16x32_bf16 v[122:125], v[146:149], v[180:183], v[122:125]
	v_mfma_f32_16x16x32_bf16 v[118:121], v[138:141], v[200:203], v[118:121]
	v_mfma_f32_16x16x32_bf16 v[114:117], v[146:149], v[200:203], v[114:117]
	v_mfma_f32_16x16x32_bf16 v[110:113], v[138:141], v[210:213], v[110:113]
	v_mfma_f32_16x16x32_bf16 v[106:109], v[146:149], v[210:213], v[106:109]
	v_mfma_f32_16x16x32_bf16 v[102:105], v[138:141], v[242:245], v[102:105]
	v_mfma_f32_16x16x32_bf16 v[98:101], v[146:149], v[242:245], v[98:101]
	s_setprio 0
	s_setprio 1
	v_mfma_f32_16x16x32_bf16 v[94:97], v[150:153], v[174:177], v[94:97]
	v_mfma_f32_16x16x32_bf16 v[90:93], v[166:169], v[174:177], v[90:93]
	v_mfma_f32_16x16x32_bf16 v[86:89], v[150:153], v[184:187], v[86:89]
	v_mfma_f32_16x16x32_bf16 v[82:85], v[166:169], v[184:187], v[82:85]
	v_mfma_f32_16x16x32_bf16 v[78:81], v[150:153], v[206:209], v[78:81]
	v_mfma_f32_16x16x32_bf16 v[74:77], v[166:169], v[206:209], v[74:77]
	v_mfma_f32_16x16x32_bf16 v[70:73], v[150:153], v[238:241], v[70:73]
	v_mfma_f32_16x16x32_bf16 v[66:69], v[166:169], v[238:241], v[66:69]
	v_mfma_f32_16x16x32_bf16 v[94:97], v[162:165], v[180:183], v[94:97]
	v_mfma_f32_16x16x32_bf16 v[90:93], v[170:173], v[180:183], v[90:93]
	v_mfma_f32_16x16x32_bf16 v[86:89], v[162:165], v[200:203], v[86:89]
	v_mfma_f32_16x16x32_bf16 v[82:85], v[170:173], v[200:203], v[82:85]
	v_mfma_f32_16x16x32_bf16 v[78:81], v[162:165], v[210:213], v[78:81]
	v_mfma_f32_16x16x32_bf16 v[74:77], v[170:173], v[210:213], v[74:77]
	v_mfma_f32_16x16x32_bf16 v[70:73], v[162:165], v[242:245], v[70:73]
	v_mfma_f32_16x16x32_bf16 v[66:69], v[170:173], v[242:245], v[66:69]
	s_setprio 0
	s_barrier
; #define PG8_STAGE(bufoff, gbase, voff) do { _Pragma("unroll") for (int _i = 0; _i < 2; ++_i) \
;         __builtin_amdgcn_global_load_lds((const unsigned*)((const char*)(gbase) + (voff)[_i]), (LAS unsigned*)(lds + (bufoff) + ldsw + _i * 8192), 16, 0, 0); } while (0)
; #define PG8_LDA(dst, b, h) do { _Pragma("unroll") for (int m = 0; m < 4; ++m) _Pragma("unroll") for (int k = 0; k < 2; ++k) dst[m][k] = *(const LAS bf16x8*)(lds + PG8_SA(b, h) + aoff + m * 2048 + k * 1024); } while (0)
; #define PG8_MMA(ai, bj, At, Bt) do { __builtin_amdgcn_s_setprio(1); _Pragma("unroll") for (int m = 0; m < 4; ++m) _Pragma("unroll") for (int n = 0; n < 2; ++n) _Pragma("unroll") for (int k = 0; k < 2; ++k) \
;         acc[ai][bj][m][n] = __builtin_amdgcn_mfma_f32_16x16x32_bf16(Bt[n][k], At[m][k], acc[ai][bj][m][n], 0, 0, 0); __builtin_amdgcn_s_setprio(0); } while (0)
; #define PG8_WAIT_V(n) asm volatile("s_waitcnt vmcnt(" #n ")" ::: "memory")
; #define PG8_WAIT_L(n) asm volatile("s_waitcnt lgkmcnt(" #n ")" ::: "memory")
; #define PG8_BAR __builtin_amdgcn_s_barrier()
; #define PG8_SCHED __builtin_amdgcn_sched_barrier(0)
; template <class Epi, class Sched, bool ALIGN_EPI>
; __device__ __forceinline__ void gemm_phase(LAS unsigned char* lds, const bf16_t* Ab, const bf16_t* Bb, int lda, int ldb, int K, const Sched& S, Epi& E) {
;     ...
;             PG8_LDA(At, 1, 1); PG8_STAGE(PG8_SB(1, 0), b3, voffB); PG8_STAGE(PG8_SB(1, 1), b3 + hstepB, voffB); PG8_STAGE(PG8_SA(1, 0), a3, voffA);
;             PG8_WAIT_V(8); PG8_WAIT_L(0); PG8_BAR; PG8_MMA(1, 0, At, B0); PG8_MMA(1, 1, At, B1); PG8_BAR; PG8_SCHED;
;         }
;         if constexpr (ALIGN_EPI) { if (wr == 0) PG8_BAR; }
	s_add_i32 s66, s87, s39
	v_lshl_add_u64 v[188:189], v[188:189], 0, s[26:27]
	s_mov_b32 m0, s66
	ds_read_b128 v[174:177], v0 offset:49152
	ds_read_b128 v[180:183], v0 offset:50176
	ds_read_b128 v[184:187], v0 offset:51200
	ds_read_b128 v[200:203], v0 offset:52224
	ds_read_b128 v[206:209], v0 offset:53248
	ds_read_b128 v[210:213], v0 offset:54272
	ds_read_b128 v[238:241], v0 offset:55296
	ds_read_b128 v[242:245], v0 offset:56320
	global_load_lds_dwordx4 v[188:189], off
	s_add_i32 m0, s66, 0x2000
	s_add_u32 s64, s64, 0x40080
	v_lshl_add_u64 v[188:189], v[196:197], 0, s[26:27]
	s_addc_u32 s65, s65, 0
	s_add_i32 s66, s88, s39
	global_load_lds_dwordx4 v[188:189], off
	v_lshl_add_u64 v[188:189], s[64:65], 0, v[160:161]
	s_mov_b32 m0, s66
	s_nop 0
	global_load_lds_dwordx4 v[188:189], off
	v_lshl_add_u64 v[188:189], s[64:65], 0, v[158:159]
	s_add_i32 m0, s66, 0x2000
	s_nop 0
	global_load_lds_dwordx4 v[188:189], off
	v_lshl_add_u64 v[188:189], v[198:199], 0, s[26:27]
	s_mov_b32 m0, s73
	s_nop 0
	global_load_lds_dwordx4 v[188:189], off
	v_lshl_add_u64 v[188:189], v[220:221], 0, s[26:27]
	s_mov_b32 m0, s74
	s_nop 0
	global_load_lds_dwordx4 v[188:189], off
	s_waitcnt vmcnt(8)
	s_waitcnt lgkmcnt(0)
	s_barrier
	s_setprio 1
	v_mfma_f32_16x16x32_bf16 v[62:65], v[134:137], v[174:177], v[62:65]
	v_mfma_f32_16x16x32_bf16 v[58:61], v[142:145], v[174:177], v[58:61]
	v_mfma_f32_16x16x32_bf16 v[54:57], v[134:137], v[184:187], v[54:57]
	v_mfma_f32_16x16x32_bf16 v[50:53], v[142:145], v[184:187], v[50:53]
	v_mfma_f32_16x16x32_bf16 v[46:49], v[134:137], v[206:209], v[46:49]
	v_mfma_f32_16x16x32_bf16 v[42:45], v[142:145], v[206:209], v[42:45]
	v_mfma_f32_16x16x32_bf16 v[38:41], v[134:137], v[238:241], v[38:41]
	v_mfma_f32_16x16x32_bf16 v[34:37], v[142:145], v[238:241], v[34:37]
	v_mfma_f32_16x16x32_bf16 v[62:65], v[138:141], v[180:183], v[62:65]
	v_mfma_f32_16x16x32_bf16 v[58:61], v[146:149], v[180:183], v[58:61]
	v_mfma_f32_16x16x32_bf16 v[54:57], v[138:141], v[200:203], v[54:57]
	v_mfma_f32_16x16x32_bf16 v[50:53], v[146:149], v[200:203], v[50:53]
	v_mfma_f32_16x16x32_bf16 v[46:49], v[138:141], v[210:213], v[46:49]
	v_mfma_f32_16x16x32_bf16 v[42:45], v[146:149], v[210:213], v[42:45]
	v_mfma_f32_16x16x32_bf16 v[38:41], v[138:141], v[242:245], v[38:41]
	v_mfma_f32_16x16x32_bf16 v[34:37], v[146:149], v[242:245], v[34:37]
	s_setprio 0
	s_setprio 1
	v_mfma_f32_16x16x32_bf16 v[30:33], v[150:153], v[174:177], v[30:33]
	v_mfma_f32_16x16x32_bf16 v[26:29], v[166:169], v[174:177], v[26:29]
	v_mfma_f32_16x16x32_bf16 v[22:25], v[150:153], v[184:187], v[22:25]
	v_mfma_f32_16x16x32_bf16 v[18:21], v[166:169], v[184:187], v[18:21]
	v_mfma_f32_16x16x32_bf16 v[14:17], v[150:153], v[206:209], v[14:17]
	v_mfma_f32_16x16x32_bf16 v[10:13], v[166:169], v[206:209], v[10:13]
	v_mfma_f32_16x16x32_bf16 v[6:9], v[150:153], v[238:241], v[6:9]
	v_mfma_f32_16x16x32_bf16 v[2:5], v[166:169], v[238:241], v[2:5]
	v_mfma_f32_16x16x32_bf16 v[30:33], v[162:165], v[180:183], v[30:33]
	v_mfma_f32_16x16x32_bf16 v[26:29], v[170:173], v[180:183], v[26:29]
	v_mfma_f32_16x16x32_bf16 v[22:25], v[162:165], v[200:203], v[22:25]
	v_mfma_f32_16x16x32_bf16 v[18:21], v[170:173], v[200:203], v[18:21]
	v_mfma_f32_16x16x32_bf16 v[14:17], v[162:165], v[210:213], v[14:17]
	v_mfma_f32_16x16x32_bf16 v[10:13], v[170:173], v[210:213], v[10:13]
	v_mfma_f32_16x16x32_bf16 v[6:9], v[162:165], v[242:245], v[6:9]
	v_mfma_f32_16x16x32_bf16 v[2:5], v[170:173], v[242:245], v[2:5]
	s_setprio 0
	s_barrier
	s_add_i32 s83, s83, 2
	s_add_u32 s62, s62, 0x100
	s_addc_u32 s63, s63, 0
	s_cmp_gt_u32 s83, 13
	s_cbranch_scc0 .LBB0_1501
	s_and_b64 vcc, exec, s[16:17]
	s_cbranch_vccz .LBB0_1504
	s_barrier

; #define PG8_STAGE(bufoff, gbase, voff) do { _Pragma("unroll") for (int _i = 0; _i < 2; ++_i) \
;         __builtin_amdgcn_global_load_lds((const unsigned*)((const char*)(gbase) + (voff)[_i]), (LAS unsigned*)(lds + (bufoff) + ldsw + _i * 8192), 16, 0, 0); } while (0)
; #define PG8_LDA(dst, b, h) do { _Pragma("unroll") for (int m = 0; m < 4; ++m) _Pragma("unroll") for (int k = 0; k < 2; ++k) dst[m][k] = *(const LAS bf16x8*)(lds + PG8_SA(b, h) + aoff + m * 2048 + k * 1024); } while (0)
; #define PG8_LDB(dst, b, h) do { _Pragma("unroll") for (int n = 0; n < 2; ++n) _Pragma("unroll") for (int k = 0; k < 2; ++k) dst[n][k] = *(const LAS bf16x8*)(lds + PG8_SB(b, h) + boff + n * 2048 + k * 1024); } while (0)
; #define PG8_MMA(ai, bj, At, Bt) do { __builtin_amdgcn_s_setprio(1); _Pragma("unroll") for (int m = 0; m < 4; ++m) _Pragma("unroll") for (int n = 0; n < 2; ++n) _Pragma("unroll") for (int k = 0; k < 2; ++k) \
;         acc[ai][bj][m][n] = __builtin_amdgcn_mfma_f32_16x16x32_bf16(Bt[n][k], At[m][k], acc[ai][bj][m][n], 0, 0, 0); __builtin_amdgcn_s_setprio(0); } while (0)
; #define PG8_WAIT_V(n) asm volatile("s_waitcnt vmcnt(" #n ")" ::: "memory")
; #define PG8_WAIT_L(n) asm volatile("s_waitcnt lgkmcnt(" #n ")" ::: "memory")
; #define PG8_BAR __builtin_amdgcn_s_barrier()
; template <class Epi, class Sched, bool ALIGN_EPI>
; __device__ __forceinline__ void gemm_phase(LAS unsigned char* lds, const bf16_t* Ab, const bf16_t* Bb, int lda, int ldb, int K, const Sched& S, Epi& E) {
;     ...
;         for (int t = 0; t < nt; t += 2) {
;             const bool last = (t == nt - 2);
;             const char* a1 = cA + (unsigned)(t + 1) * kstep;
;             const char* a2 = last ? nA : cA + (unsigned)(t + 2) * kstep; const char* b2 = last ? nB : cB + (unsigned)(t + 2) * kstep;
;             const char* a3 = a2 + kstep; const char* b3 = b2 + kstep;
;             PG8_LDB(B0, 0, 0); PG8_LDB(B1, 0, 1); PG8_SCHED; PG8_LDA(At, 0, 0); PG8_STAGE(PG8_SA(1, 1), a1 + hstepA, voffA);
;             PG8_WAIT_V(8); PG8_WAIT_L(0); PG8_BAR; PG8_MMA(0, 0, At, B0); PG8_MMA(0, 1, At, B1); PG8_BAR; PG8_SCHED;
;             PG8_LDA(At, 0, 1); PG8_STAGE(PG8_SB(0, 0), b2, voffB); PG8_STAGE(PG8_SB(0, 1), b2 + hstepB, voffB); PG8_STAGE(PG8_SA(0, 0), a2, voffA);
;             PG8_WAIT_V(8); PG8_WAIT_L(0); PG8_BAR; PG8_MMA(1, 0, At, B0); PG8_MMA(1, 1, At, B1); PG8_BAR; PG8_SCHED;
.LBB0_1644:
	s_add_u32 s62, s54, s60
	s_addc_u32 s63, s55, s61
	s_add_u32 s62, s62, 0x100
	s_addc_u32 s63, s63, 0
	s_add_u32 s79, s25, s60
	s_addc_u32 s80, s75, s61
	s_add_i32 s81, 0, 0x10000
	s_cmpk_eq_i32 s60, 0x700
	s_cselect_b32 s65, s17, s63
	s_cselect_b32 s64, s76, s62
	s_cselect_b32 s63, s53, s80
	s_cselect_b32 s62, s77, s79
	s_add_i32 s79, 0, 0x14000
	v_add_u32_e32 v154, s81, v141
	v_add_u32_e32 v170, s79, v141
	ds_read_b128 v[142:145], v154
	ds_read_b128 v[146:149], v154 offset:1024
	ds_read_b128 v[150:153], v154 offset:2048
	ds_read_b128 v[154:157], v154 offset:3072
	ds_read_b128 v[158:161], v170
	ds_read_b128 v[162:165], v170 offset:1024
	ds_read_b128 v[166:169], v170 offset:2048
	ds_read_b128 v[170:173], v170 offset:3072
	v_add_u32_e32 v190, 0, v140
	v_lshl_add_u64 v[186:187], v[136:137], 0, s[60:61]
	s_add_i32 m0, s44, 0xc000
	ds_read_b128 v[174:177], v190
	ds_read_b128 v[178:181], v190 offset:1024
	ds_read_b128 v[182:185], v190 offset:2048
	ds_read_b128 v[200:203], v190 offset:3072
	ds_read_b128 v[206:209], v190 offset:4096
	ds_read_b128 v[210:213], v190 offset:5120
	ds_read_b128 v[238:241], v190 offset:6144
	ds_read_b128 v[242:245], v190 offset:7168
	global_load_lds_dwordx4 v[186:187], off
	v_lshl_add_u64 v[186:187], v[138:139], 0, s[60:61]
	s_add_i32 m0, s44, 0xe000
	s_nop 0
	global_load_lds_dwordx4 v[186:187], off
	s_waitcnt vmcnt(8)
	s_waitcnt lgkmcnt(0)
	s_barrier
	s_setprio 1
	v_mfma_f32_16x16x32_bf16 v[126:129], v[142:145], v[174:177], v[126:129]
	v_mfma_f32_16x16x32_bf16 v[122:125], v[150:153], v[174:177], v[122:125]
	v_mfma_f32_16x16x32_bf16 v[118:121], v[142:145], v[182:185], v[118:121]
	v_mfma_f32_16x16x32_bf16 v[114:117], v[150:153], v[182:185], v[114:117]
	v_mfma_f32_16x16x32_bf16 v[110:113], v[142:145], v[206:209], v[110:113]
	v_mfma_f32_16x16x32_bf16 v[106:109], v[150:153], v[206:209], v[106:109]
	v_mfma_f32_16x16x32_bf16 v[102:105], v[142:145], v[238:241], v[102:105]
	v_mfma_f32_16x16x32_bf16 v[98:101], v[150:153], v[238:241], v[98:101]
	v_mfma_f32_16x16x32_bf16 v[126:129], v[146:149], v[178:181], v[126:129]
	v_mfma_f32_16x16x32_bf16 v[122:125], v[154:157], v[178:181], v[122:125]
	v_mfma_f32_16x16x32_bf16 v[118:121], v[146:149], v[200:203], v[118:121]
	v_mfma_f32_16x16x32_bf16 v[114:117], v[154:157], v[200:203], v[114:117]
	v_mfma_f32_16x16x32_bf16 v[110:113], v[146:149], v[210:213], v[110:113]
	v_mfma_f32_16x16x32_bf16 v[106:109], v[154:157], v[210:213], v[106:109]
	v_mfma_f32_16x16x32_bf16 v[102:105], v[146:149], v[242:245], v[102:105]
	v_mfma_f32_16x16x32_bf16 v[98:101], v[154:157], v[242:245], v[98:101]
	s_setprio 0
	s_setprio 1
	v_mfma_f32_16x16x32_bf16 v[94:97], v[158:161], v[174:177], v[94:97]
	v_mfma_f32_16x16x32_bf16 v[90:93], v[166:169], v[174:177], v[90:93]
	v_mfma_f32_16x16x32_bf16 v[86:89], v[158:161], v[182:185], v[86:89]
	v_mfma_f32_16x16x32_bf16 v[82:85], v[166:169], v[182:185], v[82:85]
	v_mfma_f32_16x16x32_bf16 v[78:81], v[158:161], v[206:209], v[78:81]
	v_mfma_f32_16x16x32_bf16 v[74:77], v[166:169], v[206:209], v[74:77]
	v_mfma_f32_16x16x32_bf16 v[70:73], v[158:161], v[238:241], v[70:73]
	v_mfma_f32_16x16x32_bf16 v[66:69], v[166:169], v[238:241], v[66:69]
	v_mfma_f32_16x16x32_bf16 v[94:97], v[162:165], v[178:181], v[94:97]
	v_mfma_f32_16x16x32_bf16 v[90:93], v[170:173], v[178:181], v[90:93]
	v_mfma_f32_16x16x32_bf16 v[86:89], v[162:165], v[200:203], v[86:89]
	v_mfma_f32_16x16x32_bf16 v[82:85], v[170:173], v[200:203], v[82:85]
	v_mfma_f32_16x16x32_bf16 v[78:81], v[162:165], v[210:213], v[78:81]
	v_mfma_f32_16x16x32_bf16 v[74:77], v[170:173], v[210:213], v[74:77]
	v_mfma_f32_16x16x32_bf16 v[70:73], v[162:165], v[242:245], v[70:73]
	v_mfma_f32_16x16x32_bf16 v[66:69], v[170:173], v[242:245], v[66:69]
	s_setprio 0
	s_barrier
	s_add_i32 s80, s81, s39
	v_lshl_add_u64 v[186:187], s[62:63], 0, v[134:135]
	s_mov_b32 m0, s80
	ds_read_b128 v[174:177], v190 offset:16384
	ds_read_b128 v[178:181], v190 offset:17408
	ds_read_b128 v[182:185], v190 offset:18432
	ds_read_b128 v[200:203], v190 offset:19456
	ds_read_b128 v[206:209], v190 offset:20480
	ds_read_b128 v[210:213], v190 offset:21504
	ds_read_b128 v[238:241], v190 offset:22528
	ds_read_b128 v[242:245], v190 offset:23552
	global_load_lds_dwordx4 v[186:187], off
	s_add_i32 m0, s80, 0x2000
	s_add_u32 s80, s62, 0x40000
	v_lshl_add_u64 v[188:189], s[62:63], 0, v[132:133]
	s_addc_u32 s81, s63, 0
	s_add_i32 s79, s79, s39
	global_load_lds_dwordx4 v[188:189], off
	v_lshl_add_u64 v[196:197], s[80:81], 0, v[134:135]
	s_mov_b32 m0, s79
	v_lshl_add_u64 v[198:199], s[64:65], 0, v[130:131]
	global_load_lds_dwordx4 v[196:197], off
	v_lshl_add_u64 v[196:197], s[80:81], 0, v[132:133]
	s_add_i32 m0, s79, 0x2000
	s_nop 0
	global_load_lds_dwordx4 v[196:197], off
	v_lshl_add_u64 v[196:197], s[64:65], 0, v[0:1]
	s_mov_b32 m0, s44
	s_nop 0
	global_load_lds_dwordx4 v[196:197], off
	s_mov_b32 m0, s31
	s_nop 0
	global_load_lds_dwordx4 v[198:199], off
	s_waitcnt vmcnt(8)
	s_waitcnt lgkmcnt(0)
	s_barrier
; #define PG8_STAGE(bufoff, gbase, voff) do { _Pragma("unroll") for (int _i = 0; _i < 2; ++_i) \
;         __builtin_amdgcn_global_load_lds((const unsigned*)((const char*)(gbase) + (voff)[_i]), (LAS unsigned*)(lds + (bufoff) + ldsw + _i * 8192), 16, 0, 0); } while (0)
; #define PG8_LDA(dst, b, h) do { _Pragma("unroll") for (int m = 0; m < 4; ++m) _Pragma("unroll") for (int k = 0; k < 2; ++k) dst[m][k] = *(const LAS bf16x8*)(lds + PG8_SA(b, h) + aoff + m * 2048 + k * 1024); } while (0)
; #define PG8_LDB(dst, b, h) do { _Pragma("unroll") for (int n = 0; n < 2; ++n) _Pragma("unroll") for (int k = 0; k < 2; ++k) dst[n][k] = *(const LAS bf16x8*)(lds + PG8_SB(b, h) + boff + n * 2048 + k * 1024); } while (0)
; #define PG8_MMA(ai, bj, At, Bt) do { __builtin_amdgcn_s_setprio(1); _Pragma("unroll") for (int m = 0; m < 4; ++m) _Pragma("unroll") for (int n = 0; n < 2; ++n) _Pragma("unroll") for (int k = 0; k < 2; ++k) \
;         acc[ai][bj][m][n] = __builtin_amdgcn_mfma_f32_16x16x32_bf16(Bt[n][k], At[m][k], acc[ai][bj][m][n], 0, 0, 0); __builtin_amdgcn_s_setprio(0); } while (0)
; #define PG8_WAIT_V(n) asm volatile("s_waitcnt vmcnt(" #n ")" ::: "memory")
; #define PG8_WAIT_L(n) asm volatile("s_waitcnt lgkmcnt(" #n ")" ::: "memory")
; #define PG8_BAR __builtin_amdgcn_s_barrier()
; #define PG8_SCHED __builtin_amdgcn_sched_barrier(0)
; template <class Epi, class Sched, bool ALIGN_EPI>
; __device__ __forceinline__ void gemm_phase(LAS unsigned char* lds, const bf16_t* Ab, const bf16_t* Bb, int lda, int ldb, int K, const Sched& S, Epi& E) {
;     ...
;             PG8_WAIT_V(8); PG8_WAIT_L(0); PG8_BAR; PG8_MMA(1, 0, At, B0); PG8_MMA(1, 1, At, B1); PG8_BAR; PG8_SCHED;
;             PG8_LDB(B0, 1, 0); PG8_LDB(B1, 1, 1); PG8_SCHED; PG8_LDA(At, 1, 0); PG8_STAGE(PG8_SA(0, 1), a2 + hstepA, voffA);
;             PG8_WAIT_V(8); PG8_WAIT_L(0); PG8_BAR; PG8_MMA(0, 0, At, B0); PG8_MMA(0, 1, At, B1); PG8_BAR; PG8_SCHED;
;             PG8_LDA(At, 1, 1); PG8_STAGE(PG8_SB(1, 0), b3, voffB); PG8_STAGE(PG8_SB(1, 1), b3 + hstepB, voffB); PG8_STAGE(PG8_SA(1, 0), a3, voffA);
	s_setprio 1
	v_mfma_f32_16x16x32_bf16 v[62:65], v[142:145], v[174:177], v[62:65]
	v_mfma_f32_16x16x32_bf16 v[58:61], v[150:153], v[174:177], v[58:61]
	v_mfma_f32_16x16x32_bf16 v[54:57], v[142:145], v[182:185], v[54:57]
	v_mfma_f32_16x16x32_bf16 v[50:53], v[150:153], v[182:185], v[50:53]
	v_mfma_f32_16x16x32_bf16 v[46:49], v[142:145], v[206:209], v[46:49]
	v_mfma_f32_16x16x32_bf16 v[42:45], v[150:153], v[206:209], v[42:45]
	v_mfma_f32_16x16x32_bf16 v[38:41], v[142:145], v[238:241], v[38:41]
	v_mfma_f32_16x16x32_bf16 v[34:37], v[150:153], v[238:241], v[34:37]
	v_mfma_f32_16x16x32_bf16 v[62:65], v[146:149], v[178:181], v[62:65]
	v_mfma_f32_16x16x32_bf16 v[58:61], v[154:157], v[178:181], v[58:61]
	v_mfma_f32_16x16x32_bf16 v[54:57], v[146:149], v[200:203], v[54:57]
	v_mfma_f32_16x16x32_bf16 v[50:53], v[154:157], v[200:203], v[50:53]
	v_mfma_f32_16x16x32_bf16 v[46:49], v[146:149], v[210:213], v[46:49]
	v_mfma_f32_16x16x32_bf16 v[42:45], v[154:157], v[210:213], v[42:45]
	v_mfma_f32_16x16x32_bf16 v[38:41], v[146:149], v[242:245], v[38:41]
	v_mfma_f32_16x16x32_bf16 v[34:37], v[154:157], v[242:245], v[34:37]
	s_setprio 0
	s_setprio 1
	v_mfma_f32_16x16x32_bf16 v[30:33], v[158:161], v[174:177], v[30:33]
	v_mfma_f32_16x16x32_bf16 v[26:29], v[166:169], v[174:177], v[26:29]
	v_mfma_f32_16x16x32_bf16 v[22:25], v[158:161], v[182:185], v[22:25]
	v_mfma_f32_16x16x32_bf16 v[18:21], v[166:169], v[182:185], v[18:21]
	v_mfma_f32_16x16x32_bf16 v[14:17], v[158:161], v[206:209], v[14:17]
	v_mfma_f32_16x16x32_bf16 v[10:13], v[166:169], v[206:209], v[10:13]
	v_mfma_f32_16x16x32_bf16 v[6:9], v[158:161], v[238:241], v[6:9]
	v_mfma_f32_16x16x32_bf16 v[2:5], v[166:169], v[238:241], v[2:5]
	v_mfma_f32_16x16x32_bf16 v[30:33], v[162:165], v[178:181], v[30:33]
	v_mfma_f32_16x16x32_bf16 v[26:29], v[170:173], v[178:181], v[26:29]
	v_mfma_f32_16x16x32_bf16 v[22:25], v[162:165], v[200:203], v[22:25]
	v_mfma_f32_16x16x32_bf16 v[18:21], v[170:173], v[200:203], v[18:21]
	v_mfma_f32_16x16x32_bf16 v[14:17], v[162:165], v[210:213], v[14:17]
	v_mfma_f32_16x16x32_bf16 v[10:13], v[170:173], v[210:213], v[10:13]
	v_mfma_f32_16x16x32_bf16 v[6:9], v[162:165], v[242:245], v[6:9]
	v_mfma_f32_16x16x32_bf16 v[2:5], v[170:173], v[242:245], v[2:5]
	s_setprio 0
	s_barrier
	s_add_i32 s79, 0, 0x18000
	s_add_i32 s80, 0, 0x1c000
	v_add_u32_e32 v154, s79, v141
	v_add_u32_e32 v170, s80, v141
	ds_read_b128 v[142:145], v154
	ds_read_b128 v[146:149], v154 offset:1024
	ds_read_b128 v[150:153], v154 offset:2048
	ds_read_b128 v[154:157], v154 offset:3072
	ds_read_b128 v[158:161], v170
	ds_read_b128 v[162:165], v170 offset:1024
	ds_read_b128 v[166:169], v170 offset:2048
	ds_read_b128 v[170:173], v170 offset:3072
	s_add_u32 s64, s64, 0x40000
	s_addc_u32 s65, s65, 0
	s_mov_b32 m0, s45
	v_lshl_add_u64 v[220:221], s[64:65], 0, v[0:1]
	ds_read_b128 v[174:177], v190 offset:32768
	ds_read_b128 v[178:181], v190 offset:33792
	ds_read_b128 v[182:185], v190 offset:34816
	ds_read_b128 v[200:203], v190 offset:35840
	ds_read_b128 v[206:209], v190 offset:36864
	ds_read_b128 v[210:213], v190 offset:37888
	ds_read_b128 v[238:241], v190 offset:38912
	ds_read_b128 v[242:245], v190 offset:39936
	global_load_lds_dwordx4 v[220:221], off
	v_lshl_add_u64 v[220:221], s[64:65], 0, v[130:131]
	s_mov_b32 m0, s46
	s_nop 0
	global_load_lds_dwordx4 v[220:221], off
	s_waitcnt vmcnt(8)
	s_waitcnt lgkmcnt(0)
	s_barrier
	s_setprio 1
	v_mfma_f32_16x16x32_bf16 v[126:129], v[142:145], v[174:177], v[126:129]
	v_mfma_f32_16x16x32_bf16 v[122:125], v[150:153], v[174:177], v[122:125]
	v_mfma_f32_16x16x32_bf16 v[118:121], v[142:145], v[182:185], v[118:121]
	v_mfma_f32_16x16x32_bf16 v[114:117], v[150:153], v[182:185], v[114:117]
	v_mfma_f32_16x16x32_bf16 v[110:113], v[142:145], v[206:209], v[110:113]
	v_mfma_f32_16x16x32_bf16 v[106:109], v[150:153], v[206:209], v[106:109]
	v_mfma_f32_16x16x32_bf16 v[102:105], v[142:145], v[238:241], v[102:105]
	v_mfma_f32_16x16x32_bf16 v[98:101], v[150:153], v[238:241], v[98:101]
	v_mfma_f32_16x16x32_bf16 v[126:129], v[146:149], v[178:181], v[126:129]
	v_mfma_f32_16x16x32_bf16 v[122:125], v[154:157], v[178:181], v[122:125]
	v_mfma_f32_16x16x32_bf16 v[118:121], v[146:149], v[200:203], v[118:121]
	v_mfma_f32_16x16x32_bf16 v[114:117], v[154:157], v[200:203], v[114:117]
	v_mfma_f32_16x16x32_bf16 v[110:113], v[146:149], v[210:213], v[110:113]
	v_mfma_f32_16x16x32_bf16 v[106:109], v[154:157], v[210:213], v[106:109]
	v_mfma_f32_16x16x32_bf16 v[102:105], v[146:149], v[242:245], v[102:105]
	v_mfma_f32_16x16x32_bf16 v[98:101], v[154:157], v[242:245], v[98:101]
	s_setprio 0
	s_setprio 1
	v_mfma_f32_16x16x32_bf16 v[94:97], v[158:161], v[174:177], v[94:97]
	v_mfma_f32_16x16x32_bf16 v[90:93], v[166:169], v[174:177], v[90:93]
	v_mfma_f32_16x16x32_bf16 v[86:89], v[158:161], v[182:185], v[86:89]
	v_mfma_f32_16x16x32_bf16 v[82:85], v[166:169], v[182:185], v[82:85]
	v_mfma_f32_16x16x32_bf16 v[78:81], v[158:161], v[206:209], v[78:81]
	v_mfma_f32_16x16x32_bf16 v[74:77], v[166:169], v[206:209], v[74:77]
	v_mfma_f32_16x16x32_bf16 v[70:73], v[158:161], v[238:241], v[70:73]
	v_mfma_f32_16x16x32_bf16 v[66:69], v[166:169], v[238:241], v[66:69]
	v_mfma_f32_16x16x32_bf16 v[94:97], v[162:165], v[178:181], v[94:97]
	v_mfma_f32_16x16x32_bf16 v[90:93], v[170:173], v[178:181], v[90:93]
	v_mfma_f32_16x16x32_bf16 v[86:89], v[162:165], v[200:203], v[86:89]
	v_mfma_f32_16x16x32_bf16 v[82:85], v[170:173], v[200:203], v[82:85]
	v_mfma_f32_16x16x32_bf16 v[78:81], v[162:165], v[210:213], v[78:81]
	v_mfma_f32_16x16x32_bf16 v[74:77], v[170:173], v[210:213], v[74:77]
	v_mfma_f32_16x16x32_bf16 v[70:73], v[162:165], v[242:245], v[70:73]
	v_mfma_f32_16x16x32_bf16 v[66:69], v[170:173], v[242:245], v[66:69]
	s_setprio 0
	s_barrier
; #define PG8_STAGE(bufoff, gbase, voff) do { _Pragma("unroll") for (int _i = 0; _i < 2; ++_i) \
;         __builtin_amdgcn_global_load_lds((const unsigned*)((const char*)(gbase) + (voff)[_i]), (LAS unsigned*)(lds + (bufoff) + ldsw + _i * 8192), 16, 0, 0); } while (0)
; #define PG8_LDA(dst, b, h) do { _Pragma("unroll") for (int m = 0; m < 4; ++m) _Pragma("unroll") for (int k = 0; k < 2; ++k) dst[m][k] = *(const LAS bf16x8*)(lds + PG8_SA(b, h) + aoff + m * 2048 + k * 1024); } while (0)
; #define PG8_MMA(ai, bj, At, Bt) do { __builtin_amdgcn_s_setprio(1); _Pragma("unroll") for (int m = 0; m < 4; ++m) _Pragma("unroll") for (int n = 0; n < 2; ++n) _Pragma("unroll") for (int k = 0; k < 2; ++k) \
;         acc[ai][bj][m][n] = __builtin_amdgcn_mfma_f32_16x16x32_bf16(Bt[n][k], At[m][k], acc[ai][bj][m][n], 0, 0, 0); __builtin_amdgcn_s_setprio(0); } while (0)
; #define PG8_WAIT_V(n) asm volatile("s_waitcnt vmcnt(" #n ")" ::: "memory")
; #define PG8_WAIT_L(n) asm volatile("s_waitcnt lgkmcnt(" #n ")" ::: "memory")
; #define PG8_BAR __builtin_amdgcn_s_barrier()
; #define PG8_SCHED __builtin_amdgcn_sched_barrier(0)
; template <class Epi, class Sched, bool ALIGN_EPI>
; __device__ __forceinline__ void gemm_phase(LAS unsigned char* lds, const bf16_t* Ab, const bf16_t* Bb, int lda, int ldb, int K, const Sched& S, Epi& E) {
;     ...
;             PG8_LDA(At, 1, 1); PG8_STAGE(PG8_SB(1, 0), b3, voffB); PG8_STAGE(PG8_SB(1, 1), b3 + hstepB, voffB); PG8_STAGE(PG8_SA(1, 0), a3, voffA);
;             PG8_WAIT_V(8); PG8_WAIT_L(0); PG8_BAR; PG8_MMA(1, 0, At, B0); PG8_MMA(1, 1, At, B1); PG8_BAR; PG8_SCHED;
;         }
	s_add_i32 s64, s79, s39
	v_lshl_add_u64 v[186:187], v[186:187], 0, s[26:27]
	s_mov_b32 m0, s64
	ds_read_b128 v[174:177], v190 offset:49152
	ds_read_b128 v[178:181], v190 offset:50176
	ds_read_b128 v[182:185], v190 offset:51200
	ds_read_b128 v[200:203], v190 offset:52224
	ds_read_b128 v[206:209], v190 offset:53248
	ds_read_b128 v[210:213], v190 offset:54272
	ds_read_b128 v[238:241], v190 offset:55296
	ds_read_b128 v[242:245], v190 offset:56320
	global_load_lds_dwordx4 v[186:187], off
	s_add_i32 m0, s64, 0x2000
	s_add_u32 s62, s62, 0x40080
	v_lshl_add_u64 v[186:187], v[188:189], 0, s[26:27]
	s_addc_u32 s63, s63, 0
	s_add_i32 s64, s80, s39
	global_load_lds_dwordx4 v[186:187], off
	v_lshl_add_u64 v[186:187], s[62:63], 0, v[134:135]
	s_mov_b32 m0, s64
	s_nop 0
	global_load_lds_dwordx4 v[186:187], off
	v_lshl_add_u64 v[186:187], s[62:63], 0, v[132:133]
	s_add_i32 m0, s64, 0x2000
	s_nop 0
	global_load_lds_dwordx4 v[186:187], off
	v_lshl_add_u64 v[186:187], v[196:197], 0, s[26:27]
	s_mov_b32 m0, s68
	s_nop 0
	global_load_lds_dwordx4 v[186:187], off
	v_lshl_add_u64 v[186:187], v[198:199], 0, s[26:27]
	s_mov_b32 m0, s69
	s_nop 0
	global_load_lds_dwordx4 v[186:187], off
	s_waitcnt vmcnt(8)
	s_waitcnt lgkmcnt(0)
	s_barrier
	s_setprio 1
	v_mfma_f32_16x16x32_bf16 v[62:65], v[142:145], v[174:177], v[62:65]
	v_mfma_f32_16x16x32_bf16 v[58:61], v[150:153], v[174:177], v[58:61]
	v_mfma_f32_16x16x32_bf16 v[54:57], v[142:145], v[182:185], v[54:57]
	v_mfma_f32_16x16x32_bf16 v[50:53], v[150:153], v[182:185], v[50:53]
	v_mfma_f32_16x16x32_bf16 v[46:49], v[142:145], v[206:209], v[46:49]
	v_mfma_f32_16x16x32_bf16 v[42:45], v[150:153], v[206:209], v[42:45]
	v_mfma_f32_16x16x32_bf16 v[38:41], v[142:145], v[238:241], v[38:41]
	v_mfma_f32_16x16x32_bf16 v[34:37], v[150:153], v[238:241], v[34:37]
	v_mfma_f32_16x16x32_bf16 v[62:65], v[146:149], v[178:181], v[62:65]
	v_mfma_f32_16x16x32_bf16 v[58:61], v[154:157], v[178:181], v[58:61]
	v_mfma_f32_16x16x32_bf16 v[54:57], v[146:149], v[200:203], v[54:57]
	v_mfma_f32_16x16x32_bf16 v[50:53], v[154:157], v[200:203], v[50:53]
	v_mfma_f32_16x16x32_bf16 v[46:49], v[146:149], v[210:213], v[46:49]
	v_mfma_f32_16x16x32_bf16 v[42:45], v[154:157], v[210:213], v[42:45]
	v_mfma_f32_16x16x32_bf16 v[38:41], v[146:149], v[242:245], v[38:41]
	v_mfma_f32_16x16x32_bf16 v[34:37], v[154:157], v[242:245], v[34:37]
	s_setprio 0
	s_setprio 1
	v_mfma_f32_16x16x32_bf16 v[30:33], v[158:161], v[174:177], v[30:33]
	v_mfma_f32_16x16x32_bf16 v[26:29], v[166:169], v[174:177], v[26:29]
	v_mfma_f32_16x16x32_bf16 v[22:25], v[158:161], v[182:185], v[22:25]
	v_mfma_f32_16x16x32_bf16 v[18:21], v[166:169], v[182:185], v[18:21]
	v_mfma_f32_16x16x32_bf16 v[14:17], v[158:161], v[206:209], v[14:17]
	v_mfma_f32_16x16x32_bf16 v[10:13], v[166:169], v[206:209], v[10:13]
	v_mfma_f32_16x16x32_bf16 v[6:9], v[158:161], v[238:241], v[6:9]
	v_mfma_f32_16x16x32_bf16 v[2:5], v[166:169], v[238:241], v[2:5]
	v_mfma_f32_16x16x32_bf16 v[30:33], v[162:165], v[178:181], v[30:33]
	v_mfma_f32_16x16x32_bf16 v[26:29], v[170:173], v[178:181], v[26:29]
	v_mfma_f32_16x16x32_bf16 v[22:25], v[162:165], v[200:203], v[22:25]
	v_mfma_f32_16x16x32_bf16 v[18:21], v[170:173], v[200:203], v[18:21]
	v_mfma_f32_16x16x32_bf16 v[14:17], v[162:165], v[210:213], v[14:17]
	v_mfma_f32_16x16x32_bf16 v[10:13], v[170:173], v[210:213], v[10:13]
	v_mfma_f32_16x16x32_bf16 v[6:9], v[162:165], v[242:245], v[6:9]
	v_mfma_f32_16x16x32_bf16 v[2:5], v[170:173], v[242:245], v[2:5]
	s_setprio 0
	s_barrier
	s_add_i32 s78, s78, 2
	s_add_u32 s60, s60, 0x100
	s_addc_u32 s61, s61, 0
	s_cmp_gt_u32 s78, 13
	s_cbranch_scc0 .LBB0_1644
	s_and_b64 vcc, exec, s[14:15]
	s_cbranch_vccz .LBB0_1647
	s_barrier

; #define PG8_STAGE(bufoff, gbase, voff) do { _Pragma("unroll") for (int _i = 0; _i < 2; ++_i) \
;         __builtin_amdgcn_global_load_lds((const unsigned*)((const char*)(gbase) + (voff)[_i]), (LAS unsigned*)(lds + (bufoff) + ldsw + _i * 8192), 16, 0, 0); } while (0)
; #define PG8_LDA(dst, b, h) do { _Pragma("unroll") for (int m = 0; m < 4; ++m) _Pragma("unroll") for (int k = 0; k < 2; ++k) dst[m][k] = *(const LAS bf16x8*)(lds + PG8_SA(b, h) + aoff + m * 2048 + k * 1024); } while (0)
; #define PG8_LDB(dst, b, h) do { _Pragma("unroll") for (int n = 0; n < 2; ++n) _Pragma("unroll") for (int k = 0; k < 2; ++k) dst[n][k] = *(const LAS bf16x8*)(lds + PG8_SB(b, h) + boff + n * 2048 + k * 1024); } while (0)
; #define PG8_MMA(ai, bj, At, Bt) do { __builtin_amdgcn_s_setprio(1); _Pragma("unroll") for (int m = 0; m < 4; ++m) _Pragma("unroll") for (int n = 0; n < 2; ++n) _Pragma("unroll") for (int k = 0; k < 2; ++k) \
;         acc[ai][bj][m][n] = __builtin_amdgcn_mfma_f32_16x16x32_bf16(Bt[n][k], At[m][k], acc[ai][bj][m][n], 0, 0, 0); __builtin_amdgcn_s_setprio(0); } while (0)
; template <class Epi, class Sched, bool ALIGN_EPI>
; __device__ __forceinline__ void gemm_phase(LAS unsigned char* lds, const bf16_t* Ab, const bf16_t* Bb, int lda, int ldb, int K, const Sched& S, Epi& E) {
;     ...
;         const bool has_next = S.next(ui + 1, nxt); nxt.ui = ui + 1;
;         const char* nA = has_next ? (const char*)(Ab + nxt.a_off) : cA; const char* nB = has_next ? (const char*)(Bb + nxt.b_off) : cB;
;         for (int t = 0; t < nt; t += 2) {
;             const bool last = (t == nt - 2);
;             const char* a1 = cA + (unsigned)(t + 1) * kstep;
;             const char* a2 = last ? nA : cA + (unsigned)(t + 2) * kstep; const char* b2 = last ? nB : cB + (unsigned)(t + 2) * kstep;
;             const char* a3 = a2 + kstep; const char* b3 = b2 + kstep;
;             PG8_LDB(B0, 0, 0); PG8_LDB(B1, 0, 1); PG8_SCHED; PG8_LDA(At, 0, 0); PG8_STAGE(PG8_SA(1, 1), a1 + hstepA, voffA);
;             PG8_WAIT_V(8); PG8_WAIT_L(0); PG8_BAR; PG8_MMA(0, 0, At, B0); PG8_MMA(0, 1, At, B1); PG8_BAR; PG8_SCHED;
;             PG8_LDA(At, 0, 1); PG8_STAGE(PG8_SB(0, 0), b2, voffB); PG8_STAGE(PG8_SB(0, 1), b2 + hstepB, voffB); PG8_STAGE(PG8_SA(0, 0), a2, voffA);
;             PG8_WAIT_V(8); PG8_WAIT_L(0); PG8_BAR; PG8_MMA(1, 0, At, B0); PG8_MMA(1, 1, At, B1); PG8_BAR; PG8_SCHED;
.LBB0_1715:
	s_lshl_b64 s[48:49], s[18:19], 1
	s_add_u32 s48, s4, s48
	s_addc_u32 s49, s5, s49
	s_and_b64 s[52:53], s[54:55], exec
	s_mov_b32 s17, s19
	s_cselect_b32 s61, s49, s7
	s_cselect_b32 s60, s48, s6
	s_lshl_b64 s[52:53], s[16:17], 1
	s_add_u32 s52, s21, s52
	s_addc_u32 s53, s22, s53
	s_and_b64 s[56:57], s[54:55], exec
	v_add_u32_e32 v5, s62, v7
	s_cselect_b32 s57, s53, s59
	s_cselect_b32 s56, s52, s58
	s_add_i32 s76, 0, 0x10000
	v_add_u32_e32 v9, s76, v5
	s_add_i32 s74, 0, 0x14000
	v_add_u32_e32 v190, s74, v5
	ds_read_b128 v[10:13], v9
	ds_read_b128 v[14:17], v9 offset:1024
	ds_read_b128 v[18:21], v9 offset:2048
	ds_read_b128 v[22:25], v9 offset:3072
	ds_read_b128 v[26:29], v190
	ds_read_b128 v[30:33], v190 offset:1024
	ds_read_b128 v[34:37], v190 offset:2048
	ds_read_b128 v[38:41], v190 offset:3072
	v_add_u32_e32 v8, s67, v3
	s_add_i32 s77, 0, 0x18000
	s_add_i32 s75, 0, 0x1c000
	v_add_u32_e32 v204, s77, v5
	v_add_u32_e32 v220, s75, v5
	s_add_u32 s72, s6, 0x40080
	s_addc_u32 s73, s7, 0
	s_add_i32 s17, s33, 0xc000
	s_mov_b32 m0, s17
	s_add_i32 s25, s33, 0xe000
	ds_read_b128 v[42:45], v8
	ds_read_b128 v[46:49], v8 offset:1024
	ds_read_b128 v[50:53], v8 offset:2048
	ds_read_b128 v[54:57], v8 offset:3072
	ds_read_b128 v[58:61], v8 offset:4096
	ds_read_b128 v[62:65], v8 offset:5120
	ds_read_b128 v[66:69], v8 offset:6144
	ds_read_b128 v[70:73], v8 offset:7168
	global_load_lds_dwordx4 v0, s[72:73]
	s_mov_b32 m0, s25
	v_mov_b32_e32 v7, v1
	global_load_lds_dwordx4 v6, s[72:73]
	s_waitcnt vmcnt(8)
	s_waitcnt lgkmcnt(0)
	s_barrier
	s_setprio 1
	v_mfma_f32_16x16x32_bf16 v[74:77], v[10:13], v[42:45], 0
	v_mfma_f32_16x16x32_bf16 v[78:81], v[18:21], v[42:45], 0
	v_mfma_f32_16x16x32_bf16 v[82:85], v[10:13], v[50:53], 0
	v_mfma_f32_16x16x32_bf16 v[86:89], v[18:21], v[50:53], 0
	v_mfma_f32_16x16x32_bf16 v[90:93], v[10:13], v[58:61], 0
	v_mfma_f32_16x16x32_bf16 v[94:97], v[18:21], v[58:61], 0
	v_mfma_f32_16x16x32_bf16 v[98:101], v[10:13], v[66:69], 0
	v_mfma_f32_16x16x32_bf16 v[102:105], v[18:21], v[66:69], 0
	v_mfma_f32_16x16x32_bf16 v[74:77], v[14:17], v[46:49], v[74:77]
	v_mfma_f32_16x16x32_bf16 v[78:81], v[22:25], v[46:49], v[78:81]
	v_mfma_f32_16x16x32_bf16 v[82:85], v[14:17], v[54:57], v[82:85]
	v_mfma_f32_16x16x32_bf16 v[86:89], v[22:25], v[54:57], v[86:89]
	v_mfma_f32_16x16x32_bf16 v[90:93], v[14:17], v[62:65], v[90:93]
	v_mfma_f32_16x16x32_bf16 v[94:97], v[22:25], v[62:65], v[94:97]
	v_mfma_f32_16x16x32_bf16 v[98:101], v[14:17], v[70:73], v[98:101]
	v_mfma_f32_16x16x32_bf16 v[102:105], v[22:25], v[70:73], v[102:105]
	s_setprio 0
	s_setprio 1
	v_mfma_f32_16x16x32_bf16 v[106:109], v[26:29], v[42:45], 0
	v_mfma_f32_16x16x32_bf16 v[42:45], v[34:37], v[42:45], 0
	v_mfma_f32_16x16x32_bf16 v[106:109], v[30:33], v[46:49], v[106:109]
	v_mfma_f32_16x16x32_bf16 v[42:45], v[38:41], v[46:49], v[42:45]
	v_mfma_f32_16x16x32_bf16 v[46:49], v[26:29], v[50:53], 0
	v_mfma_f32_16x16x32_bf16 v[50:53], v[34:37], v[50:53], 0
	v_mfma_f32_16x16x32_bf16 v[46:49], v[30:33], v[54:57], v[46:49]
	v_mfma_f32_16x16x32_bf16 v[50:53], v[38:41], v[54:57], v[50:53]
	v_mfma_f32_16x16x32_bf16 v[54:57], v[26:29], v[58:61], 0
	v_mfma_f32_16x16x32_bf16 v[58:61], v[34:37], v[58:61], 0
	v_mfma_f32_16x16x32_bf16 v[54:57], v[30:33], v[62:65], v[54:57]
	v_mfma_f32_16x16x32_bf16 v[58:61], v[38:41], v[62:65], v[58:61]
	v_mfma_f32_16x16x32_bf16 v[62:65], v[26:29], v[66:69], 0
	v_mfma_f32_16x16x32_bf16 v[66:69], v[34:37], v[66:69], 0
	v_mfma_f32_16x16x32_bf16 v[62:65], v[30:33], v[70:73], v[62:65]
	v_mfma_f32_16x16x32_bf16 v[66:69], v[38:41], v[70:73], v[66:69]
	s_setprio 0
	s_barrier
	v_mov_b32_e32 v3, v1
	s_add_i32 s76, s76, s24
	v_lshl_add_u64 v[186:187], s[58:59], 0, v[2:3]
	v_mov_b32_e32 v5, v1
	s_add_i32 s71, s76, 0x2000
	v_lshl_add_u64 v[138:139], v[186:187], 0, s[28:29]
	s_mov_b32 m0, s76
	v_lshl_add_u64 v[188:189], s[58:59], 0, v[4:5]
	s_add_u32 s78, s58, 0x40100
	ds_read_b128 v[70:73], v8 offset:16384
	ds_read_b128 v[110:113], v8 offset:17408
	ds_read_b128 v[114:117], v8 offset:18432
	ds_read_b128 v[118:121], v8 offset:19456
	ds_read_b128 v[122:125], v8 offset:20480
	ds_read_b128 v[126:129], v8 offset:21504
	ds_read_b128 v[130:133], v8 offset:22528
	ds_read_b128 v[134:137], v8 offset:23552
	global_load_lds_dwordx4 v[138:139], off
	v_lshl_add_u64 v[138:139], v[188:189], 0, s[28:29]
	s_mov_b32 m0, s71
	s_addc_u32 s79, s59, 0
	s_add_i32 s72, s74, s24
	global_load_lds_dwordx4 v[138:139], off
	s_mov_b32 m0, s72
	s_add_i32 s74, s72, 0x2000
	global_load_lds_dwordx4 v2, s[78:79]
	s_mov_b32 m0, s74
	v_lshl_add_u64 v[196:197], s[6:7], 0, v[0:1]
	global_load_lds_dwordx4 v4, s[78:79]
	v_lshl_add_u64 v[138:139], v[196:197], 0, s[28:29]
	s_mov_b32 m0, s33
	v_lshl_add_u64 v[198:199], s[6:7], 0, v[6:7]
	global_load_lds_dwordx4 v[138:139], off
	v_lshl_add_u64 v[138:139], v[198:199], 0, s[28:29]
	s_mov_b32 m0, s39
	s_nop 0
	global_load_lds_dwordx4 v[138:139], off
	s_waitcnt vmcnt(8)
	s_waitcnt lgkmcnt(0)
	s_barrier
; #define PG8_STAGE(bufoff, gbase, voff) do { _Pragma("unroll") for (int _i = 0; _i < 2; ++_i) \
;         __builtin_amdgcn_global_load_lds((const unsigned*)((const char*)(gbase) + (voff)[_i]), (LAS unsigned*)(lds + (bufoff) + ldsw + _i * 8192), 16, 0, 0); } while (0)
; #define PG8_LDA(dst, b, h) do { _Pragma("unroll") for (int m = 0; m < 4; ++m) _Pragma("unroll") for (int k = 0; k < 2; ++k) dst[m][k] = *(const LAS bf16x8*)(lds + PG8_SA(b, h) + aoff + m * 2048 + k * 1024); } while (0)
; #define PG8_LDB(dst, b, h) do { _Pragma("unroll") for (int n = 0; n < 2; ++n) _Pragma("unroll") for (int k = 0; k < 2; ++k) dst[n][k] = *(const LAS bf16x8*)(lds + PG8_SB(b, h) + boff + n * 2048 + k * 1024); } while (0)
; #define PG8_MMA(ai, bj, At, Bt) do { __builtin_amdgcn_s_setprio(1); _Pragma("unroll") for (int m = 0; m < 4; ++m) _Pragma("unroll") for (int n = 0; n < 2; ++n) _Pragma("unroll") for (int k = 0; k < 2; ++k) \
;         acc[ai][bj][m][n] = __builtin_amdgcn_mfma_f32_16x16x32_bf16(Bt[n][k], At[m][k], acc[ai][bj][m][n], 0, 0, 0); __builtin_amdgcn_s_setprio(0); } while (0)
; #define PG8_WAIT_V(n) asm volatile("s_waitcnt vmcnt(" #n ")" ::: "memory")
; #define PG8_WAIT_L(n) asm volatile("s_waitcnt lgkmcnt(" #n ")" ::: "memory")
; #define PG8_BAR __builtin_amdgcn_s_barrier()
; #define PG8_SCHED __builtin_amdgcn_sched_barrier(0)
; template <class Epi, class Sched, bool ALIGN_EPI>
; __device__ __forceinline__ void gemm_phase(LAS unsigned char* lds, const bf16_t* Ab, const bf16_t* Bb, int lda, int ldb, int K, const Sched& S, Epi& E) {
;     ...
;             PG8_WAIT_V(8); PG8_WAIT_L(0); PG8_BAR; PG8_MMA(1, 0, At, B0); PG8_MMA(1, 1, At, B1); PG8_BAR; PG8_SCHED;
;             PG8_LDB(B0, 1, 0); PG8_LDB(B1, 1, 1); PG8_SCHED; PG8_LDA(At, 1, 0); PG8_STAGE(PG8_SA(0, 1), a2 + hstepA, voffA);
;             PG8_WAIT_V(8); PG8_WAIT_L(0); PG8_BAR; PG8_MMA(0, 0, At, B0); PG8_MMA(0, 1, At, B1); PG8_BAR; PG8_SCHED;
	s_setprio 1
	v_mfma_f32_16x16x32_bf16 v[138:141], v[10:13], v[70:73], 0
	v_mfma_f32_16x16x32_bf16 v[146:149], v[10:13], v[114:117], 0
	v_mfma_f32_16x16x32_bf16 v[154:157], v[10:13], v[122:125], 0
	v_mfma_f32_16x16x32_bf16 v[10:13], v[10:13], v[130:133], 0
	v_mfma_f32_16x16x32_bf16 v[138:141], v[14:17], v[110:113], v[138:141]
	v_mfma_f32_16x16x32_bf16 v[146:149], v[14:17], v[118:121], v[146:149]
	v_mfma_f32_16x16x32_bf16 v[154:157], v[14:17], v[126:129], v[154:157]
	v_mfma_f32_16x16x32_bf16 v[10:13], v[14:17], v[134:137], v[10:13]
	v_mfma_f32_16x16x32_bf16 v[14:17], v[18:21], v[130:133], 0
	v_mfma_f32_16x16x32_bf16 v[142:145], v[18:21], v[70:73], 0
	v_mfma_f32_16x16x32_bf16 v[150:153], v[18:21], v[114:117], 0
	v_mfma_f32_16x16x32_bf16 v[158:161], v[18:21], v[122:125], 0
	v_mfma_f32_16x16x32_bf16 v[14:17], v[22:25], v[134:137], v[14:17]
	v_mfma_f32_16x16x32_bf16 v[142:145], v[22:25], v[110:113], v[142:145]
	v_mfma_f32_16x16x32_bf16 v[150:153], v[22:25], v[118:121], v[150:153]
	v_mfma_f32_16x16x32_bf16 v[158:161], v[22:25], v[126:129], v[158:161]
	s_setprio 0
	s_setprio 1
	v_mfma_f32_16x16x32_bf16 v[18:21], v[26:29], v[70:73], 0
	v_mfma_f32_16x16x32_bf16 v[22:25], v[34:37], v[70:73], 0
	v_mfma_f32_16x16x32_bf16 v[18:21], v[30:33], v[110:113], v[18:21]
	v_mfma_f32_16x16x32_bf16 v[22:25], v[38:41], v[110:113], v[22:25]
	v_mfma_f32_16x16x32_bf16 v[70:73], v[26:29], v[114:117], 0
	v_mfma_f32_16x16x32_bf16 v[110:113], v[34:37], v[114:117], 0
	v_mfma_f32_16x16x32_bf16 v[114:117], v[26:29], v[122:125], 0
	v_mfma_f32_16x16x32_bf16 v[26:29], v[26:29], v[130:133], 0
	v_mfma_f32_16x16x32_bf16 v[70:73], v[30:33], v[118:121], v[70:73]
	v_mfma_f32_16x16x32_bf16 v[110:113], v[38:41], v[118:121], v[110:113]
	v_mfma_f32_16x16x32_bf16 v[114:117], v[30:33], v[126:129], v[114:117]
	v_mfma_f32_16x16x32_bf16 v[118:121], v[34:37], v[122:125], 0
	v_mfma_f32_16x16x32_bf16 v[26:29], v[30:33], v[134:137], v[26:29]
	v_mfma_f32_16x16x32_bf16 v[30:33], v[34:37], v[130:133], 0
	v_mfma_f32_16x16x32_bf16 v[118:121], v[38:41], v[126:129], v[118:121]
	v_mfma_f32_16x16x32_bf16 v[30:33], v[38:41], v[134:137], v[30:33]
	s_setprio 0
	s_barrier
	ds_read_b128 v[34:37], v204
	ds_read_b128 v[38:41], v204 offset:1024
	ds_read_b128 v[122:125], v204 offset:2048
	ds_read_b128 v[126:129], v204 offset:3072
	ds_read_b128 v[130:133], v220
	ds_read_b128 v[134:137], v220 offset:1024
	ds_read_b128 v[162:165], v220 offset:2048
	ds_read_b128 v[166:169], v220 offset:3072
	s_add_u32 s78, s6, 0x40100
	s_addc_u32 s79, s7, 0
	s_mov_b32 m0, s44
	ds_read_b128 v[170:173], v8 offset:32768
	ds_read_b128 v[174:177], v8 offset:33792
	ds_read_b128 v[178:181], v8 offset:34816
	ds_read_b128 v[182:185], v8 offset:35840
	ds_read_b128 v[200:203], v8 offset:36864
	ds_read_b128 v[206:209], v8 offset:37888
	ds_read_b128 v[210:213], v8 offset:38912
	ds_read_b128 v[238:241], v8 offset:39936
	global_load_lds_dwordx4 v0, s[78:79]
	s_mov_b32 m0, s45
	s_nop 0
	global_load_lds_dwordx4 v6, s[78:79]
	s_waitcnt vmcnt(8)
	s_waitcnt lgkmcnt(0)
	s_barrier
	s_setprio 1
	v_mfma_f32_16x16x32_bf16 v[74:77], v[34:37], v[170:173], v[74:77]
	v_mfma_f32_16x16x32_bf16 v[78:81], v[122:125], v[170:173], v[78:81]
	v_mfma_f32_16x16x32_bf16 v[82:85], v[34:37], v[178:181], v[82:85]
	v_mfma_f32_16x16x32_bf16 v[86:89], v[122:125], v[178:181], v[86:89]
	v_mfma_f32_16x16x32_bf16 v[90:93], v[34:37], v[200:203], v[90:93]
	v_mfma_f32_16x16x32_bf16 v[94:97], v[122:125], v[200:203], v[94:97]
	v_mfma_f32_16x16x32_bf16 v[98:101], v[34:37], v[210:213], v[98:101]
	v_mfma_f32_16x16x32_bf16 v[102:105], v[122:125], v[210:213], v[102:105]
	v_mfma_f32_16x16x32_bf16 v[74:77], v[38:41], v[174:177], v[74:77]
	v_mfma_f32_16x16x32_bf16 v[78:81], v[126:129], v[174:177], v[78:81]
	v_mfma_f32_16x16x32_bf16 v[82:85], v[38:41], v[182:185], v[82:85]
	v_mfma_f32_16x16x32_bf16 v[86:89], v[126:129], v[182:185], v[86:89]
	v_mfma_f32_16x16x32_bf16 v[90:93], v[38:41], v[206:209], v[90:93]
	v_mfma_f32_16x16x32_bf16 v[94:97], v[126:129], v[206:209], v[94:97]
	v_mfma_f32_16x16x32_bf16 v[98:101], v[38:41], v[238:241], v[98:101]
	v_mfma_f32_16x16x32_bf16 v[102:105], v[126:129], v[238:241], v[102:105]
	s_setprio 0
	s_setprio 1
	v_mfma_f32_16x16x32_bf16 v[106:109], v[130:133], v[170:173], v[106:109]
	v_mfma_f32_16x16x32_bf16 v[42:45], v[162:165], v[170:173], v[42:45]
	v_mfma_f32_16x16x32_bf16 v[46:49], v[130:133], v[178:181], v[46:49]
	v_mfma_f32_16x16x32_bf16 v[50:53], v[162:165], v[178:181], v[50:53]
	v_mfma_f32_16x16x32_bf16 v[54:57], v[130:133], v[200:203], v[54:57]
	v_mfma_f32_16x16x32_bf16 v[58:61], v[162:165], v[200:203], v[58:61]
	v_mfma_f32_16x16x32_bf16 v[62:65], v[130:133], v[210:213], v[62:65]
	v_mfma_f32_16x16x32_bf16 v[66:69], v[162:165], v[210:213], v[66:69]
	v_mfma_f32_16x16x32_bf16 v[106:109], v[134:137], v[174:177], v[106:109]
	v_mfma_f32_16x16x32_bf16 v[42:45], v[166:169], v[174:177], v[42:45]
	v_mfma_f32_16x16x32_bf16 v[46:49], v[134:137], v[182:185], v[46:49]
	v_mfma_f32_16x16x32_bf16 v[50:53], v[166:169], v[182:185], v[50:53]
	v_mfma_f32_16x16x32_bf16 v[54:57], v[134:137], v[206:209], v[54:57]
	v_mfma_f32_16x16x32_bf16 v[58:61], v[166:169], v[206:209], v[58:61]
	v_mfma_f32_16x16x32_bf16 v[62:65], v[134:137], v[238:241], v[62:65]
	v_mfma_f32_16x16x32_bf16 v[66:69], v[166:169], v[238:241], v[66:69]
	s_setprio 0
	s_barrier
	s_add_i32 s77, s77, s24
	s_add_i32 s73, s77, 0x2000
	v_lshl_add_u64 v[186:187], v[186:187], 0, s[42:43]
	s_mov_b32 m0, s77
	s_add_u32 s78, s58, 0x40180
	ds_read_b128 v[170:173], v8 offset:49152
	ds_read_b128 v[174:177], v8 offset:50176
	ds_read_b128 v[178:181], v8 offset:51200
	ds_read_b128 v[182:185], v8 offset:52224
	ds_read_b128 v[200:203], v8 offset:53248
	ds_read_b128 v[206:209], v8 offset:54272
	ds_read_b128 v[210:213], v8 offset:55296
	ds_read_b128 v[238:241], v8 offset:56320
	global_load_lds_dwordx4 v[186:187], off
	v_lshl_add_u64 v[186:187], v[188:189], 0, s[42:43]
	s_mov_b32 m0, s73
	s_addc_u32 s79, s59, 0
	s_add_i32 s58, s75, s24
	global_load_lds_dwordx4 v[186:187], off
	s_mov_b32 m0, s58
	s_add_i32 s59, s58, 0x2000
	global_load_lds_dwordx4 v2, s[78:79]
	s_mov_b32 m0, s59
	v_lshl_add_u64 v[186:187], v[196:197], 0, s[42:43]
	global_load_lds_dwordx4 v4, s[78:79]
	s_mov_b32 m0, s63
	s_nop 0
	global_load_lds_dwordx4 v[186:187], off
	v_lshl_add_u64 v[186:187], v[198:199], 0, s[42:43]
	s_mov_b32 m0, s64
	s_nop 0
	global_load_lds_dwordx4 v[186:187], off
	s_waitcnt vmcnt(8)
	s_waitcnt lgkmcnt(0)
	s_barrier
	s_setprio 1
	v_mfma_f32_16x16x32_bf16 v[10:13], v[34:37], v[210:213], v[10:13]
	v_mfma_f32_16x16x32_bf16 v[14:17], v[122:125], v[210:213], v[14:17]
	v_mfma_f32_16x16x32_bf16 v[138:141], v[34:37], v[170:173], v[138:141]
	v_mfma_f32_16x16x32_bf16 v[142:145], v[122:125], v[170:173], v[142:145]
	v_mfma_f32_16x16x32_bf16 v[146:149], v[34:37], v[178:181], v[146:149]
	v_mfma_f32_16x16x32_bf16 v[150:153], v[122:125], v[178:181], v[150:153]
	v_mfma_f32_16x16x32_bf16 v[154:157], v[34:37], v[200:203], v[154:157]
	v_mfma_f32_16x16x32_bf16 v[158:161], v[122:125], v[200:203], v[158:161]
	v_mfma_f32_16x16x32_bf16 v[10:13], v[38:41], v[238:241], v[10:13]
	v_mfma_f32_16x16x32_bf16 v[14:17], v[126:129], v[238:241], v[14:17]
	v_mfma_f32_16x16x32_bf16 v[138:141], v[38:41], v[174:177], v[138:141]
	v_mfma_f32_16x16x32_bf16 v[142:145], v[126:129], v[174:177], v[142:145]
	v_mfma_f32_16x16x32_bf16 v[146:149], v[38:41], v[182:185], v[146:149]
	v_mfma_f32_16x16x32_bf16 v[150:153], v[126:129], v[182:185], v[150:153]
	v_mfma_f32_16x16x32_bf16 v[154:157], v[38:41], v[206:209], v[154:157]
	v_mfma_f32_16x16x32_bf16 v[158:161], v[126:129], v[206:209], v[158:161]
	s_setprio 0
	s_setprio 1
	v_mfma_f32_16x16x32_bf16 v[18:21], v[130:133], v[170:173], v[18:21]
	v_mfma_f32_16x16x32_bf16 v[22:25], v[162:165], v[170:173], v[22:25]
	v_mfma_f32_16x16x32_bf16 v[34:37], v[130:133], v[178:181], v[70:73]
	v_mfma_f32_16x16x32_bf16 v[38:41], v[162:165], v[178:181], v[110:113]
	v_mfma_f32_16x16x32_bf16 v[70:73], v[130:133], v[200:203], v[114:117]
	v_mfma_f32_16x16x32_bf16 v[110:113], v[162:165], v[200:203], v[118:121]
	v_mfma_f32_16x16x32_bf16 v[26:29], v[130:133], v[210:213], v[26:29]
	v_mfma_f32_16x16x32_bf16 v[30:33], v[162:165], v[210:213], v[30:33]
	v_mfma_f32_16x16x32_bf16 v[18:21], v[134:137], v[174:177], v[18:21]
	v_mfma_f32_16x16x32_bf16 v[22:25], v[166:169], v[174:177], v[22:25]
	v_mfma_f32_16x16x32_bf16 v[34:37], v[134:137], v[182:185], v[34:37]
	v_mfma_f32_16x16x32_bf16 v[38:41], v[166:169], v[182:185], v[38:41]
	v_mfma_f32_16x16x32_bf16 v[70:73], v[134:137], v[206:209], v[70:73]
	v_mfma_f32_16x16x32_bf16 v[110:113], v[166:169], v[206:209], v[110:113]
	v_mfma_f32_16x16x32_bf16 v[26:29], v[134:137], v[238:241], v[26:29]
	v_mfma_f32_16x16x32_bf16 v[30:33], v[166:169], v[238:241], v[30:33]
	s_setprio 0
	s_barrier
	ds_read_b128 v[114:117], v9
	ds_read_b128 v[118:121], v9 offset:1024
	ds_read_b128 v[122:125], v9 offset:2048
	ds_read_b128 v[126:129], v9 offset:3072
	ds_read_b128 v[130:133], v190
	ds_read_b128 v[134:137], v190 offset:1024
	ds_read_b128 v[162:165], v190 offset:2048
	ds_read_b128 v[166:169], v190 offset:3072
	s_add_u32 s6, s6, 0x40180
	s_addc_u32 s7, s7, 0
	s_mov_b32 m0, s17
	ds_read_b128 v[170:173], v8
	ds_read_b128 v[174:177], v8 offset:1024
	ds_read_b128 v[178:181], v8 offset:2048
	ds_read_b128 v[182:185], v8 offset:3072
	ds_read_b128 v[200:203], v8 offset:4096
	ds_read_b128 v[206:209], v8 offset:5120
	ds_read_b128 v[210:213], v8 offset:6144
	ds_read_b128 v[238:241], v8 offset:7168
	global_load_lds_dwordx4 v0, s[6:7]
	s_mov_b32 m0, s25
	s_nop 0
	global_load_lds_dwordx4 v6, s[6:7]
	s_waitcnt vmcnt(8)
	s_waitcnt lgkmcnt(0)
	s_barrier
	s_setprio 1
	v_mfma_f32_16x16x32_bf16 v[94:97], v[122:125], v[200:203], v[94:97]
	v_mfma_f32_16x16x32_bf16 v[74:77], v[114:117], v[170:173], v[74:77]
	v_mfma_f32_16x16x32_bf16 v[78:81], v[122:125], v[170:173], v[78:81]
	v_mfma_f32_16x16x32_bf16 v[82:85], v[114:117], v[178:181], v[82:85]
	v_mfma_f32_16x16x32_bf16 v[86:89], v[122:125], v[178:181], v[86:89]
	v_mfma_f32_16x16x32_bf16 v[90:93], v[114:117], v[200:203], v[90:93]
	v_mfma_f32_16x16x32_bf16 v[242:245], v[126:129], v[206:209], v[94:97]
	v_mfma_f32_16x16x32_bf16 v[94:97], v[114:117], v[210:213], v[98:101]
	v_mfma_f32_16x16x32_bf16 v[74:77], v[118:121], v[174:177], v[74:77]
	v_mfma_f32_16x16x32_bf16 v[78:81], v[126:129], v[174:177], v[78:81]
	v_mfma_f32_16x16x32_bf16 v[82:85], v[118:121], v[182:185], v[82:85]
	v_mfma_f32_16x16x32_bf16 v[86:89], v[126:129], v[182:185], v[86:89]
	v_mfma_f32_16x16x32_bf16 v[90:93], v[118:121], v[206:209], v[90:93]
	v_mfma_f32_16x16x32_bf16 v[98:101], v[118:121], v[238:241], v[94:97]
	v_mfma_f32_16x16x32_bf16 v[94:97], v[122:125], v[210:213], v[102:105]
	v_mfma_f32_16x16x32_bf16 v[246:249], v[126:129], v[238:241], v[94:97]
	s_setprio 0
	s_setprio 1
	v_mfma_f32_16x16x32_bf16 v[94:97], v[130:133], v[170:173], v[106:109]
	v_mfma_f32_16x16x32_bf16 v[42:45], v[162:165], v[170:173], v[42:45]
	v_mfma_f32_16x16x32_bf16 v[46:49], v[130:133], v[178:181], v[46:49]
	v_mfma_f32_16x16x32_bf16 v[50:53], v[162:165], v[178:181], v[50:53]
	v_mfma_f32_16x16x32_bf16 v[54:57], v[130:133], v[200:203], v[54:57]
	v_mfma_f32_16x16x32_bf16 v[58:61], v[162:165], v[200:203], v[58:61]
	v_mfma_f32_16x16x32_bf16 v[62:65], v[130:133], v[210:213], v[62:65]
	v_mfma_f32_16x16x32_bf16 v[66:69], v[162:165], v[210:213], v[66:69]
	v_mfma_f32_16x16x32_bf16 v[106:109], v[134:137], v[174:177], v[94:97]
	v_mfma_f32_16x16x32_bf16 v[42:45], v[166:169], v[174:177], v[42:45]
	v_mfma_f32_16x16x32_bf16 v[46:49], v[134:137], v[182:185], v[46:49]
	v_mfma_f32_16x16x32_bf16 v[50:53], v[166:169], v[182:185], v[50:53]
	v_mfma_f32_16x16x32_bf16 v[54:57], v[134:137], v[206:209], v[54:57]
	v_mfma_f32_16x16x32_bf16 v[58:61], v[166:169], v[206:209], v[58:61]
	v_mfma_f32_16x16x32_bf16 v[62:65], v[134:137], v[238:241], v[62:65]
	v_mfma_f32_16x16x32_bf16 v[66:69], v[166:169], v[238:241], v[66:69]
	s_setprio 0
	s_barrier
; #define PG8_STAGE(bufoff, gbase, voff) do { _Pragma("unroll") for (int _i = 0; _i < 2; ++_i) \
;         __builtin_amdgcn_global_load_lds((const unsigned*)((const char*)(gbase) + (voff)[_i]), (LAS unsigned*)(lds + (bufoff) + ldsw + _i * 8192), 16, 0, 0); } while (0)
; #define PG8_LDA(dst, b, h) do { _Pragma("unroll") for (int m = 0; m < 4; ++m) _Pragma("unroll") for (int k = 0; k < 2; ++k) dst[m][k] = *(const LAS bf16x8*)(lds + PG8_SA(b, h) + aoff + m * 2048 + k * 1024); } while (0)
; #define PG8_LDB(dst, b, h) do { _Pragma("unroll") for (int n = 0; n < 2; ++n) _Pragma("unroll") for (int k = 0; k < 2; ++k) dst[n][k] = *(const LAS bf16x8*)(lds + PG8_SB(b, h) + boff + n * 2048 + k * 1024); } while (0)
; #define PG8_MMA(ai, bj, At, Bt) do { __builtin_amdgcn_s_setprio(1); _Pragma("unroll") for (int m = 0; m < 4; ++m) _Pragma("unroll") for (int n = 0; n < 2; ++n) _Pragma("unroll") for (int k = 0; k < 2; ++k) \
;         acc[ai][bj][m][n] = __builtin_amdgcn_mfma_f32_16x16x32_bf16(Bt[n][k], At[m][k], acc[ai][bj][m][n], 0, 0, 0); __builtin_amdgcn_s_setprio(0); } while (0)
; #define PG8_WAIT_V(n) asm volatile("s_waitcnt vmcnt(" #n ")" ::: "memory")
; #define PG8_WAIT_L(n) asm volatile("s_waitcnt lgkmcnt(" #n ")" ::: "memory")
; #define PG8_BAR __builtin_amdgcn_s_barrier()
; #define PG8_SCHED __builtin_amdgcn_sched_barrier(0)
; template <class Epi, class Sched, bool ALIGN_EPI>
; __device__ __forceinline__ void gemm_phase(LAS unsigned char* lds, const bf16_t* Ab, const bf16_t* Bb, int lda, int ldb, int K, const Sched& S, Epi& E) {
;     ...
;             PG8_LDB(B0, 1, 0); PG8_LDB(B1, 1, 1); PG8_SCHED; PG8_LDA(At, 1, 0); PG8_STAGE(PG8_SA(0, 1), a2 + hstepA, voffA);
;             PG8_WAIT_V(8); PG8_WAIT_L(0); PG8_BAR; PG8_MMA(0, 0, At, B0); PG8_MMA(0, 1, At, B1); PG8_BAR; PG8_SCHED;
;             PG8_LDA(At, 1, 1); PG8_STAGE(PG8_SB(1, 0), b3, voffB); PG8_STAGE(PG8_SB(1, 1), b3 + hstepB, voffB); PG8_STAGE(PG8_SA(1, 0), a3, voffA);
;             PG8_WAIT_V(8); PG8_WAIT_L(0); PG8_BAR; PG8_MMA(1, 0, At, B0); PG8_MMA(1, 1, At, B1); PG8_BAR; PG8_SCHED;
	s_mov_b32 m0, s76
	ds_read_b128 v[94:97], v8 offset:16384
	ds_read_b128 v[102:105], v8 offset:17408
	ds_read_b128 v[170:173], v8 offset:18432
	ds_read_b128 v[174:177], v8 offset:19456
	ds_read_b128 v[178:181], v8 offset:20480
	ds_read_b128 v[182:185], v8 offset:21504
	ds_read_b128 v[200:203], v8 offset:22528
	ds_read_b128 v[206:209], v8 offset:23552
	global_load_lds_dwordx4 v2, s[56:57]
	s_mov_b32 m0, s71
	s_add_u32 s6, s56, 0x40000
	global_load_lds_dwordx4 v4, s[56:57]
	s_addc_u32 s7, s57, 0
	s_mov_b32 m0, s72
	v_lshl_add_u64 v[224:225], s[56:57], 0, v[2:3]
	global_load_lds_dwordx4 v2, s[6:7]
	s_mov_b32 m0, s74
	v_lshl_add_u64 v[216:217], s[56:57], 0, v[4:5]
	global_load_lds_dwordx4 v4, s[6:7]
	s_mov_b32 m0, s33
	v_lshl_add_u64 v[190:191], s[60:61], 0, v[0:1]
	global_load_lds_dwordx4 v0, s[60:61]
	s_mov_b32 m0, s39
	v_lshl_add_u64 v[214:215], s[60:61], 0, v[6:7]
	global_load_lds_dwordx4 v6, s[60:61]
	s_waitcnt vmcnt(8)
	s_waitcnt lgkmcnt(0)
	s_barrier
	s_setprio 1
	v_mfma_f32_16x16x32_bf16 v[10:13], v[114:117], v[200:203], v[10:13]
	v_mfma_f32_16x16x32_bf16 v[138:141], v[114:117], v[94:97], v[138:141]
	v_mfma_f32_16x16x32_bf16 v[142:145], v[122:125], v[94:97], v[142:145]
	v_mfma_f32_16x16x32_bf16 v[146:149], v[114:117], v[170:173], v[146:149]
	v_mfma_f32_16x16x32_bf16 v[150:153], v[122:125], v[170:173], v[150:153]
	v_mfma_f32_16x16x32_bf16 v[154:157], v[114:117], v[178:181], v[154:157]
	v_mfma_f32_16x16x32_bf16 v[158:161], v[122:125], v[178:181], v[158:161]
	v_mfma_f32_16x16x32_bf16 v[10:13], v[118:121], v[206:209], v[10:13]
	v_mfma_f32_16x16x32_bf16 v[14:17], v[122:125], v[200:203], v[14:17]
	v_mfma_f32_16x16x32_bf16 v[138:141], v[118:121], v[102:105], v[138:141]
	v_mfma_f32_16x16x32_bf16 v[142:145], v[126:129], v[102:105], v[142:145]
	v_mfma_f32_16x16x32_bf16 v[146:149], v[118:121], v[174:177], v[146:149]
	v_mfma_f32_16x16x32_bf16 v[150:153], v[126:129], v[174:177], v[150:153]
	v_mfma_f32_16x16x32_bf16 v[154:157], v[118:121], v[182:185], v[154:157]
	v_mfma_f32_16x16x32_bf16 v[158:161], v[126:129], v[182:185], v[158:161]
	v_mfma_f32_16x16x32_bf16 v[210:213], v[126:129], v[206:209], v[14:17]
	s_setprio 0
	s_setprio 1
	v_mfma_f32_16x16x32_bf16 v[14:17], v[130:133], v[94:97], v[18:21]
	v_mfma_f32_16x16x32_bf16 v[18:21], v[134:137], v[102:105], v[14:17]
	v_mfma_f32_16x16x32_bf16 v[14:17], v[162:165], v[94:97], v[22:25]
	v_mfma_f32_16x16x32_bf16 v[238:241], v[166:169], v[102:105], v[14:17]
	v_mfma_f32_16x16x32_bf16 v[14:17], v[130:133], v[170:173], v[34:37]
	v_mfma_f32_16x16x32_bf16 v[34:37], v[134:137], v[174:177], v[14:17]
	v_mfma_f32_16x16x32_bf16 v[14:17], v[162:165], v[170:173], v[38:41]
	v_mfma_f32_16x16x32_bf16 v[170:173], v[166:169], v[174:177], v[14:17]
	v_mfma_f32_16x16x32_bf16 v[14:17], v[130:133], v[178:181], v[70:73]
	v_mfma_f32_16x16x32_bf16 v[174:177], v[134:137], v[182:185], v[14:17]
	v_mfma_f32_16x16x32_bf16 v[14:17], v[162:165], v[178:181], v[110:113]
	v_mfma_f32_16x16x32_bf16 v[178:181], v[166:169], v[182:185], v[14:17]
	v_mfma_f32_16x16x32_bf16 v[14:17], v[130:133], v[200:203], v[26:29]
	v_mfma_f32_16x16x32_bf16 v[130:133], v[134:137], v[206:209], v[14:17]
	v_mfma_f32_16x16x32_bf16 v[14:17], v[162:165], v[200:203], v[30:33]
	v_mfma_f32_16x16x32_bf16 v[134:137], v[166:169], v[206:209], v[14:17]
	s_setprio 0
	s_barrier
	s_nop 4
	ds_read_b128 v[14:17], v204
	ds_read_b128 v[26:29], v204 offset:1024
	ds_read_b128 v[162:165], v204 offset:2048
	ds_read_b128 v[166:169], v204 offset:3072
	ds_read_b128 v[182:185], v220
	ds_read_b128 v[200:203], v220 offset:1024
	ds_read_b128 v[206:209], v220 offset:2048
	ds_read_b128 v[250:253], v220 offset:3072
	s_add_u32 s6, s60, 0x40000
	s_addc_u32 s7, s61, 0
	s_mov_b32 m0, s44
	ds_read_b128 v[22:25], v8 offset:32768
	ds_read_b128 v[30:33], v8 offset:33792
	ds_read_b128 v[38:41], v8 offset:34816
	ds_read_b128 v[226:229], v8 offset:35840
	ds_read_b128 v[230:233], v8 offset:36864
	ds_read_b128 v[196:199], v8 offset:37888
	ds_read_b128 v[220:223], v8 offset:38912
	ds_read_b128 v[186:189], v8 offset:39936
	global_load_lds_dwordx4 v0, s[6:7]
	s_mov_b32 m0, s45
	s_nop 0
	global_load_lds_dwordx4 v6, s[6:7]
	s_waitcnt vmcnt(8)
	s_waitcnt lgkmcnt(0)
	s_barrier
; #define PG8_MMA(ai, bj, At, Bt) do { __builtin_amdgcn_s_setprio(1); _Pragma("unroll") for (int m = 0; m < 4; ++m) _Pragma("unroll") for (int n = 0; n < 2; ++n) _Pragma("unroll") for (int k = 0; k < 2; ++k) \
;         acc[ai][bj][m][n] = __builtin_amdgcn_mfma_f32_16x16x32_bf16(Bt[n][k], At[m][k], acc[ai][bj][m][n], 0, 0, 0); __builtin_amdgcn_s_setprio(0); } while (0)
; #define PG8_WAIT_V(n) asm volatile("s_waitcnt vmcnt(" #n ")" ::: "memory")
; #define PG8_WAIT_L(n) asm volatile("s_waitcnt lgkmcnt(" #n ")" ::: "memory")
; #define PG8_BAR __builtin_amdgcn_s_barrier()
; #define PG8_SCHED __builtin_amdgcn_sched_barrier(0)
; template <class Epi, class Sched, bool ALIGN_EPI>
; __device__ __forceinline__ void gemm_phase(LAS unsigned char* lds, const bf16_t* Ab, const bf16_t* Bb, int lda, int ldb, int K, const Sched& S, Epi& E) {
;     ...
;             PG8_WAIT_V(8); PG8_WAIT_L(0); PG8_BAR; PG8_MMA(1, 0, At, B0); PG8_MMA(1, 1, At, B1); PG8_BAR; PG8_SCHED;
;         }
;         if constexpr (ALIGN_EPI) { if (wr == 0) PG8_BAR; }
	s_setprio 1
	v_mfma_f32_16x16x32_bf16 v[70:73], v[14:17], v[22:25], v[74:77]
	v_mfma_f32_16x16x32_bf16 v[126:129], v[26:29], v[30:33], v[70:73]
	v_mfma_f32_16x16x32_bf16 v[70:73], v[162:165], v[22:25], v[78:81]
	v_mfma_f32_16x16x32_bf16 v[118:121], v[166:169], v[30:33], v[70:73]
	v_mfma_f32_16x16x32_bf16 v[70:73], v[14:17], v[38:41], v[82:85]
	v_mfma_f32_16x16x32_bf16 v[110:113], v[26:29], v[226:229], v[70:73]
	v_mfma_f32_16x16x32_bf16 v[70:73], v[162:165], v[38:41], v[86:89]
	v_mfma_f32_16x16x32_bf16 v[102:105], v[166:169], v[226:229], v[70:73]
	v_mfma_f32_16x16x32_bf16 v[70:73], v[14:17], v[230:233], v[90:93]
	v_mfma_f32_16x16x32_bf16 v[94:97], v[26:29], v[196:199], v[70:73]
	v_mfma_f32_16x16x32_bf16 v[70:73], v[162:165], v[230:233], v[242:245]
	v_mfma_f32_16x16x32_bf16 v[86:89], v[166:169], v[196:199], v[70:73]
	v_mfma_f32_16x16x32_bf16 v[70:73], v[14:17], v[220:223], v[98:101]
	v_mfma_f32_16x16x32_bf16 v[78:81], v[26:29], v[186:189], v[70:73]
	v_mfma_f32_16x16x32_bf16 v[70:73], v[162:165], v[220:223], v[246:249]
	v_mfma_f32_16x16x32_bf16 v[70:73], v[166:169], v[186:189], v[70:73]
	s_setprio 0
	s_setprio 1
	v_mfma_f32_16x16x32_bf16 v[74:77], v[182:185], v[22:25], v[106:109]
	v_mfma_f32_16x16x32_bf16 v[22:25], v[206:209], v[22:25], v[42:45]
	v_mfma_f32_16x16x32_bf16 v[114:117], v[250:253], v[30:33], v[22:25]
	v_mfma_f32_16x16x32_bf16 v[22:25], v[182:185], v[38:41], v[46:49]
	v_mfma_f32_16x16x32_bf16 v[106:109], v[200:203], v[226:229], v[22:25]
	v_mfma_f32_16x16x32_bf16 v[22:25], v[206:209], v[38:41], v[50:53]
	v_mfma_f32_16x16x32_bf16 v[98:101], v[250:253], v[226:229], v[22:25]
	v_mfma_f32_16x16x32_bf16 v[22:25], v[182:185], v[230:233], v[54:57]
	v_mfma_f32_16x16x32_bf16 v[90:93], v[200:203], v[196:199], v[22:25]
	v_mfma_f32_16x16x32_bf16 v[22:25], v[206:209], v[230:233], v[58:61]
	v_mfma_f32_16x16x32_bf16 v[82:85], v[250:253], v[196:199], v[22:25]
	v_mfma_f32_16x16x32_bf16 v[22:25], v[182:185], v[220:223], v[62:65]
	v_mfma_f32_16x16x32_bf16 v[122:125], v[200:203], v[30:33], v[74:77]
	v_mfma_f32_16x16x32_bf16 v[74:77], v[200:203], v[186:189], v[22:25]
	v_mfma_f32_16x16x32_bf16 v[22:25], v[206:209], v[220:223], v[66:69]
	v_mfma_f32_16x16x32_bf16 v[62:65], v[250:253], v[186:189], v[22:25]
	s_setprio 0
	s_barrier
	s_mov_b32 m0, s77
	v_lshl_add_u64 v[6:7], v[224:225], 0, s[26:27]
	ds_read_b128 v[42:45], v8 offset:49152
	ds_read_b128 v[50:53], v8 offset:50176
	ds_read_b128 v[186:189], v8 offset:51200
	ds_read_b128 v[196:199], v8 offset:52224
	ds_read_b128 v[220:223], v8 offset:53248
	ds_read_b128 v[226:229], v8 offset:54272
	ds_read_b128 v[230:233], v8 offset:55296
	ds_read_b128 v[242:245], v8 offset:56320
	global_load_lds_dwordx4 v[6:7], off
	v_lshl_add_u64 v[6:7], v[216:217], 0, s[26:27]
	s_mov_b32 m0, s73
	s_add_u32 s6, s56, 0x40080
	global_load_lds_dwordx4 v[6:7], off
	s_addc_u32 s7, s57, 0
	s_mov_b32 m0, s58
	s_nop 0
	global_load_lds_dwordx4 v2, s[6:7]
	s_mov_b32 m0, s59
	v_lshl_add_u64 v[2:3], v[190:191], 0, s[26:27]
	global_load_lds_dwordx4 v4, s[6:7]
	s_mov_b32 m0, s63
	s_nop 0
	global_load_lds_dwordx4 v[2:3], off
	v_lshl_add_u64 v[2:3], v[214:215], 0, s[26:27]
	s_mov_b32 m0, s64
	s_nop 0
	global_load_lds_dwordx4 v[2:3], off
	s_waitcnt vmcnt(8)
	s_waitcnt lgkmcnt(0)
	s_barrier
	s_setprio 1
	v_mfma_f32_16x16x32_bf16 v[2:5], v[14:17], v[42:45], v[138:141]
	v_mfma_f32_16x16x32_bf16 v[66:69], v[26:29], v[50:53], v[2:5]
	v_mfma_f32_16x16x32_bf16 v[2:5], v[162:165], v[42:45], v[142:145]
	v_mfma_f32_16x16x32_bf16 v[54:57], v[166:169], v[50:53], v[2:5]
	v_mfma_f32_16x16x32_bf16 v[2:5], v[14:17], v[186:189], v[146:149]
	v_mfma_f32_16x16x32_bf16 v[46:49], v[26:29], v[196:199], v[2:5]
	v_mfma_f32_16x16x32_bf16 v[2:5], v[162:165], v[186:189], v[150:153]
	v_mfma_f32_16x16x32_bf16 v[38:41], v[166:169], v[196:199], v[2:5]
	v_mfma_f32_16x16x32_bf16 v[2:5], v[14:17], v[220:223], v[154:157]
	v_mfma_f32_16x16x32_bf16 v[30:33], v[26:29], v[226:229], v[2:5]
	v_mfma_f32_16x16x32_bf16 v[2:5], v[162:165], v[220:223], v[158:161]
	v_mfma_f32_16x16x32_bf16 v[22:25], v[166:169], v[226:229], v[2:5]
	v_mfma_f32_16x16x32_bf16 v[2:5], v[14:17], v[230:233], v[10:13]
	v_mfma_f32_16x16x32_bf16 v[14:17], v[26:29], v[242:245], v[2:5]
	v_mfma_f32_16x16x32_bf16 v[2:5], v[162:165], v[230:233], v[210:213]
	v_mfma_f32_16x16x32_bf16 v[6:9], v[166:169], v[242:245], v[2:5]
	s_setprio 0
	s_setprio 1
	v_mfma_f32_16x16x32_bf16 v[2:5], v[182:185], v[42:45], v[18:21]
	v_mfma_f32_16x16x32_bf16 v[58:61], v[200:203], v[50:53], v[2:5]
	v_mfma_f32_16x16x32_bf16 v[2:5], v[206:209], v[42:45], v[238:241]
	v_mfma_f32_16x16x32_bf16 v[50:53], v[250:253], v[50:53], v[2:5]
	v_mfma_f32_16x16x32_bf16 v[2:5], v[182:185], v[186:189], v[34:37]
	v_mfma_f32_16x16x32_bf16 v[42:45], v[200:203], v[196:199], v[2:5]
	v_mfma_f32_16x16x32_bf16 v[2:5], v[206:209], v[186:189], v[170:173]
	v_mfma_f32_16x16x32_bf16 v[34:37], v[250:253], v[196:199], v[2:5]
	v_mfma_f32_16x16x32_bf16 v[2:5], v[182:185], v[220:223], v[174:177]
	v_mfma_f32_16x16x32_bf16 v[26:29], v[200:203], v[226:229], v[2:5]
	v_mfma_f32_16x16x32_bf16 v[2:5], v[206:209], v[220:223], v[178:181]
	v_mfma_f32_16x16x32_bf16 v[18:21], v[250:253], v[226:229], v[2:5]
	v_mfma_f32_16x16x32_bf16 v[2:5], v[182:185], v[230:233], v[130:133]
	v_mfma_f32_16x16x32_bf16 v[10:13], v[200:203], v[242:245], v[2:5]
	v_mfma_f32_16x16x32_bf16 v[2:5], v[206:209], v[230:233], v[134:137]
	v_mfma_f32_16x16x32_bf16 v[2:5], v[250:253], v[242:245], v[2:5]
	s_setprio 0
	s_barrier
	s_andn2_b64 vcc, exec, s[12:13]
	s_cbranch_vccnz .LBB0_1717
	s_barrier

; #define PG8_STAGE(bufoff, gbase, voff) do { _Pragma("unroll") for (int _i = 0; _i < 2; ++_i) \
;         __builtin_amdgcn_global_load_lds((const unsigned*)((const char*)(gbase) + (voff)[_i]), (LAS unsigned*)(lds + (bufoff) + ldsw + _i * 8192), 16, 0, 0); } while (0)
; #define PG8_LDA(dst, b, h) do { _Pragma("unroll") for (int m = 0; m < 4; ++m) _Pragma("unroll") for (int k = 0; k < 2; ++k) dst[m][k] = *(const LAS bf16x8*)(lds + PG8_SA(b, h) + aoff + m * 2048 + k * 1024); } while (0)
; #define PG8_LDB(dst, b, h) do { _Pragma("unroll") for (int n = 0; n < 2; ++n) _Pragma("unroll") for (int k = 0; k < 2; ++k) dst[n][k] = *(const LAS bf16x8*)(lds + PG8_SB(b, h) + boff + n * 2048 + k * 1024); } while (0)
; #define PG8_MMA(ai, bj, At, Bt) do { __builtin_amdgcn_s_setprio(1); _Pragma("unroll") for (int m = 0; m < 4; ++m) _Pragma("unroll") for (int n = 0; n < 2; ++n) _Pragma("unroll") for (int k = 0; k < 2; ++k) \
;         acc[ai][bj][m][n] = __builtin_amdgcn_mfma_f32_16x16x32_bf16(Bt[n][k], At[m][k], acc[ai][bj][m][n], 0, 0, 0); __builtin_amdgcn_s_setprio(0); } while (0)
; template <class Epi, class Sched, bool ALIGN_EPI>
; __device__ __forceinline__ void gemm_phase(LAS unsigned char* lds, const bf16_t* Ab, const bf16_t* Bb, int lda, int ldb, int K, const Sched& S, Epi& E) {
;     ...
;         const bool has_next = S.next(ui + 1, nxt); nxt.ui = ui + 1;
;         const char* nA = has_next ? (const char*)(Ab + nxt.a_off) : cA; const char* nB = has_next ? (const char*)(Bb + nxt.b_off) : cB;
;         for (int t = 0; t < nt; t += 2) {
;             const bool last = (t == nt - 2);
;             const char* a1 = cA + (unsigned)(t + 1) * kstep;
;             const char* a2 = last ? nA : cA + (unsigned)(t + 2) * kstep; const char* b2 = last ? nB : cB + (unsigned)(t + 2) * kstep;
;             const char* a3 = a2 + kstep; const char* b3 = b2 + kstep;
;             PG8_LDB(B0, 0, 0); PG8_LDB(B1, 0, 1); PG8_SCHED; PG8_LDA(At, 0, 0); PG8_STAGE(PG8_SA(1, 1), a1 + hstepA, voffA);
;             PG8_WAIT_V(8); PG8_WAIT_L(0); PG8_BAR; PG8_MMA(0, 0, At, B0); PG8_MMA(0, 1, At, B1); PG8_BAR; PG8_SCHED;
;             PG8_LDA(At, 0, 1); PG8_STAGE(PG8_SB(0, 0), b2, voffB); PG8_STAGE(PG8_SB(0, 1), b2 + hstepB, voffB); PG8_STAGE(PG8_SA(0, 0), a2, voffA);
;             PG8_WAIT_V(8); PG8_WAIT_L(0); PG8_BAR; PG8_MMA(1, 0, At, B0); PG8_MMA(1, 1, At, B1); PG8_BAR; PG8_SCHED;
.LBB0_1815:
	s_lshl_b64 s[12:13], s[18:19], 1
	s_add_u32 s12, s5, s12
	s_addc_u32 s13, s21, s13
	s_and_b64 s[14:15], s[16:17], exec
	s_mov_b32 s11, s19
	s_cselect_b32 s55, s13, s49
	s_cselect_b32 s54, s12, s48
	s_lshl_b64 s[14:15], s[10:11], 1
	s_add_u32 s14, s22, s14
	s_addc_u32 s15, s24, s15
	s_and_b64 s[50:51], s[16:17], exec
	s_cselect_b32 s51, s15, s53
	s_cselect_b32 s50, s14, s52
	s_add_i32 s69, 0, 0x10000
	v_add_u32_e32 v9, s69, v16
	s_add_i32 s66, 0, 0x14000
	s_add_i32 s70, 0, 0x18000
	s_add_i32 s68, 0, 0x1c000
	v_add_u32_e32 v204, s66, v16
	v_add_u32_e32 v216, s70, v16
	v_add_u32_e32 v217, s68, v16
	ds_read_b128 v[10:13], v9
	ds_read_b128 v[14:17], v9 offset:1024
	ds_read_b128 v[18:21], v9 offset:2048
	ds_read_b128 v[22:25], v9 offset:3072
	ds_read_b128 v[26:29], v204
	ds_read_b128 v[30:33], v204 offset:1024
	ds_read_b128 v[34:37], v204 offset:2048
	ds_read_b128 v[38:41], v204 offset:3072
	v_add_u32_e32 v8, s58, v7
	s_add_u32 s64, s48, 0x40080
	s_addc_u32 s65, s49, 0
	s_add_i32 s11, s31, 0xc000
	s_mov_b32 m0, s11
	s_add_i32 s63, s31, 0xe000
	ds_read_b128 v[42:45], v8
	ds_read_b128 v[46:49], v8 offset:1024
	ds_read_b128 v[50:53], v8 offset:2048
	ds_read_b128 v[54:57], v8 offset:3072
	ds_read_b128 v[58:61], v8 offset:4096
	ds_read_b128 v[62:65], v8 offset:5120
	ds_read_b128 v[66:69], v8 offset:6144
	ds_read_b128 v[70:73], v8 offset:7168
	global_load_lds_dwordx4 v0, s[64:65]
	s_mov_b32 m0, s63
	v_mov_b32_e32 v7, v1
	global_load_lds_dwordx4 v6, s[64:65]
	s_waitcnt vmcnt(8)
	s_waitcnt lgkmcnt(0)
	s_barrier
	s_setprio 1
	v_mfma_f32_16x16x32_bf16 v[74:77], v[10:13], v[42:45], 0
	v_mfma_f32_16x16x32_bf16 v[78:81], v[18:21], v[42:45], 0
	v_mfma_f32_16x16x32_bf16 v[82:85], v[10:13], v[50:53], 0
	v_mfma_f32_16x16x32_bf16 v[86:89], v[18:21], v[50:53], 0
	v_mfma_f32_16x16x32_bf16 v[90:93], v[10:13], v[58:61], 0
	v_mfma_f32_16x16x32_bf16 v[94:97], v[18:21], v[58:61], 0
	v_mfma_f32_16x16x32_bf16 v[98:101], v[10:13], v[66:69], 0
	v_mfma_f32_16x16x32_bf16 v[102:105], v[18:21], v[66:69], 0
	v_mfma_f32_16x16x32_bf16 v[74:77], v[14:17], v[46:49], v[74:77]
	v_mfma_f32_16x16x32_bf16 v[78:81], v[22:25], v[46:49], v[78:81]
	v_mfma_f32_16x16x32_bf16 v[82:85], v[14:17], v[54:57], v[82:85]
	v_mfma_f32_16x16x32_bf16 v[86:89], v[22:25], v[54:57], v[86:89]
	v_mfma_f32_16x16x32_bf16 v[90:93], v[14:17], v[62:65], v[90:93]
	v_mfma_f32_16x16x32_bf16 v[94:97], v[22:25], v[62:65], v[94:97]
	v_mfma_f32_16x16x32_bf16 v[98:101], v[14:17], v[70:73], v[98:101]
	v_mfma_f32_16x16x32_bf16 v[102:105], v[22:25], v[70:73], v[102:105]
	s_setprio 0
	s_setprio 1
	v_mfma_f32_16x16x32_bf16 v[106:109], v[26:29], v[42:45], 0
	v_mfma_f32_16x16x32_bf16 v[42:45], v[34:37], v[42:45], 0
	v_mfma_f32_16x16x32_bf16 v[106:109], v[30:33], v[46:49], v[106:109]
	v_mfma_f32_16x16x32_bf16 v[42:45], v[38:41], v[46:49], v[42:45]
	v_mfma_f32_16x16x32_bf16 v[46:49], v[26:29], v[50:53], 0
	v_mfma_f32_16x16x32_bf16 v[50:53], v[34:37], v[50:53], 0
	v_mfma_f32_16x16x32_bf16 v[46:49], v[30:33], v[54:57], v[46:49]
	v_mfma_f32_16x16x32_bf16 v[50:53], v[38:41], v[54:57], v[50:53]
	v_mfma_f32_16x16x32_bf16 v[54:57], v[26:29], v[58:61], 0
	v_mfma_f32_16x16x32_bf16 v[58:61], v[34:37], v[58:61], 0
	v_mfma_f32_16x16x32_bf16 v[54:57], v[30:33], v[62:65], v[54:57]
	v_mfma_f32_16x16x32_bf16 v[58:61], v[38:41], v[62:65], v[58:61]
	v_mfma_f32_16x16x32_bf16 v[62:65], v[26:29], v[66:69], 0
	v_mfma_f32_16x16x32_bf16 v[66:69], v[34:37], v[66:69], 0
	v_mfma_f32_16x16x32_bf16 v[62:65], v[30:33], v[70:73], v[62:65]
	v_mfma_f32_16x16x32_bf16 v[66:69], v[38:41], v[70:73], v[66:69]
	s_setprio 0
	s_barrier
	v_mov_b32_e32 v3, v1
	s_add_i32 s69, s69, s25
	v_lshl_add_u64 v[190:191], s[52:53], 0, v[2:3]
	v_mov_b32_e32 v5, v1
	s_add_i32 s64, s69, 0x2000
	v_lshl_add_u64 v[138:139], v[190:191], 0, s[28:29]
	s_mov_b32 m0, s69
	v_lshl_add_u64 v[210:211], s[52:53], 0, v[4:5]
	s_add_u32 s72, s52, 0x10100
	ds_read_b128 v[70:73], v8 offset:16384
	ds_read_b128 v[110:113], v8 offset:17408
	ds_read_b128 v[114:117], v8 offset:18432
	ds_read_b128 v[118:121], v8 offset:19456
	ds_read_b128 v[122:125], v8 offset:20480
	ds_read_b128 v[126:129], v8 offset:21504
	ds_read_b128 v[130:133], v8 offset:22528
	ds_read_b128 v[134:137], v8 offset:23552
	global_load_lds_dwordx4 v[138:139], off
	v_lshl_add_u64 v[138:139], v[210:211], 0, s[28:29]
	s_mov_b32 m0, s64
	s_addc_u32 s73, s53, 0
	s_add_i32 s65, s66, s25
	global_load_lds_dwordx4 v[138:139], off
	s_mov_b32 m0, s65
	s_add_i32 s67, s65, 0x2000
	global_load_lds_dwordx4 v2, s[72:73]
	s_mov_b32 m0, s67
	v_lshl_add_u64 v[212:213], s[48:49], 0, v[0:1]
	global_load_lds_dwordx4 v4, s[72:73]
	v_lshl_add_u64 v[138:139], v[212:213], 0, s[28:29]
	s_mov_b32 m0, s31
	v_lshl_add_u64 v[214:215], s[48:49], 0, v[6:7]
	global_load_lds_dwordx4 v[138:139], off
	v_lshl_add_u64 v[138:139], v[214:215], 0, s[28:29]
	s_mov_b32 m0, s33
	s_nop 0
	global_load_lds_dwordx4 v[138:139], off
	s_waitcnt vmcnt(8)
	s_waitcnt lgkmcnt(0)
	s_barrier
; #define PG8_STAGE(bufoff, gbase, voff) do { _Pragma("unroll") for (int _i = 0; _i < 2; ++_i) \
;         __builtin_amdgcn_global_load_lds((const unsigned*)((const char*)(gbase) + (voff)[_i]), (LAS unsigned*)(lds + (bufoff) + ldsw + _i * 8192), 16, 0, 0); } while (0)
; #define PG8_LDA(dst, b, h) do { _Pragma("unroll") for (int m = 0; m < 4; ++m) _Pragma("unroll") for (int k = 0; k < 2; ++k) dst[m][k] = *(const LAS bf16x8*)(lds + PG8_SA(b, h) + aoff + m * 2048 + k * 1024); } while (0)
; #define PG8_LDB(dst, b, h) do { _Pragma("unroll") for (int n = 0; n < 2; ++n) _Pragma("unroll") for (int k = 0; k < 2; ++k) dst[n][k] = *(const LAS bf16x8*)(lds + PG8_SB(b, h) + boff + n * 2048 + k * 1024); } while (0)
; #define PG8_MMA(ai, bj, At, Bt) do { __builtin_amdgcn_s_setprio(1); _Pragma("unroll") for (int m = 0; m < 4; ++m) _Pragma("unroll") for (int n = 0; n < 2; ++n) _Pragma("unroll") for (int k = 0; k < 2; ++k) \
;         acc[ai][bj][m][n] = __builtin_amdgcn_mfma_f32_16x16x32_bf16(Bt[n][k], At[m][k], acc[ai][bj][m][n], 0, 0, 0); __builtin_amdgcn_s_setprio(0); } while (0)
; #define PG8_WAIT_V(n) asm volatile("s_waitcnt vmcnt(" #n ")" ::: "memory")
; #define PG8_WAIT_L(n) asm volatile("s_waitcnt lgkmcnt(" #n ")" ::: "memory")
; #define PG8_BAR __builtin_amdgcn_s_barrier()
; #define PG8_SCHED __builtin_amdgcn_sched_barrier(0)
; template <class Epi, class Sched, bool ALIGN_EPI>
; __device__ __forceinline__ void gemm_phase(LAS unsigned char* lds, const bf16_t* Ab, const bf16_t* Bb, int lda, int ldb, int K, const Sched& S, Epi& E) {
;     ...
;             PG8_WAIT_V(8); PG8_WAIT_L(0); PG8_BAR; PG8_MMA(1, 0, At, B0); PG8_MMA(1, 1, At, B1); PG8_BAR; PG8_SCHED;
;             PG8_LDB(B0, 1, 0); PG8_LDB(B1, 1, 1); PG8_SCHED; PG8_LDA(At, 1, 0); PG8_STAGE(PG8_SA(0, 1), a2 + hstepA, voffA);
;             PG8_WAIT_V(8); PG8_WAIT_L(0); PG8_BAR; PG8_MMA(0, 0, At, B0); PG8_MMA(0, 1, At, B1); PG8_BAR; PG8_SCHED;
	s_setprio 1
	v_mfma_f32_16x16x32_bf16 v[138:141], v[10:13], v[70:73], 0
	v_mfma_f32_16x16x32_bf16 v[146:149], v[10:13], v[114:117], 0
	v_mfma_f32_16x16x32_bf16 v[154:157], v[10:13], v[122:125], 0
	v_mfma_f32_16x16x32_bf16 v[10:13], v[10:13], v[130:133], 0
	v_mfma_f32_16x16x32_bf16 v[138:141], v[14:17], v[110:113], v[138:141]
	v_mfma_f32_16x16x32_bf16 v[146:149], v[14:17], v[118:121], v[146:149]
	v_mfma_f32_16x16x32_bf16 v[154:157], v[14:17], v[126:129], v[154:157]
	v_mfma_f32_16x16x32_bf16 v[10:13], v[14:17], v[134:137], v[10:13]
	v_mfma_f32_16x16x32_bf16 v[14:17], v[18:21], v[130:133], 0
	v_mfma_f32_16x16x32_bf16 v[142:145], v[18:21], v[70:73], 0
	v_mfma_f32_16x16x32_bf16 v[150:153], v[18:21], v[114:117], 0
	v_mfma_f32_16x16x32_bf16 v[158:161], v[18:21], v[122:125], 0
	v_mfma_f32_16x16x32_bf16 v[14:17], v[22:25], v[134:137], v[14:17]
	v_mfma_f32_16x16x32_bf16 v[142:145], v[22:25], v[110:113], v[142:145]
	v_mfma_f32_16x16x32_bf16 v[150:153], v[22:25], v[118:121], v[150:153]
	v_mfma_f32_16x16x32_bf16 v[158:161], v[22:25], v[126:129], v[158:161]
	s_setprio 0
	s_setprio 1
	v_mfma_f32_16x16x32_bf16 v[18:21], v[26:29], v[70:73], 0
	v_mfma_f32_16x16x32_bf16 v[22:25], v[34:37], v[70:73], 0
	v_mfma_f32_16x16x32_bf16 v[18:21], v[30:33], v[110:113], v[18:21]
	v_mfma_f32_16x16x32_bf16 v[22:25], v[38:41], v[110:113], v[22:25]
	v_mfma_f32_16x16x32_bf16 v[70:73], v[26:29], v[114:117], 0
	v_mfma_f32_16x16x32_bf16 v[110:113], v[34:37], v[114:117], 0
	v_mfma_f32_16x16x32_bf16 v[114:117], v[26:29], v[122:125], 0
	v_mfma_f32_16x16x32_bf16 v[26:29], v[26:29], v[130:133], 0
	v_mfma_f32_16x16x32_bf16 v[70:73], v[30:33], v[118:121], v[70:73]
	v_mfma_f32_16x16x32_bf16 v[110:113], v[38:41], v[118:121], v[110:113]
	v_mfma_f32_16x16x32_bf16 v[114:117], v[30:33], v[126:129], v[114:117]
	v_mfma_f32_16x16x32_bf16 v[118:121], v[34:37], v[122:125], 0
	v_mfma_f32_16x16x32_bf16 v[26:29], v[30:33], v[134:137], v[26:29]
	v_mfma_f32_16x16x32_bf16 v[30:33], v[34:37], v[130:133], 0
	v_mfma_f32_16x16x32_bf16 v[118:121], v[38:41], v[126:129], v[118:121]
	v_mfma_f32_16x16x32_bf16 v[30:33], v[38:41], v[134:137], v[30:33]
	s_setprio 0
	s_barrier
	ds_read_b128 v[34:37], v216
	ds_read_b128 v[38:41], v216 offset:1024
	ds_read_b128 v[122:125], v216 offset:2048
	ds_read_b128 v[126:129], v216 offset:3072
	ds_read_b128 v[130:133], v217
	ds_read_b128 v[134:137], v217 offset:1024
	ds_read_b128 v[162:165], v217 offset:2048
	ds_read_b128 v[166:169], v217 offset:3072
	s_add_u32 s72, s48, 0x40100
	s_addc_u32 s73, s49, 0
	s_mov_b32 m0, s39
	ds_read_b128 v[170:173], v8 offset:32768
	ds_read_b128 v[174:177], v8 offset:33792
	ds_read_b128 v[178:181], v8 offset:34816
	ds_read_b128 v[182:185], v8 offset:35840
	ds_read_b128 v[186:189], v8 offset:36864
	ds_read_b128 v[196:199], v8 offset:37888
	ds_read_b128 v[200:203], v8 offset:38912
	ds_read_b128 v[206:209], v8 offset:39936
	global_load_lds_dwordx4 v0, s[72:73]
	s_mov_b32 m0, s44
	s_nop 0
	global_load_lds_dwordx4 v6, s[72:73]
	s_waitcnt vmcnt(8)
	s_waitcnt lgkmcnt(0)
	s_barrier
	s_setprio 1
	v_mfma_f32_16x16x32_bf16 v[74:77], v[34:37], v[170:173], v[74:77]
	v_mfma_f32_16x16x32_bf16 v[78:81], v[122:125], v[170:173], v[78:81]
	v_mfma_f32_16x16x32_bf16 v[82:85], v[34:37], v[178:181], v[82:85]
	v_mfma_f32_16x16x32_bf16 v[86:89], v[122:125], v[178:181], v[86:89]
	v_mfma_f32_16x16x32_bf16 v[90:93], v[34:37], v[186:189], v[90:93]
	v_mfma_f32_16x16x32_bf16 v[94:97], v[122:125], v[186:189], v[94:97]
	v_mfma_f32_16x16x32_bf16 v[98:101], v[34:37], v[200:203], v[98:101]
	v_mfma_f32_16x16x32_bf16 v[102:105], v[122:125], v[200:203], v[102:105]
	v_mfma_f32_16x16x32_bf16 v[74:77], v[38:41], v[174:177], v[74:77]
	v_mfma_f32_16x16x32_bf16 v[78:81], v[126:129], v[174:177], v[78:81]
	v_mfma_f32_16x16x32_bf16 v[82:85], v[38:41], v[182:185], v[82:85]
	v_mfma_f32_16x16x32_bf16 v[86:89], v[126:129], v[182:185], v[86:89]
	v_mfma_f32_16x16x32_bf16 v[90:93], v[38:41], v[196:199], v[90:93]
	v_mfma_f32_16x16x32_bf16 v[94:97], v[126:129], v[196:199], v[94:97]
	v_mfma_f32_16x16x32_bf16 v[98:101], v[38:41], v[206:209], v[98:101]
	v_mfma_f32_16x16x32_bf16 v[102:105], v[126:129], v[206:209], v[102:105]
	s_setprio 0
	s_setprio 1
	v_mfma_f32_16x16x32_bf16 v[106:109], v[130:133], v[170:173], v[106:109]
	v_mfma_f32_16x16x32_bf16 v[42:45], v[162:165], v[170:173], v[42:45]
	v_mfma_f32_16x16x32_bf16 v[46:49], v[130:133], v[178:181], v[46:49]
	v_mfma_f32_16x16x32_bf16 v[50:53], v[162:165], v[178:181], v[50:53]
	v_mfma_f32_16x16x32_bf16 v[54:57], v[130:133], v[186:189], v[54:57]
	v_mfma_f32_16x16x32_bf16 v[58:61], v[162:165], v[186:189], v[58:61]
	v_mfma_f32_16x16x32_bf16 v[62:65], v[130:133], v[200:203], v[62:65]
	v_mfma_f32_16x16x32_bf16 v[66:69], v[162:165], v[200:203], v[66:69]
	v_mfma_f32_16x16x32_bf16 v[106:109], v[134:137], v[174:177], v[106:109]
	v_mfma_f32_16x16x32_bf16 v[42:45], v[166:169], v[174:177], v[42:45]
	v_mfma_f32_16x16x32_bf16 v[46:49], v[134:137], v[182:185], v[46:49]
	v_mfma_f32_16x16x32_bf16 v[50:53], v[166:169], v[182:185], v[50:53]
	v_mfma_f32_16x16x32_bf16 v[54:57], v[134:137], v[196:199], v[54:57]
	v_mfma_f32_16x16x32_bf16 v[58:61], v[166:169], v[196:199], v[58:61]
	v_mfma_f32_16x16x32_bf16 v[62:65], v[134:137], v[206:209], v[62:65]
	v_mfma_f32_16x16x32_bf16 v[66:69], v[166:169], v[206:209], v[66:69]
	s_setprio 0
	s_barrier
	s_add_i32 s70, s70, s25
	s_add_i32 s66, s70, 0x2000
	v_lshl_add_u64 v[190:191], v[190:191], 0, s[42:43]
	s_mov_b32 m0, s70
	s_add_u32 s72, s52, 0x10180
	ds_read_b128 v[170:173], v8 offset:49152
	ds_read_b128 v[174:177], v8 offset:50176
	ds_read_b128 v[178:181], v8 offset:51200
	ds_read_b128 v[182:185], v8 offset:52224
	ds_read_b128 v[186:189], v8 offset:53248
	ds_read_b128 v[196:199], v8 offset:54272
	ds_read_b128 v[200:203], v8 offset:55296
	ds_read_b128 v[206:209], v8 offset:56320
	global_load_lds_dwordx4 v[190:191], off
	v_lshl_add_u64 v[190:191], v[210:211], 0, s[42:43]
	s_mov_b32 m0, s66
	s_addc_u32 s73, s53, 0
	s_add_i32 s52, s68, s25
	global_load_lds_dwordx4 v[190:191], off
	s_mov_b32 m0, s52
	s_add_i32 s53, s52, 0x2000
	global_load_lds_dwordx4 v2, s[72:73]
	s_mov_b32 m0, s53
	v_lshl_add_u64 v[190:191], v[212:213], 0, s[42:43]
	global_load_lds_dwordx4 v4, s[72:73]
	s_mov_b32 m0, s47
	s_nop 0
	global_load_lds_dwordx4 v[190:191], off
	v_lshl_add_u64 v[190:191], v[214:215], 0, s[42:43]
	s_mov_b32 m0, s56
	s_nop 0
	global_load_lds_dwordx4 v[190:191], off
	s_waitcnt vmcnt(8)
	s_waitcnt lgkmcnt(0)
	s_barrier
	s_setprio 1
	v_mfma_f32_16x16x32_bf16 v[14:17], v[122:125], v[200:203], v[14:17]
	v_mfma_f32_16x16x32_bf16 v[138:141], v[34:37], v[170:173], v[138:141]
	v_mfma_f32_16x16x32_bf16 v[142:145], v[122:125], v[170:173], v[142:145]
	v_mfma_f32_16x16x32_bf16 v[146:149], v[34:37], v[178:181], v[146:149]
	v_mfma_f32_16x16x32_bf16 v[150:153], v[122:125], v[178:181], v[150:153]
	v_mfma_f32_16x16x32_bf16 v[154:157], v[34:37], v[186:189], v[154:157]
	v_mfma_f32_16x16x32_bf16 v[158:161], v[122:125], v[186:189], v[158:161]
	v_mfma_f32_16x16x32_bf16 v[10:13], v[34:37], v[200:203], v[10:13]
	v_mfma_f32_16x16x32_bf16 v[14:17], v[126:129], v[206:209], v[14:17]
	v_mfma_f32_16x16x32_bf16 v[138:141], v[38:41], v[174:177], v[138:141]
	v_mfma_f32_16x16x32_bf16 v[142:145], v[126:129], v[174:177], v[142:145]
	v_mfma_f32_16x16x32_bf16 v[146:149], v[38:41], v[182:185], v[146:149]
	v_mfma_f32_16x16x32_bf16 v[150:153], v[126:129], v[182:185], v[150:153]
	v_mfma_f32_16x16x32_bf16 v[154:157], v[38:41], v[196:199], v[154:157]
	v_mfma_f32_16x16x32_bf16 v[158:161], v[126:129], v[196:199], v[158:161]
	v_mfma_f32_16x16x32_bf16 v[10:13], v[38:41], v[206:209], v[10:13]
	s_setprio 0
	s_setprio 1
	v_mfma_f32_16x16x32_bf16 v[18:21], v[130:133], v[170:173], v[18:21]
	v_mfma_f32_16x16x32_bf16 v[22:25], v[162:165], v[170:173], v[22:25]
	v_mfma_f32_16x16x32_bf16 v[34:37], v[130:133], v[178:181], v[70:73]
	v_mfma_f32_16x16x32_bf16 v[38:41], v[162:165], v[178:181], v[110:113]
	v_mfma_f32_16x16x32_bf16 v[70:73], v[130:133], v[186:189], v[114:117]
	v_mfma_f32_16x16x32_bf16 v[110:113], v[162:165], v[186:189], v[118:121]
	v_mfma_f32_16x16x32_bf16 v[26:29], v[130:133], v[200:203], v[26:29]
	v_mfma_f32_16x16x32_bf16 v[30:33], v[162:165], v[200:203], v[30:33]
	v_mfma_f32_16x16x32_bf16 v[18:21], v[134:137], v[174:177], v[18:21]
	v_mfma_f32_16x16x32_bf16 v[22:25], v[166:169], v[174:177], v[22:25]
	v_mfma_f32_16x16x32_bf16 v[34:37], v[134:137], v[182:185], v[34:37]
	v_mfma_f32_16x16x32_bf16 v[38:41], v[166:169], v[182:185], v[38:41]
	v_mfma_f32_16x16x32_bf16 v[70:73], v[134:137], v[196:199], v[70:73]
	v_mfma_f32_16x16x32_bf16 v[110:113], v[166:169], v[196:199], v[110:113]
	v_mfma_f32_16x16x32_bf16 v[26:29], v[134:137], v[206:209], v[26:29]
	v_mfma_f32_16x16x32_bf16 v[30:33], v[166:169], v[206:209], v[30:33]
	s_setprio 0
	s_barrier
	ds_read_b128 v[114:117], v9
	ds_read_b128 v[118:121], v9 offset:1024
	ds_read_b128 v[122:125], v9 offset:2048
	ds_read_b128 v[126:129], v9 offset:3072
	ds_read_b128 v[130:133], v204
	ds_read_b128 v[134:137], v204 offset:1024
	ds_read_b128 v[162:165], v204 offset:2048
	ds_read_b128 v[166:169], v204 offset:3072
	s_add_u32 s48, s48, 0x40180
	s_addc_u32 s49, s49, 0
	s_mov_b32 m0, s11
	ds_read_b128 v[170:173], v8
	ds_read_b128 v[174:177], v8 offset:1024
	ds_read_b128 v[178:181], v8 offset:2048
	ds_read_b128 v[182:185], v8 offset:3072
	ds_read_b128 v[186:189], v8 offset:4096
	ds_read_b128 v[196:199], v8 offset:5120
	ds_read_b128 v[200:203], v8 offset:6144
	ds_read_b128 v[206:209], v8 offset:7168
	global_load_lds_dwordx4 v0, s[48:49]
	s_mov_b32 m0, s63
	s_nop 0
	global_load_lds_dwordx4 v6, s[48:49]
	s_waitcnt vmcnt(8)
	s_waitcnt lgkmcnt(0)
	s_barrier
	s_setprio 1
	v_mfma_f32_16x16x32_bf16 v[74:77], v[114:117], v[170:173], v[74:77]
	v_mfma_f32_16x16x32_bf16 v[78:81], v[122:125], v[170:173], v[78:81]
	v_mfma_f32_16x16x32_bf16 v[82:85], v[114:117], v[178:181], v[82:85]
	v_mfma_f32_16x16x32_bf16 v[86:89], v[122:125], v[178:181], v[86:89]
	v_mfma_f32_16x16x32_bf16 v[90:93], v[114:117], v[186:189], v[90:93]
	v_mfma_f32_16x16x32_bf16 v[94:97], v[122:125], v[186:189], v[94:97]
	v_mfma_f32_16x16x32_bf16 v[98:101], v[114:117], v[200:203], v[98:101]
	v_mfma_f32_16x16x32_bf16 v[102:105], v[122:125], v[200:203], v[102:105]
	v_mfma_f32_16x16x32_bf16 v[74:77], v[118:121], v[174:177], v[74:77]
	v_mfma_f32_16x16x32_bf16 v[78:81], v[126:129], v[174:177], v[78:81]
	v_mfma_f32_16x16x32_bf16 v[82:85], v[118:121], v[182:185], v[82:85]
	v_mfma_f32_16x16x32_bf16 v[86:89], v[126:129], v[182:185], v[86:89]
	v_mfma_f32_16x16x32_bf16 v[90:93], v[118:121], v[196:199], v[90:93]
	v_mfma_f32_16x16x32_bf16 v[94:97], v[126:129], v[196:199], v[94:97]
	v_mfma_f32_16x16x32_bf16 v[98:101], v[118:121], v[206:209], v[98:101]
	v_mfma_f32_16x16x32_bf16 v[102:105], v[126:129], v[206:209], v[102:105]
	s_setprio 0
	s_setprio 1
	v_mfma_f32_16x16x32_bf16 v[106:109], v[130:133], v[170:173], v[106:109]
	v_mfma_f32_16x16x32_bf16 v[42:45], v[162:165], v[170:173], v[42:45]
	v_mfma_f32_16x16x32_bf16 v[46:49], v[130:133], v[178:181], v[46:49]
	v_mfma_f32_16x16x32_bf16 v[50:53], v[162:165], v[178:181], v[50:53]
	v_mfma_f32_16x16x32_bf16 v[54:57], v[130:133], v[186:189], v[54:57]
	v_mfma_f32_16x16x32_bf16 v[58:61], v[162:165], v[186:189], v[58:61]
	v_mfma_f32_16x16x32_bf16 v[62:65], v[130:133], v[200:203], v[62:65]
	v_mfma_f32_16x16x32_bf16 v[66:69], v[162:165], v[200:203], v[66:69]
	v_mfma_f32_16x16x32_bf16 v[106:109], v[134:137], v[174:177], v[106:109]
	v_mfma_f32_16x16x32_bf16 v[42:45], v[166:169], v[174:177], v[42:45]
	v_mfma_f32_16x16x32_bf16 v[46:49], v[134:137], v[182:185], v[46:49]
	v_mfma_f32_16x16x32_bf16 v[50:53], v[166:169], v[182:185], v[50:53]
	v_mfma_f32_16x16x32_bf16 v[54:57], v[134:137], v[196:199], v[54:57]
	v_mfma_f32_16x16x32_bf16 v[58:61], v[166:169], v[196:199], v[58:61]
	v_mfma_f32_16x16x32_bf16 v[62:65], v[134:137], v[206:209], v[62:65]
	v_mfma_f32_16x16x32_bf16 v[66:69], v[166:169], v[206:209], v[66:69]
	s_setprio 0
	s_barrier
; #define PG8_STAGE(bufoff, gbase, voff) do { _Pragma("unroll") for (int _i = 0; _i < 2; ++_i) \
;         __builtin_amdgcn_global_load_lds((const unsigned*)((const char*)(gbase) + (voff)[_i]), (LAS unsigned*)(lds + (bufoff) + ldsw + _i * 8192), 16, 0, 0); } while (0)
; #define PG8_LDA(dst, b, h) do { _Pragma("unroll") for (int m = 0; m < 4; ++m) _Pragma("unroll") for (int k = 0; k < 2; ++k) dst[m][k] = *(const LAS bf16x8*)(lds + PG8_SA(b, h) + aoff + m * 2048 + k * 1024); } while (0)
; #define PG8_LDB(dst, b, h) do { _Pragma("unroll") for (int n = 0; n < 2; ++n) _Pragma("unroll") for (int k = 0; k < 2; ++k) dst[n][k] = *(const LAS bf16x8*)(lds + PG8_SB(b, h) + boff + n * 2048 + k * 1024); } while (0)
; #define PG8_MMA(ai, bj, At, Bt) do { __builtin_amdgcn_s_setprio(1); _Pragma("unroll") for (int m = 0; m < 4; ++m) _Pragma("unroll") for (int n = 0; n < 2; ++n) _Pragma("unroll") for (int k = 0; k < 2; ++k) \
;         acc[ai][bj][m][n] = __builtin_amdgcn_mfma_f32_16x16x32_bf16(Bt[n][k], At[m][k], acc[ai][bj][m][n], 0, 0, 0); __builtin_amdgcn_s_setprio(0); } while (0)
; #define PG8_WAIT_V(n) asm volatile("s_waitcnt vmcnt(" #n ")" ::: "memory")
; #define PG8_WAIT_L(n) asm volatile("s_waitcnt lgkmcnt(" #n ")" ::: "memory")
; #define PG8_BAR __builtin_amdgcn_s_barrier()
; #define PG8_SCHED __builtin_amdgcn_sched_barrier(0)
; template <class Epi, class Sched, bool ALIGN_EPI>
; __device__ __forceinline__ void gemm_phase(LAS unsigned char* lds, const bf16_t* Ab, const bf16_t* Bb, int lda, int ldb, int K, const Sched& S, Epi& E) {
;     ...
;             PG8_LDB(B0, 1, 0); PG8_LDB(B1, 1, 1); PG8_SCHED; PG8_LDA(At, 1, 0); PG8_STAGE(PG8_SA(0, 1), a2 + hstepA, voffA);
;             PG8_WAIT_V(8); PG8_WAIT_L(0); PG8_BAR; PG8_MMA(0, 0, At, B0); PG8_MMA(0, 1, At, B1); PG8_BAR; PG8_SCHED;
;             PG8_LDA(At, 1, 1); PG8_STAGE(PG8_SB(1, 0), b3, voffB); PG8_STAGE(PG8_SB(1, 1), b3 + hstepB, voffB); PG8_STAGE(PG8_SA(1, 0), a3, voffA);
;             PG8_WAIT_V(8); PG8_WAIT_L(0); PG8_BAR; PG8_MMA(1, 0, At, B0); PG8_MMA(1, 1, At, B1); PG8_BAR; PG8_SCHED;
	s_mov_b32 m0, s69
	ds_read_b128 v[170:173], v8 offset:16384
	ds_read_b128 v[174:177], v8 offset:17408
	ds_read_b128 v[178:181], v8 offset:18432
	ds_read_b128 v[182:185], v8 offset:19456
	ds_read_b128 v[186:189], v8 offset:20480
	ds_read_b128 v[196:199], v8 offset:21504
	ds_read_b128 v[200:203], v8 offset:22528
	ds_read_b128 v[206:209], v8 offset:23552
	global_load_lds_dwordx4 v2, s[50:51]
	s_mov_b32 m0, s64
	s_add_u32 s48, s50, 0x10000
	global_load_lds_dwordx4 v4, s[50:51]
	s_addc_u32 s49, s51, 0
	s_mov_b32 m0, s65
	v_lshl_add_u64 v[190:191], s[50:51], 0, v[2:3]
	global_load_lds_dwordx4 v2, s[48:49]
	s_mov_b32 m0, s67
	v_lshl_add_u64 v[210:211], s[50:51], 0, v[4:5]
	global_load_lds_dwordx4 v4, s[48:49]
	s_mov_b32 m0, s31
	v_lshl_add_u64 v[212:213], s[54:55], 0, v[0:1]
	global_load_lds_dwordx4 v0, s[54:55]
	s_mov_b32 m0, s33
	v_lshl_add_u64 v[214:215], s[54:55], 0, v[6:7]
	global_load_lds_dwordx4 v6, s[54:55]
	s_waitcnt vmcnt(8)
	s_waitcnt lgkmcnt(0)
	s_barrier
	s_setprio 1
	v_mfma_f32_16x16x32_bf16 v[14:17], v[122:125], v[200:203], v[14:17]
	v_mfma_f32_16x16x32_bf16 v[138:141], v[114:117], v[170:173], v[138:141]
	v_mfma_f32_16x16x32_bf16 v[142:145], v[122:125], v[170:173], v[142:145]
	v_mfma_f32_16x16x32_bf16 v[146:149], v[114:117], v[178:181], v[146:149]
	v_mfma_f32_16x16x32_bf16 v[150:153], v[122:125], v[178:181], v[150:153]
	v_mfma_f32_16x16x32_bf16 v[154:157], v[114:117], v[186:189], v[154:157]
	v_mfma_f32_16x16x32_bf16 v[158:161], v[122:125], v[186:189], v[158:161]
	v_mfma_f32_16x16x32_bf16 v[10:13], v[114:117], v[200:203], v[10:13]
	v_mfma_f32_16x16x32_bf16 v[14:17], v[126:129], v[206:209], v[14:17]
	v_mfma_f32_16x16x32_bf16 v[138:141], v[118:121], v[174:177], v[138:141]
	v_mfma_f32_16x16x32_bf16 v[142:145], v[126:129], v[174:177], v[142:145]
	v_mfma_f32_16x16x32_bf16 v[146:149], v[118:121], v[182:185], v[146:149]
	v_mfma_f32_16x16x32_bf16 v[150:153], v[126:129], v[182:185], v[150:153]
	v_mfma_f32_16x16x32_bf16 v[154:157], v[118:121], v[196:199], v[154:157]
	v_mfma_f32_16x16x32_bf16 v[158:161], v[126:129], v[196:199], v[158:161]
	v_mfma_f32_16x16x32_bf16 v[10:13], v[118:121], v[206:209], v[10:13]
	s_setprio 0
	s_setprio 1
	v_mfma_f32_16x16x32_bf16 v[18:21], v[130:133], v[170:173], v[18:21]
	v_mfma_f32_16x16x32_bf16 v[22:25], v[162:165], v[170:173], v[22:25]
	v_mfma_f32_16x16x32_bf16 v[34:37], v[130:133], v[178:181], v[34:37]
	v_mfma_f32_16x16x32_bf16 v[38:41], v[162:165], v[178:181], v[38:41]
	v_mfma_f32_16x16x32_bf16 v[70:73], v[130:133], v[186:189], v[70:73]
	v_mfma_f32_16x16x32_bf16 v[110:113], v[162:165], v[186:189], v[110:113]
	v_mfma_f32_16x16x32_bf16 v[26:29], v[130:133], v[200:203], v[26:29]
	v_mfma_f32_16x16x32_bf16 v[30:33], v[162:165], v[200:203], v[30:33]
	v_mfma_f32_16x16x32_bf16 v[18:21], v[134:137], v[174:177], v[18:21]
	v_mfma_f32_16x16x32_bf16 v[22:25], v[166:169], v[174:177], v[22:25]
	v_mfma_f32_16x16x32_bf16 v[34:37], v[134:137], v[182:185], v[34:37]
	v_mfma_f32_16x16x32_bf16 v[38:41], v[166:169], v[182:185], v[38:41]
	v_mfma_f32_16x16x32_bf16 v[70:73], v[134:137], v[196:199], v[70:73]
	v_mfma_f32_16x16x32_bf16 v[110:113], v[166:169], v[196:199], v[110:113]
	v_mfma_f32_16x16x32_bf16 v[26:29], v[134:137], v[206:209], v[26:29]
	v_mfma_f32_16x16x32_bf16 v[30:33], v[166:169], v[206:209], v[30:33]
	s_setprio 0
	s_barrier
	ds_read_b128 v[114:117], v216
	ds_read_b128 v[118:121], v216 offset:1024
	ds_read_b128 v[122:125], v216 offset:2048
	ds_read_b128 v[126:129], v216 offset:3072
	ds_read_b128 v[130:133], v217
	ds_read_b128 v[134:137], v217 offset:1024
	ds_read_b128 v[162:165], v217 offset:2048
	ds_read_b128 v[166:169], v217 offset:3072
	s_add_u32 s48, s54, 0x40000
	s_addc_u32 s49, s55, 0
	s_mov_b32 m0, s39
	ds_read_b128 v[170:173], v8 offset:32768
	ds_read_b128 v[174:177], v8 offset:33792
	ds_read_b128 v[178:181], v8 offset:34816
	ds_read_b128 v[182:185], v8 offset:35840
	ds_read_b128 v[186:189], v8 offset:36864
	ds_read_b128 v[196:199], v8 offset:37888
	ds_read_b128 v[200:203], v8 offset:38912
	ds_read_b128 v[206:209], v8 offset:39936
	global_load_lds_dwordx4 v0, s[48:49]
	s_mov_b32 m0, s44
	s_nop 0
	global_load_lds_dwordx4 v6, s[48:49]
	s_waitcnt vmcnt(8)
	s_waitcnt lgkmcnt(0)
	s_barrier
	s_setprio 1
	v_mfma_f32_16x16x32_bf16 v[74:77], v[114:117], v[170:173], v[74:77]
	v_mfma_f32_16x16x32_bf16 v[78:81], v[122:125], v[170:173], v[78:81]
	v_mfma_f32_16x16x32_bf16 v[82:85], v[114:117], v[178:181], v[82:85]
	v_mfma_f32_16x16x32_bf16 v[86:89], v[122:125], v[178:181], v[86:89]
	v_mfma_f32_16x16x32_bf16 v[90:93], v[114:117], v[186:189], v[90:93]
	v_mfma_f32_16x16x32_bf16 v[94:97], v[122:125], v[186:189], v[94:97]
	v_mfma_f32_16x16x32_bf16 v[98:101], v[114:117], v[200:203], v[98:101]
	v_mfma_f32_16x16x32_bf16 v[102:105], v[122:125], v[200:203], v[102:105]
	v_mfma_f32_16x16x32_bf16 v[74:77], v[118:121], v[174:177], v[74:77]
	v_mfma_f32_16x16x32_bf16 v[78:81], v[126:129], v[174:177], v[78:81]
	v_mfma_f32_16x16x32_bf16 v[82:85], v[118:121], v[182:185], v[82:85]
	v_mfma_f32_16x16x32_bf16 v[86:89], v[126:129], v[182:185], v[86:89]
	v_mfma_f32_16x16x32_bf16 v[90:93], v[118:121], v[196:199], v[90:93]
	v_mfma_f32_16x16x32_bf16 v[94:97], v[126:129], v[196:199], v[94:97]
	v_mfma_f32_16x16x32_bf16 v[98:101], v[118:121], v[206:209], v[98:101]
	v_mfma_f32_16x16x32_bf16 v[102:105], v[126:129], v[206:209], v[102:105]
	s_setprio 0
	s_setprio 1
	v_mfma_f32_16x16x32_bf16 v[106:109], v[130:133], v[170:173], v[106:109]
	v_mfma_f32_16x16x32_bf16 v[42:45], v[162:165], v[170:173], v[42:45]
	v_mfma_f32_16x16x32_bf16 v[46:49], v[130:133], v[178:181], v[46:49]
	v_mfma_f32_16x16x32_bf16 v[50:53], v[162:165], v[178:181], v[50:53]
	v_mfma_f32_16x16x32_bf16 v[54:57], v[130:133], v[186:189], v[54:57]
	v_mfma_f32_16x16x32_bf16 v[58:61], v[162:165], v[186:189], v[58:61]
	v_mfma_f32_16x16x32_bf16 v[62:65], v[130:133], v[200:203], v[62:65]
	v_mfma_f32_16x16x32_bf16 v[66:69], v[162:165], v[200:203], v[66:69]
	v_mfma_f32_16x16x32_bf16 v[106:109], v[134:137], v[174:177], v[106:109]
	v_mfma_f32_16x16x32_bf16 v[42:45], v[166:169], v[174:177], v[42:45]
	v_mfma_f32_16x16x32_bf16 v[46:49], v[134:137], v[182:185], v[46:49]
	v_mfma_f32_16x16x32_bf16 v[50:53], v[166:169], v[182:185], v[50:53]
	v_mfma_f32_16x16x32_bf16 v[54:57], v[134:137], v[196:199], v[54:57]
	v_mfma_f32_16x16x32_bf16 v[58:61], v[166:169], v[196:199], v[58:61]
	v_mfma_f32_16x16x32_bf16 v[62:65], v[134:137], v[206:209], v[62:65]
	v_mfma_f32_16x16x32_bf16 v[66:69], v[166:169], v[206:209], v[66:69]
	s_setprio 0
	s_barrier
; __device__ __forceinline__ u32x4 pack8(f32x4 a, f32x4 b) { u32x4 w; w.x = cvtpk(a[0], a[1]); w.y = cvtpk(a[2], a[3]); w.z = cvtpk(b[0], b[1]); w.w = cvtpk(b[2], b[3]); return w; }
; #define PG8_MMA(ai, bj, At, Bt) do { __builtin_amdgcn_s_setprio(1); _Pragma("unroll") for (int m = 0; m < 4; ++m) _Pragma("unroll") for (int n = 0; n < 2; ++n) _Pragma("unroll") for (int k = 0; k < 2; ++k) \
;         acc[ai][bj][m][n] = __builtin_amdgcn_mfma_f32_16x16x32_bf16(Bt[n][k], At[m][k], acc[ai][bj][m][n], 0, 0, 0); __builtin_amdgcn_s_setprio(0); } while (0)
; #define PG8_WAIT_V(n) asm volatile("s_waitcnt vmcnt(" #n ")" ::: "memory")
; #define PG8_WAIT_L(n) asm volatile("s_waitcnt lgkmcnt(" #n ")" ::: "memory")
; #define PG8_BAR __builtin_amdgcn_s_barrier()
; #define PG8_SCHED __builtin_amdgcn_sched_barrier(0)
; template <class Epi, class Sched, bool ALIGN_EPI>
; __device__ __forceinline__ void gemm_phase(LAS unsigned char* lds, const bf16_t* Ab, const bf16_t* Bb, int lda, int ldb, int K, const Sched& S, Epi& E) {
;     ...
;             PG8_WAIT_V(8); PG8_WAIT_L(0); PG8_BAR; PG8_MMA(1, 0, At, B0); PG8_MMA(1, 1, At, B1); PG8_BAR; PG8_SCHED;
;         }
;         if constexpr (ALIGN_EPI) { if (wr == 0) PG8_BAR; }
;     __device__ __forceinline__ void operator()(AccRef acc, const Unit& u, int wr, int wc, int fr, int fq) const {
;         const int b = u.bz >> 2, h = u.bz & 3;
; #pragma unroll
;         for (int ai = 0; ai < 2; ++ai)
; #pragma unroll
;             for (int m = 0; m < 4; ++m) {
;                 const size_t row = (size_t)b * SEQ + u.pm * 256 + ai * 128 + wr * 64 + m * 16 + fr;
; #pragma unroll
;                 for (int bj = 0; bj < 2; ++bj)
;                     *(u32x4*)(O + row * D + h * 256 + bj * 128 + wc * 32 + 8 * fq) = pack8(acc[ai][bj][m][0], acc[ai][bj][m][1]);
;             }
	s_mov_b32 m0, s70
	v_lshl_add_u64 v[190:191], v[190:191], 0, s[26:27]
	ds_read_b128 v[170:173], v8 offset:49152
	ds_read_b128 v[174:177], v8 offset:50176
	ds_read_b128 v[178:181], v8 offset:51200
	ds_read_b128 v[182:185], v8 offset:52224
	ds_read_b128 v[186:189], v8 offset:53248
	ds_read_b128 v[196:199], v8 offset:54272
	ds_read_b128 v[200:203], v8 offset:55296
	ds_read_b128 v[6:9], v8 offset:56320
	global_load_lds_dwordx4 v[190:191], off
	v_lshl_add_u64 v[190:191], v[210:211], 0, s[26:27]
	s_mov_b32 m0, s66
	s_add_u32 s48, s50, 0x10080
	global_load_lds_dwordx4 v[190:191], off
	s_addc_u32 s49, s51, 0
	s_mov_b32 m0, s52
	s_nop 0
	global_load_lds_dwordx4 v2, s[48:49]
	s_mov_b32 m0, s53
	v_lshl_add_u64 v[2:3], v[212:213], 0, s[26:27]
	global_load_lds_dwordx4 v4, s[48:49]
	s_mov_b32 m0, s47
	s_nop 0
	global_load_lds_dwordx4 v[2:3], off
	v_lshl_add_u64 v[2:3], v[214:215], 0, s[26:27]
	s_mov_b32 m0, s56
	s_nop 0
	global_load_lds_dwordx4 v[2:3], off
	s_waitcnt vmcnt(8)
	s_waitcnt lgkmcnt(0)
	s_barrier
	s_setprio 1
	v_mfma_f32_16x16x32_bf16 v[2:5], v[114:117], v[170:173], v[138:141]
	v_mfma_f32_16x16x32_bf16 v[14:17], v[122:125], v[200:203], v[14:17]
	v_mfma_f32_16x16x32_bf16 v[2:5], v[118:121], v[174:177], v[2:5]
	v_mfma_f32_16x16x32_bf16 v[138:141], v[122:125], v[170:173], v[142:145]
	v_mfma_f32_16x16x32_bf16 v[142:145], v[114:117], v[178:181], v[146:149]
	v_mfma_f32_16x16x32_bf16 v[146:149], v[122:125], v[178:181], v[150:153]
	v_mfma_f32_16x16x32_bf16 v[150:153], v[114:117], v[186:189], v[154:157]
	v_mfma_f32_16x16x32_bf16 v[154:157], v[122:125], v[186:189], v[158:161]
	v_mfma_f32_16x16x32_bf16 v[10:13], v[114:117], v[200:203], v[10:13]
	v_mfma_f32_16x16x32_bf16 v[14:17], v[126:129], v[6:9], v[14:17]
	v_mfma_f32_16x16x32_bf16 v[138:141], v[126:129], v[174:177], v[138:141]
	v_mfma_f32_16x16x32_bf16 v[142:145], v[118:121], v[182:185], v[142:145]
	v_mfma_f32_16x16x32_bf16 v[146:149], v[126:129], v[182:185], v[146:149]
	v_mfma_f32_16x16x32_bf16 v[150:153], v[118:121], v[196:199], v[150:153]
	v_mfma_f32_16x16x32_bf16 v[154:157], v[126:129], v[196:199], v[154:157]
	v_mfma_f32_16x16x32_bf16 v[10:13], v[118:121], v[6:9], v[10:13]
	s_setprio 0
	s_setprio 1
	v_mfma_f32_16x16x32_bf16 v[26:29], v[130:133], v[200:203], v[26:29]
	v_mfma_f32_16x16x32_bf16 v[30:33], v[162:165], v[200:203], v[30:33]
	v_mfma_f32_16x16x32_bf16 v[18:21], v[130:133], v[170:173], v[18:21]
	v_mfma_f32_16x16x32_bf16 v[22:25], v[162:165], v[170:173], v[22:25]
	v_mfma_f32_16x16x32_bf16 v[34:37], v[130:133], v[178:181], v[34:37]
	v_mfma_f32_16x16x32_bf16 v[38:41], v[162:165], v[178:181], v[38:41]
	v_mfma_f32_16x16x32_bf16 v[70:73], v[130:133], v[186:189], v[70:73]
	v_mfma_f32_16x16x32_bf16 v[110:113], v[162:165], v[186:189], v[110:113]
	v_mfma_f32_16x16x32_bf16 v[26:29], v[134:137], v[6:9], v[26:29]
	v_mfma_f32_16x16x32_bf16 v[6:9], v[166:169], v[6:9], v[30:33]
	v_mfma_f32_16x16x32_bf16 v[18:21], v[134:137], v[174:177], v[18:21]
	v_mfma_f32_16x16x32_bf16 v[22:25], v[166:169], v[174:177], v[22:25]
	v_mfma_f32_16x16x32_bf16 v[34:37], v[134:137], v[182:185], v[34:37]
	v_mfma_f32_16x16x32_bf16 v[38:41], v[166:169], v[182:185], v[38:41]
	v_mfma_f32_16x16x32_bf16 v[70:73], v[134:137], v[196:199], v[70:73]
	v_mfma_f32_16x16x32_bf16 v[110:113], v[166:169], v[196:199], v[110:113]
	s_setprio 0
	s_barrier
	s_ashr_i32 s48, s9, 2
	s_ashr_i32 s49, s48, 31
	s_lshl_b32 s11, s62, 8
	s_lshl_b64 s[48:49], s[48:49], 13
	s_ashr_i32 s50, s11, 31
	s_add_u32 s11, s11, s45
	s_addc_u32 s50, s50, s57
	s_add_u32 s11, s11, s48
	v_mov_b32_e32 v0, v236
	s_addc_u32 s48, s50, s49
	v_mov_b32_e32 v31, s48
	v_and_or_b32 v30, v0, 15, s11
	v_lshlrev_b64 v[114:115], 11, v[30:31]
	s_lshl_b32 s9, s9, 9
	v_cvt_pk_bf16_f32 v30, v74, v75
	v_lshl_add_u64 v[74:75], s[6:7], 0, v[114:115]
	s_and_b32 s48, s9, 0x600
	s_mov_b32 s49, s19
	v_lshl_add_u64 v[74:75], v[74:75], 0, s[48:49]
	s_mov_b32 s9, s19
	v_lshl_add_u64 v[74:75], v[74:75], 0, s[8:9]
	v_and_b32_e32 v0, 48, v0
	v_cvt_pk_bf16_f32 v31, v76, v77
	v_cvt_pk_bf16_f32 v32, v78, v79
	v_cvt_pk_bf16_f32 v33, v80, v81
	v_lshl_add_u64 v[74:75], v[74:75], 0, v[0:1]
	global_store_dwordx4 v[74:75], v[30:33], off
	v_cvt_pk_bf16_f32 v2, v2, v3
	v_cvt_pk_bf16_f32 v3, v4, v5
	v_cvt_pk_bf16_f32 v32, v42, v43
	v_or_b32_e32 v42, 0x8000, v114
	v_mov_b32_e32 v43, v115
	v_lshl_add_u64 v[42:43], s[6:7], 0, v[42:43]
	v_lshl_add_u64 v[42:43], v[42:43], 0, s[48:49]
	v_cvt_pk_bf16_f32 v30, v106, v107
	v_cvt_pk_bf16_f32 v31, v108, v109
	v_cvt_pk_bf16_f32 v33, v44, v45
	v_lshl_add_u64 v[42:43], v[42:43], 0, s[8:9]
	global_store_dwordx4 v[74:75], v[30:33], off offset:256
	v_lshl_add_u64 v[42:43], v[42:43], 0, v[0:1]
	v_cvt_pk_bf16_f32 v4, v138, v139
	v_cvt_pk_bf16_f32 v30, v82, v83
	v_cvt_pk_bf16_f32 v31, v84, v85
	v_cvt_pk_bf16_f32 v32, v86, v87
	v_cvt_pk_bf16_f32 v33, v88, v89
	global_store_dwordx4 v[42:43], v[30:33], off
	v_cvt_pk_bf16_f32 v5, v140, v141
	s_nop 0
	v_cvt_pk_bf16_f32 v30, v46, v47
	v_cvt_pk_bf16_f32 v31, v48, v49
	v_cvt_pk_bf16_f32 v32, v50, v51
	v_cvt_pk_bf16_f32 v33, v52, v53
	global_store_dwordx4 v[42:43], v[30:33], off offset:256
	v_or_b32_e32 v42, 0x10000, v114
	v_mov_b32_e32 v43, v115
	v_lshl_add_u64 v[42:43], s[6:7], 0, v[42:43]
	v_lshl_add_u64 v[42:43], v[42:43], 0, s[48:49]
	v_lshl_add_u64 v[42:43], v[42:43], 0, s[8:9]
	v_cvt_pk_bf16_f32 v30, v90, v91
	v_cvt_pk_bf16_f32 v31, v92, v93
	v_cvt_pk_bf16_f32 v32, v94, v95
	v_cvt_pk_bf16_f32 v33, v96, v97
	v_lshl_add_u64 v[42:43], v[42:43], 0, v[0:1]
	global_store_dwordx4 v[42:43], v[30:33], off
; __device__ __forceinline__ u32x4 pack8(f32x4 a, f32x4 b) { u32x4 w; w.x = cvtpk(a[0], a[1]); w.y = cvtpk(a[2], a[3]); w.z = cvtpk(b[0], b[1]); w.w = cvtpk(b[2], b[3]); return w; }
; template <class Epi, class Sched, bool ALIGN_EPI>
; __device__ __forceinline__ void gemm_phase(LAS unsigned char* lds, const bf16_t* Ab, const bf16_t* Bb, int lda, int ldb, int K, const Sched& S, Epi& E) {
;     ...
;         cur = nxt; cA = nA; cB = nB; ++ui;
;         { int t3 = threadIdx.x; asm volatile("" : "+v"(t3)); PG8_LANEOFFS(t3); }
;     __device__ __forceinline__ void operator()(AccRef acc, const Unit& u, int wr, int wc, int fr, int fq) const {
;         const int b = u.bz >> 2, h = u.bz & 3;
; #pragma unroll
;         for (int ai = 0; ai < 2; ++ai)
; #pragma unroll
;             for (int m = 0; m < 4; ++m) {
;                 const size_t row = (size_t)b * SEQ + u.pm * 256 + ai * 128 + wr * 64 + m * 16 + fr;
; #pragma unroll
;                 for (int bj = 0; bj < 2; ++bj)
;                     *(u32x4*)(O + row * D + h * 256 + bj * 128 + wc * 32 + 8 * fq) = pack8(acc[ai][bj][m][0], acc[ai][bj][m][1]);
;             }
	v_or_b32_e32 v114, 0x18000, v114
	s_nop 0
	v_cvt_pk_bf16_f32 v30, v54, v55
	v_cvt_pk_bf16_f32 v31, v56, v57
	v_cvt_pk_bf16_f32 v32, v58, v59
	v_cvt_pk_bf16_f32 v33, v60, v61
	global_store_dwordx4 v[42:43], v[30:33], off offset:256
	v_lshl_add_u64 v[42:43], s[6:7], 0, v[114:115]
	v_lshl_add_u64 v[42:43], v[42:43], 0, s[48:49]
	v_lshl_add_u64 v[42:43], v[42:43], 0, s[8:9]
	v_cvt_pk_bf16_f32 v30, v98, v99
	v_cvt_pk_bf16_f32 v31, v100, v101
	v_cvt_pk_bf16_f32 v32, v102, v103
	v_cvt_pk_bf16_f32 v33, v104, v105
	v_lshl_add_u64 v[42:43], v[42:43], 0, v[0:1]
	global_store_dwordx4 v[42:43], v[30:33], off
	s_mov_b32 s9, 0x40000
	s_mov_b64 s[48:49], 0x40000
	v_cvt_pk_bf16_f32 v30, v62, v63
	v_cvt_pk_bf16_f32 v31, v64, v65
	v_cvt_pk_bf16_f32 v32, v66, v67
	v_cvt_pk_bf16_f32 v33, v68, v69
	global_store_dwordx4 v[42:43], v[30:33], off offset:256
	s_nop 1
	v_add_co_u32_e32 v32, vcc, s9, v74
	s_mov_b32 s9, 0x48000
	s_nop 0
	v_addc_co_u32_e32 v33, vcc, 0, v75, vcc
	v_lshl_add_u64 v[30:31], v[74:75], 0, s[48:49]
	global_store_dwordx4 v[32:33], v[2:5], off
	s_mov_b64 s[48:49], 0x48000
	s_nop 0
	v_cvt_pk_bf16_f32 v2, v18, v19
	v_cvt_pk_bf16_f32 v3, v20, v21
	v_cvt_pk_bf16_f32 v4, v22, v23
	v_cvt_pk_bf16_f32 v5, v24, v25
	v_add_co_u32_e32 v20, vcc, s9, v74
	global_store_dwordx4 v[30:31], v[2:5], off offset:256
	s_nop 0
	v_addc_co_u32_e32 v21, vcc, 0, v75, vcc
	v_cvt_pk_bf16_f32 v2, v142, v143
	v_cvt_pk_bf16_f32 v3, v144, v145
	v_cvt_pk_bf16_f32 v4, v146, v147
	v_cvt_pk_bf16_f32 v5, v148, v149
	s_mov_b32 s9, 0x50000
	v_lshl_add_u64 v[18:19], v[74:75], 0, s[48:49]
	global_store_dwordx4 v[20:21], v[2:5], off
	v_add_co_u32_e32 v20, vcc, s9, v74
	s_nop 0
	v_cvt_pk_bf16_f32 v2, v34, v35
	v_cvt_pk_bf16_f32 v3, v36, v37
	v_cvt_pk_bf16_f32 v4, v38, v39
	v_cvt_pk_bf16_f32 v5, v40, v41
	global_store_dwordx4 v[18:19], v[2:5], off offset:256
	s_mov_b64 s[48:49], 0x50000
	v_addc_co_u32_e32 v21, vcc, 0, v75, vcc
	v_cvt_pk_bf16_f32 v2, v150, v151
	v_cvt_pk_bf16_f32 v3, v152, v153
	v_cvt_pk_bf16_f32 v4, v154, v155
	v_cvt_pk_bf16_f32 v5, v156, v157
	v_lshl_add_u64 v[18:19], v[74:75], 0, s[48:49]
	global_store_dwordx4 v[20:21], v[2:5], off
	s_mov_b32 s9, 0x58000
	s_mov_b64 s[48:49], 0x58000
	v_cvt_pk_bf16_f32 v2, v70, v71
	v_cvt_pk_bf16_f32 v3, v72, v73
	v_cvt_pk_bf16_f32 v4, v110, v111
	v_cvt_pk_bf16_f32 v5, v112, v113
	global_store_dwordx4 v[18:19], v[2:5], off offset:256
	s_nop 1
	v_cvt_pk_bf16_f32 v3, v12, v13
	v_add_co_u32_e32 v12, vcc, s9, v74
	v_cvt_pk_bf16_f32 v2, v10, v11
	v_cvt_pk_bf16_f32 v4, v14, v15
	v_cvt_pk_bf16_f32 v5, v16, v17
	v_addc_co_u32_e32 v13, vcc, 0, v75, vcc
	v_lshl_add_u64 v[10:11], v[74:75], 0, s[48:49]
	global_store_dwordx4 v[12:13], v[2:5], off
	s_mov_b64 s[48:49], -1
	s_andn2_b64 vcc, exec, s[16:17]
	v_cvt_pk_bf16_f32 v2, v26, v27
	v_cvt_pk_bf16_f32 v3, v28, v29
	v_cvt_pk_bf16_f32 v4, v6, v7
	v_cvt_pk_bf16_f32 v5, v8, v9
	v_readfirstlane_b32 s9, v0
	global_store_dwordx4 v[10:11], v[2:5], off offset:256
	s_cbranch_vccnz .LBB0_1812
	s_nop 0
	v_mov_b32_e32 v3, v236
	s_mov_b32 s9, 0x7fffe0
	v_bfe_i32 v2, v3, 27, 1
	v_lshlrev_b32_e32 v4, 4, v3
	v_lshrrev_b32_e32 v2, 22, v2
	v_add_u32_e32 v2, v4, v2
	v_and_b32_e32 v2, 0xfffffc00, v2
	v_sub_u32_e32 v2, v4, v2
	v_lshrrev_b32_e32 v5, 4, v2
	v_bitop3_b32 v2, v5, v2, 32 bitop3:0x6c
	v_ashrrev_i32_e32 v6, 31, v2
	v_ashrrev_i32_e32 v0, 31, v3
	v_lshrrev_b32_e32 v6, 26, v6
	v_lshrrev_b32_e32 v0, 26, v0
	v_add_u32_e32 v6, v2, v6
	v_add_u32_e32 v0, v3, v0
	v_ashrrev_i32_e32 v7, 6, v6
	v_and_b32_e32 v6, 0xc0, v6
	v_ashrrev_i32_e32 v0, 6, v0
	v_sub_u32_e32 v2, v2, v6
	v_lshlrev_b32_e32 v5, 3, v0
	v_lshlrev_b32_e32 v0, 5, v0
	v_ashrrev_i16_sdwa v2, v254, sext(v2) dst_sel:DWORD dst_unused:UNUSED_PAD src0_sel:DWORD src1_sel:BYTE_0
	v_and_b32_e32 v5, -16, v5
	v_and_b32_e32 v0, 32, v0
	v_bfe_i32 v2, v2, 0, 16
	v_add_u32_e32 v5, v7, v5
	v_and_b32_e32 v7, 3, v7
	v_add_lshl_u32 v2, v0, v2, 1
	v_add_u32_e32 v4, 0x2000, v4
	v_lshlrev_b32_e32 v6, 1, v5
	v_lshrrev_b32_e32 v8, 2, v5
	v_and_or_b32 v7, v5, s9, v7
	v_lshl_add_u32 v0, v5, 11, v2
	v_ashrrev_i32_e32 v5, 31, v4
	v_lshrrev_b32_e32 v5, 22, v5
	v_and_b32_e32 v6, 24, v6
	v_and_b32_e32 v8, 4, v8
	v_add_u32_e32 v5, v4, v5
	v_or3_b32 v6, v7, v8, v6
	v_ashrrev_i32_e32 v5, 10, v5
	v_lshl_add_u32 v2, v6, 9, v2
	v_mul_i32_i24_e32 v6, 0x400, v5
	v_sub_u32_e32 v4, v4, v6
	v_lshrrev_b32_e32 v6, 4, v4
	v_bitop3_b32 v4, v6, v4, 32 bitop3:0x6c
	v_ashrrev_i32_e32 v7, 31, v4
	v_lshrrev_b32_e32 v7, 26, v7
	v_lshlrev_b32_e32 v6, 3, v5
	v_add_u32_e32 v7, v4, v7
	v_and_b32_e32 v6, -16, v6
	v_ashrrev_i32_e32 v8, 6, v7
	v_and_b32_e32 v7, 0xc0, v7
	v_add_u32_e32 v6, v8, v6
	v_sub_u32_e32 v4, v4, v7
	v_lshlrev_b32_e32 v5, 5, v5
	v_ashrrev_i16_sdwa v4, v254, sext(v4) dst_sel:DWORD dst_unused:UNUSED_PAD src0_sel:DWORD src1_sel:BYTE_0
	v_lshlrev_b32_e32 v7, 1, v6
	v_lshrrev_b32_e32 v9, 2, v6
	v_and_b32_e32 v8, 3, v8
	v_and_b32_e32 v5, 32, v5
	v_bfe_i32 v4, v4, 0, 16
	v_and_b32_e32 v7, 24, v7
	v_and_b32_e32 v9, 4, v9
	v_and_or_b32 v8, v6, s9, v8
	v_or3_b32 v7, v8, v9, v7
	v_add_lshl_u32 v4, v5, v4, 1
	v_and_b32_e32 v5, 15, v3
	v_lshl_add_u32 v6, v6, 11, v4
	v_lshl_add_u32 v4, v7, 9, v4
	v_or_b32_e32 v7, s45, v5
	v_and_b32_e32 v8, 48, v3
	v_lshlrev_b32_e32 v9, 6, v7
	v_lshlrev_b32_e32 v7, 2, v7
	v_lshlrev_b32_e32 v3, 2, v3
	v_and_b32_e32 v9, 0x3c0, v9
	v_and_b32_e32 v7, 32, v7
	v_lshl_or_b32 v5, v5, 6, v8
	v_and_b32_e32 v3, 32, v3
	v_bitop3_b32 v7, v9, v7, v8 bitop3:0x36
	v_bitop3_b32 v16, v5, s46, v3 bitop3:0xde
	s_add_i32 s9, s61, s2
	s_mov_b64 s[48:49], 0
	s_branch .LBB0_1812

; #define PG8_STAGE(bufoff, gbase, voff) do { _Pragma("unroll") for (int _i = 0; _i < 2; ++_i) \
;         __builtin_amdgcn_global_load_lds((const unsigned*)((const char*)(gbase) + (voff)[_i]), (LAS unsigned*)(lds + (bufoff) + ldsw + _i * 8192), 16, 0, 0); } while (0)
; #define PG8_LDA(dst, b, h) do { _Pragma("unroll") for (int m = 0; m < 4; ++m) _Pragma("unroll") for (int k = 0; k < 2; ++k) dst[m][k] = *(const LAS bf16x8*)(lds + PG8_SA(b, h) + aoff + m * 2048 + k * 1024); } while (0)
; #define PG8_LDB(dst, b, h) do { _Pragma("unroll") for (int n = 0; n < 2; ++n) _Pragma("unroll") for (int k = 0; k < 2; ++k) dst[n][k] = *(const LAS bf16x8*)(lds + PG8_SB(b, h) + boff + n * 2048 + k * 1024); } while (0)
; #define PG8_MMA(ai, bj, At, Bt) do { __builtin_amdgcn_s_setprio(1); _Pragma("unroll") for (int m = 0; m < 4; ++m) _Pragma("unroll") for (int n = 0; n < 2; ++n) _Pragma("unroll") for (int k = 0; k < 2; ++k) \
;         acc[ai][bj][m][n] = __builtin_amdgcn_mfma_f32_16x16x32_bf16(Bt[n][k], At[m][k], acc[ai][bj][m][n], 0, 0, 0); __builtin_amdgcn_s_setprio(0); } while (0)
; #define PG8_WAIT_V(n) asm volatile("s_waitcnt vmcnt(" #n ")" ::: "memory")
; #define PG8_WAIT_L(n) asm volatile("s_waitcnt lgkmcnt(" #n ")" ::: "memory")
; #define PG8_BAR __builtin_amdgcn_s_barrier()
; template <class Epi, class Sched, bool ALIGN_EPI>
; __device__ __forceinline__ void gemm_phase(LAS unsigned char* lds, const bf16_t* Ab, const bf16_t* Bb, int lda, int ldb, int K, const Sched& S, Epi& E) {
;     ...
;         for (int t = 0; t < nt; t += 2) {
;             const bool last = (t == nt - 2);
;             const char* a1 = cA + (unsigned)(t + 1) * kstep;
;             const char* a2 = last ? nA : cA + (unsigned)(t + 2) * kstep; const char* b2 = last ? nB : cB + (unsigned)(t + 2) * kstep;
;             const char* a3 = a2 + kstep; const char* b3 = b2 + kstep;
;             PG8_LDB(B0, 0, 0); PG8_LDB(B1, 0, 1); PG8_SCHED; PG8_LDA(At, 0, 0); PG8_STAGE(PG8_SA(1, 1), a1 + hstepA, voffA);
;             PG8_WAIT_V(8); PG8_WAIT_L(0); PG8_BAR; PG8_MMA(0, 0, At, B0); PG8_MMA(0, 1, At, B1); PG8_BAR; PG8_SCHED;
;             PG8_LDA(At, 0, 1); PG8_STAGE(PG8_SB(0, 0), b2, voffB); PG8_STAGE(PG8_SB(0, 1), b2 + hstepB, voffB); PG8_STAGE(PG8_SA(0, 0), a2, voffA);
;             PG8_WAIT_V(8); PG8_WAIT_L(0); PG8_BAR; PG8_MMA(1, 0, At, B0); PG8_MMA(1, 1, At, B1); PG8_BAR; PG8_SCHED;
.LBB0_1892:
	s_add_u32 s56, s54, 0xfffc0080
	s_addc_u32 s57, s55, -1
	s_add_i32 s77, 0, 0x10000
	s_cmp_eq_u32 s76, 12
	s_cselect_b32 s59, s17, s57
	s_cselect_b32 s58, s18, s56
	s_cselect_b32 s57, s25, s75
	s_cselect_b32 s56, s49, s74
	s_add_i32 s80, 0, 0x14000
	v_add_u32_e32 v150, s77, v136
	v_add_u32_e32 v166, s80, v136
	ds_read_b128 v[138:141], v150
	ds_read_b128 v[142:145], v150 offset:1024
	ds_read_b128 v[146:149], v150 offset:2048
	ds_read_b128 v[150:153], v150 offset:3072
	ds_read_b128 v[154:157], v166
	ds_read_b128 v[158:161], v166 offset:1024
	ds_read_b128 v[162:165], v166 offset:2048
	ds_read_b128 v[166:169], v166 offset:3072
	v_lshl_add_u64 v[190:191], s[54:55], 0, v[0:1]
	s_add_i32 m0, s33, 0xc000
	ds_read_b128 v[170:173], v137
	ds_read_b128 v[174:177], v137 offset:1024
	ds_read_b128 v[178:181], v137 offset:2048
	ds_read_b128 v[182:185], v137 offset:3072
	ds_read_b128 v[186:189], v137 offset:4096
	ds_read_b128 v[196:199], v137 offset:5120
	ds_read_b128 v[200:203], v137 offset:6144
	ds_read_b128 v[206:209], v137 offset:7168
	global_load_lds_dwordx4 v[190:191], off
	v_lshl_add_u64 v[190:191], s[54:55], 0, v[134:135]
	s_add_i32 m0, s33, 0xe000
	s_nop 0
	global_load_lds_dwordx4 v[190:191], off
	s_waitcnt vmcnt(8)
	s_waitcnt lgkmcnt(0)
	s_barrier
	s_setprio 1
	v_mfma_f32_16x16x32_bf16 v[126:129], v[138:141], v[170:173], v[126:129]
	v_mfma_f32_16x16x32_bf16 v[122:125], v[146:149], v[170:173], v[122:125]
	v_mfma_f32_16x16x32_bf16 v[110:113], v[138:141], v[178:181], v[110:113]
	v_mfma_f32_16x16x32_bf16 v[106:109], v[146:149], v[178:181], v[106:109]
	v_mfma_f32_16x16x32_bf16 v[94:97], v[138:141], v[186:189], v[94:97]
	v_mfma_f32_16x16x32_bf16 v[90:93], v[146:149], v[186:189], v[90:93]
	v_mfma_f32_16x16x32_bf16 v[78:81], v[138:141], v[200:203], v[78:81]
	v_mfma_f32_16x16x32_bf16 v[74:77], v[146:149], v[200:203], v[74:77]
	v_mfma_f32_16x16x32_bf16 v[126:129], v[142:145], v[174:177], v[126:129]
	v_mfma_f32_16x16x32_bf16 v[122:125], v[150:153], v[174:177], v[122:125]
	v_mfma_f32_16x16x32_bf16 v[110:113], v[142:145], v[182:185], v[110:113]
	v_mfma_f32_16x16x32_bf16 v[106:109], v[150:153], v[182:185], v[106:109]
	v_mfma_f32_16x16x32_bf16 v[94:97], v[142:145], v[196:199], v[94:97]
	v_mfma_f32_16x16x32_bf16 v[90:93], v[150:153], v[196:199], v[90:93]
	v_mfma_f32_16x16x32_bf16 v[78:81], v[142:145], v[206:209], v[78:81]
	v_mfma_f32_16x16x32_bf16 v[74:77], v[150:153], v[206:209], v[74:77]
	s_setprio 0
	s_setprio 1
	v_mfma_f32_16x16x32_bf16 v[118:121], v[154:157], v[170:173], v[118:121]
	v_mfma_f32_16x16x32_bf16 v[114:117], v[162:165], v[170:173], v[114:117]
	v_mfma_f32_16x16x32_bf16 v[102:105], v[154:157], v[178:181], v[102:105]
	v_mfma_f32_16x16x32_bf16 v[98:101], v[162:165], v[178:181], v[98:101]
	v_mfma_f32_16x16x32_bf16 v[86:89], v[154:157], v[186:189], v[86:89]
	v_mfma_f32_16x16x32_bf16 v[82:85], v[162:165], v[186:189], v[82:85]
	v_mfma_f32_16x16x32_bf16 v[70:73], v[154:157], v[200:203], v[70:73]
	v_mfma_f32_16x16x32_bf16 v[66:69], v[162:165], v[200:203], v[66:69]
	v_mfma_f32_16x16x32_bf16 v[118:121], v[158:161], v[174:177], v[118:121]
	v_mfma_f32_16x16x32_bf16 v[114:117], v[166:169], v[174:177], v[114:117]
	v_mfma_f32_16x16x32_bf16 v[102:105], v[158:161], v[182:185], v[102:105]
	v_mfma_f32_16x16x32_bf16 v[98:101], v[166:169], v[182:185], v[98:101]
	v_mfma_f32_16x16x32_bf16 v[86:89], v[158:161], v[196:199], v[86:89]
	v_mfma_f32_16x16x32_bf16 v[82:85], v[166:169], v[196:199], v[82:85]
	v_mfma_f32_16x16x32_bf16 v[70:73], v[158:161], v[206:209], v[70:73]
	v_mfma_f32_16x16x32_bf16 v[66:69], v[166:169], v[206:209], v[66:69]
	s_setprio 0
	s_barrier
	s_add_i32 s77, s77, s24
	v_lshl_add_u64 v[190:191], s[56:57], 0, v[130:131]
	s_mov_b32 m0, s77
	ds_read_b128 v[170:173], v137 offset:16384
	ds_read_b128 v[174:177], v137 offset:17408
	ds_read_b128 v[178:181], v137 offset:18432
	ds_read_b128 v[182:185], v137 offset:19456
	ds_read_b128 v[186:189], v137 offset:20480
	ds_read_b128 v[196:199], v137 offset:21504
	ds_read_b128 v[200:203], v137 offset:22528
	ds_read_b128 v[206:209], v137 offset:23552
	global_load_lds_dwordx4 v[190:191], off
	s_add_i32 m0, s77, 0x2000
	s_add_u32 s78, s56, 0x40000
	v_lshl_add_u64 v[210:211], s[56:57], 0, v[132:133]
	s_addc_u32 s79, s57, 0
	s_add_i32 s77, s80, s24
	global_load_lds_dwordx4 v[210:211], off
	v_lshl_add_u64 v[212:213], s[78:79], 0, v[130:131]
	s_mov_b32 m0, s77
	v_lshl_add_u64 v[214:215], s[58:59], 0, v[134:135]
	global_load_lds_dwordx4 v[212:213], off
	v_lshl_add_u64 v[212:213], s[78:79], 0, v[132:133]
	s_add_i32 m0, s77, 0x2000
	s_nop 0
	global_load_lds_dwordx4 v[212:213], off
	v_lshl_add_u64 v[212:213], s[58:59], 0, v[0:1]
	s_mov_b32 m0, s33
	s_nop 0
	global_load_lds_dwordx4 v[212:213], off
	s_mov_b32 m0, s31
	s_nop 0
	global_load_lds_dwordx4 v[214:215], off
	s_waitcnt vmcnt(8)
	s_waitcnt lgkmcnt(0)
	s_barrier
; #define PG8_STAGE(bufoff, gbase, voff) do { _Pragma("unroll") for (int _i = 0; _i < 2; ++_i) \
;         __builtin_amdgcn_global_load_lds((const unsigned*)((const char*)(gbase) + (voff)[_i]), (LAS unsigned*)(lds + (bufoff) + ldsw + _i * 8192), 16, 0, 0); } while (0)
; #define PG8_LDA(dst, b, h) do { _Pragma("unroll") for (int m = 0; m < 4; ++m) _Pragma("unroll") for (int k = 0; k < 2; ++k) dst[m][k] = *(const LAS bf16x8*)(lds + PG8_SA(b, h) + aoff + m * 2048 + k * 1024); } while (0)
; #define PG8_LDB(dst, b, h) do { _Pragma("unroll") for (int n = 0; n < 2; ++n) _Pragma("unroll") for (int k = 0; k < 2; ++k) dst[n][k] = *(const LAS bf16x8*)(lds + PG8_SB(b, h) + boff + n * 2048 + k * 1024); } while (0)
; #define PG8_MMA(ai, bj, At, Bt) do { __builtin_amdgcn_s_setprio(1); _Pragma("unroll") for (int m = 0; m < 4; ++m) _Pragma("unroll") for (int n = 0; n < 2; ++n) _Pragma("unroll") for (int k = 0; k < 2; ++k) \
;         acc[ai][bj][m][n] = __builtin_amdgcn_mfma_f32_16x16x32_bf16(Bt[n][k], At[m][k], acc[ai][bj][m][n], 0, 0, 0); __builtin_amdgcn_s_setprio(0); } while (0)
; #define PG8_WAIT_V(n) asm volatile("s_waitcnt vmcnt(" #n ")" ::: "memory")
; #define PG8_WAIT_L(n) asm volatile("s_waitcnt lgkmcnt(" #n ")" ::: "memory")
; #define PG8_BAR __builtin_amdgcn_s_barrier()
; #define PG8_SCHED __builtin_amdgcn_sched_barrier(0)
; template <class Epi, class Sched, bool ALIGN_EPI>
; __device__ __forceinline__ void gemm_phase(LAS unsigned char* lds, const bf16_t* Ab, const bf16_t* Bb, int lda, int ldb, int K, const Sched& S, Epi& E) {
;     ...
;             PG8_WAIT_V(8); PG8_WAIT_L(0); PG8_BAR; PG8_MMA(1, 0, At, B0); PG8_MMA(1, 1, At, B1); PG8_BAR; PG8_SCHED;
;             PG8_LDB(B0, 1, 0); PG8_LDB(B1, 1, 1); PG8_SCHED; PG8_LDA(At, 1, 0); PG8_STAGE(PG8_SA(0, 1), a2 + hstepA, voffA);
;             PG8_WAIT_V(8); PG8_WAIT_L(0); PG8_BAR; PG8_MMA(0, 0, At, B0); PG8_MMA(0, 1, At, B1); PG8_BAR; PG8_SCHED;
;             PG8_LDA(At, 1, 1); PG8_STAGE(PG8_SB(1, 0), b3, voffB); PG8_STAGE(PG8_SB(1, 1), b3 + hstepB, voffB); PG8_STAGE(PG8_SA(1, 0), a3, voffA);
	s_setprio 1
	v_mfma_f32_16x16x32_bf16 v[62:65], v[138:141], v[170:173], v[62:65]
	v_mfma_f32_16x16x32_bf16 v[58:61], v[146:149], v[170:173], v[58:61]
	v_mfma_f32_16x16x32_bf16 v[46:49], v[138:141], v[178:181], v[46:49]
	v_mfma_f32_16x16x32_bf16 v[42:45], v[146:149], v[178:181], v[42:45]
	v_mfma_f32_16x16x32_bf16 v[30:33], v[138:141], v[186:189], v[30:33]
	v_mfma_f32_16x16x32_bf16 v[26:29], v[146:149], v[186:189], v[26:29]
	v_mfma_f32_16x16x32_bf16 v[14:17], v[138:141], v[200:203], v[14:17]
	v_mfma_f32_16x16x32_bf16 v[10:13], v[146:149], v[200:203], v[10:13]
	v_mfma_f32_16x16x32_bf16 v[62:65], v[142:145], v[174:177], v[62:65]
	v_mfma_f32_16x16x32_bf16 v[58:61], v[150:153], v[174:177], v[58:61]
	v_mfma_f32_16x16x32_bf16 v[46:49], v[142:145], v[182:185], v[46:49]
	v_mfma_f32_16x16x32_bf16 v[42:45], v[150:153], v[182:185], v[42:45]
	v_mfma_f32_16x16x32_bf16 v[30:33], v[142:145], v[196:199], v[30:33]
	v_mfma_f32_16x16x32_bf16 v[26:29], v[150:153], v[196:199], v[26:29]
	v_mfma_f32_16x16x32_bf16 v[14:17], v[142:145], v[206:209], v[14:17]
	v_mfma_f32_16x16x32_bf16 v[10:13], v[150:153], v[206:209], v[10:13]
	s_setprio 0
	s_setprio 1
	v_mfma_f32_16x16x32_bf16 v[54:57], v[154:157], v[170:173], v[54:57]
	v_mfma_f32_16x16x32_bf16 v[50:53], v[162:165], v[170:173], v[50:53]
	v_mfma_f32_16x16x32_bf16 v[38:41], v[154:157], v[178:181], v[38:41]
	v_mfma_f32_16x16x32_bf16 v[34:37], v[162:165], v[178:181], v[34:37]
	v_mfma_f32_16x16x32_bf16 v[22:25], v[154:157], v[186:189], v[22:25]
	v_mfma_f32_16x16x32_bf16 v[18:21], v[162:165], v[186:189], v[18:21]
	v_mfma_f32_16x16x32_bf16 v[6:9], v[154:157], v[200:203], v[6:9]
	v_mfma_f32_16x16x32_bf16 v[2:5], v[162:165], v[200:203], v[2:5]
	v_mfma_f32_16x16x32_bf16 v[54:57], v[158:161], v[174:177], v[54:57]
	v_mfma_f32_16x16x32_bf16 v[50:53], v[166:169], v[174:177], v[50:53]
	v_mfma_f32_16x16x32_bf16 v[38:41], v[158:161], v[182:185], v[38:41]
	v_mfma_f32_16x16x32_bf16 v[34:37], v[166:169], v[182:185], v[34:37]
	v_mfma_f32_16x16x32_bf16 v[22:25], v[158:161], v[196:199], v[22:25]
	v_mfma_f32_16x16x32_bf16 v[18:21], v[166:169], v[196:199], v[18:21]
	v_mfma_f32_16x16x32_bf16 v[6:9], v[158:161], v[206:209], v[6:9]
	v_mfma_f32_16x16x32_bf16 v[2:5], v[166:169], v[206:209], v[2:5]
	s_setprio 0
	s_barrier
	s_add_i32 s77, 0, 0x18000
	s_add_i32 s78, 0, 0x1c000
	v_add_u32_e32 v150, s77, v136
	v_add_u32_e32 v166, s78, v136
	ds_read_b128 v[138:141], v150
	ds_read_b128 v[142:145], v150 offset:1024
	ds_read_b128 v[146:149], v150 offset:2048
	ds_read_b128 v[150:153], v150 offset:3072
	ds_read_b128 v[154:157], v166
	ds_read_b128 v[158:161], v166 offset:1024
	ds_read_b128 v[162:165], v166 offset:2048
	ds_read_b128 v[166:169], v166 offset:3072
	s_add_u32 s58, s58, 0x40000
	s_addc_u32 s59, s59, 0
	s_mov_b32 m0, s39
	v_lshl_add_u64 v[216:217], s[58:59], 0, v[0:1]
	ds_read_b128 v[170:173], v137 offset:32768
	ds_read_b128 v[174:177], v137 offset:33792
	ds_read_b128 v[178:181], v137 offset:34816
	ds_read_b128 v[182:185], v137 offset:35840
	ds_read_b128 v[186:189], v137 offset:36864
	ds_read_b128 v[196:199], v137 offset:37888
	ds_read_b128 v[200:203], v137 offset:38912
	ds_read_b128 v[206:209], v137 offset:39936
	global_load_lds_dwordx4 v[216:217], off
	v_lshl_add_u64 v[216:217], s[58:59], 0, v[134:135]
	s_mov_b32 m0, s44
	s_nop 0
	global_load_lds_dwordx4 v[216:217], off
	s_waitcnt vmcnt(8)
	s_waitcnt lgkmcnt(0)
	s_barrier
	s_setprio 1
	v_mfma_f32_16x16x32_bf16 v[126:129], v[138:141], v[170:173], v[126:129]
	v_mfma_f32_16x16x32_bf16 v[122:125], v[146:149], v[170:173], v[122:125]
	v_mfma_f32_16x16x32_bf16 v[110:113], v[138:141], v[178:181], v[110:113]
	v_mfma_f32_16x16x32_bf16 v[106:109], v[146:149], v[178:181], v[106:109]
	v_mfma_f32_16x16x32_bf16 v[94:97], v[138:141], v[186:189], v[94:97]
	v_mfma_f32_16x16x32_bf16 v[90:93], v[146:149], v[186:189], v[90:93]
	v_mfma_f32_16x16x32_bf16 v[78:81], v[138:141], v[200:203], v[78:81]
	v_mfma_f32_16x16x32_bf16 v[74:77], v[146:149], v[200:203], v[74:77]
	v_mfma_f32_16x16x32_bf16 v[126:129], v[142:145], v[174:177], v[126:129]
	v_mfma_f32_16x16x32_bf16 v[122:125], v[150:153], v[174:177], v[122:125]
	v_mfma_f32_16x16x32_bf16 v[110:113], v[142:145], v[182:185], v[110:113]
	v_mfma_f32_16x16x32_bf16 v[106:109], v[150:153], v[182:185], v[106:109]
	v_mfma_f32_16x16x32_bf16 v[94:97], v[142:145], v[196:199], v[94:97]
	v_mfma_f32_16x16x32_bf16 v[90:93], v[150:153], v[196:199], v[90:93]
	v_mfma_f32_16x16x32_bf16 v[78:81], v[142:145], v[206:209], v[78:81]
	v_mfma_f32_16x16x32_bf16 v[74:77], v[150:153], v[206:209], v[74:77]
	s_setprio 0
	s_setprio 1
	v_mfma_f32_16x16x32_bf16 v[118:121], v[154:157], v[170:173], v[118:121]
	v_mfma_f32_16x16x32_bf16 v[114:117], v[162:165], v[170:173], v[114:117]
	v_mfma_f32_16x16x32_bf16 v[102:105], v[154:157], v[178:181], v[102:105]
	v_mfma_f32_16x16x32_bf16 v[98:101], v[162:165], v[178:181], v[98:101]
	v_mfma_f32_16x16x32_bf16 v[86:89], v[154:157], v[186:189], v[86:89]
	v_mfma_f32_16x16x32_bf16 v[82:85], v[162:165], v[186:189], v[82:85]
	v_mfma_f32_16x16x32_bf16 v[70:73], v[154:157], v[200:203], v[70:73]
	v_mfma_f32_16x16x32_bf16 v[66:69], v[162:165], v[200:203], v[66:69]
	v_mfma_f32_16x16x32_bf16 v[118:121], v[158:161], v[174:177], v[118:121]
	v_mfma_f32_16x16x32_bf16 v[114:117], v[166:169], v[174:177], v[114:117]
	v_mfma_f32_16x16x32_bf16 v[102:105], v[158:161], v[182:185], v[102:105]
	v_mfma_f32_16x16x32_bf16 v[98:101], v[166:169], v[182:185], v[98:101]
	v_mfma_f32_16x16x32_bf16 v[86:89], v[158:161], v[196:199], v[86:89]
	v_mfma_f32_16x16x32_bf16 v[82:85], v[166:169], v[196:199], v[82:85]
	v_mfma_f32_16x16x32_bf16 v[70:73], v[158:161], v[206:209], v[70:73]
	v_mfma_f32_16x16x32_bf16 v[66:69], v[166:169], v[206:209], v[66:69]
	s_setprio 0
	s_barrier
; #define PG8_STAGE(bufoff, gbase, voff) do { _Pragma("unroll") for (int _i = 0; _i < 2; ++_i) \
;         __builtin_amdgcn_global_load_lds((const unsigned*)((const char*)(gbase) + (voff)[_i]), (LAS unsigned*)(lds + (bufoff) + ldsw + _i * 8192), 16, 0, 0); } while (0)
; #define PG8_LDA(dst, b, h) do { _Pragma("unroll") for (int m = 0; m < 4; ++m) _Pragma("unroll") for (int k = 0; k < 2; ++k) dst[m][k] = *(const LAS bf16x8*)(lds + PG8_SA(b, h) + aoff + m * 2048 + k * 1024); } while (0)
; #define PG8_MMA(ai, bj, At, Bt) do { __builtin_amdgcn_s_setprio(1); _Pragma("unroll") for (int m = 0; m < 4; ++m) _Pragma("unroll") for (int n = 0; n < 2; ++n) _Pragma("unroll") for (int k = 0; k < 2; ++k) \
;         acc[ai][bj][m][n] = __builtin_amdgcn_mfma_f32_16x16x32_bf16(Bt[n][k], At[m][k], acc[ai][bj][m][n], 0, 0, 0); __builtin_amdgcn_s_setprio(0); } while (0)
; #define PG8_WAIT_V(n) asm volatile("s_waitcnt vmcnt(" #n ")" ::: "memory")
; #define PG8_WAIT_L(n) asm volatile("s_waitcnt lgkmcnt(" #n ")" ::: "memory")
; #define PG8_BAR __builtin_amdgcn_s_barrier()
; #define PG8_SCHED __builtin_amdgcn_sched_barrier(0)
; template <class Epi, class Sched, bool ALIGN_EPI>
; __device__ __forceinline__ void gemm_phase(LAS unsigned char* lds, const bf16_t* Ab, const bf16_t* Bb, int lda, int ldb, int K, const Sched& S, Epi& E) {
;     ...
;             PG8_LDA(At, 1, 1); PG8_STAGE(PG8_SB(1, 0), b3, voffB); PG8_STAGE(PG8_SB(1, 1), b3 + hstepB, voffB); PG8_STAGE(PG8_SA(1, 0), a3, voffA);
;             PG8_WAIT_V(8); PG8_WAIT_L(0); PG8_BAR; PG8_MMA(1, 0, At, B0); PG8_MMA(1, 1, At, B1); PG8_BAR; PG8_SCHED;
;         }
	s_add_i32 s58, s77, s24
	v_lshl_add_u64 v[190:191], v[190:191], 0, s[26:27]
	s_mov_b32 m0, s58
	ds_read_b128 v[170:173], v137 offset:49152
	ds_read_b128 v[174:177], v137 offset:50176
	ds_read_b128 v[178:181], v137 offset:51200
	ds_read_b128 v[182:185], v137 offset:52224
	ds_read_b128 v[186:189], v137 offset:53248
	ds_read_b128 v[196:199], v137 offset:54272
	ds_read_b128 v[200:203], v137 offset:55296
	ds_read_b128 v[206:209], v137 offset:56320
	global_load_lds_dwordx4 v[190:191], off
	s_add_i32 m0, s58, 0x2000
	s_add_u32 s56, s56, 0x40080
	v_lshl_add_u64 v[190:191], v[210:211], 0, s[26:27]
	s_addc_u32 s57, s57, 0
	s_add_i32 s58, s78, s24
	global_load_lds_dwordx4 v[190:191], off
	v_lshl_add_u64 v[190:191], s[56:57], 0, v[130:131]
	s_mov_b32 m0, s58
	s_nop 0
	global_load_lds_dwordx4 v[190:191], off
	v_lshl_add_u64 v[190:191], s[56:57], 0, v[132:133]
	s_add_i32 m0, s58, 0x2000
	s_nop 0
	global_load_lds_dwordx4 v[190:191], off
	v_lshl_add_u64 v[190:191], v[212:213], 0, s[26:27]
	s_mov_b32 m0, s62
	s_nop 0
	global_load_lds_dwordx4 v[190:191], off
	v_lshl_add_u64 v[190:191], v[214:215], 0, s[26:27]
	s_mov_b32 m0, s63
	s_nop 0
	global_load_lds_dwordx4 v[190:191], off
	s_waitcnt vmcnt(8)
	s_waitcnt lgkmcnt(0)
	s_barrier
	s_setprio 1
	v_mfma_f32_16x16x32_bf16 v[62:65], v[138:141], v[170:173], v[62:65]
	v_mfma_f32_16x16x32_bf16 v[58:61], v[146:149], v[170:173], v[58:61]
	v_mfma_f32_16x16x32_bf16 v[46:49], v[138:141], v[178:181], v[46:49]
	v_mfma_f32_16x16x32_bf16 v[42:45], v[146:149], v[178:181], v[42:45]
	v_mfma_f32_16x16x32_bf16 v[30:33], v[138:141], v[186:189], v[30:33]
	v_mfma_f32_16x16x32_bf16 v[26:29], v[146:149], v[186:189], v[26:29]
	v_mfma_f32_16x16x32_bf16 v[14:17], v[138:141], v[200:203], v[14:17]
	v_mfma_f32_16x16x32_bf16 v[10:13], v[146:149], v[200:203], v[10:13]
	v_mfma_f32_16x16x32_bf16 v[62:65], v[142:145], v[174:177], v[62:65]
	v_mfma_f32_16x16x32_bf16 v[58:61], v[150:153], v[174:177], v[58:61]
	v_mfma_f32_16x16x32_bf16 v[46:49], v[142:145], v[182:185], v[46:49]
	v_mfma_f32_16x16x32_bf16 v[42:45], v[150:153], v[182:185], v[42:45]
	v_mfma_f32_16x16x32_bf16 v[30:33], v[142:145], v[196:199], v[30:33]
	v_mfma_f32_16x16x32_bf16 v[26:29], v[150:153], v[196:199], v[26:29]
	v_mfma_f32_16x16x32_bf16 v[14:17], v[142:145], v[206:209], v[14:17]
	v_mfma_f32_16x16x32_bf16 v[10:13], v[150:153], v[206:209], v[10:13]
	s_setprio 0
	s_setprio 1
	v_mfma_f32_16x16x32_bf16 v[54:57], v[154:157], v[170:173], v[54:57]
	v_mfma_f32_16x16x32_bf16 v[50:53], v[162:165], v[170:173], v[50:53]
	v_mfma_f32_16x16x32_bf16 v[38:41], v[154:157], v[178:181], v[38:41]
	v_mfma_f32_16x16x32_bf16 v[34:37], v[162:165], v[178:181], v[34:37]
	v_mfma_f32_16x16x32_bf16 v[22:25], v[154:157], v[186:189], v[22:25]
	v_mfma_f32_16x16x32_bf16 v[18:21], v[162:165], v[186:189], v[18:21]
	v_mfma_f32_16x16x32_bf16 v[6:9], v[154:157], v[200:203], v[6:9]
	v_mfma_f32_16x16x32_bf16 v[2:5], v[162:165], v[200:203], v[2:5]
	v_mfma_f32_16x16x32_bf16 v[54:57], v[158:161], v[174:177], v[54:57]
	v_mfma_f32_16x16x32_bf16 v[50:53], v[166:169], v[174:177], v[50:53]
	v_mfma_f32_16x16x32_bf16 v[38:41], v[158:161], v[182:185], v[38:41]
	v_mfma_f32_16x16x32_bf16 v[34:37], v[166:169], v[182:185], v[34:37]
	v_mfma_f32_16x16x32_bf16 v[22:25], v[158:161], v[196:199], v[22:25]
	v_mfma_f32_16x16x32_bf16 v[18:21], v[166:169], v[196:199], v[18:21]
	v_mfma_f32_16x16x32_bf16 v[6:9], v[158:161], v[206:209], v[6:9]
	v_mfma_f32_16x16x32_bf16 v[2:5], v[166:169], v[206:209], v[2:5]
	s_setprio 0
	s_barrier
	s_add_i32 s76, s76, 2
	s_add_u32 s74, s74, 0x100
	s_addc_u32 s75, s75, 0
	s_add_u32 s54, s54, 0x100
	s_addc_u32 s55, s55, 0
	s_cmp_gt_u32 s76, 13
	s_cbranch_scc0 .LBB0_1892
	s_and_b64 vcc, exec, s[14:15]
	s_cbranch_vccz .LBB0_1895
	s_barrier

; #define PG8_STAGE(bufoff, gbase, voff) do { _Pragma("unroll") for (int _i = 0; _i < 2; ++_i) \
;         __builtin_amdgcn_global_load_lds((const unsigned*)((const char*)(gbase) + (voff)[_i]), (LAS unsigned*)(lds + (bufoff) + ldsw + _i * 8192), 16, 0, 0); } while (0)
; #define PG8_LDA(dst, b, h) do { _Pragma("unroll") for (int m = 0; m < 4; ++m) _Pragma("unroll") for (int k = 0; k < 2; ++k) dst[m][k] = *(const LAS bf16x8*)(lds + PG8_SA(b, h) + aoff + m * 2048 + k * 1024); } while (0)
; #define PG8_LDB(dst, b, h) do { _Pragma("unroll") for (int n = 0; n < 2; ++n) _Pragma("unroll") for (int k = 0; k < 2; ++k) dst[n][k] = *(const LAS bf16x8*)(lds + PG8_SB(b, h) + boff + n * 2048 + k * 1024); } while (0)
; #define PG8_MMA(ai, bj, At, Bt) do { __builtin_amdgcn_s_setprio(1); _Pragma("unroll") for (int m = 0; m < 4; ++m) _Pragma("unroll") for (int n = 0; n < 2; ++n) _Pragma("unroll") for (int k = 0; k < 2; ++k) \
;         acc[ai][bj][m][n] = __builtin_amdgcn_mfma_f32_16x16x32_bf16(Bt[n][k], At[m][k], acc[ai][bj][m][n], 0, 0, 0); __builtin_amdgcn_s_setprio(0); } while (0)
; #define PG8_WAIT_V(n) asm volatile("s_waitcnt vmcnt(" #n ")" ::: "memory")
; #define PG8_WAIT_L(n) asm volatile("s_waitcnt lgkmcnt(" #n ")" ::: "memory")
; #define PG8_BAR __builtin_amdgcn_s_barrier()
; template <class Epi, class Sched, bool ALIGN_EPI>
; __device__ __forceinline__ void gemm_phase(LAS unsigned char* lds, const bf16_t* Ab, const bf16_t* Bb, int lda, int ldb, int K, const Sched& S, Epi& E) {
;     ...
;         for (int t = 0; t < nt; t += 2) {
;             const bool last = (t == nt - 2);
;             const char* a1 = cA + (unsigned)(t + 1) * kstep;
;             const char* a2 = last ? nA : cA + (unsigned)(t + 2) * kstep; const char* b2 = last ? nB : cB + (unsigned)(t + 2) * kstep;
;             const char* a3 = a2 + kstep; const char* b3 = b2 + kstep;
;             PG8_LDB(B0, 0, 0); PG8_LDB(B1, 0, 1); PG8_SCHED; PG8_LDA(At, 0, 0); PG8_STAGE(PG8_SA(1, 1), a1 + hstepA, voffA);
;             PG8_WAIT_V(8); PG8_WAIT_L(0); PG8_BAR; PG8_MMA(0, 0, At, B0); PG8_MMA(0, 1, At, B1); PG8_BAR; PG8_SCHED;
;             PG8_LDA(At, 0, 1); PG8_STAGE(PG8_SB(0, 0), b2, voffB); PG8_STAGE(PG8_SB(0, 1), b2 + hstepB, voffB); PG8_STAGE(PG8_SA(0, 0), a2, voffA);
;             PG8_WAIT_V(8); PG8_WAIT_L(0); PG8_BAR; PG8_MMA(1, 0, At, B0); PG8_MMA(1, 1, At, B1); PG8_BAR; PG8_SCHED;
.LBB0_2002:
	s_add_u32 s60, s52, s58
	s_addc_u32 s61, s53, s59
	s_add_u32 s60, s60, 0x100
	s_addc_u32 s61, s61, 0
	s_add_u32 s77, s25, s58
	s_addc_u32 s78, s31, s59
	s_add_i32 s79, 0, 0x10000
	s_cmpk_eq_i32 s58, 0x700
	s_cselect_b32 s63, s17, s61
	s_cselect_b32 s62, s74, s60
	s_cselect_b32 s61, s51, s78
	s_cselect_b32 s60, s75, s77
	s_add_i32 s77, 0, 0x14000
	v_add_u32_e32 v154, s79, v141
	v_add_u32_e32 v170, s77, v141
	ds_read_b128 v[142:145], v154
	ds_read_b128 v[146:149], v154 offset:1024
	ds_read_b128 v[150:153], v154 offset:2048
	ds_read_b128 v[154:157], v154 offset:3072
	ds_read_b128 v[158:161], v170
	ds_read_b128 v[162:165], v170 offset:1024
	ds_read_b128 v[166:169], v170 offset:2048
	ds_read_b128 v[170:173], v170 offset:3072
	v_add_u32_e32 v204, 0, v140
	v_lshl_add_u64 v[190:191], v[136:137], 0, s[58:59]
	s_add_i32 m0, s44, 0xc000
	ds_read_b128 v[174:177], v204
	ds_read_b128 v[178:181], v204 offset:1024
	ds_read_b128 v[182:185], v204 offset:2048
	ds_read_b128 v[186:189], v204 offset:3072
	ds_read_b128 v[196:199], v204 offset:4096
	ds_read_b128 v[200:203], v204 offset:5120
	ds_read_b128 v[206:209], v204 offset:6144
	ds_read_b128 v[210:213], v204 offset:7168
	global_load_lds_dwordx4 v[190:191], off
	v_lshl_add_u64 v[190:191], v[138:139], 0, s[58:59]
	s_add_i32 m0, s44, 0xe000
	s_nop 0
	global_load_lds_dwordx4 v[190:191], off
	s_waitcnt vmcnt(8)
	s_waitcnt lgkmcnt(0)
	s_barrier
	s_setprio 1
	v_mfma_f32_16x16x32_bf16 v[126:129], v[142:145], v[174:177], v[126:129]
	v_mfma_f32_16x16x32_bf16 v[122:125], v[150:153], v[174:177], v[122:125]
	v_mfma_f32_16x16x32_bf16 v[118:121], v[142:145], v[182:185], v[118:121]
	v_mfma_f32_16x16x32_bf16 v[114:117], v[150:153], v[182:185], v[114:117]
	v_mfma_f32_16x16x32_bf16 v[110:113], v[142:145], v[196:199], v[110:113]
	v_mfma_f32_16x16x32_bf16 v[106:109], v[150:153], v[196:199], v[106:109]
	v_mfma_f32_16x16x32_bf16 v[102:105], v[142:145], v[206:209], v[102:105]
	v_mfma_f32_16x16x32_bf16 v[98:101], v[150:153], v[206:209], v[98:101]
	v_mfma_f32_16x16x32_bf16 v[126:129], v[146:149], v[178:181], v[126:129]
	v_mfma_f32_16x16x32_bf16 v[122:125], v[154:157], v[178:181], v[122:125]
	v_mfma_f32_16x16x32_bf16 v[118:121], v[146:149], v[186:189], v[118:121]
	v_mfma_f32_16x16x32_bf16 v[114:117], v[154:157], v[186:189], v[114:117]
	v_mfma_f32_16x16x32_bf16 v[110:113], v[146:149], v[200:203], v[110:113]
	v_mfma_f32_16x16x32_bf16 v[106:109], v[154:157], v[200:203], v[106:109]
	v_mfma_f32_16x16x32_bf16 v[102:105], v[146:149], v[210:213], v[102:105]
	v_mfma_f32_16x16x32_bf16 v[98:101], v[154:157], v[210:213], v[98:101]
	s_setprio 0
	s_setprio 1
	v_mfma_f32_16x16x32_bf16 v[94:97], v[158:161], v[174:177], v[94:97]
	v_mfma_f32_16x16x32_bf16 v[90:93], v[166:169], v[174:177], v[90:93]
	v_mfma_f32_16x16x32_bf16 v[86:89], v[158:161], v[182:185], v[86:89]
	v_mfma_f32_16x16x32_bf16 v[82:85], v[166:169], v[182:185], v[82:85]
	v_mfma_f32_16x16x32_bf16 v[78:81], v[158:161], v[196:199], v[78:81]
	v_mfma_f32_16x16x32_bf16 v[74:77], v[166:169], v[196:199], v[74:77]
	v_mfma_f32_16x16x32_bf16 v[70:73], v[158:161], v[206:209], v[70:73]
	v_mfma_f32_16x16x32_bf16 v[66:69], v[166:169], v[206:209], v[66:69]
	v_mfma_f32_16x16x32_bf16 v[94:97], v[162:165], v[178:181], v[94:97]
	v_mfma_f32_16x16x32_bf16 v[90:93], v[170:173], v[178:181], v[90:93]
	v_mfma_f32_16x16x32_bf16 v[86:89], v[162:165], v[186:189], v[86:89]
	v_mfma_f32_16x16x32_bf16 v[82:85], v[170:173], v[186:189], v[82:85]
	v_mfma_f32_16x16x32_bf16 v[78:81], v[162:165], v[200:203], v[78:81]
	v_mfma_f32_16x16x32_bf16 v[74:77], v[170:173], v[200:203], v[74:77]
	v_mfma_f32_16x16x32_bf16 v[70:73], v[162:165], v[210:213], v[70:73]
	v_mfma_f32_16x16x32_bf16 v[66:69], v[170:173], v[210:213], v[66:69]
	s_setprio 0
	s_barrier
	s_add_i32 s78, s79, s39
	v_lshl_add_u64 v[190:191], s[60:61], 0, v[134:135]
	s_mov_b32 m0, s78
	ds_read_b128 v[174:177], v204 offset:16384
	ds_read_b128 v[178:181], v204 offset:17408
	ds_read_b128 v[182:185], v204 offset:18432
	ds_read_b128 v[186:189], v204 offset:19456
	ds_read_b128 v[196:199], v204 offset:20480
	ds_read_b128 v[200:203], v204 offset:21504
	ds_read_b128 v[206:209], v204 offset:22528
	ds_read_b128 v[210:213], v204 offset:23552
	global_load_lds_dwordx4 v[190:191], off
	s_add_i32 m0, s78, 0x2000
	s_add_u32 s78, s60, 0x40000
	v_lshl_add_u64 v[214:215], s[60:61], 0, v[132:133]
	s_addc_u32 s79, s61, 0
	s_add_i32 s77, s77, s39
	global_load_lds_dwordx4 v[214:215], off
	v_lshl_add_u64 v[216:217], s[78:79], 0, v[134:135]
	s_mov_b32 m0, s77
	v_lshl_add_u64 v[220:221], s[62:63], 0, v[130:131]
	global_load_lds_dwordx4 v[216:217], off
	v_lshl_add_u64 v[216:217], s[78:79], 0, v[132:133]
	s_add_i32 m0, s77, 0x2000
	s_nop 0
	global_load_lds_dwordx4 v[216:217], off
	v_lshl_add_u64 v[216:217], s[62:63], 0, v[0:1]
	s_mov_b32 m0, s44
	s_nop 0
	global_load_lds_dwordx4 v[216:217], off
	s_mov_b32 m0, s45
	s_nop 0
	global_load_lds_dwordx4 v[220:221], off
	s_waitcnt vmcnt(8)
	s_waitcnt lgkmcnt(0)
	s_barrier
; #define PG8_STAGE(bufoff, gbase, voff) do { _Pragma("unroll") for (int _i = 0; _i < 2; ++_i) \
;         __builtin_amdgcn_global_load_lds((const unsigned*)((const char*)(gbase) + (voff)[_i]), (LAS unsigned*)(lds + (bufoff) + ldsw + _i * 8192), 16, 0, 0); } while (0)
; #define PG8_LDA(dst, b, h) do { _Pragma("unroll") for (int m = 0; m < 4; ++m) _Pragma("unroll") for (int k = 0; k < 2; ++k) dst[m][k] = *(const LAS bf16x8*)(lds + PG8_SA(b, h) + aoff + m * 2048 + k * 1024); } while (0)
; #define PG8_LDB(dst, b, h) do { _Pragma("unroll") for (int n = 0; n < 2; ++n) _Pragma("unroll") for (int k = 0; k < 2; ++k) dst[n][k] = *(const LAS bf16x8*)(lds + PG8_SB(b, h) + boff + n * 2048 + k * 1024); } while (0)
; #define PG8_MMA(ai, bj, At, Bt) do { __builtin_amdgcn_s_setprio(1); _Pragma("unroll") for (int m = 0; m < 4; ++m) _Pragma("unroll") for (int n = 0; n < 2; ++n) _Pragma("unroll") for (int k = 0; k < 2; ++k) \
;         acc[ai][bj][m][n] = __builtin_amdgcn_mfma_f32_16x16x32_bf16(Bt[n][k], At[m][k], acc[ai][bj][m][n], 0, 0, 0); __builtin_amdgcn_s_setprio(0); } while (0)
; #define PG8_WAIT_V(n) asm volatile("s_waitcnt vmcnt(" #n ")" ::: "memory")
; #define PG8_WAIT_L(n) asm volatile("s_waitcnt lgkmcnt(" #n ")" ::: "memory")
; #define PG8_BAR __builtin_amdgcn_s_barrier()
; #define PG8_SCHED __builtin_amdgcn_sched_barrier(0)
; template <class Epi, class Sched, bool ALIGN_EPI>
; __device__ __forceinline__ void gemm_phase(LAS unsigned char* lds, const bf16_t* Ab, const bf16_t* Bb, int lda, int ldb, int K, const Sched& S, Epi& E) {
;     ...
;             PG8_WAIT_V(8); PG8_WAIT_L(0); PG8_BAR; PG8_MMA(1, 0, At, B0); PG8_MMA(1, 1, At, B1); PG8_BAR; PG8_SCHED;
;             PG8_LDB(B0, 1, 0); PG8_LDB(B1, 1, 1); PG8_SCHED; PG8_LDA(At, 1, 0); PG8_STAGE(PG8_SA(0, 1), a2 + hstepA, voffA);
;             PG8_WAIT_V(8); PG8_WAIT_L(0); PG8_BAR; PG8_MMA(0, 0, At, B0); PG8_MMA(0, 1, At, B1); PG8_BAR; PG8_SCHED;
;             PG8_LDA(At, 1, 1); PG8_STAGE(PG8_SB(1, 0), b3, voffB); PG8_STAGE(PG8_SB(1, 1), b3 + hstepB, voffB); PG8_STAGE(PG8_SA(1, 0), a3, voffA);
	s_setprio 1
	v_mfma_f32_16x16x32_bf16 v[62:65], v[142:145], v[174:177], v[62:65]
	v_mfma_f32_16x16x32_bf16 v[58:61], v[150:153], v[174:177], v[58:61]
	v_mfma_f32_16x16x32_bf16 v[54:57], v[142:145], v[182:185], v[54:57]
	v_mfma_f32_16x16x32_bf16 v[50:53], v[150:153], v[182:185], v[50:53]
	v_mfma_f32_16x16x32_bf16 v[46:49], v[142:145], v[196:199], v[46:49]
	v_mfma_f32_16x16x32_bf16 v[42:45], v[150:153], v[196:199], v[42:45]
	v_mfma_f32_16x16x32_bf16 v[38:41], v[142:145], v[206:209], v[38:41]
	v_mfma_f32_16x16x32_bf16 v[34:37], v[150:153], v[206:209], v[34:37]
	v_mfma_f32_16x16x32_bf16 v[62:65], v[146:149], v[178:181], v[62:65]
	v_mfma_f32_16x16x32_bf16 v[58:61], v[154:157], v[178:181], v[58:61]
	v_mfma_f32_16x16x32_bf16 v[54:57], v[146:149], v[186:189], v[54:57]
	v_mfma_f32_16x16x32_bf16 v[50:53], v[154:157], v[186:189], v[50:53]
	v_mfma_f32_16x16x32_bf16 v[46:49], v[146:149], v[200:203], v[46:49]
	v_mfma_f32_16x16x32_bf16 v[42:45], v[154:157], v[200:203], v[42:45]
	v_mfma_f32_16x16x32_bf16 v[38:41], v[146:149], v[210:213], v[38:41]
	v_mfma_f32_16x16x32_bf16 v[34:37], v[154:157], v[210:213], v[34:37]
	s_setprio 0
	s_setprio 1
	v_mfma_f32_16x16x32_bf16 v[30:33], v[158:161], v[174:177], v[30:33]
	v_mfma_f32_16x16x32_bf16 v[26:29], v[166:169], v[174:177], v[26:29]
	v_mfma_f32_16x16x32_bf16 v[22:25], v[158:161], v[182:185], v[22:25]
	v_mfma_f32_16x16x32_bf16 v[18:21], v[166:169], v[182:185], v[18:21]
	v_mfma_f32_16x16x32_bf16 v[14:17], v[158:161], v[196:199], v[14:17]
	v_mfma_f32_16x16x32_bf16 v[10:13], v[166:169], v[196:199], v[10:13]
	v_mfma_f32_16x16x32_bf16 v[6:9], v[158:161], v[206:209], v[6:9]
	v_mfma_f32_16x16x32_bf16 v[2:5], v[166:169], v[206:209], v[2:5]
	v_mfma_f32_16x16x32_bf16 v[30:33], v[162:165], v[178:181], v[30:33]
	v_mfma_f32_16x16x32_bf16 v[26:29], v[170:173], v[178:181], v[26:29]
	v_mfma_f32_16x16x32_bf16 v[22:25], v[162:165], v[186:189], v[22:25]
	v_mfma_f32_16x16x32_bf16 v[18:21], v[170:173], v[186:189], v[18:21]
	v_mfma_f32_16x16x32_bf16 v[14:17], v[162:165], v[200:203], v[14:17]
	v_mfma_f32_16x16x32_bf16 v[10:13], v[170:173], v[200:203], v[10:13]
	v_mfma_f32_16x16x32_bf16 v[6:9], v[162:165], v[210:213], v[6:9]
	v_mfma_f32_16x16x32_bf16 v[2:5], v[170:173], v[210:213], v[2:5]
	s_setprio 0
	s_barrier
	s_add_i32 s77, 0, 0x18000
	s_add_i32 s78, 0, 0x1c000
	v_add_u32_e32 v154, s77, v141
	v_add_u32_e32 v170, s78, v141
	ds_read_b128 v[142:145], v154
	ds_read_b128 v[146:149], v154 offset:1024
	ds_read_b128 v[150:153], v154 offset:2048
	ds_read_b128 v[154:157], v154 offset:3072
	ds_read_b128 v[158:161], v170
	ds_read_b128 v[162:165], v170 offset:1024
	ds_read_b128 v[166:169], v170 offset:2048
	ds_read_b128 v[170:173], v170 offset:3072
	s_add_u32 s62, s62, 0x40000
	s_addc_u32 s63, s63, 0
	s_mov_b32 m0, s46
	v_lshl_add_u64 v[222:223], s[62:63], 0, v[0:1]
	ds_read_b128 v[174:177], v204 offset:32768
	ds_read_b128 v[178:181], v204 offset:33792
	ds_read_b128 v[182:185], v204 offset:34816
	ds_read_b128 v[186:189], v204 offset:35840
	ds_read_b128 v[196:199], v204 offset:36864
	ds_read_b128 v[200:203], v204 offset:37888
	ds_read_b128 v[206:209], v204 offset:38912
	ds_read_b128 v[210:213], v204 offset:39936
	global_load_lds_dwordx4 v[222:223], off
	v_lshl_add_u64 v[222:223], s[62:63], 0, v[130:131]
	s_mov_b32 m0, s47
	s_nop 0
	global_load_lds_dwordx4 v[222:223], off
	s_waitcnt vmcnt(8)
	s_waitcnt lgkmcnt(0)
	s_barrier
	s_setprio 1
	v_mfma_f32_16x16x32_bf16 v[126:129], v[142:145], v[174:177], v[126:129]
	v_mfma_f32_16x16x32_bf16 v[122:125], v[150:153], v[174:177], v[122:125]
	v_mfma_f32_16x16x32_bf16 v[118:121], v[142:145], v[182:185], v[118:121]
	v_mfma_f32_16x16x32_bf16 v[114:117], v[150:153], v[182:185], v[114:117]
	v_mfma_f32_16x16x32_bf16 v[110:113], v[142:145], v[196:199], v[110:113]
	v_mfma_f32_16x16x32_bf16 v[106:109], v[150:153], v[196:199], v[106:109]
	v_mfma_f32_16x16x32_bf16 v[102:105], v[142:145], v[206:209], v[102:105]
	v_mfma_f32_16x16x32_bf16 v[98:101], v[150:153], v[206:209], v[98:101]
	v_mfma_f32_16x16x32_bf16 v[126:129], v[146:149], v[178:181], v[126:129]
	v_mfma_f32_16x16x32_bf16 v[122:125], v[154:157], v[178:181], v[122:125]
	v_mfma_f32_16x16x32_bf16 v[118:121], v[146:149], v[186:189], v[118:121]
	v_mfma_f32_16x16x32_bf16 v[114:117], v[154:157], v[186:189], v[114:117]
	v_mfma_f32_16x16x32_bf16 v[110:113], v[146:149], v[200:203], v[110:113]
	v_mfma_f32_16x16x32_bf16 v[106:109], v[154:157], v[200:203], v[106:109]
	v_mfma_f32_16x16x32_bf16 v[102:105], v[146:149], v[210:213], v[102:105]
	v_mfma_f32_16x16x32_bf16 v[98:101], v[154:157], v[210:213], v[98:101]
	s_setprio 0
	s_setprio 1
	v_mfma_f32_16x16x32_bf16 v[94:97], v[158:161], v[174:177], v[94:97]
	v_mfma_f32_16x16x32_bf16 v[90:93], v[166:169], v[174:177], v[90:93]
	v_mfma_f32_16x16x32_bf16 v[86:89], v[158:161], v[182:185], v[86:89]
	v_mfma_f32_16x16x32_bf16 v[82:85], v[166:169], v[182:185], v[82:85]
	v_mfma_f32_16x16x32_bf16 v[78:81], v[158:161], v[196:199], v[78:81]
	v_mfma_f32_16x16x32_bf16 v[74:77], v[166:169], v[196:199], v[74:77]
	v_mfma_f32_16x16x32_bf16 v[70:73], v[158:161], v[206:209], v[70:73]
	v_mfma_f32_16x16x32_bf16 v[66:69], v[166:169], v[206:209], v[66:69]
	v_mfma_f32_16x16x32_bf16 v[94:97], v[162:165], v[178:181], v[94:97]
	v_mfma_f32_16x16x32_bf16 v[90:93], v[170:173], v[178:181], v[90:93]
	v_mfma_f32_16x16x32_bf16 v[86:89], v[162:165], v[186:189], v[86:89]
	v_mfma_f32_16x16x32_bf16 v[82:85], v[170:173], v[186:189], v[82:85]
	v_mfma_f32_16x16x32_bf16 v[78:81], v[162:165], v[200:203], v[78:81]
	v_mfma_f32_16x16x32_bf16 v[74:77], v[170:173], v[200:203], v[74:77]
	v_mfma_f32_16x16x32_bf16 v[70:73], v[162:165], v[210:213], v[70:73]
	v_mfma_f32_16x16x32_bf16 v[66:69], v[170:173], v[210:213], v[66:69]
	s_setprio 0
	s_barrier
; #define PG8_STAGE(bufoff, gbase, voff) do { _Pragma("unroll") for (int _i = 0; _i < 2; ++_i) \
;         __builtin_amdgcn_global_load_lds((const unsigned*)((const char*)(gbase) + (voff)[_i]), (LAS unsigned*)(lds + (bufoff) + ldsw + _i * 8192), 16, 0, 0); } while (0)
; #define PG8_LDA(dst, b, h) do { _Pragma("unroll") for (int m = 0; m < 4; ++m) _Pragma("unroll") for (int k = 0; k < 2; ++k) dst[m][k] = *(const LAS bf16x8*)(lds + PG8_SA(b, h) + aoff + m * 2048 + k * 1024); } while (0)
; #define PG8_MMA(ai, bj, At, Bt) do { __builtin_amdgcn_s_setprio(1); _Pragma("unroll") for (int m = 0; m < 4; ++m) _Pragma("unroll") for (int n = 0; n < 2; ++n) _Pragma("unroll") for (int k = 0; k < 2; ++k) \
;         acc[ai][bj][m][n] = __builtin_amdgcn_mfma_f32_16x16x32_bf16(Bt[n][k], At[m][k], acc[ai][bj][m][n], 0, 0, 0); __builtin_amdgcn_s_setprio(0); } while (0)
; #define PG8_WAIT_V(n) asm volatile("s_waitcnt vmcnt(" #n ")" ::: "memory")
; #define PG8_WAIT_L(n) asm volatile("s_waitcnt lgkmcnt(" #n ")" ::: "memory")
; #define PG8_BAR __builtin_amdgcn_s_barrier()
; #define PG8_SCHED __builtin_amdgcn_sched_barrier(0)
; template <class Epi, class Sched, bool ALIGN_EPI>
; __device__ __forceinline__ void gemm_phase(LAS unsigned char* lds, const bf16_t* Ab, const bf16_t* Bb, int lda, int ldb, int K, const Sched& S, Epi& E) {
;     ...
;             PG8_LDA(At, 1, 1); PG8_STAGE(PG8_SB(1, 0), b3, voffB); PG8_STAGE(PG8_SB(1, 1), b3 + hstepB, voffB); PG8_STAGE(PG8_SA(1, 0), a3, voffA);
;             PG8_WAIT_V(8); PG8_WAIT_L(0); PG8_BAR; PG8_MMA(1, 0, At, B0); PG8_MMA(1, 1, At, B1); PG8_BAR; PG8_SCHED;
;         }
	s_add_i32 s62, s77, s39
	v_lshl_add_u64 v[190:191], v[190:191], 0, s[26:27]
	s_mov_b32 m0, s62
	ds_read_b128 v[174:177], v204 offset:49152
	ds_read_b128 v[178:181], v204 offset:50176
	ds_read_b128 v[182:185], v204 offset:51200
	ds_read_b128 v[186:189], v204 offset:52224
	ds_read_b128 v[196:199], v204 offset:53248
	ds_read_b128 v[200:203], v204 offset:54272
	ds_read_b128 v[206:209], v204 offset:55296
	ds_read_b128 v[210:213], v204 offset:56320
	global_load_lds_dwordx4 v[190:191], off
	s_add_i32 m0, s62, 0x2000
	s_add_u32 s60, s60, 0x40080
	v_lshl_add_u64 v[190:191], v[214:215], 0, s[26:27]
	s_addc_u32 s61, s61, 0
	s_add_i32 s62, s78, s39
	global_load_lds_dwordx4 v[190:191], off
	v_lshl_add_u64 v[190:191], s[60:61], 0, v[134:135]
	s_mov_b32 m0, s62
	s_nop 0
	global_load_lds_dwordx4 v[190:191], off
	v_lshl_add_u64 v[190:191], s[60:61], 0, v[132:133]
	s_add_i32 m0, s62, 0x2000
	s_nop 0
	global_load_lds_dwordx4 v[190:191], off
	v_lshl_add_u64 v[190:191], v[216:217], 0, s[26:27]
	s_mov_b32 m0, s67
	s_nop 0
	global_load_lds_dwordx4 v[190:191], off
	v_lshl_add_u64 v[190:191], v[220:221], 0, s[26:27]
	s_mov_b32 m0, s68
	s_nop 0
	global_load_lds_dwordx4 v[190:191], off
	s_waitcnt vmcnt(8)
	s_waitcnt lgkmcnt(0)
	s_barrier
	s_setprio 1
	v_mfma_f32_16x16x32_bf16 v[62:65], v[142:145], v[174:177], v[62:65]
	v_mfma_f32_16x16x32_bf16 v[58:61], v[150:153], v[174:177], v[58:61]
	v_mfma_f32_16x16x32_bf16 v[54:57], v[142:145], v[182:185], v[54:57]
	v_mfma_f32_16x16x32_bf16 v[50:53], v[150:153], v[182:185], v[50:53]
	v_mfma_f32_16x16x32_bf16 v[46:49], v[142:145], v[196:199], v[46:49]
	v_mfma_f32_16x16x32_bf16 v[42:45], v[150:153], v[196:199], v[42:45]
	v_mfma_f32_16x16x32_bf16 v[38:41], v[142:145], v[206:209], v[38:41]
	v_mfma_f32_16x16x32_bf16 v[34:37], v[150:153], v[206:209], v[34:37]
	v_mfma_f32_16x16x32_bf16 v[62:65], v[146:149], v[178:181], v[62:65]
	v_mfma_f32_16x16x32_bf16 v[58:61], v[154:157], v[178:181], v[58:61]
	v_mfma_f32_16x16x32_bf16 v[54:57], v[146:149], v[186:189], v[54:57]
	v_mfma_f32_16x16x32_bf16 v[50:53], v[154:157], v[186:189], v[50:53]
	v_mfma_f32_16x16x32_bf16 v[46:49], v[146:149], v[200:203], v[46:49]
	v_mfma_f32_16x16x32_bf16 v[42:45], v[154:157], v[200:203], v[42:45]
	v_mfma_f32_16x16x32_bf16 v[38:41], v[146:149], v[210:213], v[38:41]
	v_mfma_f32_16x16x32_bf16 v[34:37], v[154:157], v[210:213], v[34:37]
	s_setprio 0
	s_setprio 1
	v_mfma_f32_16x16x32_bf16 v[30:33], v[158:161], v[174:177], v[30:33]
	v_mfma_f32_16x16x32_bf16 v[26:29], v[166:169], v[174:177], v[26:29]
	v_mfma_f32_16x16x32_bf16 v[22:25], v[158:161], v[182:185], v[22:25]
	v_mfma_f32_16x16x32_bf16 v[18:21], v[166:169], v[182:185], v[18:21]
	v_mfma_f32_16x16x32_bf16 v[14:17], v[158:161], v[196:199], v[14:17]
	v_mfma_f32_16x16x32_bf16 v[10:13], v[166:169], v[196:199], v[10:13]
	v_mfma_f32_16x16x32_bf16 v[6:9], v[158:161], v[206:209], v[6:9]
	v_mfma_f32_16x16x32_bf16 v[2:5], v[166:169], v[206:209], v[2:5]
	v_mfma_f32_16x16x32_bf16 v[30:33], v[162:165], v[178:181], v[30:33]
	v_mfma_f32_16x16x32_bf16 v[26:29], v[170:173], v[178:181], v[26:29]
	v_mfma_f32_16x16x32_bf16 v[22:25], v[162:165], v[186:189], v[22:25]
	v_mfma_f32_16x16x32_bf16 v[18:21], v[170:173], v[186:189], v[18:21]
	v_mfma_f32_16x16x32_bf16 v[14:17], v[162:165], v[200:203], v[14:17]
	v_mfma_f32_16x16x32_bf16 v[10:13], v[170:173], v[200:203], v[10:13]
	v_mfma_f32_16x16x32_bf16 v[6:9], v[162:165], v[210:213], v[6:9]
	v_mfma_f32_16x16x32_bf16 v[2:5], v[170:173], v[210:213], v[2:5]
	s_setprio 0
	s_barrier
	s_add_i32 s76, s76, 2
	s_add_u32 s58, s58, 0x100
	s_addc_u32 s59, s59, 0
	s_cmp_gt_u32 s76, 13
	s_cbranch_scc0 .LBB0_2002
	s_and_b64 vcc, exec, s[14:15]
	s_cbranch_vccz .LBB0_2005
	s_barrier

; #define PG8_STAGE(bufoff, gbase, voff) do { _Pragma("unroll") for (int _i = 0; _i < 2; ++_i) \
;         __builtin_amdgcn_global_load_lds((const unsigned*)((const char*)(gbase) + (voff)[_i]), (LAS unsigned*)(lds + (bufoff) + ldsw + _i * 8192), 16, 0, 0); } while (0)
; #define PG8_LDA(dst, b, h) do { _Pragma("unroll") for (int m = 0; m < 4; ++m) _Pragma("unroll") for (int k = 0; k < 2; ++k) dst[m][k] = *(const LAS bf16x8*)(lds + PG8_SA(b, h) + aoff + m * 2048 + k * 1024); } while (0)
; #define PG8_LDB(dst, b, h) do { _Pragma("unroll") for (int n = 0; n < 2; ++n) _Pragma("unroll") for (int k = 0; k < 2; ++k) dst[n][k] = *(const LAS bf16x8*)(lds + PG8_SB(b, h) + boff + n * 2048 + k * 1024); } while (0)
; #define PG8_MMA(ai, bj, At, Bt) do { __builtin_amdgcn_s_setprio(1); _Pragma("unroll") for (int m = 0; m < 4; ++m) _Pragma("unroll") for (int n = 0; n < 2; ++n) _Pragma("unroll") for (int k = 0; k < 2; ++k) \
;         acc[ai][bj][m][n] = __builtin_amdgcn_mfma_f32_16x16x32_bf16(Bt[n][k], At[m][k], acc[ai][bj][m][n], 0, 0, 0); __builtin_amdgcn_s_setprio(0); } while (0)
; #define PG8_WAIT_V(n) asm volatile("s_waitcnt vmcnt(" #n ")" ::: "memory")
; #define PG8_WAIT_L(n) asm volatile("s_waitcnt lgkmcnt(" #n ")" ::: "memory")
; #define PG8_BAR __builtin_amdgcn_s_barrier()
; template <class Epi, class Sched, bool ALIGN_EPI>
; __device__ __forceinline__ void gemm_phase(LAS unsigned char* lds, const bf16_t* Ab, const bf16_t* Bb, int lda, int ldb, int K, const Sched& S, Epi& E) {
;     ...
;         for (int t = 0; t < nt; t += 2) {
;             const bool last = (t == nt - 2);
;             const char* a1 = cA + (unsigned)(t + 1) * kstep;
;             const char* a2 = last ? nA : cA + (unsigned)(t + 2) * kstep; const char* b2 = last ? nB : cB + (unsigned)(t + 2) * kstep;
;             const char* a3 = a2 + kstep; const char* b3 = b2 + kstep;
;             PG8_LDB(B0, 0, 0); PG8_LDB(B1, 0, 1); PG8_SCHED; PG8_LDA(At, 0, 0); PG8_STAGE(PG8_SA(1, 1), a1 + hstepA, voffA);
;             PG8_WAIT_V(8); PG8_WAIT_L(0); PG8_BAR; PG8_MMA(0, 0, At, B0); PG8_MMA(0, 1, At, B1); PG8_BAR; PG8_SCHED;
;             PG8_LDA(At, 0, 1); PG8_STAGE(PG8_SB(0, 0), b2, voffB); PG8_STAGE(PG8_SB(0, 1), b2 + hstepB, voffB); PG8_STAGE(PG8_SA(0, 0), a2, voffA);
;             PG8_WAIT_V(8); PG8_WAIT_L(0); PG8_BAR; PG8_MMA(1, 0, At, B0); PG8_MMA(1, 1, At, B1); PG8_BAR; PG8_SCHED;
.LBB0_2082:
	s_add_u32 s54, s52, 0xfff50080
	s_addc_u32 s55, s53, -1
	s_add_i32 s77, 0, 0x10000
	s_cmp_eq_u32 s76, 40
	s_cselect_b32 s57, s17, s55
	s_cselect_b32 s56, s18, s54
	s_cselect_b32 s55, s25, s75
	s_cselect_b32 s54, s45, s74
	s_add_i32 s80, 0, 0x14000
	v_add_u32_e32 v150, s77, v136
	v_add_u32_e32 v166, s80, v136
	ds_read_b128 v[138:141], v150
	ds_read_b128 v[142:145], v150 offset:1024
	ds_read_b128 v[146:149], v150 offset:2048
	ds_read_b128 v[150:153], v150 offset:3072
	ds_read_b128 v[154:157], v166
	ds_read_b128 v[158:161], v166 offset:1024
	ds_read_b128 v[162:165], v166 offset:2048
	ds_read_b128 v[166:169], v166 offset:3072
	v_lshl_add_u64 v[190:191], s[52:53], 0, v[0:1]
	s_add_i32 m0, s33, 0xc000
	ds_read_b128 v[170:173], v137
	ds_read_b128 v[174:177], v137 offset:1024
	ds_read_b128 v[178:181], v137 offset:2048
	ds_read_b128 v[182:185], v137 offset:3072
	ds_read_b128 v[186:189], v137 offset:4096
	ds_read_b128 v[196:199], v137 offset:5120
	ds_read_b128 v[200:203], v137 offset:6144
	ds_read_b128 v[206:209], v137 offset:7168
	global_load_lds_dwordx4 v[190:191], off
	v_lshl_add_u64 v[190:191], s[52:53], 0, v[132:133]
	s_add_i32 m0, s33, 0xe000
	s_nop 0
	global_load_lds_dwordx4 v[190:191], off
	s_waitcnt vmcnt(8)
	s_waitcnt lgkmcnt(0)
	s_barrier
	s_setprio 1
	v_mfma_f32_16x16x32_bf16 v[126:129], v[138:141], v[170:173], v[126:129]
	v_mfma_f32_16x16x32_bf16 v[122:125], v[146:149], v[170:173], v[122:125]
	v_mfma_f32_16x16x32_bf16 v[110:113], v[138:141], v[178:181], v[110:113]
	v_mfma_f32_16x16x32_bf16 v[106:109], v[146:149], v[178:181], v[106:109]
	v_mfma_f32_16x16x32_bf16 v[94:97], v[138:141], v[186:189], v[94:97]
	v_mfma_f32_16x16x32_bf16 v[90:93], v[146:149], v[186:189], v[90:93]
	v_mfma_f32_16x16x32_bf16 v[78:81], v[138:141], v[200:203], v[78:81]
	v_mfma_f32_16x16x32_bf16 v[74:77], v[146:149], v[200:203], v[74:77]
	v_mfma_f32_16x16x32_bf16 v[126:129], v[142:145], v[174:177], v[126:129]
	v_mfma_f32_16x16x32_bf16 v[122:125], v[150:153], v[174:177], v[122:125]
	v_mfma_f32_16x16x32_bf16 v[110:113], v[142:145], v[182:185], v[110:113]
	v_mfma_f32_16x16x32_bf16 v[106:109], v[150:153], v[182:185], v[106:109]
	v_mfma_f32_16x16x32_bf16 v[94:97], v[142:145], v[196:199], v[94:97]
	v_mfma_f32_16x16x32_bf16 v[90:93], v[150:153], v[196:199], v[90:93]
	v_mfma_f32_16x16x32_bf16 v[78:81], v[142:145], v[206:209], v[78:81]
	v_mfma_f32_16x16x32_bf16 v[74:77], v[150:153], v[206:209], v[74:77]
	s_setprio 0
	s_setprio 1
	v_mfma_f32_16x16x32_bf16 v[118:121], v[154:157], v[170:173], v[118:121]
	v_mfma_f32_16x16x32_bf16 v[114:117], v[162:165], v[170:173], v[114:117]
	v_mfma_f32_16x16x32_bf16 v[102:105], v[154:157], v[178:181], v[102:105]
	v_mfma_f32_16x16x32_bf16 v[98:101], v[162:165], v[178:181], v[98:101]
	v_mfma_f32_16x16x32_bf16 v[86:89], v[154:157], v[186:189], v[86:89]
	v_mfma_f32_16x16x32_bf16 v[82:85], v[162:165], v[186:189], v[82:85]
	v_mfma_f32_16x16x32_bf16 v[70:73], v[154:157], v[200:203], v[70:73]
	v_mfma_f32_16x16x32_bf16 v[66:69], v[162:165], v[200:203], v[66:69]
	v_mfma_f32_16x16x32_bf16 v[118:121], v[158:161], v[174:177], v[118:121]
	v_mfma_f32_16x16x32_bf16 v[114:117], v[166:169], v[174:177], v[114:117]
	v_mfma_f32_16x16x32_bf16 v[102:105], v[158:161], v[182:185], v[102:105]
	v_mfma_f32_16x16x32_bf16 v[98:101], v[166:169], v[182:185], v[98:101]
	v_mfma_f32_16x16x32_bf16 v[86:89], v[158:161], v[196:199], v[86:89]
	v_mfma_f32_16x16x32_bf16 v[82:85], v[166:169], v[196:199], v[82:85]
	v_mfma_f32_16x16x32_bf16 v[70:73], v[158:161], v[206:209], v[70:73]
	v_mfma_f32_16x16x32_bf16 v[66:69], v[166:169], v[206:209], v[66:69]
	s_setprio 0
	s_barrier
	s_add_i32 s77, s77, s24
	v_lshl_add_u64 v[190:191], s[54:55], 0, v[130:131]
	s_mov_b32 m0, s77
	ds_read_b128 v[170:173], v137 offset:16384
	ds_read_b128 v[174:177], v137 offset:17408
	ds_read_b128 v[178:181], v137 offset:18432
	ds_read_b128 v[182:185], v137 offset:19456
	ds_read_b128 v[186:189], v137 offset:20480
	ds_read_b128 v[196:199], v137 offset:21504
	ds_read_b128 v[200:203], v137 offset:22528
	ds_read_b128 v[206:209], v137 offset:23552
	global_load_lds_dwordx4 v[190:191], off
	s_add_i32 m0, s77, 0x2000
	s_add_u32 s78, s54, 0xb0000
	v_lshl_add_u64 v[210:211], s[54:55], 0, v[134:135]
	s_addc_u32 s79, s55, 0
	s_add_i32 s77, s80, s24
	global_load_lds_dwordx4 v[210:211], off
	v_lshl_add_u64 v[212:213], s[78:79], 0, v[130:131]
	s_mov_b32 m0, s77
	v_lshl_add_u64 v[214:215], s[56:57], 0, v[132:133]
	global_load_lds_dwordx4 v[212:213], off
	v_lshl_add_u64 v[212:213], s[78:79], 0, v[134:135]
	s_add_i32 m0, s77, 0x2000
	s_nop 0
	global_load_lds_dwordx4 v[212:213], off
	v_lshl_add_u64 v[212:213], s[56:57], 0, v[0:1]
	s_mov_b32 m0, s33
	s_nop 0
	global_load_lds_dwordx4 v[212:213], off
	s_mov_b32 m0, s31
	s_nop 0
	global_load_lds_dwordx4 v[214:215], off
	s_waitcnt vmcnt(8)
	s_waitcnt lgkmcnt(0)
	s_barrier
; #define PG8_STAGE(bufoff, gbase, voff) do { _Pragma("unroll") for (int _i = 0; _i < 2; ++_i) \
;         __builtin_amdgcn_global_load_lds((const unsigned*)((const char*)(gbase) + (voff)[_i]), (LAS unsigned*)(lds + (bufoff) + ldsw + _i * 8192), 16, 0, 0); } while (0)
; #define PG8_LDA(dst, b, h) do { _Pragma("unroll") for (int m = 0; m < 4; ++m) _Pragma("unroll") for (int k = 0; k < 2; ++k) dst[m][k] = *(const LAS bf16x8*)(lds + PG8_SA(b, h) + aoff + m * 2048 + k * 1024); } while (0)
; #define PG8_LDB(dst, b, h) do { _Pragma("unroll") for (int n = 0; n < 2; ++n) _Pragma("unroll") for (int k = 0; k < 2; ++k) dst[n][k] = *(const LAS bf16x8*)(lds + PG8_SB(b, h) + boff + n * 2048 + k * 1024); } while (0)
; #define PG8_MMA(ai, bj, At, Bt) do { __builtin_amdgcn_s_setprio(1); _Pragma("unroll") for (int m = 0; m < 4; ++m) _Pragma("unroll") for (int n = 0; n < 2; ++n) _Pragma("unroll") for (int k = 0; k < 2; ++k) \
;         acc[ai][bj][m][n] = __builtin_amdgcn_mfma_f32_16x16x32_bf16(Bt[n][k], At[m][k], acc[ai][bj][m][n], 0, 0, 0); __builtin_amdgcn_s_setprio(0); } while (0)
; #define PG8_WAIT_V(n) asm volatile("s_waitcnt vmcnt(" #n ")" ::: "memory")
; #define PG8_WAIT_L(n) asm volatile("s_waitcnt lgkmcnt(" #n ")" ::: "memory")
; #define PG8_BAR __builtin_amdgcn_s_barrier()
; #define PG8_SCHED __builtin_amdgcn_sched_barrier(0)
; template <class Epi, class Sched, bool ALIGN_EPI>
; __device__ __forceinline__ void gemm_phase(LAS unsigned char* lds, const bf16_t* Ab, const bf16_t* Bb, int lda, int ldb, int K, const Sched& S, Epi& E) {
;     ...
;             PG8_WAIT_V(8); PG8_WAIT_L(0); PG8_BAR; PG8_MMA(1, 0, At, B0); PG8_MMA(1, 1, At, B1); PG8_BAR; PG8_SCHED;
;             PG8_LDB(B0, 1, 0); PG8_LDB(B1, 1, 1); PG8_SCHED; PG8_LDA(At, 1, 0); PG8_STAGE(PG8_SA(0, 1), a2 + hstepA, voffA);
;             PG8_WAIT_V(8); PG8_WAIT_L(0); PG8_BAR; PG8_MMA(0, 0, At, B0); PG8_MMA(0, 1, At, B1); PG8_BAR; PG8_SCHED;
;             PG8_LDA(At, 1, 1); PG8_STAGE(PG8_SB(1, 0), b3, voffB); PG8_STAGE(PG8_SB(1, 1), b3 + hstepB, voffB); PG8_STAGE(PG8_SA(1, 0), a3, voffA);
	s_setprio 1
	v_mfma_f32_16x16x32_bf16 v[62:65], v[138:141], v[170:173], v[62:65]
	v_mfma_f32_16x16x32_bf16 v[58:61], v[146:149], v[170:173], v[58:61]
	v_mfma_f32_16x16x32_bf16 v[46:49], v[138:141], v[178:181], v[46:49]
	v_mfma_f32_16x16x32_bf16 v[42:45], v[146:149], v[178:181], v[42:45]
	v_mfma_f32_16x16x32_bf16 v[30:33], v[138:141], v[186:189], v[30:33]
	v_mfma_f32_16x16x32_bf16 v[26:29], v[146:149], v[186:189], v[26:29]
	v_mfma_f32_16x16x32_bf16 v[14:17], v[138:141], v[200:203], v[14:17]
	v_mfma_f32_16x16x32_bf16 v[10:13], v[146:149], v[200:203], v[10:13]
	v_mfma_f32_16x16x32_bf16 v[62:65], v[142:145], v[174:177], v[62:65]
	v_mfma_f32_16x16x32_bf16 v[58:61], v[150:153], v[174:177], v[58:61]
	v_mfma_f32_16x16x32_bf16 v[46:49], v[142:145], v[182:185], v[46:49]
	v_mfma_f32_16x16x32_bf16 v[42:45], v[150:153], v[182:185], v[42:45]
	v_mfma_f32_16x16x32_bf16 v[30:33], v[142:145], v[196:199], v[30:33]
	v_mfma_f32_16x16x32_bf16 v[26:29], v[150:153], v[196:199], v[26:29]
	v_mfma_f32_16x16x32_bf16 v[14:17], v[142:145], v[206:209], v[14:17]
	v_mfma_f32_16x16x32_bf16 v[10:13], v[150:153], v[206:209], v[10:13]
	s_setprio 0
	s_setprio 1
	v_mfma_f32_16x16x32_bf16 v[54:57], v[154:157], v[170:173], v[54:57]
	v_mfma_f32_16x16x32_bf16 v[50:53], v[162:165], v[170:173], v[50:53]
	v_mfma_f32_16x16x32_bf16 v[38:41], v[154:157], v[178:181], v[38:41]
	v_mfma_f32_16x16x32_bf16 v[34:37], v[162:165], v[178:181], v[34:37]
	v_mfma_f32_16x16x32_bf16 v[22:25], v[154:157], v[186:189], v[22:25]
	v_mfma_f32_16x16x32_bf16 v[18:21], v[162:165], v[186:189], v[18:21]
	v_mfma_f32_16x16x32_bf16 v[6:9], v[154:157], v[200:203], v[6:9]
	v_mfma_f32_16x16x32_bf16 v[2:5], v[162:165], v[200:203], v[2:5]
	v_mfma_f32_16x16x32_bf16 v[54:57], v[158:161], v[174:177], v[54:57]
	v_mfma_f32_16x16x32_bf16 v[50:53], v[166:169], v[174:177], v[50:53]
	v_mfma_f32_16x16x32_bf16 v[38:41], v[158:161], v[182:185], v[38:41]
	v_mfma_f32_16x16x32_bf16 v[34:37], v[166:169], v[182:185], v[34:37]
	v_mfma_f32_16x16x32_bf16 v[22:25], v[158:161], v[196:199], v[22:25]
	v_mfma_f32_16x16x32_bf16 v[18:21], v[166:169], v[196:199], v[18:21]
	v_mfma_f32_16x16x32_bf16 v[6:9], v[158:161], v[206:209], v[6:9]
	v_mfma_f32_16x16x32_bf16 v[2:5], v[166:169], v[206:209], v[2:5]
	s_setprio 0
	s_barrier
	s_add_i32 s77, 0, 0x18000
	s_add_i32 s78, 0, 0x1c000
	v_add_u32_e32 v150, s77, v136
	v_add_u32_e32 v166, s78, v136
	ds_read_b128 v[138:141], v150
	ds_read_b128 v[142:145], v150 offset:1024
	ds_read_b128 v[146:149], v150 offset:2048
	ds_read_b128 v[150:153], v150 offset:3072
	ds_read_b128 v[154:157], v166
	ds_read_b128 v[158:161], v166 offset:1024
	ds_read_b128 v[162:165], v166 offset:2048
	ds_read_b128 v[166:169], v166 offset:3072
	s_add_u32 s56, s56, 0xb0000
	s_addc_u32 s57, s57, 0
	s_mov_b32 m0, s39
	v_lshl_add_u64 v[216:217], s[56:57], 0, v[0:1]
	ds_read_b128 v[170:173], v137 offset:32768
	ds_read_b128 v[174:177], v137 offset:33792
	ds_read_b128 v[178:181], v137 offset:34816
	ds_read_b128 v[182:185], v137 offset:35840
	ds_read_b128 v[186:189], v137 offset:36864
	ds_read_b128 v[196:199], v137 offset:37888
	ds_read_b128 v[200:203], v137 offset:38912
	ds_read_b128 v[206:209], v137 offset:39936
	global_load_lds_dwordx4 v[216:217], off
	v_lshl_add_u64 v[216:217], s[56:57], 0, v[132:133]
	s_mov_b32 m0, s46
	s_nop 0
	global_load_lds_dwordx4 v[216:217], off
	s_waitcnt vmcnt(8)
	s_waitcnt lgkmcnt(0)
	s_barrier
	s_setprio 1
	v_mfma_f32_16x16x32_bf16 v[126:129], v[138:141], v[170:173], v[126:129]
	v_mfma_f32_16x16x32_bf16 v[122:125], v[146:149], v[170:173], v[122:125]
	v_mfma_f32_16x16x32_bf16 v[110:113], v[138:141], v[178:181], v[110:113]
	v_mfma_f32_16x16x32_bf16 v[106:109], v[146:149], v[178:181], v[106:109]
	v_mfma_f32_16x16x32_bf16 v[94:97], v[138:141], v[186:189], v[94:97]
	v_mfma_f32_16x16x32_bf16 v[90:93], v[146:149], v[186:189], v[90:93]
	v_mfma_f32_16x16x32_bf16 v[78:81], v[138:141], v[200:203], v[78:81]
	v_mfma_f32_16x16x32_bf16 v[74:77], v[146:149], v[200:203], v[74:77]
	v_mfma_f32_16x16x32_bf16 v[126:129], v[142:145], v[174:177], v[126:129]
	v_mfma_f32_16x16x32_bf16 v[122:125], v[150:153], v[174:177], v[122:125]
	v_mfma_f32_16x16x32_bf16 v[110:113], v[142:145], v[182:185], v[110:113]
	v_mfma_f32_16x16x32_bf16 v[106:109], v[150:153], v[182:185], v[106:109]
	v_mfma_f32_16x16x32_bf16 v[94:97], v[142:145], v[196:199], v[94:97]
	v_mfma_f32_16x16x32_bf16 v[90:93], v[150:153], v[196:199], v[90:93]
	v_mfma_f32_16x16x32_bf16 v[78:81], v[142:145], v[206:209], v[78:81]
	v_mfma_f32_16x16x32_bf16 v[74:77], v[150:153], v[206:209], v[74:77]
	s_setprio 0
	s_setprio 1
	v_mfma_f32_16x16x32_bf16 v[118:121], v[154:157], v[170:173], v[118:121]
	v_mfma_f32_16x16x32_bf16 v[114:117], v[162:165], v[170:173], v[114:117]
	v_mfma_f32_16x16x32_bf16 v[102:105], v[154:157], v[178:181], v[102:105]
	v_mfma_f32_16x16x32_bf16 v[98:101], v[162:165], v[178:181], v[98:101]
	v_mfma_f32_16x16x32_bf16 v[86:89], v[154:157], v[186:189], v[86:89]
	v_mfma_f32_16x16x32_bf16 v[82:85], v[162:165], v[186:189], v[82:85]
	v_mfma_f32_16x16x32_bf16 v[70:73], v[154:157], v[200:203], v[70:73]
	v_mfma_f32_16x16x32_bf16 v[66:69], v[162:165], v[200:203], v[66:69]
	v_mfma_f32_16x16x32_bf16 v[118:121], v[158:161], v[174:177], v[118:121]
	v_mfma_f32_16x16x32_bf16 v[114:117], v[166:169], v[174:177], v[114:117]
	v_mfma_f32_16x16x32_bf16 v[102:105], v[158:161], v[182:185], v[102:105]
	v_mfma_f32_16x16x32_bf16 v[98:101], v[166:169], v[182:185], v[98:101]
	v_mfma_f32_16x16x32_bf16 v[86:89], v[158:161], v[196:199], v[86:89]
	v_mfma_f32_16x16x32_bf16 v[82:85], v[166:169], v[196:199], v[82:85]
	v_mfma_f32_16x16x32_bf16 v[70:73], v[158:161], v[206:209], v[70:73]
	v_mfma_f32_16x16x32_bf16 v[66:69], v[166:169], v[206:209], v[66:69]
	s_setprio 0
	s_barrier
; #define PG8_STAGE(bufoff, gbase, voff) do { _Pragma("unroll") for (int _i = 0; _i < 2; ++_i) \
;         __builtin_amdgcn_global_load_lds((const unsigned*)((const char*)(gbase) + (voff)[_i]), (LAS unsigned*)(lds + (bufoff) + ldsw + _i * 8192), 16, 0, 0); } while (0)
; #define PG8_LDA(dst, b, h) do { _Pragma("unroll") for (int m = 0; m < 4; ++m) _Pragma("unroll") for (int k = 0; k < 2; ++k) dst[m][k] = *(const LAS bf16x8*)(lds + PG8_SA(b, h) + aoff + m * 2048 + k * 1024); } while (0)
; #define PG8_MMA(ai, bj, At, Bt) do { __builtin_amdgcn_s_setprio(1); _Pragma("unroll") for (int m = 0; m < 4; ++m) _Pragma("unroll") for (int n = 0; n < 2; ++n) _Pragma("unroll") for (int k = 0; k < 2; ++k) \
;         acc[ai][bj][m][n] = __builtin_amdgcn_mfma_f32_16x16x32_bf16(Bt[n][k], At[m][k], acc[ai][bj][m][n], 0, 0, 0); __builtin_amdgcn_s_setprio(0); } while (0)
; #define PG8_WAIT_V(n) asm volatile("s_waitcnt vmcnt(" #n ")" ::: "memory")
; #define PG8_WAIT_L(n) asm volatile("s_waitcnt lgkmcnt(" #n ")" ::: "memory")
; #define PG8_BAR __builtin_amdgcn_s_barrier()
; #define PG8_SCHED __builtin_amdgcn_sched_barrier(0)
; template <class Epi, class Sched, bool ALIGN_EPI>
; __device__ __forceinline__ void gemm_phase(LAS unsigned char* lds, const bf16_t* Ab, const bf16_t* Bb, int lda, int ldb, int K, const Sched& S, Epi& E) {
;     ...
;             PG8_LDA(At, 1, 1); PG8_STAGE(PG8_SB(1, 0), b3, voffB); PG8_STAGE(PG8_SB(1, 1), b3 + hstepB, voffB); PG8_STAGE(PG8_SA(1, 0), a3, voffA);
;             PG8_WAIT_V(8); PG8_WAIT_L(0); PG8_BAR; PG8_MMA(1, 0, At, B0); PG8_MMA(1, 1, At, B1); PG8_BAR; PG8_SCHED;
;         }
	s_add_i32 s56, s77, s24
	v_lshl_add_u64 v[190:191], v[190:191], 0, s[26:27]
	s_mov_b32 m0, s56
	ds_read_b128 v[170:173], v137 offset:49152
	ds_read_b128 v[174:177], v137 offset:50176
	ds_read_b128 v[178:181], v137 offset:51200
	ds_read_b128 v[182:185], v137 offset:52224
	ds_read_b128 v[186:189], v137 offset:53248
	ds_read_b128 v[196:199], v137 offset:54272
	ds_read_b128 v[200:203], v137 offset:55296
	ds_read_b128 v[206:209], v137 offset:56320
	global_load_lds_dwordx4 v[190:191], off
	s_add_i32 m0, s56, 0x2000
	s_add_u32 s54, s54, 0xb0080
	v_lshl_add_u64 v[190:191], v[210:211], 0, s[26:27]
	s_addc_u32 s55, s55, 0
	s_add_i32 s56, s78, s24
	global_load_lds_dwordx4 v[190:191], off
	v_lshl_add_u64 v[190:191], s[54:55], 0, v[130:131]
	s_mov_b32 m0, s56
	s_nop 0
	global_load_lds_dwordx4 v[190:191], off
	v_lshl_add_u64 v[190:191], s[54:55], 0, v[134:135]
	s_add_i32 m0, s56, 0x2000
	s_nop 0
	global_load_lds_dwordx4 v[190:191], off
	v_lshl_add_u64 v[190:191], v[212:213], 0, s[26:27]
	s_mov_b32 m0, s62
	s_nop 0
	global_load_lds_dwordx4 v[190:191], off
	v_lshl_add_u64 v[190:191], v[214:215], 0, s[26:27]
	s_mov_b32 m0, s63
	s_nop 0
	global_load_lds_dwordx4 v[190:191], off
	s_waitcnt vmcnt(8)
	s_waitcnt lgkmcnt(0)
	s_barrier
	s_setprio 1
	v_mfma_f32_16x16x32_bf16 v[62:65], v[138:141], v[170:173], v[62:65]
	v_mfma_f32_16x16x32_bf16 v[58:61], v[146:149], v[170:173], v[58:61]
	v_mfma_f32_16x16x32_bf16 v[46:49], v[138:141], v[178:181], v[46:49]
	v_mfma_f32_16x16x32_bf16 v[42:45], v[146:149], v[178:181], v[42:45]
	v_mfma_f32_16x16x32_bf16 v[30:33], v[138:141], v[186:189], v[30:33]
	v_mfma_f32_16x16x32_bf16 v[26:29], v[146:149], v[186:189], v[26:29]
	v_mfma_f32_16x16x32_bf16 v[14:17], v[138:141], v[200:203], v[14:17]
	v_mfma_f32_16x16x32_bf16 v[10:13], v[146:149], v[200:203], v[10:13]
	v_mfma_f32_16x16x32_bf16 v[62:65], v[142:145], v[174:177], v[62:65]
	v_mfma_f32_16x16x32_bf16 v[58:61], v[150:153], v[174:177], v[58:61]
	v_mfma_f32_16x16x32_bf16 v[46:49], v[142:145], v[182:185], v[46:49]
	v_mfma_f32_16x16x32_bf16 v[42:45], v[150:153], v[182:185], v[42:45]
	v_mfma_f32_16x16x32_bf16 v[30:33], v[142:145], v[196:199], v[30:33]
	v_mfma_f32_16x16x32_bf16 v[26:29], v[150:153], v[196:199], v[26:29]
	v_mfma_f32_16x16x32_bf16 v[14:17], v[142:145], v[206:209], v[14:17]
	v_mfma_f32_16x16x32_bf16 v[10:13], v[150:153], v[206:209], v[10:13]
	s_setprio 0
	s_setprio 1
	v_mfma_f32_16x16x32_bf16 v[54:57], v[154:157], v[170:173], v[54:57]
	v_mfma_f32_16x16x32_bf16 v[50:53], v[162:165], v[170:173], v[50:53]
	v_mfma_f32_16x16x32_bf16 v[38:41], v[154:157], v[178:181], v[38:41]
	v_mfma_f32_16x16x32_bf16 v[34:37], v[162:165], v[178:181], v[34:37]
	v_mfma_f32_16x16x32_bf16 v[22:25], v[154:157], v[186:189], v[22:25]
	v_mfma_f32_16x16x32_bf16 v[18:21], v[162:165], v[186:189], v[18:21]
	v_mfma_f32_16x16x32_bf16 v[6:9], v[154:157], v[200:203], v[6:9]
	v_mfma_f32_16x16x32_bf16 v[2:5], v[162:165], v[200:203], v[2:5]
	v_mfma_f32_16x16x32_bf16 v[54:57], v[158:161], v[174:177], v[54:57]
	v_mfma_f32_16x16x32_bf16 v[50:53], v[166:169], v[174:177], v[50:53]
	v_mfma_f32_16x16x32_bf16 v[38:41], v[158:161], v[182:185], v[38:41]
	v_mfma_f32_16x16x32_bf16 v[34:37], v[166:169], v[182:185], v[34:37]
	v_mfma_f32_16x16x32_bf16 v[22:25], v[158:161], v[196:199], v[22:25]
	v_mfma_f32_16x16x32_bf16 v[18:21], v[166:169], v[196:199], v[18:21]
	v_mfma_f32_16x16x32_bf16 v[6:9], v[158:161], v[206:209], v[6:9]
	v_mfma_f32_16x16x32_bf16 v[2:5], v[166:169], v[206:209], v[2:5]
	s_setprio 0
	s_barrier
	s_add_i32 s76, s76, 2
	s_add_u32 s74, s74, 0x100
	s_addc_u32 s75, s75, 0
	s_add_u32 s52, s52, 0x100
	s_addc_u32 s53, s53, 0
	s_cmp_gt_u32 s76, 41
	s_cbranch_scc0 .LBB0_2082
	s_and_b64 vcc, exec, s[14:15]
	s_cbranch_vccz .LBB0_2085
	s_barrier
